# hand-written sliding-window depthwise conv (weights hoisted, 20 row loads in flight) + carried-MFMA GEMM schedule
# speedup vs baseline: 1.0326x; 1.0326x over previous
.LBB0_208:
	s_and_b32 s8, s66, 0xffffff80
	s_ashr_i32 s9, s8, 31
	s_lshl_b32 s7, s68, 11
	s_lshl_b64 s[8:9], s[8:9], 11
	s_and_b32 s20, s7, 0xfc0000
	s_add_i32 s2, s2, s3
	s_cmpk_gt_i32 s2, 0xc3f
	s_cselect_b64 s[54:55], -1, 0
	s_lshl_b32 s7, s2, 18
	s_and_b32 s7, s7, 0xfc0000
	s_add_u32 s7, s18, s7
	v_lshl_add_u64 v[126:127], v[114:115], 0, s[8:9]
	s_addc_u32 s10, s19, 0
	s_ashr_i32 s8, s2, 6
	s_ashr_i32 s9, s8, 31
	s_lshl_b64 s[8:9], s[8:9], 18
	v_lshl_add_u64 v[128:129], v[116:117], 0, s[20:21]
	s_add_u32 s20, s16, s8
	s_addc_u32 s11, s17, s9
	s_cmpk_lt_i32 s2, 0xc40
	s_cselect_b64 vcc, -1, 0
	s_and_b64 s[8:9], vcc, exec
	s_cselect_b32 s9, s10, 0
	s_cselect_b32 s8, s7, 0
	v_lshl_add_u64 v[2:3], s[8:9], 0, v[118:119]
	v_lshl_add_u64 v[0:1], v[122:123], 0, s[44:45]
	s_cselect_b32 s11, s11, 0
	s_cselect_b32 s10, s20, 0
	v_lshl_add_u64 v[2:3], v[2:3], 0, v[120:121]
	v_cndmask_b32_e32 v97, v1, v3, vcc
	v_cndmask_b32_e32 v98, v0, v2, vcc
	v_lshl_add_u64 v[0:1], s[10:11], 0, v[118:119]
	v_lshl_add_u64 v[0:1], v[0:1], 0, v[120:121]
	v_lshl_add_u64 v[2:3], v[124:125], 0, s[44:45]
	v_cndmask_b32_e32 v142, v2, v0, vcc
	v_mov_b32_e32 v0, 0
	v_lshl_add_u64 v[144:145], v[122:123], 0, s[28:29]
	v_lshl_add_u64 v[130:131], v[122:123], 0, s[30:31]
	v_lshl_add_u64 v[148:149], v[122:123], 0, s[34:35]
	v_lshl_add_u64 v[132:133], v[122:123], 0, s[36:37]
	v_lshl_add_u64 v[150:151], v[122:123], 0, s[38:39]
	v_lshl_add_u64 v[134:135], v[122:123], 0, s[40:41]
	v_lshl_add_u64 v[152:153], v[122:123], 0, s[42:43]
	v_lshl_add_u64 v[146:147], v[124:125], 0, s[28:29]
	v_lshl_add_u64 v[136:137], v[124:125], 0, s[30:31]
	v_lshl_add_u64 v[154:155], v[124:125], 0, s[34:35]
	v_lshl_add_u64 v[138:139], v[124:125], 0, s[36:37]
	v_lshl_add_u64 v[156:157], v[124:125], 0, s[38:39]
	v_lshl_add_u64 v[140:141], v[124:125], 0, s[40:41]
	v_lshl_add_u64 v[158:159], v[124:125], 0, s[42:43]
	v_cndmask_b32_e32 v143, v3, v1, vcc
	s_mov_b32 s7, -2
	v_mov_b32_e32 v1, v0
	v_mov_b32_e32 v2, v0
	v_mov_b32_e32 v3, v0
	v_mov_b32_e32 v20, v0
	v_mov_b32_e32 v21, v0
	v_mov_b32_e32 v22, v0
	v_mov_b32_e32 v23, v0
	v_mov_b32_e32 v24, v0
	v_mov_b32_e32 v25, v0
	v_mov_b32_e32 v26, v0
	v_mov_b32_e32 v27, v0
	v_mov_b32_e32 v32, v0
	v_mov_b32_e32 v33, v0
	v_mov_b32_e32 v34, v0
	v_mov_b32_e32 v35, v0
	v_mov_b32_e32 v8, v0
	v_mov_b32_e32 v9, v0
	v_mov_b32_e32 v10, v0
	v_mov_b32_e32 v11, v0
	v_mov_b32_e32 v4, v0
	v_mov_b32_e32 v5, v0
	v_mov_b32_e32 v6, v0
	v_mov_b32_e32 v7, v0
	v_mov_b32_e32 v12, v0
	v_mov_b32_e32 v13, v0
	v_mov_b32_e32 v14, v0
	v_mov_b32_e32 v15, v0
	v_mov_b32_e32 v16, v0
	v_mov_b32_e32 v17, v0
	v_mov_b32_e32 v18, v0
	v_mov_b32_e32 v19, v0
	v_mov_b32_e32 v28, v0
	v_mov_b32_e32 v29, v0
	v_mov_b32_e32 v30, v0
	v_mov_b32_e32 v31, v0
	v_mov_b32_e32 v36, v0
	v_mov_b32_e32 v37, v0
	v_mov_b32_e32 v38, v0
	v_mov_b32_e32 v39, v0
	v_mov_b32_e32 v40, v0
	v_mov_b32_e32 v41, v0
	v_mov_b32_e32 v42, v0
	v_mov_b32_e32 v43, v0
	v_mov_b32_e32 v44, v0
	v_mov_b32_e32 v45, v0
	v_mov_b32_e32 v46, v0
	v_mov_b32_e32 v47, v0
	v_mov_b32_e32 v48, v0
	v_mov_b32_e32 v49, v0
	v_mov_b32_e32 v50, v0
	v_mov_b32_e32 v51, v0
	v_mov_b32_e32 v52, v0
	v_mov_b32_e32 v53, v0
	v_mov_b32_e32 v54, v0
	v_mov_b32_e32 v55, v0
	v_mov_b32_e32 v56, v0
	v_mov_b32_e32 v57, v0
	v_mov_b32_e32 v58, v0
	v_mov_b32_e32 v59, v0
	v_mov_b32_e32 v60, v0
	v_mov_b32_e32 v61, v0
	v_mov_b32_e32 v62, v0
	v_mov_b32_e32 v63, v0
	v_readfirstlane_b32 s8, v122
	v_readfirstlane_b32 s9, v123
	v_readfirstlane_b32 s62, v124
	v_readfirstlane_b32 s63, v125
	v_readfirstlane_b32 s7, v247
	s_nop 3
	s_mul_i32 s64, s7, 0x4000
	s_sub_u32 s8, s8, s64
	s_subb_u32 s9, s9, 0
	s_sub_u32 s62, s62, s64
	s_subb_u32 s63, s63, 0
	s_lshl_b32 s7, s7, 12
	s_add_u32 m0, s7, 0x0
	v_mov_b32_e32 v60, 0
	global_load_lds_dwordx4 v248, s[8:9]
	v_mov_b32_e32 v61, 0
	s_add_u32 m0, s7, 0x400
	v_mov_b32_e32 v62, 0
	global_load_lds_dwordx4 v249, s[8:9]
	v_mov_b32_e32 v63, 0
	s_add_u32 m0, s7, 0x800
	v_mov_b32_e32 v56, 0
	global_load_lds_dwordx4 v250, s[8:9]
	v_mov_b32_e32 v57, 0
	s_add_u32 m0, s7, 0xc00
	v_mov_b32_e32 v58, 0
	global_load_lds_dwordx4 v251, s[8:9]
	v_mov_b32_e32 v59, 0
	s_add_u32 m0, s7, 0x8000
	v_mov_b32_e32 v52, 0
	global_load_lds_dwordx4 v248, s[62:63]
	v_mov_b32_e32 v53, 0
	s_add_u32 m0, s7, 0x8400
	v_mov_b32_e32 v54, 0
	global_load_lds_dwordx4 v249, s[62:63]
	v_mov_b32_e32 v55, 0
	s_add_u32 m0, s7, 0x8800
	v_mov_b32_e32 v48, 0
	global_load_lds_dwordx4 v250, s[62:63]
	v_mov_b32_e32 v49, 0
	s_add_u32 m0, s7, 0x8c00
	v_mov_b32_e32 v50, 0
	global_load_lds_dwordx4 v251, s[62:63]
	v_mov_b32_e32 v51, 0
	s_add_u32 s8, s8, 0x80
	s_addc_u32 s9, s9, 0
	s_add_u32 s62, s62, 0x80
	s_addc_u32 s63, s63, 0
	s_add_u32 m0, s7, 0x4000
	v_mov_b32_e32 v44, 0
	global_load_lds_dwordx4 v248, s[8:9]
	v_mov_b32_e32 v45, 0
	s_add_u32 m0, s7, 0x4400
	v_mov_b32_e32 v46, 0
	global_load_lds_dwordx4 v249, s[8:9]
	v_mov_b32_e32 v47, 0
	s_add_u32 m0, s7, 0x4800
	v_mov_b32_e32 v40, 0
	global_load_lds_dwordx4 v250, s[8:9]
	v_mov_b32_e32 v41, 0
	s_add_u32 m0, s7, 0x4c00
	v_mov_b32_e32 v42, 0
	global_load_lds_dwordx4 v251, s[8:9]
	v_mov_b32_e32 v43, 0
	s_add_u32 m0, s7, 0xc000
	v_mov_b32_e32 v36, 0
	global_load_lds_dwordx4 v248, s[62:63]
	v_mov_b32_e32 v37, 0
	s_add_u32 m0, s7, 0xc400
	v_mov_b32_e32 v38, 0
	global_load_lds_dwordx4 v249, s[62:63]
	v_mov_b32_e32 v39, 0
	s_add_u32 m0, s7, 0xc800
	v_mov_b32_e32 v28, 0
	global_load_lds_dwordx4 v250, s[62:63]
	v_mov_b32_e32 v29, 0
	s_add_u32 m0, s7, 0xcc00
	v_mov_b32_e32 v30, 0
	global_load_lds_dwordx4 v251, s[62:63]
	v_mov_b32_e32 v31, 0
	s_add_u32 s8, s8, 0x80
	s_addc_u32 s9, s9, 0
	s_add_u32 s62, s62, 0x80
	s_addc_u32 s63, s63, 0
	v_mov_b32_e32 v16, 0
	v_mov_b32_e32 v17, 0
	v_mov_b32_e32 v18, 0
	v_mov_b32_e32 v19, 0
	v_mov_b32_e32 v12, 0
	v_mov_b32_e32 v13, 0
	v_mov_b32_e32 v14, 0
	v_mov_b32_e32 v15, 0
	v_mov_b32_e32 v4, 0
	v_mov_b32_e32 v5, 0
	v_mov_b32_e32 v6, 0
	v_mov_b32_e32 v7, 0
	v_mov_b32_e32 v8, 0
	v_mov_b32_e32 v9, 0
	v_mov_b32_e32 v10, 0
	v_mov_b32_e32 v11, 0
	v_mov_b32_e32 v32, 0
	v_mov_b32_e32 v33, 0
	v_mov_b32_e32 v34, 0
	v_mov_b32_e32 v35, 0
	v_mov_b32_e32 v24, 0
	v_mov_b32_e32 v25, 0
	v_mov_b32_e32 v26, 0
	v_mov_b32_e32 v27, 0
	v_mov_b32_e32 v20, 0
	v_mov_b32_e32 v21, 0
	v_mov_b32_e32 v22, 0
	v_mov_b32_e32 v23, 0
	v_mov_b32_e32 v0, 0
	v_mov_b32_e32 v1, 0
	v_mov_b32_e32 v2, 0
	v_mov_b32_e32 v3, 0
	s_waitcnt vmcnt(8)
	s_barrier
	ds_read_b128 v[80:83], v252 offset:0
	ds_read_b128 v[144:147], v254 offset:32768
	ds_read_b128 v[148:151], v254 offset:34816
	ds_read_b128 v[152:155], v254 offset:36864
	ds_read_b128 v[156:159], v254 offset:38912
	ds_read_b128 v[84:87], v252 offset:2048
	ds_read_b128 v[88:91], v252 offset:4096
	ds_read_b128 v[92:95], v252 offset:6144
	ds_read_b128 v[124:127], v253 offset:0
	ds_read_b128 v[172:175], v255 offset:32768
	ds_read_b128 v[176:179], v255 offset:34816
	ds_read_b128 v[180:183], v255 offset:36864
	ds_read_b128 v[184:187], v255 offset:38912
	s_waitcnt lgkmcnt(11)
	v_mfma_f32_16x16x32_bf16 v[60:63], v[80:83], v[144:147], v[60:63]
	s_waitcnt lgkmcnt(10)
	v_mfma_f32_16x16x32_bf16 v[56:59], v[80:83], v[148:151], v[56:59]
	s_waitcnt lgkmcnt(9)
	v_mfma_f32_16x16x32_bf16 v[52:55], v[80:83], v[152:155], v[52:55]
	s_waitcnt lgkmcnt(8)
	v_mfma_f32_16x16x32_bf16 v[48:51], v[80:83], v[156:159], v[48:51]
	ds_read_b128 v[132:135], v253 offset:2048
	ds_read_b128 v[136:139], v253 offset:4096
	ds_read_b128 v[140:143], v253 offset:6144
	s_waitcnt lgkmcnt(10)
	v_mfma_f32_16x16x32_bf16 v[44:47], v[84:87], v[144:147], v[44:47]
	v_mfma_f32_16x16x32_bf16 v[40:43], v[84:87], v[148:151], v[40:43]
	v_mfma_f32_16x16x32_bf16 v[36:39], v[84:87], v[152:155], v[36:39]
	v_mfma_f32_16x16x32_bf16 v[28:31], v[84:87], v[156:159], v[28:31]
	s_waitcnt lgkmcnt(0)
	s_barrier
	s_add_u32 m0, s7, 0x0
	v_mfma_f32_16x16x32_bf16 v[16:19], v[88:91], v[144:147], v[16:19]
	global_load_lds_dwordx4 v248, s[8:9]
	s_add_u32 m0, s7, 0x400
	v_mfma_f32_16x16x32_bf16 v[12:15], v[88:91], v[148:151], v[12:15]
	global_load_lds_dwordx4 v249, s[8:9]
	s_add_u32 m0, s7, 0x800
	v_mfma_f32_16x16x32_bf16 v[4:7], v[88:91], v[152:155], v[4:7]
	global_load_lds_dwordx4 v250, s[8:9]
	s_add_u32 m0, s7, 0xc00
	v_mfma_f32_16x16x32_bf16 v[8:11], v[88:91], v[156:159], v[8:11]
	global_load_lds_dwordx4 v251, s[8:9]
	s_add_u32 m0, s7, 0x8000
	v_mfma_f32_16x16x32_bf16 v[32:35], v[92:95], v[144:147], v[32:35]
	global_load_lds_dwordx4 v248, s[62:63]
	s_add_u32 m0, s7, 0x8400
	v_mfma_f32_16x16x32_bf16 v[24:27], v[92:95], v[148:151], v[24:27]
	global_load_lds_dwordx4 v249, s[62:63]
	s_add_u32 m0, s7, 0x8800
	v_mfma_f32_16x16x32_bf16 v[20:23], v[92:95], v[152:155], v[20:23]
	global_load_lds_dwordx4 v250, s[62:63]
	s_add_u32 m0, s7, 0x8c00
	v_mfma_f32_16x16x32_bf16 v[0:3], v[92:95], v[156:159], v[0:3]
	global_load_lds_dwordx4 v251, s[62:63]
	s_add_u32 s8, s8, 0x80
	s_addc_u32 s9, s9, 0
	s_add_u32 s62, s62, 0x80
	s_addc_u32 s63, s63, 0
	s_waitcnt vmcnt(8)
	s_barrier
	ds_read_b128 v[80:83], v252 offset:16384
	ds_read_b128 v[144:147], v254 offset:49152
	ds_read_b128 v[148:151], v254 offset:51200
	ds_read_b128 v[152:155], v254 offset:53248
	ds_read_b128 v[156:159], v254 offset:55296
	ds_read_b128 v[84:87], v252 offset:18432
	ds_read_b128 v[88:91], v252 offset:20480
	ds_read_b128 v[92:95], v252 offset:22528
	v_mfma_f32_16x16x32_bf16 v[60:63], v[124:127], v[172:175], v[60:63]
	v_mfma_f32_16x16x32_bf16 v[56:59], v[124:127], v[176:179], v[56:59]
	v_mfma_f32_16x16x32_bf16 v[52:55], v[124:127], v[180:183], v[52:55]
	v_mfma_f32_16x16x32_bf16 v[48:51], v[124:127], v[184:187], v[48:51]
	v_mfma_f32_16x16x32_bf16 v[44:47], v[132:135], v[172:175], v[44:47]
	v_mfma_f32_16x16x32_bf16 v[40:43], v[132:135], v[176:179], v[40:43]
	v_mfma_f32_16x16x32_bf16 v[36:39], v[132:135], v[180:183], v[36:39]
	v_mfma_f32_16x16x32_bf16 v[28:31], v[132:135], v[184:187], v[28:31]
	v_mfma_f32_16x16x32_bf16 v[16:19], v[136:139], v[172:175], v[16:19]
	v_mfma_f32_16x16x32_bf16 v[12:15], v[136:139], v[176:179], v[12:15]
	v_mfma_f32_16x16x32_bf16 v[4:7], v[136:139], v[180:183], v[4:7]
	v_mfma_f32_16x16x32_bf16 v[8:11], v[136:139], v[184:187], v[8:11]
	v_mfma_f32_16x16x32_bf16 v[32:35], v[140:143], v[172:175], v[32:35]
	v_mfma_f32_16x16x32_bf16 v[24:27], v[140:143], v[176:179], v[24:27]
	v_mfma_f32_16x16x32_bf16 v[20:23], v[140:143], v[180:183], v[20:23]
	v_mfma_f32_16x16x32_bf16 v[0:3], v[140:143], v[184:187], v[0:3]
	ds_read_b128 v[124:127], v253 offset:16384
	ds_read_b128 v[172:175], v255 offset:49152
	ds_read_b128 v[176:179], v255 offset:51200
	ds_read_b128 v[180:183], v255 offset:53248
	ds_read_b128 v[184:187], v255 offset:55296
	ds_read_b128 v[132:135], v253 offset:18432
	ds_read_b128 v[136:139], v253 offset:20480
	ds_read_b128 v[140:143], v253 offset:22528
	s_waitcnt lgkmcnt(14)
	v_mfma_f32_16x16x32_bf16 v[60:63], v[80:83], v[144:147], v[60:63]
	s_waitcnt lgkmcnt(13)
	v_mfma_f32_16x16x32_bf16 v[56:59], v[80:83], v[148:151], v[56:59]
	s_waitcnt lgkmcnt(12)
	v_mfma_f32_16x16x32_bf16 v[52:55], v[80:83], v[152:155], v[52:55]
	s_waitcnt lgkmcnt(11)
	v_mfma_f32_16x16x32_bf16 v[48:51], v[80:83], v[156:159], v[48:51]
	s_waitcnt lgkmcnt(10)
	v_mfma_f32_16x16x32_bf16 v[44:47], v[84:87], v[144:147], v[44:47]
	v_mfma_f32_16x16x32_bf16 v[40:43], v[84:87], v[148:151], v[40:43]
	v_mfma_f32_16x16x32_bf16 v[36:39], v[84:87], v[152:155], v[36:39]
	v_mfma_f32_16x16x32_bf16 v[28:31], v[84:87], v[156:159], v[28:31]
	s_waitcnt lgkmcnt(0)
	s_barrier
	s_add_u32 m0, s7, 0x4000
	v_mfma_f32_16x16x32_bf16 v[16:19], v[88:91], v[144:147], v[16:19]
	global_load_lds_dwordx4 v248, s[8:9]
	s_add_u32 m0, s7, 0x4400
	v_mfma_f32_16x16x32_bf16 v[12:15], v[88:91], v[148:151], v[12:15]
	global_load_lds_dwordx4 v249, s[8:9]
	s_add_u32 m0, s7, 0x4800
	v_mfma_f32_16x16x32_bf16 v[4:7], v[88:91], v[152:155], v[4:7]
	global_load_lds_dwordx4 v250, s[8:9]
	s_add_u32 m0, s7, 0x4c00
	v_mfma_f32_16x16x32_bf16 v[8:11], v[88:91], v[156:159], v[8:11]
	global_load_lds_dwordx4 v251, s[8:9]
	s_add_u32 m0, s7, 0xc000
	v_mfma_f32_16x16x32_bf16 v[32:35], v[92:95], v[144:147], v[32:35]
	global_load_lds_dwordx4 v248, s[62:63]
	s_add_u32 m0, s7, 0xc400
	v_mfma_f32_16x16x32_bf16 v[24:27], v[92:95], v[148:151], v[24:27]
	global_load_lds_dwordx4 v249, s[62:63]
	s_add_u32 m0, s7, 0xc800
	v_mfma_f32_16x16x32_bf16 v[20:23], v[92:95], v[152:155], v[20:23]
	global_load_lds_dwordx4 v250, s[62:63]
	s_add_u32 m0, s7, 0xcc00
	v_mfma_f32_16x16x32_bf16 v[0:3], v[92:95], v[156:159], v[0:3]
	global_load_lds_dwordx4 v251, s[62:63]
	s_add_u32 s8, s8, 0x80
	s_addc_u32 s9, s9, 0
	s_add_u32 s62, s62, 0x80
	s_addc_u32 s63, s63, 0
	s_mov_b32 s32, 6
.Lg2_loop:
	s_waitcnt vmcnt(8)
	s_barrier
	ds_read_b128 v[80:83], v252 offset:0
	ds_read_b128 v[144:147], v254 offset:32768
	ds_read_b128 v[148:151], v254 offset:34816
	ds_read_b128 v[152:155], v254 offset:36864
	ds_read_b128 v[156:159], v254 offset:38912
	ds_read_b128 v[84:87], v252 offset:2048
	ds_read_b128 v[88:91], v252 offset:4096
	ds_read_b128 v[92:95], v252 offset:6144
	v_mfma_f32_16x16x32_bf16 v[60:63], v[124:127], v[172:175], v[60:63]
	v_mfma_f32_16x16x32_bf16 v[56:59], v[124:127], v[176:179], v[56:59]
	v_mfma_f32_16x16x32_bf16 v[52:55], v[124:127], v[180:183], v[52:55]
	v_mfma_f32_16x16x32_bf16 v[48:51], v[124:127], v[184:187], v[48:51]
	v_mfma_f32_16x16x32_bf16 v[44:47], v[132:135], v[172:175], v[44:47]
	v_mfma_f32_16x16x32_bf16 v[40:43], v[132:135], v[176:179], v[40:43]
	v_mfma_f32_16x16x32_bf16 v[36:39], v[132:135], v[180:183], v[36:39]
	v_mfma_f32_16x16x32_bf16 v[28:31], v[132:135], v[184:187], v[28:31]
	v_mfma_f32_16x16x32_bf16 v[16:19], v[136:139], v[172:175], v[16:19]
	v_mfma_f32_16x16x32_bf16 v[12:15], v[136:139], v[176:179], v[12:15]
	v_mfma_f32_16x16x32_bf16 v[4:7], v[136:139], v[180:183], v[4:7]
	v_mfma_f32_16x16x32_bf16 v[8:11], v[136:139], v[184:187], v[8:11]
	v_mfma_f32_16x16x32_bf16 v[32:35], v[140:143], v[172:175], v[32:35]
	v_mfma_f32_16x16x32_bf16 v[24:27], v[140:143], v[176:179], v[24:27]
	v_mfma_f32_16x16x32_bf16 v[20:23], v[140:143], v[180:183], v[20:23]
	v_mfma_f32_16x16x32_bf16 v[0:3], v[140:143], v[184:187], v[0:3]
	ds_read_b128 v[124:127], v253 offset:0
	ds_read_b128 v[172:175], v255 offset:32768
	ds_read_b128 v[176:179], v255 offset:34816
	ds_read_b128 v[180:183], v255 offset:36864
	ds_read_b128 v[184:187], v255 offset:38912
	ds_read_b128 v[132:135], v253 offset:2048
	ds_read_b128 v[136:139], v253 offset:4096
	ds_read_b128 v[140:143], v253 offset:6144
	s_waitcnt lgkmcnt(14)
	v_mfma_f32_16x16x32_bf16 v[60:63], v[80:83], v[144:147], v[60:63]
	s_waitcnt lgkmcnt(13)
	v_mfma_f32_16x16x32_bf16 v[56:59], v[80:83], v[148:151], v[56:59]
	s_waitcnt lgkmcnt(12)
	v_mfma_f32_16x16x32_bf16 v[52:55], v[80:83], v[152:155], v[52:55]
	s_waitcnt lgkmcnt(11)
	v_mfma_f32_16x16x32_bf16 v[48:51], v[80:83], v[156:159], v[48:51]
	s_waitcnt lgkmcnt(10)
	v_mfma_f32_16x16x32_bf16 v[44:47], v[84:87], v[144:147], v[44:47]
	v_mfma_f32_16x16x32_bf16 v[40:43], v[84:87], v[148:151], v[40:43]
	v_mfma_f32_16x16x32_bf16 v[36:39], v[84:87], v[152:155], v[36:39]
	v_mfma_f32_16x16x32_bf16 v[28:31], v[84:87], v[156:159], v[28:31]
	s_waitcnt lgkmcnt(0)
	s_barrier
	s_add_u32 m0, s7, 0x0
	v_mfma_f32_16x16x32_bf16 v[16:19], v[88:91], v[144:147], v[16:19]
	global_load_lds_dwordx4 v248, s[8:9]
	s_add_u32 m0, s7, 0x400
	v_mfma_f32_16x16x32_bf16 v[12:15], v[88:91], v[148:151], v[12:15]
	global_load_lds_dwordx4 v249, s[8:9]
	s_add_u32 m0, s7, 0x800
	v_mfma_f32_16x16x32_bf16 v[4:7], v[88:91], v[152:155], v[4:7]
	global_load_lds_dwordx4 v250, s[8:9]
	s_add_u32 m0, s7, 0xc00
	v_mfma_f32_16x16x32_bf16 v[8:11], v[88:91], v[156:159], v[8:11]
	global_load_lds_dwordx4 v251, s[8:9]
	s_add_u32 m0, s7, 0x8000
	v_mfma_f32_16x16x32_bf16 v[32:35], v[92:95], v[144:147], v[32:35]
	global_load_lds_dwordx4 v248, s[62:63]
	s_add_u32 m0, s7, 0x8400
	v_mfma_f32_16x16x32_bf16 v[24:27], v[92:95], v[148:151], v[24:27]
	global_load_lds_dwordx4 v249, s[62:63]
	s_add_u32 m0, s7, 0x8800
	v_mfma_f32_16x16x32_bf16 v[20:23], v[92:95], v[152:155], v[20:23]
	global_load_lds_dwordx4 v250, s[62:63]
	s_add_u32 m0, s7, 0x8c00
	v_mfma_f32_16x16x32_bf16 v[0:3], v[92:95], v[156:159], v[0:3]
	global_load_lds_dwordx4 v251, s[62:63]
	s_add_u32 s8, s8, 0x80
	s_addc_u32 s9, s9, 0
	s_add_u32 s62, s62, 0x80
	s_addc_u32 s63, s63, 0
	s_waitcnt vmcnt(8)
	s_barrier
	ds_read_b128 v[80:83], v252 offset:16384
	ds_read_b128 v[144:147], v254 offset:49152
	ds_read_b128 v[148:151], v254 offset:51200
	ds_read_b128 v[152:155], v254 offset:53248
	ds_read_b128 v[156:159], v254 offset:55296
	ds_read_b128 v[84:87], v252 offset:18432
	ds_read_b128 v[88:91], v252 offset:20480
	ds_read_b128 v[92:95], v252 offset:22528
	v_mfma_f32_16x16x32_bf16 v[60:63], v[124:127], v[172:175], v[60:63]
	v_mfma_f32_16x16x32_bf16 v[56:59], v[124:127], v[176:179], v[56:59]
	v_mfma_f32_16x16x32_bf16 v[52:55], v[124:127], v[180:183], v[52:55]
	v_mfma_f32_16x16x32_bf16 v[48:51], v[124:127], v[184:187], v[48:51]
	v_mfma_f32_16x16x32_bf16 v[44:47], v[132:135], v[172:175], v[44:47]
	v_mfma_f32_16x16x32_bf16 v[40:43], v[132:135], v[176:179], v[40:43]
	v_mfma_f32_16x16x32_bf16 v[36:39], v[132:135], v[180:183], v[36:39]
	v_mfma_f32_16x16x32_bf16 v[28:31], v[132:135], v[184:187], v[28:31]
	v_mfma_f32_16x16x32_bf16 v[16:19], v[136:139], v[172:175], v[16:19]
	v_mfma_f32_16x16x32_bf16 v[12:15], v[136:139], v[176:179], v[12:15]
	v_mfma_f32_16x16x32_bf16 v[4:7], v[136:139], v[180:183], v[4:7]
	v_mfma_f32_16x16x32_bf16 v[8:11], v[136:139], v[184:187], v[8:11]
	v_mfma_f32_16x16x32_bf16 v[32:35], v[140:143], v[172:175], v[32:35]
	v_mfma_f32_16x16x32_bf16 v[24:27], v[140:143], v[176:179], v[24:27]
	v_mfma_f32_16x16x32_bf16 v[20:23], v[140:143], v[180:183], v[20:23]
	v_mfma_f32_16x16x32_bf16 v[0:3], v[140:143], v[184:187], v[0:3]
	ds_read_b128 v[124:127], v253 offset:16384
	ds_read_b128 v[172:175], v255 offset:49152
	ds_read_b128 v[176:179], v255 offset:51200
	ds_read_b128 v[180:183], v255 offset:53248
	ds_read_b128 v[184:187], v255 offset:55296
	ds_read_b128 v[132:135], v253 offset:18432
	ds_read_b128 v[136:139], v253 offset:20480
	ds_read_b128 v[140:143], v253 offset:22528
	s_waitcnt lgkmcnt(14)
	v_mfma_f32_16x16x32_bf16 v[60:63], v[80:83], v[144:147], v[60:63]
	s_waitcnt lgkmcnt(13)
	v_mfma_f32_16x16x32_bf16 v[56:59], v[80:83], v[148:151], v[56:59]
	s_waitcnt lgkmcnt(12)
	v_mfma_f32_16x16x32_bf16 v[52:55], v[80:83], v[152:155], v[52:55]
	s_waitcnt lgkmcnt(11)
	v_mfma_f32_16x16x32_bf16 v[48:51], v[80:83], v[156:159], v[48:51]
	s_waitcnt lgkmcnt(10)
	v_mfma_f32_16x16x32_bf16 v[44:47], v[84:87], v[144:147], v[44:47]
	v_mfma_f32_16x16x32_bf16 v[40:43], v[84:87], v[148:151], v[40:43]
	v_mfma_f32_16x16x32_bf16 v[36:39], v[84:87], v[152:155], v[36:39]
	v_mfma_f32_16x16x32_bf16 v[28:31], v[84:87], v[156:159], v[28:31]
	s_waitcnt lgkmcnt(0)
	s_barrier
	s_add_u32 m0, s7, 0x4000
	v_mfma_f32_16x16x32_bf16 v[16:19], v[88:91], v[144:147], v[16:19]
	global_load_lds_dwordx4 v248, s[8:9]
	s_add_u32 m0, s7, 0x4400
	v_mfma_f32_16x16x32_bf16 v[12:15], v[88:91], v[148:151], v[12:15]
	global_load_lds_dwordx4 v249, s[8:9]
	s_add_u32 m0, s7, 0x4800
	v_mfma_f32_16x16x32_bf16 v[4:7], v[88:91], v[152:155], v[4:7]
	global_load_lds_dwordx4 v250, s[8:9]
	s_add_u32 m0, s7, 0x4c00
	v_mfma_f32_16x16x32_bf16 v[8:11], v[88:91], v[156:159], v[8:11]
	global_load_lds_dwordx4 v251, s[8:9]
	s_add_u32 m0, s7, 0xc000
	v_mfma_f32_16x16x32_bf16 v[32:35], v[92:95], v[144:147], v[32:35]
	global_load_lds_dwordx4 v248, s[62:63]
	s_add_u32 m0, s7, 0xc400
	v_mfma_f32_16x16x32_bf16 v[24:27], v[92:95], v[148:151], v[24:27]
	global_load_lds_dwordx4 v249, s[62:63]
	s_add_u32 m0, s7, 0xc800
	v_mfma_f32_16x16x32_bf16 v[20:23], v[92:95], v[152:155], v[20:23]
	global_load_lds_dwordx4 v250, s[62:63]
	s_add_u32 m0, s7, 0xcc00
	v_mfma_f32_16x16x32_bf16 v[0:3], v[92:95], v[156:159], v[0:3]
	global_load_lds_dwordx4 v251, s[62:63]
	s_add_u32 s8, s8, 0x80
	s_addc_u32 s9, s9, 0
	s_add_u32 s62, s62, 0x80
	s_addc_u32 s63, s63, 0
	s_sub_u32 s32, s32, 1
	s_cmp_lg_u32 s32, 0
	s_cbranch_scc1 .Lg2_loop
	s_waitcnt vmcnt(8)
	s_barrier
	ds_read_b128 v[80:83], v252 offset:0
	ds_read_b128 v[144:147], v254 offset:32768
	ds_read_b128 v[148:151], v254 offset:34816
	ds_read_b128 v[152:155], v254 offset:36864
	ds_read_b128 v[156:159], v254 offset:38912
	ds_read_b128 v[84:87], v252 offset:2048
	ds_read_b128 v[88:91], v252 offset:4096
	ds_read_b128 v[92:95], v252 offset:6144
	v_mfma_f32_16x16x32_bf16 v[60:63], v[124:127], v[172:175], v[60:63]
	v_mfma_f32_16x16x32_bf16 v[56:59], v[124:127], v[176:179], v[56:59]
	v_mfma_f32_16x16x32_bf16 v[52:55], v[124:127], v[180:183], v[52:55]
	v_mfma_f32_16x16x32_bf16 v[48:51], v[124:127], v[184:187], v[48:51]
	v_mfma_f32_16x16x32_bf16 v[44:47], v[132:135], v[172:175], v[44:47]
	v_mfma_f32_16x16x32_bf16 v[40:43], v[132:135], v[176:179], v[40:43]
	v_mfma_f32_16x16x32_bf16 v[36:39], v[132:135], v[180:183], v[36:39]
	v_mfma_f32_16x16x32_bf16 v[28:31], v[132:135], v[184:187], v[28:31]
	v_mfma_f32_16x16x32_bf16 v[16:19], v[136:139], v[172:175], v[16:19]
	v_mfma_f32_16x16x32_bf16 v[12:15], v[136:139], v[176:179], v[12:15]
	v_mfma_f32_16x16x32_bf16 v[4:7], v[136:139], v[180:183], v[4:7]
	v_mfma_f32_16x16x32_bf16 v[8:11], v[136:139], v[184:187], v[8:11]
	v_mfma_f32_16x16x32_bf16 v[32:35], v[140:143], v[172:175], v[32:35]
	v_mfma_f32_16x16x32_bf16 v[24:27], v[140:143], v[176:179], v[24:27]
	v_mfma_f32_16x16x32_bf16 v[20:23], v[140:143], v[180:183], v[20:23]
	v_mfma_f32_16x16x32_bf16 v[0:3], v[140:143], v[184:187], v[0:3]
	ds_read_b128 v[124:127], v253 offset:0
	ds_read_b128 v[172:175], v255 offset:32768
	ds_read_b128 v[176:179], v255 offset:34816
	ds_read_b128 v[180:183], v255 offset:36864
	ds_read_b128 v[184:187], v255 offset:38912
	ds_read_b128 v[132:135], v253 offset:2048
	ds_read_b128 v[136:139], v253 offset:4096
	ds_read_b128 v[140:143], v253 offset:6144
	s_waitcnt lgkmcnt(14)
	v_mfma_f32_16x16x32_bf16 v[60:63], v[80:83], v[144:147], v[60:63]
	s_waitcnt lgkmcnt(13)
	v_mfma_f32_16x16x32_bf16 v[56:59], v[80:83], v[148:151], v[56:59]
	s_waitcnt lgkmcnt(12)
	v_mfma_f32_16x16x32_bf16 v[52:55], v[80:83], v[152:155], v[52:55]
	s_waitcnt lgkmcnt(11)
	v_mfma_f32_16x16x32_bf16 v[48:51], v[80:83], v[156:159], v[48:51]
	s_waitcnt lgkmcnt(10)
	v_mfma_f32_16x16x32_bf16 v[44:47], v[84:87], v[144:147], v[44:47]
	v_mfma_f32_16x16x32_bf16 v[40:43], v[84:87], v[148:151], v[40:43]
	v_mfma_f32_16x16x32_bf16 v[36:39], v[84:87], v[152:155], v[36:39]
	v_mfma_f32_16x16x32_bf16 v[28:31], v[84:87], v[156:159], v[28:31]
	s_waitcnt lgkmcnt(0)
	s_barrier
	v_mfma_f32_16x16x32_bf16 v[16:19], v[88:91], v[144:147], v[16:19]
	v_mfma_f32_16x16x32_bf16 v[12:15], v[88:91], v[148:151], v[12:15]
	v_mfma_f32_16x16x32_bf16 v[4:7], v[88:91], v[152:155], v[4:7]
	v_mfma_f32_16x16x32_bf16 v[8:11], v[88:91], v[156:159], v[8:11]
	v_mfma_f32_16x16x32_bf16 v[32:35], v[92:95], v[144:147], v[32:35]
	v_mfma_f32_16x16x32_bf16 v[24:27], v[92:95], v[148:151], v[24:27]
	v_mfma_f32_16x16x32_bf16 v[20:23], v[92:95], v[152:155], v[20:23]
	v_mfma_f32_16x16x32_bf16 v[0:3], v[92:95], v[156:159], v[0:3]
	s_waitcnt vmcnt(0)
	s_barrier
	ds_read_b128 v[80:83], v252 offset:16384
	ds_read_b128 v[144:147], v254 offset:49152
	ds_read_b128 v[148:151], v254 offset:51200
	ds_read_b128 v[152:155], v254 offset:53248
	ds_read_b128 v[156:159], v254 offset:55296
	ds_read_b128 v[84:87], v252 offset:18432
	ds_read_b128 v[88:91], v252 offset:20480
	ds_read_b128 v[92:95], v252 offset:22528
	v_mfma_f32_16x16x32_bf16 v[60:63], v[124:127], v[172:175], v[60:63]
	v_mfma_f32_16x16x32_bf16 v[56:59], v[124:127], v[176:179], v[56:59]
	v_mfma_f32_16x16x32_bf16 v[52:55], v[124:127], v[180:183], v[52:55]
	v_mfma_f32_16x16x32_bf16 v[48:51], v[124:127], v[184:187], v[48:51]
	v_mfma_f32_16x16x32_bf16 v[44:47], v[132:135], v[172:175], v[44:47]
	v_mfma_f32_16x16x32_bf16 v[40:43], v[132:135], v[176:179], v[40:43]
	v_mfma_f32_16x16x32_bf16 v[36:39], v[132:135], v[180:183], v[36:39]
	v_mfma_f32_16x16x32_bf16 v[28:31], v[132:135], v[184:187], v[28:31]
	v_mfma_f32_16x16x32_bf16 v[16:19], v[136:139], v[172:175], v[16:19]
	v_mfma_f32_16x16x32_bf16 v[12:15], v[136:139], v[176:179], v[12:15]
	v_mfma_f32_16x16x32_bf16 v[4:7], v[136:139], v[180:183], v[4:7]
	v_mfma_f32_16x16x32_bf16 v[8:11], v[136:139], v[184:187], v[8:11]
	v_mfma_f32_16x16x32_bf16 v[32:35], v[140:143], v[172:175], v[32:35]
	v_mfma_f32_16x16x32_bf16 v[24:27], v[140:143], v[176:179], v[24:27]
	v_mfma_f32_16x16x32_bf16 v[20:23], v[140:143], v[180:183], v[20:23]
	v_mfma_f32_16x16x32_bf16 v[0:3], v[140:143], v[184:187], v[0:3]
	ds_read_b128 v[124:127], v253 offset:16384
	ds_read_b128 v[172:175], v255 offset:49152
	ds_read_b128 v[176:179], v255 offset:51200
	ds_read_b128 v[180:183], v255 offset:53248
	ds_read_b128 v[184:187], v255 offset:55296
	ds_read_b128 v[132:135], v253 offset:18432
	ds_read_b128 v[136:139], v253 offset:20480
	ds_read_b128 v[140:143], v253 offset:22528
	s_waitcnt lgkmcnt(14)
	v_mfma_f32_16x16x32_bf16 v[60:63], v[80:83], v[144:147], v[60:63]
	s_waitcnt lgkmcnt(13)
	v_mfma_f32_16x16x32_bf16 v[56:59], v[80:83], v[148:151], v[56:59]
	s_waitcnt lgkmcnt(12)
	v_mfma_f32_16x16x32_bf16 v[52:55], v[80:83], v[152:155], v[52:55]
	s_waitcnt lgkmcnt(11)
	v_mfma_f32_16x16x32_bf16 v[48:51], v[80:83], v[156:159], v[48:51]
	s_waitcnt lgkmcnt(10)
	v_mfma_f32_16x16x32_bf16 v[44:47], v[84:87], v[144:147], v[44:47]
	v_mfma_f32_16x16x32_bf16 v[40:43], v[84:87], v[148:151], v[40:43]
	v_mfma_f32_16x16x32_bf16 v[36:39], v[84:87], v[152:155], v[36:39]
	v_mfma_f32_16x16x32_bf16 v[28:31], v[84:87], v[156:159], v[28:31]
	s_waitcnt lgkmcnt(0)
	s_barrier
	v_mfma_f32_16x16x32_bf16 v[16:19], v[88:91], v[144:147], v[16:19]
	v_mfma_f32_16x16x32_bf16 v[12:15], v[88:91], v[148:151], v[12:15]
	v_mfma_f32_16x16x32_bf16 v[4:7], v[88:91], v[152:155], v[4:7]
	v_mfma_f32_16x16x32_bf16 v[8:11], v[88:91], v[156:159], v[8:11]
	v_mfma_f32_16x16x32_bf16 v[32:35], v[92:95], v[144:147], v[32:35]
	v_mfma_f32_16x16x32_bf16 v[24:27], v[92:95], v[148:151], v[24:27]
	v_mfma_f32_16x16x32_bf16 v[20:23], v[92:95], v[152:155], v[20:23]
	v_mfma_f32_16x16x32_bf16 v[0:3], v[92:95], v[156:159], v[0:3]
	v_mfma_f32_16x16x32_bf16 v[60:63], v[124:127], v[172:175], v[60:63]
	v_mfma_f32_16x16x32_bf16 v[56:59], v[124:127], v[176:179], v[56:59]
	v_mfma_f32_16x16x32_bf16 v[52:55], v[124:127], v[180:183], v[52:55]
	v_mfma_f32_16x16x32_bf16 v[48:51], v[124:127], v[184:187], v[48:51]
	v_mfma_f32_16x16x32_bf16 v[44:47], v[132:135], v[172:175], v[44:47]
	v_mfma_f32_16x16x32_bf16 v[40:43], v[132:135], v[176:179], v[40:43]
	v_mfma_f32_16x16x32_bf16 v[36:39], v[132:135], v[180:183], v[36:39]
	v_mfma_f32_16x16x32_bf16 v[28:31], v[132:135], v[184:187], v[28:31]
	v_mfma_f32_16x16x32_bf16 v[16:19], v[136:139], v[172:175], v[16:19]
	v_mfma_f32_16x16x32_bf16 v[12:15], v[136:139], v[176:179], v[12:15]
	v_mfma_f32_16x16x32_bf16 v[4:7], v[136:139], v[180:183], v[4:7]
	v_mfma_f32_16x16x32_bf16 v[8:11], v[136:139], v[184:187], v[8:11]
	v_mfma_f32_16x16x32_bf16 v[32:35], v[140:143], v[172:175], v[32:35]
	v_mfma_f32_16x16x32_bf16 v[24:27], v[140:143], v[176:179], v[24:27]
	v_mfma_f32_16x16x32_bf16 v[20:23], v[140:143], v[180:183], v[20:23]
	v_mfma_f32_16x16x32_bf16 v[0:3], v[140:143], v[184:187], v[0:3]
	s_nop 7
	s_nop 1
	v_add_u32_e32 v80, s12, v168
	v_or_b32_e32 v64, s6, v169
	s_cmpk_gt_i32 s6, 0x3ff
	s_mov_b64 s[6:7], -1
	s_cbranch_scc0 .LBB0_416
	s_cmpk_gt_u32 s13, 0xbff
	s_cbranch_scc0 .LBB0_413
	s_cmpk_gt_u32 s13, 0x13ff
	s_cbranch_scc0 .LBB0_236
	s_cmpk_gt_u32 s13, 0x17ff
	s_cbranch_scc0 .LBB0_217
	s_and_saveexec_b64 s[6:7], s[4:5]
	s_cbranch_execz .LBB0_216
	v_lshlrev_b32_e32 v98, 7, v80
	v_lshl_add_u64 v[66:67], v[104:105], 0, v[98:99]
	global_store_dword v[66:67], v60, off
	global_store_dword v[66:67], v61, off offset:128
	global_store_dword v[66:67], v62, off offset:256
	global_store_dword v[66:67], v63, off offset:384
	global_store_dword v[66:67], v56, off offset:64
	global_store_dword v[66:67], v57, off offset:192
	global_store_dword v[66:67], v58, off offset:320
	global_store_dword v[66:67], v59, off offset:448
	global_store_dword v[66:67], v44, off offset:2048
	global_store_dword v[66:67], v45, off offset:2176
	global_store_dword v[66:67], v46, off offset:2304
	global_store_dword v[66:67], v47, off offset:2432
	global_store_dword v[66:67], v40, off offset:2112
	global_store_dword v[66:67], v41, off offset:2240
	global_store_dword v[66:67], v42, off offset:2368
	global_store_dword v[66:67], v43, off offset:2496
	v_or_b32_e32 v66, 0x1000, v98
	v_mov_b32_e32 v67, v99
	v_lshl_add_u64 v[68:69], v[104:105], 0, v[66:67]
	global_store_dword v[68:69], v16, off
	v_or_b32_e32 v68, 0x1080, v98
	v_mov_b32_e32 v69, v99
	v_lshl_add_u64 v[70:71], v[104:105], 0, v[68:69]
	global_store_dword v[70:71], v17, off
	v_or_b32_e32 v70, 0x1100, v98
	v_mov_b32_e32 v71, v99
	v_lshl_add_u64 v[66:67], v[106:107], 0, v[66:67]
	v_lshl_add_u64 v[72:73], v[104:105], 0, v[70:71]
	global_store_dword v[66:67], v12, off
	v_lshl_add_u64 v[66:67], v[106:107], 0, v[68:69]
	global_store_dword v[72:73], v18, off
	v_or_b32_e32 v72, 0x1180, v98
	v_mov_b32_e32 v73, v99
	global_store_dword v[66:67], v13, off
	v_lshl_add_u64 v[66:67], v[106:107], 0, v[70:71]
	global_store_dword v[66:67], v14, off
	v_lshl_add_u64 v[66:67], v[106:107], 0, v[72:73]
	global_store_dword v[66:67], v15, off
	v_or_b32_e32 v66, 0x1800, v98
	v_mov_b32_e32 v67, v99
	v_lshl_add_u64 v[68:69], v[104:105], 0, v[66:67]
	global_store_dword v[68:69], v32, off
	v_or_b32_e32 v68, 0x1880, v98
	v_mov_b32_e32 v69, v99
	v_lshl_add_u64 v[70:71], v[104:105], 0, v[68:69]
	v_lshl_add_u64 v[66:67], v[106:107], 0, v[66:67]
	global_store_dword v[70:71], v33, off
	v_or_b32_e32 v70, 0x1900, v98
	v_mov_b32_e32 v71, v99
	global_store_dword v[66:67], v24, off
	v_lshl_add_u64 v[66:67], v[106:107], 0, v[68:69]
	v_lshl_add_u64 v[74:75], v[104:105], 0, v[72:73]
	v_lshl_add_u64 v[72:73], v[104:105], 0, v[70:71]
	v_or_b32_e32 v98, 0x1980, v98
	global_store_dword v[66:67], v25, off
	v_lshl_add_u64 v[66:67], v[106:107], 0, v[70:71]
	global_store_dword v[72:73], v34, off
	v_lshl_add_u64 v[72:73], v[104:105], 0, v[98:99]
	global_store_dword v[66:67], v26, off
	v_lshl_add_u64 v[66:67], v[106:107], 0, v[98:99]
	global_store_dword v[74:75], v19, off
	global_store_dword v[72:73], v35, off
	global_store_dword v[66:67], v27, off

.LBB0_472:
	s_cmp_gt_i32 s60, 3
	s_cselect_b64 s[2:3], -1, 0
	s_cmp_lt_i32 s61, 3
	s_cselect_b64 s[4:5], -1, 0
	s_or_b64 s[2:3], s[2:3], s[4:5]
	s_and_b64 vcc, exec, s[2:3]
	v_lshl_add_u32 v128, s58, 8, v162
	s_cbranch_vccnz .LBB0_545
	s_mov_b64 s[16:17], s[0:1]
	s_load_dword s2, s[0:1], 0xf0
	s_load_dwordx2 s[14:15], s[16:17], 0xe0
	v_lshl_add_u32 v8, s58, 8, v162
	s_add_u32 s6, s0, 0xf0
	s_mov_b32 s3, 0x200000
	s_addc_u32 s7, s1, 0
	s_waitcnt lgkmcnt(0)
	s_lshl_b32 s12, s2, 8
	v_cmp_gt_i32_e32 vcc, s3, v8
	s_and_saveexec_b64 s[18:19], vcc
	s_cbranch_execz .LBB0_486
	s_load_dwordx4 s[48:51], s[0:1], 0x68
	s_load_dword s64, s[0:1], 0xf0
	v_lshlrev_b32_e32 v26, 4, v162
	v_lshlrev_b32_e32 v27, 5, v162
	s_waitcnt lgkmcnt(0)
	global_load_dwordx4 v[28:31], v27, s[48:49]
	global_load_dwordx4 v[32:35], v27, s[48:49] offset:16
	s_add_u32 s48, s48, 0x2000
	s_addc_u32 s49, s49, 0
	global_load_dwordx4 v[36:39], v27, s[48:49]
	global_load_dwordx4 v[40:43], v27, s[48:49] offset:16
	s_add_u32 s48, s48, 0x2000
	s_addc_u32 s49, s49, 0
	global_load_dwordx4 v[44:47], v27, s[48:49]
	global_load_dwordx4 v[48:51], v27, s[48:49] offset:16
	s_add_u32 s48, s48, 0x2000
	s_addc_u32 s49, s49, 0
	global_load_dwordx4 v[52:55], v27, s[48:49]
	global_load_dwordx4 v[56:59], v27, s[48:49] offset:16
	s_add_u32 s48, s48, 0x2000
	s_addc_u32 s49, s49, 0
	global_load_dwordx4 v[60:63], v27, s[48:49]
	global_load_dwordx4 v[64:67], v27, s[48:49] offset:16
	global_load_dwordx4 v[68:71], v27, s[50:51]
	global_load_dwordx4 v[72:75], v27, s[50:51] offset:16
	s_mov_b32 s3, s58
.Lcv3_rb:
	s_cmp_lt_u32 s3, 0x200
	s_cbranch_scc0 .Lcv3_end
	s_lshl_b32 s32, s3, 4
	s_cmp_lt_u32 s32, 0x1000
	s_mov_b32 s59, 0x3ff
	s_cselect_b32 s59, 0xff, s59
	s_and_b32 s65, s32, s59
	s_cmp_lg_u32 s65, 0
	s_cselect_b32 s62, -1, 0
	s_add_u32 s65, s65, 15
	s_cmp_lg_u32 s65, s59
	s_cselect_b32 s63, -1, 0
	s_lshl_b32 s65, s32, 12
	s_add_u32 s4, s14, 0xab7a100
	s_addc_u32 s5, s15, 0
	s_add_u32 s4, s4, s65
	s_addc_u32 s5, s5, 0
	s_sub_u32 s4, s4, 0x2000
	s_subb_u32 s5, s5, 0
	s_add_u32 s54, s14, 0x1037a100
	s_addc_u32 s55, s15, 0
	s_add_u32 s54, s54, s65
	s_addc_u32 s55, s55, 0
	global_load_dwordx4 v[76:79], v26, s[4:5]
	s_add_u32 s4, s4, 0x1000
	s_addc_u32 s5, s5, 0
	global_load_dwordx4 v[80:83], v26, s[4:5]
	s_add_u32 s4, s4, 0x1000
	s_addc_u32 s5, s5, 0
	global_load_dwordx4 v[84:87], v26, s[4:5]
	s_add_u32 s4, s4, 0x1000
	s_addc_u32 s5, s5, 0
	global_load_dwordx4 v[88:91], v26, s[4:5]
	s_add_u32 s4, s4, 0x1000
	s_addc_u32 s5, s5, 0
	global_load_dwordx4 v[92:95], v26, s[4:5]
	s_add_u32 s4, s4, 0x1000
	s_addc_u32 s5, s5, 0
	global_load_dwordx4 v[96:99], v26, s[4:5]
	s_add_u32 s4, s4, 0x1000
	s_addc_u32 s5, s5, 0
	global_load_dwordx4 v[100:103], v26, s[4:5]
	s_add_u32 s4, s4, 0x1000
	s_addc_u32 s5, s5, 0
	global_load_dwordx4 v[104:107], v26, s[4:5]
	s_add_u32 s4, s4, 0x1000
	s_addc_u32 s5, s5, 0
	global_load_dwordx4 v[108:111], v26, s[4:5]
	s_add_u32 s4, s4, 0x1000
	s_addc_u32 s5, s5, 0
	global_load_dwordx4 v[112:115], v26, s[4:5]
	s_add_u32 s4, s4, 0x1000
	s_addc_u32 s5, s5, 0
	global_load_dwordx4 v[116:119], v26, s[4:5]
	s_add_u32 s4, s4, 0x1000
	s_addc_u32 s5, s5, 0
	global_load_dwordx4 v[120:123], v26, s[4:5]
	s_add_u32 s4, s4, 0x1000
	s_addc_u32 s5, s5, 0
	global_load_dwordx4 v[124:127], v26, s[4:5]
	s_add_u32 s4, s4, 0x1000
	s_addc_u32 s5, s5, 0
	global_load_dwordx4 v[132:135], v26, s[4:5]
	s_add_u32 s4, s4, 0x1000
	s_addc_u32 s5, s5, 0
	global_load_dwordx4 v[136:139], v26, s[4:5]
	s_add_u32 s4, s4, 0x1000
	s_addc_u32 s5, s5, 0
	global_load_dwordx4 v[140:143], v26, s[4:5]
	s_add_u32 s4, s4, 0x1000
	s_addc_u32 s5, s5, 0
	global_load_dwordx4 v[144:147], v26, s[4:5]
	s_add_u32 s4, s4, 0x1000
	s_addc_u32 s5, s5, 0
	global_load_dwordx4 v[148:151], v26, s[4:5]
	s_add_u32 s4, s4, 0x1000
	s_addc_u32 s5, s5, 0
	global_load_dwordx4 v[152:155], v26, s[4:5]
	s_add_u32 s4, s4, 0x1000
	s_addc_u32 s5, s5, 0
	global_load_dwordx4 v[156:159], v26, s[4:5]
	s_waitcnt vmcnt(19)
	v_and_b32_e32 v76, s62, v76
	v_and_b32_e32 v77, s62, v77
	v_and_b32_e32 v78, s62, v78
	v_and_b32_e32 v79, s62, v79
	v_lshlrev_b32_e32 v172, 16, v76
	v_and_b32_e32 v173, 0xffff0000, v76
	v_lshlrev_b32_e32 v174, 16, v77
	v_and_b32_e32 v175, 0xffff0000, v77
	v_lshlrev_b32_e32 v176, 16, v78
	v_and_b32_e32 v177, 0xffff0000, v78
	v_lshlrev_b32_e32 v178, 16, v79
	v_and_b32_e32 v179, 0xffff0000, v79
	v_pk_fma_f32 v[180:181], v[28:29], v[172:173], v[68:69]
	v_pk_fma_f32 v[182:183], v[30:31], v[174:175], v[70:71]
	v_pk_fma_f32 v[184:185], v[32:33], v[176:177], v[72:73]
	v_pk_fma_f32 v[186:187], v[34:35], v[178:179], v[74:75]
	s_waitcnt vmcnt(18)
	v_and_b32_e32 v80, s62, v80
	v_and_b32_e32 v81, s62, v81
	v_and_b32_e32 v82, s62, v82
	v_and_b32_e32 v83, s62, v83
	v_lshlrev_b32_e32 v172, 16, v80
	v_and_b32_e32 v173, 0xffff0000, v80
	v_lshlrev_b32_e32 v174, 16, v81
	v_and_b32_e32 v175, 0xffff0000, v81
	v_lshlrev_b32_e32 v176, 16, v82
	v_and_b32_e32 v177, 0xffff0000, v82
	v_lshlrev_b32_e32 v178, 16, v83
	v_and_b32_e32 v179, 0xffff0000, v83
	v_pk_fma_f32 v[188:189], v[28:29], v[172:173], v[68:69]
	v_pk_fma_f32 v[190:191], v[30:31], v[174:175], v[70:71]
	v_pk_fma_f32 v[192:193], v[32:33], v[176:177], v[72:73]
	v_pk_fma_f32 v[194:195], v[34:35], v[178:179], v[74:75]
	v_pk_fma_f32 v[180:181], v[36:37], v[172:173], v[180:181]
	v_pk_fma_f32 v[182:183], v[38:39], v[174:175], v[182:183]
	v_pk_fma_f32 v[184:185], v[40:41], v[176:177], v[184:185]
	v_pk_fma_f32 v[186:187], v[42:43], v[178:179], v[186:187]
	s_waitcnt vmcnt(17)
	v_lshlrev_b32_e32 v172, 16, v84
	v_and_b32_e32 v173, 0xffff0000, v84
	v_lshlrev_b32_e32 v174, 16, v85
	v_and_b32_e32 v175, 0xffff0000, v85
	v_lshlrev_b32_e32 v176, 16, v86
	v_and_b32_e32 v177, 0xffff0000, v86
	v_lshlrev_b32_e32 v178, 16, v87
	v_and_b32_e32 v179, 0xffff0000, v87
	v_pk_fma_f32 v[196:197], v[28:29], v[172:173], v[68:69]
	v_pk_fma_f32 v[198:199], v[30:31], v[174:175], v[70:71]
	v_pk_fma_f32 v[200:201], v[32:33], v[176:177], v[72:73]
	v_pk_fma_f32 v[202:203], v[34:35], v[178:179], v[74:75]
	v_pk_fma_f32 v[188:189], v[36:37], v[172:173], v[188:189]
	v_pk_fma_f32 v[190:191], v[38:39], v[174:175], v[190:191]
	v_pk_fma_f32 v[192:193], v[40:41], v[176:177], v[192:193]
	v_pk_fma_f32 v[194:195], v[42:43], v[178:179], v[194:195]
	v_pk_fma_f32 v[180:181], v[44:45], v[172:173], v[180:181]
	v_pk_fma_f32 v[182:183], v[46:47], v[174:175], v[182:183]
	v_pk_fma_f32 v[184:185], v[48:49], v[176:177], v[184:185]
	v_pk_fma_f32 v[186:187], v[50:51], v[178:179], v[186:187]
	s_waitcnt vmcnt(16)
	v_lshlrev_b32_e32 v172, 16, v88
	v_and_b32_e32 v173, 0xffff0000, v88
	v_lshlrev_b32_e32 v174, 16, v89
	v_and_b32_e32 v175, 0xffff0000, v89
	v_lshlrev_b32_e32 v176, 16, v90
	v_and_b32_e32 v177, 0xffff0000, v90
	v_lshlrev_b32_e32 v178, 16, v91
	v_and_b32_e32 v179, 0xffff0000, v91
	v_pk_fma_f32 v[204:205], v[28:29], v[172:173], v[68:69]
	v_pk_fma_f32 v[206:207], v[30:31], v[174:175], v[70:71]
	v_pk_fma_f32 v[208:209], v[32:33], v[176:177], v[72:73]
	v_pk_fma_f32 v[210:211], v[34:35], v[178:179], v[74:75]
	v_pk_fma_f32 v[196:197], v[36:37], v[172:173], v[196:197]
	v_pk_fma_f32 v[198:199], v[38:39], v[174:175], v[198:199]
	v_pk_fma_f32 v[200:201], v[40:41], v[176:177], v[200:201]
	v_pk_fma_f32 v[202:203], v[42:43], v[178:179], v[202:203]
	v_pk_fma_f32 v[188:189], v[44:45], v[172:173], v[188:189]
	v_pk_fma_f32 v[190:191], v[46:47], v[174:175], v[190:191]
	v_pk_fma_f32 v[192:193], v[48:49], v[176:177], v[192:193]
	v_pk_fma_f32 v[194:195], v[50:51], v[178:179], v[194:195]
	v_pk_fma_f32 v[180:181], v[52:53], v[172:173], v[180:181]
	v_pk_fma_f32 v[182:183], v[54:55], v[174:175], v[182:183]
	v_pk_fma_f32 v[184:185], v[56:57], v[176:177], v[184:185]
	v_pk_fma_f32 v[186:187], v[58:59], v[178:179], v[186:187]
	s_waitcnt vmcnt(15)
	v_lshlrev_b32_e32 v172, 16, v92
	v_and_b32_e32 v173, 0xffff0000, v92
	v_lshlrev_b32_e32 v174, 16, v93
	v_and_b32_e32 v175, 0xffff0000, v93
	v_lshlrev_b32_e32 v176, 16, v94
	v_and_b32_e32 v177, 0xffff0000, v94
	v_lshlrev_b32_e32 v178, 16, v95
	v_and_b32_e32 v179, 0xffff0000, v95
	v_pk_fma_f32 v[212:213], v[28:29], v[172:173], v[68:69]
	v_pk_fma_f32 v[214:215], v[30:31], v[174:175], v[70:71]
	v_pk_fma_f32 v[216:217], v[32:33], v[176:177], v[72:73]
	v_pk_fma_f32 v[218:219], v[34:35], v[178:179], v[74:75]
	v_pk_fma_f32 v[204:205], v[36:37], v[172:173], v[204:205]
	v_pk_fma_f32 v[206:207], v[38:39], v[174:175], v[206:207]
	v_pk_fma_f32 v[208:209], v[40:41], v[176:177], v[208:209]
	v_pk_fma_f32 v[210:211], v[42:43], v[178:179], v[210:211]
	v_pk_fma_f32 v[196:197], v[44:45], v[172:173], v[196:197]
	v_pk_fma_f32 v[198:199], v[46:47], v[174:175], v[198:199]
	v_pk_fma_f32 v[200:201], v[48:49], v[176:177], v[200:201]
	v_pk_fma_f32 v[202:203], v[50:51], v[178:179], v[202:203]
	v_pk_fma_f32 v[188:189], v[52:53], v[172:173], v[188:189]
	v_pk_fma_f32 v[190:191], v[54:55], v[174:175], v[190:191]
	v_pk_fma_f32 v[192:193], v[56:57], v[176:177], v[192:193]
	v_pk_fma_f32 v[194:195], v[58:59], v[178:179], v[194:195]
	v_pk_fma_f32 v[180:181], v[60:61], v[172:173], v[180:181]
	v_pk_fma_f32 v[182:183], v[62:63], v[174:175], v[182:183]
	v_pk_fma_f32 v[184:185], v[64:65], v[176:177], v[184:185]
	v_pk_fma_f32 v[186:187], v[66:67], v[178:179], v[186:187]
	v_mul_f32_e32 v220, 0xbfb8aa3b, v180
	v_mul_f32_e32 v221, 0xbfb8aa3b, v181
	v_mul_f32_e32 v222, 0xbfb8aa3b, v182
	v_mul_f32_e32 v223, 0xbfb8aa3b, v183
	v_mul_f32_e32 v224, 0xbfb8aa3b, v184
	v_mul_f32_e32 v225, 0xbfb8aa3b, v185
	v_mul_f32_e32 v226, 0xbfb8aa3b, v186
	v_mul_f32_e32 v227, 0xbfb8aa3b, v187
	v_exp_f32_e32 v220, v220
	v_exp_f32_e32 v221, v221
	v_exp_f32_e32 v222, v222
	v_exp_f32_e32 v223, v223
	v_exp_f32_e32 v224, v224
	v_exp_f32_e32 v225, v225
	v_exp_f32_e32 v226, v226
	v_exp_f32_e32 v227, v227
	v_add_f32_e32 v220, 1.0, v220
	v_add_f32_e32 v221, 1.0, v221
	v_add_f32_e32 v222, 1.0, v222
	v_add_f32_e32 v223, 1.0, v223
	v_add_f32_e32 v224, 1.0, v224
	v_add_f32_e32 v225, 1.0, v225
	v_add_f32_e32 v226, 1.0, v226
	v_add_f32_e32 v227, 1.0, v227
	v_rcp_f32_e32 v220, v220
	v_rcp_f32_e32 v221, v221
	v_rcp_f32_e32 v222, v222
	v_rcp_f32_e32 v223, v223
	v_rcp_f32_e32 v224, v224
	v_rcp_f32_e32 v225, v225
	v_rcp_f32_e32 v226, v226
	v_rcp_f32_e32 v227, v227
	v_mul_f32_e32 v220, v180, v220
	v_mul_f32_e32 v221, v181, v221
	v_mul_f32_e32 v222, v182, v222
	v_mul_f32_e32 v223, v183, v223
	v_mul_f32_e32 v224, v184, v224
	v_mul_f32_e32 v225, v185, v225
	v_mul_f32_e32 v226, v186, v226
	v_mul_f32_e32 v227, v187, v227
	v_cvt_pk_bf16_f32 v180, v220, v221
	v_cvt_pk_bf16_f32 v181, v222, v223
	v_cvt_pk_bf16_f32 v182, v224, v225
	v_cvt_pk_bf16_f32 v183, v226, v227
	global_store_dwordx4 v26, v[180:183], s[54:55]
	s_add_u32 s54, s54, 0x1000
	s_addc_u32 s55, s55, 0
	s_waitcnt vmcnt(15)
	v_lshlrev_b32_e32 v172, 16, v96
	v_and_b32_e32 v173, 0xffff0000, v96
	v_lshlrev_b32_e32 v174, 16, v97
	v_and_b32_e32 v175, 0xffff0000, v97
	v_lshlrev_b32_e32 v176, 16, v98
	v_and_b32_e32 v177, 0xffff0000, v98
	v_lshlrev_b32_e32 v178, 16, v99
	v_and_b32_e32 v179, 0xffff0000, v99
	v_pk_fma_f32 v[180:181], v[28:29], v[172:173], v[68:69]
	v_pk_fma_f32 v[182:183], v[30:31], v[174:175], v[70:71]
	v_pk_fma_f32 v[184:185], v[32:33], v[176:177], v[72:73]
	v_pk_fma_f32 v[186:187], v[34:35], v[178:179], v[74:75]
	v_pk_fma_f32 v[212:213], v[36:37], v[172:173], v[212:213]
	v_pk_fma_f32 v[214:215], v[38:39], v[174:175], v[214:215]
	v_pk_fma_f32 v[216:217], v[40:41], v[176:177], v[216:217]
	v_pk_fma_f32 v[218:219], v[42:43], v[178:179], v[218:219]
	v_pk_fma_f32 v[204:205], v[44:45], v[172:173], v[204:205]
	v_pk_fma_f32 v[206:207], v[46:47], v[174:175], v[206:207]
	v_pk_fma_f32 v[208:209], v[48:49], v[176:177], v[208:209]
	v_pk_fma_f32 v[210:211], v[50:51], v[178:179], v[210:211]
	v_pk_fma_f32 v[196:197], v[52:53], v[172:173], v[196:197]
	v_pk_fma_f32 v[198:199], v[54:55], v[174:175], v[198:199]
	v_pk_fma_f32 v[200:201], v[56:57], v[176:177], v[200:201]
	v_pk_fma_f32 v[202:203], v[58:59], v[178:179], v[202:203]
	v_pk_fma_f32 v[188:189], v[60:61], v[172:173], v[188:189]
	v_pk_fma_f32 v[190:191], v[62:63], v[174:175], v[190:191]
	v_pk_fma_f32 v[192:193], v[64:65], v[176:177], v[192:193]
	v_pk_fma_f32 v[194:195], v[66:67], v[178:179], v[194:195]
	v_mul_f32_e32 v220, 0xbfb8aa3b, v188
	v_mul_f32_e32 v221, 0xbfb8aa3b, v189
	v_mul_f32_e32 v222, 0xbfb8aa3b, v190
	v_mul_f32_e32 v223, 0xbfb8aa3b, v191
	v_mul_f32_e32 v224, 0xbfb8aa3b, v192
	v_mul_f32_e32 v225, 0xbfb8aa3b, v193
	v_mul_f32_e32 v226, 0xbfb8aa3b, v194
	v_mul_f32_e32 v227, 0xbfb8aa3b, v195
	v_exp_f32_e32 v220, v220
	v_exp_f32_e32 v221, v221
	v_exp_f32_e32 v222, v222
	v_exp_f32_e32 v223, v223
	v_exp_f32_e32 v224, v224
	v_exp_f32_e32 v225, v225
	v_exp_f32_e32 v226, v226
	v_exp_f32_e32 v227, v227
	v_add_f32_e32 v220, 1.0, v220
	v_add_f32_e32 v221, 1.0, v221
	v_add_f32_e32 v222, 1.0, v222
	v_add_f32_e32 v223, 1.0, v223
	v_add_f32_e32 v224, 1.0, v224
	v_add_f32_e32 v225, 1.0, v225
	v_add_f32_e32 v226, 1.0, v226
	v_add_f32_e32 v227, 1.0, v227
	v_rcp_f32_e32 v220, v220
	v_rcp_f32_e32 v221, v221
	v_rcp_f32_e32 v222, v222
	v_rcp_f32_e32 v223, v223
	v_rcp_f32_e32 v224, v224
	v_rcp_f32_e32 v225, v225
	v_rcp_f32_e32 v226, v226
	v_rcp_f32_e32 v227, v227
	v_mul_f32_e32 v220, v188, v220
	v_mul_f32_e32 v221, v189, v221
	v_mul_f32_e32 v222, v190, v222
	v_mul_f32_e32 v223, v191, v223
	v_mul_f32_e32 v224, v192, v224
	v_mul_f32_e32 v225, v193, v225
	v_mul_f32_e32 v226, v194, v226
	v_mul_f32_e32 v227, v195, v227
	v_cvt_pk_bf16_f32 v188, v220, v221
	v_cvt_pk_bf16_f32 v189, v222, v223
	v_cvt_pk_bf16_f32 v190, v224, v225
	v_cvt_pk_bf16_f32 v191, v226, v227
	global_store_dwordx4 v26, v[188:191], s[54:55]
	s_add_u32 s54, s54, 0x1000
	s_addc_u32 s55, s55, 0
	s_waitcnt vmcnt(15)
	v_lshlrev_b32_e32 v172, 16, v100
	v_and_b32_e32 v173, 0xffff0000, v100
	v_lshlrev_b32_e32 v174, 16, v101
	v_and_b32_e32 v175, 0xffff0000, v101
	v_lshlrev_b32_e32 v176, 16, v102
	v_and_b32_e32 v177, 0xffff0000, v102
	v_lshlrev_b32_e32 v178, 16, v103
	v_and_b32_e32 v179, 0xffff0000, v103
	v_pk_fma_f32 v[188:189], v[28:29], v[172:173], v[68:69]
	v_pk_fma_f32 v[190:191], v[30:31], v[174:175], v[70:71]
	v_pk_fma_f32 v[192:193], v[32:33], v[176:177], v[72:73]
	v_pk_fma_f32 v[194:195], v[34:35], v[178:179], v[74:75]
	v_pk_fma_f32 v[180:181], v[36:37], v[172:173], v[180:181]
	v_pk_fma_f32 v[182:183], v[38:39], v[174:175], v[182:183]
	v_pk_fma_f32 v[184:185], v[40:41], v[176:177], v[184:185]
	v_pk_fma_f32 v[186:187], v[42:43], v[178:179], v[186:187]
	v_pk_fma_f32 v[212:213], v[44:45], v[172:173], v[212:213]
	v_pk_fma_f32 v[214:215], v[46:47], v[174:175], v[214:215]
	v_pk_fma_f32 v[216:217], v[48:49], v[176:177], v[216:217]
	v_pk_fma_f32 v[218:219], v[50:51], v[178:179], v[218:219]
	v_pk_fma_f32 v[204:205], v[52:53], v[172:173], v[204:205]
	v_pk_fma_f32 v[206:207], v[54:55], v[174:175], v[206:207]
	v_pk_fma_f32 v[208:209], v[56:57], v[176:177], v[208:209]
	v_pk_fma_f32 v[210:211], v[58:59], v[178:179], v[210:211]
	v_pk_fma_f32 v[196:197], v[60:61], v[172:173], v[196:197]
	v_pk_fma_f32 v[198:199], v[62:63], v[174:175], v[198:199]
	v_pk_fma_f32 v[200:201], v[64:65], v[176:177], v[200:201]
	v_pk_fma_f32 v[202:203], v[66:67], v[178:179], v[202:203]
	v_mul_f32_e32 v220, 0xbfb8aa3b, v196
	v_mul_f32_e32 v221, 0xbfb8aa3b, v197
	v_mul_f32_e32 v222, 0xbfb8aa3b, v198
	v_mul_f32_e32 v223, 0xbfb8aa3b, v199
	v_mul_f32_e32 v224, 0xbfb8aa3b, v200
	v_mul_f32_e32 v225, 0xbfb8aa3b, v201
	v_mul_f32_e32 v226, 0xbfb8aa3b, v202
	v_mul_f32_e32 v227, 0xbfb8aa3b, v203
	v_exp_f32_e32 v220, v220
	v_exp_f32_e32 v221, v221
	v_exp_f32_e32 v222, v222
	v_exp_f32_e32 v223, v223
	v_exp_f32_e32 v224, v224
	v_exp_f32_e32 v225, v225
	v_exp_f32_e32 v226, v226
	v_exp_f32_e32 v227, v227
	v_add_f32_e32 v220, 1.0, v220
	v_add_f32_e32 v221, 1.0, v221
	v_add_f32_e32 v222, 1.0, v222
	v_add_f32_e32 v223, 1.0, v223
	v_add_f32_e32 v224, 1.0, v224
	v_add_f32_e32 v225, 1.0, v225
	v_add_f32_e32 v226, 1.0, v226
	v_add_f32_e32 v227, 1.0, v227
	v_rcp_f32_e32 v220, v220
	v_rcp_f32_e32 v221, v221
	v_rcp_f32_e32 v222, v222
	v_rcp_f32_e32 v223, v223
	v_rcp_f32_e32 v224, v224
	v_rcp_f32_e32 v225, v225
	v_rcp_f32_e32 v226, v226
	v_rcp_f32_e32 v227, v227
	v_mul_f32_e32 v220, v196, v220
	v_mul_f32_e32 v221, v197, v221
	v_mul_f32_e32 v222, v198, v222
	v_mul_f32_e32 v223, v199, v223
	v_mul_f32_e32 v224, v200, v224
	v_mul_f32_e32 v225, v201, v225
	v_mul_f32_e32 v226, v202, v226
	v_mul_f32_e32 v227, v203, v227
	v_cvt_pk_bf16_f32 v196, v220, v221
	v_cvt_pk_bf16_f32 v197, v222, v223
	v_cvt_pk_bf16_f32 v198, v224, v225
	v_cvt_pk_bf16_f32 v199, v226, v227
	global_store_dwordx4 v26, v[196:199], s[54:55]
	s_add_u32 s54, s54, 0x1000
	s_addc_u32 s55, s55, 0
	s_waitcnt vmcnt(15)
	v_lshlrev_b32_e32 v172, 16, v104
	v_and_b32_e32 v173, 0xffff0000, v104
	v_lshlrev_b32_e32 v174, 16, v105
	v_and_b32_e32 v175, 0xffff0000, v105
	v_lshlrev_b32_e32 v176, 16, v106
	v_and_b32_e32 v177, 0xffff0000, v106
	v_lshlrev_b32_e32 v178, 16, v107
	v_and_b32_e32 v179, 0xffff0000, v107
	v_pk_fma_f32 v[196:197], v[28:29], v[172:173], v[68:69]
	v_pk_fma_f32 v[198:199], v[30:31], v[174:175], v[70:71]
	v_pk_fma_f32 v[200:201], v[32:33], v[176:177], v[72:73]
	v_pk_fma_f32 v[202:203], v[34:35], v[178:179], v[74:75]
	v_pk_fma_f32 v[188:189], v[36:37], v[172:173], v[188:189]
	v_pk_fma_f32 v[190:191], v[38:39], v[174:175], v[190:191]
	v_pk_fma_f32 v[192:193], v[40:41], v[176:177], v[192:193]
	v_pk_fma_f32 v[194:195], v[42:43], v[178:179], v[194:195]
	v_pk_fma_f32 v[180:181], v[44:45], v[172:173], v[180:181]
	v_pk_fma_f32 v[182:183], v[46:47], v[174:175], v[182:183]
	v_pk_fma_f32 v[184:185], v[48:49], v[176:177], v[184:185]
	v_pk_fma_f32 v[186:187], v[50:51], v[178:179], v[186:187]
	v_pk_fma_f32 v[212:213], v[52:53], v[172:173], v[212:213]
	v_pk_fma_f32 v[214:215], v[54:55], v[174:175], v[214:215]
	v_pk_fma_f32 v[216:217], v[56:57], v[176:177], v[216:217]
	v_pk_fma_f32 v[218:219], v[58:59], v[178:179], v[218:219]
	v_pk_fma_f32 v[204:205], v[60:61], v[172:173], v[204:205]
	v_pk_fma_f32 v[206:207], v[62:63], v[174:175], v[206:207]
	v_pk_fma_f32 v[208:209], v[64:65], v[176:177], v[208:209]
	v_pk_fma_f32 v[210:211], v[66:67], v[178:179], v[210:211]
	v_mul_f32_e32 v220, 0xbfb8aa3b, v204
	v_mul_f32_e32 v221, 0xbfb8aa3b, v205
	v_mul_f32_e32 v222, 0xbfb8aa3b, v206
	v_mul_f32_e32 v223, 0xbfb8aa3b, v207
	v_mul_f32_e32 v224, 0xbfb8aa3b, v208
	v_mul_f32_e32 v225, 0xbfb8aa3b, v209
	v_mul_f32_e32 v226, 0xbfb8aa3b, v210
	v_mul_f32_e32 v227, 0xbfb8aa3b, v211
	v_exp_f32_e32 v220, v220
	v_exp_f32_e32 v221, v221
	v_exp_f32_e32 v222, v222
	v_exp_f32_e32 v223, v223
	v_exp_f32_e32 v224, v224
	v_exp_f32_e32 v225, v225
	v_exp_f32_e32 v226, v226
	v_exp_f32_e32 v227, v227
	v_add_f32_e32 v220, 1.0, v220
	v_add_f32_e32 v221, 1.0, v221
	v_add_f32_e32 v222, 1.0, v222
	v_add_f32_e32 v223, 1.0, v223
	v_add_f32_e32 v224, 1.0, v224
	v_add_f32_e32 v225, 1.0, v225
	v_add_f32_e32 v226, 1.0, v226
	v_add_f32_e32 v227, 1.0, v227
	v_rcp_f32_e32 v220, v220
	v_rcp_f32_e32 v221, v221
	v_rcp_f32_e32 v222, v222
	v_rcp_f32_e32 v223, v223
	v_rcp_f32_e32 v224, v224
	v_rcp_f32_e32 v225, v225
	v_rcp_f32_e32 v226, v226
	v_rcp_f32_e32 v227, v227
	v_mul_f32_e32 v220, v204, v220
	v_mul_f32_e32 v221, v205, v221
	v_mul_f32_e32 v222, v206, v222
	v_mul_f32_e32 v223, v207, v223
	v_mul_f32_e32 v224, v208, v224
	v_mul_f32_e32 v225, v209, v225
	v_mul_f32_e32 v226, v210, v226
	v_mul_f32_e32 v227, v211, v227
	v_cvt_pk_bf16_f32 v204, v220, v221
	v_cvt_pk_bf16_f32 v205, v222, v223
	v_cvt_pk_bf16_f32 v206, v224, v225
	v_cvt_pk_bf16_f32 v207, v226, v227
	global_store_dwordx4 v26, v[204:207], s[54:55]
	s_add_u32 s54, s54, 0x1000
	s_addc_u32 s55, s55, 0
	s_waitcnt vmcnt(15)
	v_lshlrev_b32_e32 v172, 16, v108
	v_and_b32_e32 v173, 0xffff0000, v108
	v_lshlrev_b32_e32 v174, 16, v109
	v_and_b32_e32 v175, 0xffff0000, v109
	v_lshlrev_b32_e32 v176, 16, v110
	v_and_b32_e32 v177, 0xffff0000, v110
	v_lshlrev_b32_e32 v178, 16, v111
	v_and_b32_e32 v179, 0xffff0000, v111
	v_pk_fma_f32 v[204:205], v[28:29], v[172:173], v[68:69]
	v_pk_fma_f32 v[206:207], v[30:31], v[174:175], v[70:71]
	v_pk_fma_f32 v[208:209], v[32:33], v[176:177], v[72:73]
	v_pk_fma_f32 v[210:211], v[34:35], v[178:179], v[74:75]
	v_pk_fma_f32 v[196:197], v[36:37], v[172:173], v[196:197]
	v_pk_fma_f32 v[198:199], v[38:39], v[174:175], v[198:199]
	v_pk_fma_f32 v[200:201], v[40:41], v[176:177], v[200:201]
	v_pk_fma_f32 v[202:203], v[42:43], v[178:179], v[202:203]
	v_pk_fma_f32 v[188:189], v[44:45], v[172:173], v[188:189]
	v_pk_fma_f32 v[190:191], v[46:47], v[174:175], v[190:191]
	v_pk_fma_f32 v[192:193], v[48:49], v[176:177], v[192:193]
	v_pk_fma_f32 v[194:195], v[50:51], v[178:179], v[194:195]
	v_pk_fma_f32 v[180:181], v[52:53], v[172:173], v[180:181]
	v_pk_fma_f32 v[182:183], v[54:55], v[174:175], v[182:183]
	v_pk_fma_f32 v[184:185], v[56:57], v[176:177], v[184:185]
	v_pk_fma_f32 v[186:187], v[58:59], v[178:179], v[186:187]
	v_pk_fma_f32 v[212:213], v[60:61], v[172:173], v[212:213]
	v_pk_fma_f32 v[214:215], v[62:63], v[174:175], v[214:215]
	v_pk_fma_f32 v[216:217], v[64:65], v[176:177], v[216:217]
	v_pk_fma_f32 v[218:219], v[66:67], v[178:179], v[218:219]
	v_mul_f32_e32 v220, 0xbfb8aa3b, v212
	v_mul_f32_e32 v221, 0xbfb8aa3b, v213
	v_mul_f32_e32 v222, 0xbfb8aa3b, v214
	v_mul_f32_e32 v223, 0xbfb8aa3b, v215
	v_mul_f32_e32 v224, 0xbfb8aa3b, v216
	v_mul_f32_e32 v225, 0xbfb8aa3b, v217
	v_mul_f32_e32 v226, 0xbfb8aa3b, v218
	v_mul_f32_e32 v227, 0xbfb8aa3b, v219
	v_exp_f32_e32 v220, v220
	v_exp_f32_e32 v221, v221
	v_exp_f32_e32 v222, v222
	v_exp_f32_e32 v223, v223
	v_exp_f32_e32 v224, v224
	v_exp_f32_e32 v225, v225
	v_exp_f32_e32 v226, v226
	v_exp_f32_e32 v227, v227
	v_add_f32_e32 v220, 1.0, v220
	v_add_f32_e32 v221, 1.0, v221
	v_add_f32_e32 v222, 1.0, v222
	v_add_f32_e32 v223, 1.0, v223
	v_add_f32_e32 v224, 1.0, v224
	v_add_f32_e32 v225, 1.0, v225
	v_add_f32_e32 v226, 1.0, v226
	v_add_f32_e32 v227, 1.0, v227
	v_rcp_f32_e32 v220, v220
	v_rcp_f32_e32 v221, v221
	v_rcp_f32_e32 v222, v222
	v_rcp_f32_e32 v223, v223
	v_rcp_f32_e32 v224, v224
	v_rcp_f32_e32 v225, v225
	v_rcp_f32_e32 v226, v226
	v_rcp_f32_e32 v227, v227
	v_mul_f32_e32 v220, v212, v220
	v_mul_f32_e32 v221, v213, v221
	v_mul_f32_e32 v222, v214, v222
	v_mul_f32_e32 v223, v215, v223
	v_mul_f32_e32 v224, v216, v224
	v_mul_f32_e32 v225, v217, v225
	v_mul_f32_e32 v226, v218, v226
	v_mul_f32_e32 v227, v219, v227
	v_cvt_pk_bf16_f32 v212, v220, v221
	v_cvt_pk_bf16_f32 v213, v222, v223
	v_cvt_pk_bf16_f32 v214, v224, v225
	v_cvt_pk_bf16_f32 v215, v226, v227
	global_store_dwordx4 v26, v[212:215], s[54:55]
	s_add_u32 s54, s54, 0x1000
	s_addc_u32 s55, s55, 0
	s_waitcnt vmcnt(15)
	v_lshlrev_b32_e32 v172, 16, v112
	v_and_b32_e32 v173, 0xffff0000, v112
	v_lshlrev_b32_e32 v174, 16, v113
	v_and_b32_e32 v175, 0xffff0000, v113
	v_lshlrev_b32_e32 v176, 16, v114
	v_and_b32_e32 v177, 0xffff0000, v114
	v_lshlrev_b32_e32 v178, 16, v115
	v_and_b32_e32 v179, 0xffff0000, v115
	v_pk_fma_f32 v[212:213], v[28:29], v[172:173], v[68:69]
	v_pk_fma_f32 v[214:215], v[30:31], v[174:175], v[70:71]
	v_pk_fma_f32 v[216:217], v[32:33], v[176:177], v[72:73]
	v_pk_fma_f32 v[218:219], v[34:35], v[178:179], v[74:75]
	v_pk_fma_f32 v[204:205], v[36:37], v[172:173], v[204:205]
	v_pk_fma_f32 v[206:207], v[38:39], v[174:175], v[206:207]
	v_pk_fma_f32 v[208:209], v[40:41], v[176:177], v[208:209]
	v_pk_fma_f32 v[210:211], v[42:43], v[178:179], v[210:211]
	v_pk_fma_f32 v[196:197], v[44:45], v[172:173], v[196:197]
	v_pk_fma_f32 v[198:199], v[46:47], v[174:175], v[198:199]
	v_pk_fma_f32 v[200:201], v[48:49], v[176:177], v[200:201]
	v_pk_fma_f32 v[202:203], v[50:51], v[178:179], v[202:203]
	v_pk_fma_f32 v[188:189], v[52:53], v[172:173], v[188:189]
	v_pk_fma_f32 v[190:191], v[54:55], v[174:175], v[190:191]
	v_pk_fma_f32 v[192:193], v[56:57], v[176:177], v[192:193]
	v_pk_fma_f32 v[194:195], v[58:59], v[178:179], v[194:195]
	v_pk_fma_f32 v[180:181], v[60:61], v[172:173], v[180:181]
	v_pk_fma_f32 v[182:183], v[62:63], v[174:175], v[182:183]
	v_pk_fma_f32 v[184:185], v[64:65], v[176:177], v[184:185]
	v_pk_fma_f32 v[186:187], v[66:67], v[178:179], v[186:187]
	v_mul_f32_e32 v220, 0xbfb8aa3b, v180
	v_mul_f32_e32 v221, 0xbfb8aa3b, v181
	v_mul_f32_e32 v222, 0xbfb8aa3b, v182
	v_mul_f32_e32 v223, 0xbfb8aa3b, v183
	v_mul_f32_e32 v224, 0xbfb8aa3b, v184
	v_mul_f32_e32 v225, 0xbfb8aa3b, v185
	v_mul_f32_e32 v226, 0xbfb8aa3b, v186
	v_mul_f32_e32 v227, 0xbfb8aa3b, v187
	v_exp_f32_e32 v220, v220
	v_exp_f32_e32 v221, v221
	v_exp_f32_e32 v222, v222
	v_exp_f32_e32 v223, v223
	v_exp_f32_e32 v224, v224
	v_exp_f32_e32 v225, v225
	v_exp_f32_e32 v226, v226
	v_exp_f32_e32 v227, v227
	v_add_f32_e32 v220, 1.0, v220
	v_add_f32_e32 v221, 1.0, v221
	v_add_f32_e32 v222, 1.0, v222
	v_add_f32_e32 v223, 1.0, v223
	v_add_f32_e32 v224, 1.0, v224
	v_add_f32_e32 v225, 1.0, v225
	v_add_f32_e32 v226, 1.0, v226
	v_add_f32_e32 v227, 1.0, v227
	v_rcp_f32_e32 v220, v220
	v_rcp_f32_e32 v221, v221
	v_rcp_f32_e32 v222, v222
	v_rcp_f32_e32 v223, v223
	v_rcp_f32_e32 v224, v224
	v_rcp_f32_e32 v225, v225
	v_rcp_f32_e32 v226, v226
	v_rcp_f32_e32 v227, v227
	v_mul_f32_e32 v220, v180, v220
	v_mul_f32_e32 v221, v181, v221
	v_mul_f32_e32 v222, v182, v222
	v_mul_f32_e32 v223, v183, v223
	v_mul_f32_e32 v224, v184, v224
	v_mul_f32_e32 v225, v185, v225
	v_mul_f32_e32 v226, v186, v226
	v_mul_f32_e32 v227, v187, v227
	v_cvt_pk_bf16_f32 v180, v220, v221
	v_cvt_pk_bf16_f32 v181, v222, v223
	v_cvt_pk_bf16_f32 v182, v224, v225
	v_cvt_pk_bf16_f32 v183, v226, v227
	global_store_dwordx4 v26, v[180:183], s[54:55]
	s_add_u32 s54, s54, 0x1000
	s_addc_u32 s55, s55, 0
	s_waitcnt vmcnt(15)
	v_lshlrev_b32_e32 v172, 16, v116
	v_and_b32_e32 v173, 0xffff0000, v116
	v_lshlrev_b32_e32 v174, 16, v117
	v_and_b32_e32 v175, 0xffff0000, v117
	v_lshlrev_b32_e32 v176, 16, v118
	v_and_b32_e32 v177, 0xffff0000, v118
	v_lshlrev_b32_e32 v178, 16, v119
	v_and_b32_e32 v179, 0xffff0000, v119
	v_pk_fma_f32 v[180:181], v[28:29], v[172:173], v[68:69]
	v_pk_fma_f32 v[182:183], v[30:31], v[174:175], v[70:71]
	v_pk_fma_f32 v[184:185], v[32:33], v[176:177], v[72:73]
	v_pk_fma_f32 v[186:187], v[34:35], v[178:179], v[74:75]
	v_pk_fma_f32 v[212:213], v[36:37], v[172:173], v[212:213]
	v_pk_fma_f32 v[214:215], v[38:39], v[174:175], v[214:215]
	v_pk_fma_f32 v[216:217], v[40:41], v[176:177], v[216:217]
	v_pk_fma_f32 v[218:219], v[42:43], v[178:179], v[218:219]
	v_pk_fma_f32 v[204:205], v[44:45], v[172:173], v[204:205]
	v_pk_fma_f32 v[206:207], v[46:47], v[174:175], v[206:207]
	v_pk_fma_f32 v[208:209], v[48:49], v[176:177], v[208:209]
	v_pk_fma_f32 v[210:211], v[50:51], v[178:179], v[210:211]
	v_pk_fma_f32 v[196:197], v[52:53], v[172:173], v[196:197]
	v_pk_fma_f32 v[198:199], v[54:55], v[174:175], v[198:199]
	v_pk_fma_f32 v[200:201], v[56:57], v[176:177], v[200:201]
	v_pk_fma_f32 v[202:203], v[58:59], v[178:179], v[202:203]
	v_pk_fma_f32 v[188:189], v[60:61], v[172:173], v[188:189]
	v_pk_fma_f32 v[190:191], v[62:63], v[174:175], v[190:191]
	v_pk_fma_f32 v[192:193], v[64:65], v[176:177], v[192:193]
	v_pk_fma_f32 v[194:195], v[66:67], v[178:179], v[194:195]
	v_mul_f32_e32 v220, 0xbfb8aa3b, v188
	v_mul_f32_e32 v221, 0xbfb8aa3b, v189
	v_mul_f32_e32 v222, 0xbfb8aa3b, v190
	v_mul_f32_e32 v223, 0xbfb8aa3b, v191
	v_mul_f32_e32 v224, 0xbfb8aa3b, v192
	v_mul_f32_e32 v225, 0xbfb8aa3b, v193
	v_mul_f32_e32 v226, 0xbfb8aa3b, v194
	v_mul_f32_e32 v227, 0xbfb8aa3b, v195
	v_exp_f32_e32 v220, v220
	v_exp_f32_e32 v221, v221
	v_exp_f32_e32 v222, v222
	v_exp_f32_e32 v223, v223
	v_exp_f32_e32 v224, v224
	v_exp_f32_e32 v225, v225
	v_exp_f32_e32 v226, v226
	v_exp_f32_e32 v227, v227
	v_add_f32_e32 v220, 1.0, v220
	v_add_f32_e32 v221, 1.0, v221
	v_add_f32_e32 v222, 1.0, v222
	v_add_f32_e32 v223, 1.0, v223
	v_add_f32_e32 v224, 1.0, v224
	v_add_f32_e32 v225, 1.0, v225
	v_add_f32_e32 v226, 1.0, v226
	v_add_f32_e32 v227, 1.0, v227
	v_rcp_f32_e32 v220, v220
	v_rcp_f32_e32 v221, v221
	v_rcp_f32_e32 v222, v222
	v_rcp_f32_e32 v223, v223
	v_rcp_f32_e32 v224, v224
	v_rcp_f32_e32 v225, v225
	v_rcp_f32_e32 v226, v226
	v_rcp_f32_e32 v227, v227
	v_mul_f32_e32 v220, v188, v220
	v_mul_f32_e32 v221, v189, v221
	v_mul_f32_e32 v222, v190, v222
	v_mul_f32_e32 v223, v191, v223
	v_mul_f32_e32 v224, v192, v224
	v_mul_f32_e32 v225, v193, v225
	v_mul_f32_e32 v226, v194, v226
	v_mul_f32_e32 v227, v195, v227
	v_cvt_pk_bf16_f32 v188, v220, v221
	v_cvt_pk_bf16_f32 v189, v222, v223
	v_cvt_pk_bf16_f32 v190, v224, v225
	v_cvt_pk_bf16_f32 v191, v226, v227
	global_store_dwordx4 v26, v[188:191], s[54:55]
	s_add_u32 s54, s54, 0x1000
	s_addc_u32 s55, s55, 0
	s_waitcnt vmcnt(15)
	v_lshlrev_b32_e32 v172, 16, v120
	v_and_b32_e32 v173, 0xffff0000, v120
	v_lshlrev_b32_e32 v174, 16, v121
	v_and_b32_e32 v175, 0xffff0000, v121
	v_lshlrev_b32_e32 v176, 16, v122
	v_and_b32_e32 v177, 0xffff0000, v122
	v_lshlrev_b32_e32 v178, 16, v123
	v_and_b32_e32 v179, 0xffff0000, v123
	v_pk_fma_f32 v[188:189], v[28:29], v[172:173], v[68:69]
	v_pk_fma_f32 v[190:191], v[30:31], v[174:175], v[70:71]
	v_pk_fma_f32 v[192:193], v[32:33], v[176:177], v[72:73]
	v_pk_fma_f32 v[194:195], v[34:35], v[178:179], v[74:75]
	v_pk_fma_f32 v[180:181], v[36:37], v[172:173], v[180:181]
	v_pk_fma_f32 v[182:183], v[38:39], v[174:175], v[182:183]
	v_pk_fma_f32 v[184:185], v[40:41], v[176:177], v[184:185]
	v_pk_fma_f32 v[186:187], v[42:43], v[178:179], v[186:187]
	v_pk_fma_f32 v[212:213], v[44:45], v[172:173], v[212:213]
	v_pk_fma_f32 v[214:215], v[46:47], v[174:175], v[214:215]
	v_pk_fma_f32 v[216:217], v[48:49], v[176:177], v[216:217]
	v_pk_fma_f32 v[218:219], v[50:51], v[178:179], v[218:219]
	v_pk_fma_f32 v[204:205], v[52:53], v[172:173], v[204:205]
	v_pk_fma_f32 v[206:207], v[54:55], v[174:175], v[206:207]
	v_pk_fma_f32 v[208:209], v[56:57], v[176:177], v[208:209]
	v_pk_fma_f32 v[210:211], v[58:59], v[178:179], v[210:211]
	v_pk_fma_f32 v[196:197], v[60:61], v[172:173], v[196:197]
	v_pk_fma_f32 v[198:199], v[62:63], v[174:175], v[198:199]
	v_pk_fma_f32 v[200:201], v[64:65], v[176:177], v[200:201]
	v_pk_fma_f32 v[202:203], v[66:67], v[178:179], v[202:203]
	v_mul_f32_e32 v220, 0xbfb8aa3b, v196
	v_mul_f32_e32 v221, 0xbfb8aa3b, v197
	v_mul_f32_e32 v222, 0xbfb8aa3b, v198
	v_mul_f32_e32 v223, 0xbfb8aa3b, v199
	v_mul_f32_e32 v224, 0xbfb8aa3b, v200
	v_mul_f32_e32 v225, 0xbfb8aa3b, v201
	v_mul_f32_e32 v226, 0xbfb8aa3b, v202
	v_mul_f32_e32 v227, 0xbfb8aa3b, v203
	v_exp_f32_e32 v220, v220
	v_exp_f32_e32 v221, v221
	v_exp_f32_e32 v222, v222
	v_exp_f32_e32 v223, v223
	v_exp_f32_e32 v224, v224
	v_exp_f32_e32 v225, v225
	v_exp_f32_e32 v226, v226
	v_exp_f32_e32 v227, v227
	v_add_f32_e32 v220, 1.0, v220
	v_add_f32_e32 v221, 1.0, v221
	v_add_f32_e32 v222, 1.0, v222
	v_add_f32_e32 v223, 1.0, v223
	v_add_f32_e32 v224, 1.0, v224
	v_add_f32_e32 v225, 1.0, v225
	v_add_f32_e32 v226, 1.0, v226
	v_add_f32_e32 v227, 1.0, v227
	v_rcp_f32_e32 v220, v220
	v_rcp_f32_e32 v221, v221
	v_rcp_f32_e32 v222, v222
	v_rcp_f32_e32 v223, v223
	v_rcp_f32_e32 v224, v224
	v_rcp_f32_e32 v225, v225
	v_rcp_f32_e32 v226, v226
	v_rcp_f32_e32 v227, v227
	v_mul_f32_e32 v220, v196, v220
	v_mul_f32_e32 v221, v197, v221
	v_mul_f32_e32 v222, v198, v222
	v_mul_f32_e32 v223, v199, v223
	v_mul_f32_e32 v224, v200, v224
	v_mul_f32_e32 v225, v201, v225
	v_mul_f32_e32 v226, v202, v226
	v_mul_f32_e32 v227, v203, v227
	v_cvt_pk_bf16_f32 v196, v220, v221
	v_cvt_pk_bf16_f32 v197, v222, v223
	v_cvt_pk_bf16_f32 v198, v224, v225
	v_cvt_pk_bf16_f32 v199, v226, v227
	global_store_dwordx4 v26, v[196:199], s[54:55]
	s_add_u32 s54, s54, 0x1000
	s_addc_u32 s55, s55, 0
	s_waitcnt vmcnt(15)
	v_lshlrev_b32_e32 v172, 16, v124
	v_and_b32_e32 v173, 0xffff0000, v124
	v_lshlrev_b32_e32 v174, 16, v125
	v_and_b32_e32 v175, 0xffff0000, v125
	v_lshlrev_b32_e32 v176, 16, v126
	v_and_b32_e32 v177, 0xffff0000, v126
	v_lshlrev_b32_e32 v178, 16, v127
	v_and_b32_e32 v179, 0xffff0000, v127
	v_pk_fma_f32 v[196:197], v[28:29], v[172:173], v[68:69]
	v_pk_fma_f32 v[198:199], v[30:31], v[174:175], v[70:71]
	v_pk_fma_f32 v[200:201], v[32:33], v[176:177], v[72:73]
	v_pk_fma_f32 v[202:203], v[34:35], v[178:179], v[74:75]
	v_pk_fma_f32 v[188:189], v[36:37], v[172:173], v[188:189]
	v_pk_fma_f32 v[190:191], v[38:39], v[174:175], v[190:191]
	v_pk_fma_f32 v[192:193], v[40:41], v[176:177], v[192:193]
	v_pk_fma_f32 v[194:195], v[42:43], v[178:179], v[194:195]
	v_pk_fma_f32 v[180:181], v[44:45], v[172:173], v[180:181]
	v_pk_fma_f32 v[182:183], v[46:47], v[174:175], v[182:183]
	v_pk_fma_f32 v[184:185], v[48:49], v[176:177], v[184:185]
	v_pk_fma_f32 v[186:187], v[50:51], v[178:179], v[186:187]
	v_pk_fma_f32 v[212:213], v[52:53], v[172:173], v[212:213]
	v_pk_fma_f32 v[214:215], v[54:55], v[174:175], v[214:215]
	v_pk_fma_f32 v[216:217], v[56:57], v[176:177], v[216:217]
	v_pk_fma_f32 v[218:219], v[58:59], v[178:179], v[218:219]
	v_pk_fma_f32 v[204:205], v[60:61], v[172:173], v[204:205]
	v_pk_fma_f32 v[206:207], v[62:63], v[174:175], v[206:207]
	v_pk_fma_f32 v[208:209], v[64:65], v[176:177], v[208:209]
	v_pk_fma_f32 v[210:211], v[66:67], v[178:179], v[210:211]
	v_mul_f32_e32 v220, 0xbfb8aa3b, v204
	v_mul_f32_e32 v221, 0xbfb8aa3b, v205
	v_mul_f32_e32 v222, 0xbfb8aa3b, v206
	v_mul_f32_e32 v223, 0xbfb8aa3b, v207
	v_mul_f32_e32 v224, 0xbfb8aa3b, v208
	v_mul_f32_e32 v225, 0xbfb8aa3b, v209
	v_mul_f32_e32 v226, 0xbfb8aa3b, v210
	v_mul_f32_e32 v227, 0xbfb8aa3b, v211
	v_exp_f32_e32 v220, v220
	v_exp_f32_e32 v221, v221
	v_exp_f32_e32 v222, v222
	v_exp_f32_e32 v223, v223
	v_exp_f32_e32 v224, v224
	v_exp_f32_e32 v225, v225
	v_exp_f32_e32 v226, v226
	v_exp_f32_e32 v227, v227
	v_add_f32_e32 v220, 1.0, v220
	v_add_f32_e32 v221, 1.0, v221
	v_add_f32_e32 v222, 1.0, v222
	v_add_f32_e32 v223, 1.0, v223
	v_add_f32_e32 v224, 1.0, v224
	v_add_f32_e32 v225, 1.0, v225
	v_add_f32_e32 v226, 1.0, v226
	v_add_f32_e32 v227, 1.0, v227
	v_rcp_f32_e32 v220, v220
	v_rcp_f32_e32 v221, v221
	v_rcp_f32_e32 v222, v222
	v_rcp_f32_e32 v223, v223
	v_rcp_f32_e32 v224, v224
	v_rcp_f32_e32 v225, v225
	v_rcp_f32_e32 v226, v226
	v_rcp_f32_e32 v227, v227
	v_mul_f32_e32 v220, v204, v220
	v_mul_f32_e32 v221, v205, v221
	v_mul_f32_e32 v222, v206, v222
	v_mul_f32_e32 v223, v207, v223
	v_mul_f32_e32 v224, v208, v224
	v_mul_f32_e32 v225, v209, v225
	v_mul_f32_e32 v226, v210, v226
	v_mul_f32_e32 v227, v211, v227
	v_cvt_pk_bf16_f32 v204, v220, v221
	v_cvt_pk_bf16_f32 v205, v222, v223
	v_cvt_pk_bf16_f32 v206, v224, v225
	v_cvt_pk_bf16_f32 v207, v226, v227
	global_store_dwordx4 v26, v[204:207], s[54:55]
	s_add_u32 s54, s54, 0x1000
	s_addc_u32 s55, s55, 0
	s_waitcnt vmcnt(15)
	v_lshlrev_b32_e32 v172, 16, v132
	v_and_b32_e32 v173, 0xffff0000, v132
	v_lshlrev_b32_e32 v174, 16, v133
	v_and_b32_e32 v175, 0xffff0000, v133
	v_lshlrev_b32_e32 v176, 16, v134
	v_and_b32_e32 v177, 0xffff0000, v134
	v_lshlrev_b32_e32 v178, 16, v135
	v_and_b32_e32 v179, 0xffff0000, v135
	v_pk_fma_f32 v[204:205], v[28:29], v[172:173], v[68:69]
	v_pk_fma_f32 v[206:207], v[30:31], v[174:175], v[70:71]
	v_pk_fma_f32 v[208:209], v[32:33], v[176:177], v[72:73]
	v_pk_fma_f32 v[210:211], v[34:35], v[178:179], v[74:75]
	v_pk_fma_f32 v[196:197], v[36:37], v[172:173], v[196:197]
	v_pk_fma_f32 v[198:199], v[38:39], v[174:175], v[198:199]
	v_pk_fma_f32 v[200:201], v[40:41], v[176:177], v[200:201]
	v_pk_fma_f32 v[202:203], v[42:43], v[178:179], v[202:203]
	v_pk_fma_f32 v[188:189], v[44:45], v[172:173], v[188:189]
	v_pk_fma_f32 v[190:191], v[46:47], v[174:175], v[190:191]
	v_pk_fma_f32 v[192:193], v[48:49], v[176:177], v[192:193]
	v_pk_fma_f32 v[194:195], v[50:51], v[178:179], v[194:195]
	v_pk_fma_f32 v[180:181], v[52:53], v[172:173], v[180:181]
	v_pk_fma_f32 v[182:183], v[54:55], v[174:175], v[182:183]
	v_pk_fma_f32 v[184:185], v[56:57], v[176:177], v[184:185]
	v_pk_fma_f32 v[186:187], v[58:59], v[178:179], v[186:187]
	v_pk_fma_f32 v[212:213], v[60:61], v[172:173], v[212:213]
	v_pk_fma_f32 v[214:215], v[62:63], v[174:175], v[214:215]
	v_pk_fma_f32 v[216:217], v[64:65], v[176:177], v[216:217]
	v_pk_fma_f32 v[218:219], v[66:67], v[178:179], v[218:219]
	v_mul_f32_e32 v220, 0xbfb8aa3b, v212
	v_mul_f32_e32 v221, 0xbfb8aa3b, v213
	v_mul_f32_e32 v222, 0xbfb8aa3b, v214
	v_mul_f32_e32 v223, 0xbfb8aa3b, v215
	v_mul_f32_e32 v224, 0xbfb8aa3b, v216
	v_mul_f32_e32 v225, 0xbfb8aa3b, v217
	v_mul_f32_e32 v226, 0xbfb8aa3b, v218
	v_mul_f32_e32 v227, 0xbfb8aa3b, v219
	v_exp_f32_e32 v220, v220
	v_exp_f32_e32 v221, v221
	v_exp_f32_e32 v222, v222
	v_exp_f32_e32 v223, v223
	v_exp_f32_e32 v224, v224
	v_exp_f32_e32 v225, v225
	v_exp_f32_e32 v226, v226
	v_exp_f32_e32 v227, v227
	v_add_f32_e32 v220, 1.0, v220
	v_add_f32_e32 v221, 1.0, v221
	v_add_f32_e32 v222, 1.0, v222
	v_add_f32_e32 v223, 1.0, v223
	v_add_f32_e32 v224, 1.0, v224
	v_add_f32_e32 v225, 1.0, v225
	v_add_f32_e32 v226, 1.0, v226
	v_add_f32_e32 v227, 1.0, v227
	v_rcp_f32_e32 v220, v220
	v_rcp_f32_e32 v221, v221
	v_rcp_f32_e32 v222, v222
	v_rcp_f32_e32 v223, v223
	v_rcp_f32_e32 v224, v224
	v_rcp_f32_e32 v225, v225
	v_rcp_f32_e32 v226, v226
	v_rcp_f32_e32 v227, v227
	v_mul_f32_e32 v220, v212, v220
	v_mul_f32_e32 v221, v213, v221
	v_mul_f32_e32 v222, v214, v222
	v_mul_f32_e32 v223, v215, v223
	v_mul_f32_e32 v224, v216, v224
	v_mul_f32_e32 v225, v217, v225
	v_mul_f32_e32 v226, v218, v226
	v_mul_f32_e32 v227, v219, v227
	v_cvt_pk_bf16_f32 v212, v220, v221
	v_cvt_pk_bf16_f32 v213, v222, v223
	v_cvt_pk_bf16_f32 v214, v224, v225
	v_cvt_pk_bf16_f32 v215, v226, v227
	global_store_dwordx4 v26, v[212:215], s[54:55]
	s_add_u32 s54, s54, 0x1000
	s_addc_u32 s55, s55, 0
	s_waitcnt vmcnt(15)
	v_lshlrev_b32_e32 v172, 16, v136
	v_and_b32_e32 v173, 0xffff0000, v136
	v_lshlrev_b32_e32 v174, 16, v137
	v_and_b32_e32 v175, 0xffff0000, v137
	v_lshlrev_b32_e32 v176, 16, v138
	v_and_b32_e32 v177, 0xffff0000, v138
	v_lshlrev_b32_e32 v178, 16, v139
	v_and_b32_e32 v179, 0xffff0000, v139
	v_pk_fma_f32 v[212:213], v[28:29], v[172:173], v[68:69]
	v_pk_fma_f32 v[214:215], v[30:31], v[174:175], v[70:71]
	v_pk_fma_f32 v[216:217], v[32:33], v[176:177], v[72:73]
	v_pk_fma_f32 v[218:219], v[34:35], v[178:179], v[74:75]
	v_pk_fma_f32 v[204:205], v[36:37], v[172:173], v[204:205]
	v_pk_fma_f32 v[206:207], v[38:39], v[174:175], v[206:207]
	v_pk_fma_f32 v[208:209], v[40:41], v[176:177], v[208:209]
	v_pk_fma_f32 v[210:211], v[42:43], v[178:179], v[210:211]
	v_pk_fma_f32 v[196:197], v[44:45], v[172:173], v[196:197]
	v_pk_fma_f32 v[198:199], v[46:47], v[174:175], v[198:199]
	v_pk_fma_f32 v[200:201], v[48:49], v[176:177], v[200:201]
	v_pk_fma_f32 v[202:203], v[50:51], v[178:179], v[202:203]
	v_pk_fma_f32 v[188:189], v[52:53], v[172:173], v[188:189]
	v_pk_fma_f32 v[190:191], v[54:55], v[174:175], v[190:191]
	v_pk_fma_f32 v[192:193], v[56:57], v[176:177], v[192:193]
	v_pk_fma_f32 v[194:195], v[58:59], v[178:179], v[194:195]
	v_pk_fma_f32 v[180:181], v[60:61], v[172:173], v[180:181]
	v_pk_fma_f32 v[182:183], v[62:63], v[174:175], v[182:183]
	v_pk_fma_f32 v[184:185], v[64:65], v[176:177], v[184:185]
	v_pk_fma_f32 v[186:187], v[66:67], v[178:179], v[186:187]
	v_mul_f32_e32 v220, 0xbfb8aa3b, v180
	v_mul_f32_e32 v221, 0xbfb8aa3b, v181
	v_mul_f32_e32 v222, 0xbfb8aa3b, v182
	v_mul_f32_e32 v223, 0xbfb8aa3b, v183
	v_mul_f32_e32 v224, 0xbfb8aa3b, v184
	v_mul_f32_e32 v225, 0xbfb8aa3b, v185
	v_mul_f32_e32 v226, 0xbfb8aa3b, v186
	v_mul_f32_e32 v227, 0xbfb8aa3b, v187
	v_exp_f32_e32 v220, v220
	v_exp_f32_e32 v221, v221
	v_exp_f32_e32 v222, v222
	v_exp_f32_e32 v223, v223
	v_exp_f32_e32 v224, v224
	v_exp_f32_e32 v225, v225
	v_exp_f32_e32 v226, v226
	v_exp_f32_e32 v227, v227
	v_add_f32_e32 v220, 1.0, v220
	v_add_f32_e32 v221, 1.0, v221
	v_add_f32_e32 v222, 1.0, v222
	v_add_f32_e32 v223, 1.0, v223
	v_add_f32_e32 v224, 1.0, v224
	v_add_f32_e32 v225, 1.0, v225
	v_add_f32_e32 v226, 1.0, v226
	v_add_f32_e32 v227, 1.0, v227
	v_rcp_f32_e32 v220, v220
	v_rcp_f32_e32 v221, v221
	v_rcp_f32_e32 v222, v222
	v_rcp_f32_e32 v223, v223
	v_rcp_f32_e32 v224, v224
	v_rcp_f32_e32 v225, v225
	v_rcp_f32_e32 v226, v226
	v_rcp_f32_e32 v227, v227
	v_mul_f32_e32 v220, v180, v220
	v_mul_f32_e32 v221, v181, v221
	v_mul_f32_e32 v222, v182, v222
	v_mul_f32_e32 v223, v183, v223
	v_mul_f32_e32 v224, v184, v224
	v_mul_f32_e32 v225, v185, v225
	v_mul_f32_e32 v226, v186, v226
	v_mul_f32_e32 v227, v187, v227
	v_cvt_pk_bf16_f32 v180, v220, v221
	v_cvt_pk_bf16_f32 v181, v222, v223
	v_cvt_pk_bf16_f32 v182, v224, v225
	v_cvt_pk_bf16_f32 v183, v226, v227
	global_store_dwordx4 v26, v[180:183], s[54:55]
	s_add_u32 s54, s54, 0x1000
	s_addc_u32 s55, s55, 0
	s_waitcnt vmcnt(15)
	v_lshlrev_b32_e32 v172, 16, v140
	v_and_b32_e32 v173, 0xffff0000, v140
	v_lshlrev_b32_e32 v174, 16, v141
	v_and_b32_e32 v175, 0xffff0000, v141
	v_lshlrev_b32_e32 v176, 16, v142
	v_and_b32_e32 v177, 0xffff0000, v142
	v_lshlrev_b32_e32 v178, 16, v143
	v_and_b32_e32 v179, 0xffff0000, v143
	v_pk_fma_f32 v[180:181], v[28:29], v[172:173], v[68:69]
	v_pk_fma_f32 v[182:183], v[30:31], v[174:175], v[70:71]
	v_pk_fma_f32 v[184:185], v[32:33], v[176:177], v[72:73]
	v_pk_fma_f32 v[186:187], v[34:35], v[178:179], v[74:75]
	v_pk_fma_f32 v[212:213], v[36:37], v[172:173], v[212:213]
	v_pk_fma_f32 v[214:215], v[38:39], v[174:175], v[214:215]
	v_pk_fma_f32 v[216:217], v[40:41], v[176:177], v[216:217]
	v_pk_fma_f32 v[218:219], v[42:43], v[178:179], v[218:219]
	v_pk_fma_f32 v[204:205], v[44:45], v[172:173], v[204:205]
	v_pk_fma_f32 v[206:207], v[46:47], v[174:175], v[206:207]
	v_pk_fma_f32 v[208:209], v[48:49], v[176:177], v[208:209]
	v_pk_fma_f32 v[210:211], v[50:51], v[178:179], v[210:211]
	v_pk_fma_f32 v[196:197], v[52:53], v[172:173], v[196:197]
	v_pk_fma_f32 v[198:199], v[54:55], v[174:175], v[198:199]
	v_pk_fma_f32 v[200:201], v[56:57], v[176:177], v[200:201]
	v_pk_fma_f32 v[202:203], v[58:59], v[178:179], v[202:203]
	v_pk_fma_f32 v[188:189], v[60:61], v[172:173], v[188:189]
	v_pk_fma_f32 v[190:191], v[62:63], v[174:175], v[190:191]
	v_pk_fma_f32 v[192:193], v[64:65], v[176:177], v[192:193]
	v_pk_fma_f32 v[194:195], v[66:67], v[178:179], v[194:195]
	v_mul_f32_e32 v220, 0xbfb8aa3b, v188
	v_mul_f32_e32 v221, 0xbfb8aa3b, v189
	v_mul_f32_e32 v222, 0xbfb8aa3b, v190
	v_mul_f32_e32 v223, 0xbfb8aa3b, v191
	v_mul_f32_e32 v224, 0xbfb8aa3b, v192
	v_mul_f32_e32 v225, 0xbfb8aa3b, v193
	v_mul_f32_e32 v226, 0xbfb8aa3b, v194
	v_mul_f32_e32 v227, 0xbfb8aa3b, v195
	v_exp_f32_e32 v220, v220
	v_exp_f32_e32 v221, v221
	v_exp_f32_e32 v222, v222
	v_exp_f32_e32 v223, v223
	v_exp_f32_e32 v224, v224
	v_exp_f32_e32 v225, v225
	v_exp_f32_e32 v226, v226
	v_exp_f32_e32 v227, v227
	v_add_f32_e32 v220, 1.0, v220
	v_add_f32_e32 v221, 1.0, v221
	v_add_f32_e32 v222, 1.0, v222
	v_add_f32_e32 v223, 1.0, v223
	v_add_f32_e32 v224, 1.0, v224
	v_add_f32_e32 v225, 1.0, v225
	v_add_f32_e32 v226, 1.0, v226
	v_add_f32_e32 v227, 1.0, v227
	v_rcp_f32_e32 v220, v220
	v_rcp_f32_e32 v221, v221
	v_rcp_f32_e32 v222, v222
	v_rcp_f32_e32 v223, v223
	v_rcp_f32_e32 v224, v224
	v_rcp_f32_e32 v225, v225
	v_rcp_f32_e32 v226, v226
	v_rcp_f32_e32 v227, v227
	v_mul_f32_e32 v220, v188, v220
	v_mul_f32_e32 v221, v189, v221
	v_mul_f32_e32 v222, v190, v222
	v_mul_f32_e32 v223, v191, v223
	v_mul_f32_e32 v224, v192, v224
	v_mul_f32_e32 v225, v193, v225
	v_mul_f32_e32 v226, v194, v226
	v_mul_f32_e32 v227, v195, v227
	v_cvt_pk_bf16_f32 v188, v220, v221
	v_cvt_pk_bf16_f32 v189, v222, v223
	v_cvt_pk_bf16_f32 v190, v224, v225
	v_cvt_pk_bf16_f32 v191, v226, v227
	global_store_dwordx4 v26, v[188:191], s[54:55]
	s_add_u32 s54, s54, 0x1000
	s_addc_u32 s55, s55, 0
	s_waitcnt vmcnt(15)
	v_lshlrev_b32_e32 v172, 16, v144
	v_and_b32_e32 v173, 0xffff0000, v144
	v_lshlrev_b32_e32 v174, 16, v145
	v_and_b32_e32 v175, 0xffff0000, v145
	v_lshlrev_b32_e32 v176, 16, v146
	v_and_b32_e32 v177, 0xffff0000, v146
	v_lshlrev_b32_e32 v178, 16, v147
	v_and_b32_e32 v179, 0xffff0000, v147
	v_pk_fma_f32 v[180:181], v[36:37], v[172:173], v[180:181]
	v_pk_fma_f32 v[182:183], v[38:39], v[174:175], v[182:183]
	v_pk_fma_f32 v[184:185], v[40:41], v[176:177], v[184:185]
	v_pk_fma_f32 v[186:187], v[42:43], v[178:179], v[186:187]
	v_pk_fma_f32 v[212:213], v[44:45], v[172:173], v[212:213]
	v_pk_fma_f32 v[214:215], v[46:47], v[174:175], v[214:215]
	v_pk_fma_f32 v[216:217], v[48:49], v[176:177], v[216:217]
	v_pk_fma_f32 v[218:219], v[50:51], v[178:179], v[218:219]
	v_pk_fma_f32 v[204:205], v[52:53], v[172:173], v[204:205]
	v_pk_fma_f32 v[206:207], v[54:55], v[174:175], v[206:207]
	v_pk_fma_f32 v[208:209], v[56:57], v[176:177], v[208:209]
	v_pk_fma_f32 v[210:211], v[58:59], v[178:179], v[210:211]
	v_pk_fma_f32 v[196:197], v[60:61], v[172:173], v[196:197]
	v_pk_fma_f32 v[198:199], v[62:63], v[174:175], v[198:199]
	v_pk_fma_f32 v[200:201], v[64:65], v[176:177], v[200:201]
	v_pk_fma_f32 v[202:203], v[66:67], v[178:179], v[202:203]
	v_mul_f32_e32 v220, 0xbfb8aa3b, v196
	v_mul_f32_e32 v221, 0xbfb8aa3b, v197
	v_mul_f32_e32 v222, 0xbfb8aa3b, v198
	v_mul_f32_e32 v223, 0xbfb8aa3b, v199
	v_mul_f32_e32 v224, 0xbfb8aa3b, v200
	v_mul_f32_e32 v225, 0xbfb8aa3b, v201
	v_mul_f32_e32 v226, 0xbfb8aa3b, v202
	v_mul_f32_e32 v227, 0xbfb8aa3b, v203
	v_exp_f32_e32 v220, v220
	v_exp_f32_e32 v221, v221
	v_exp_f32_e32 v222, v222
	v_exp_f32_e32 v223, v223
	v_exp_f32_e32 v224, v224
	v_exp_f32_e32 v225, v225
	v_exp_f32_e32 v226, v226
	v_exp_f32_e32 v227, v227
	v_add_f32_e32 v220, 1.0, v220
	v_add_f32_e32 v221, 1.0, v221
	v_add_f32_e32 v222, 1.0, v222
	v_add_f32_e32 v223, 1.0, v223
	v_add_f32_e32 v224, 1.0, v224
	v_add_f32_e32 v225, 1.0, v225
	v_add_f32_e32 v226, 1.0, v226
	v_add_f32_e32 v227, 1.0, v227
	v_rcp_f32_e32 v220, v220
	v_rcp_f32_e32 v221, v221
	v_rcp_f32_e32 v222, v222
	v_rcp_f32_e32 v223, v223
	v_rcp_f32_e32 v224, v224
	v_rcp_f32_e32 v225, v225
	v_rcp_f32_e32 v226, v226
	v_rcp_f32_e32 v227, v227
	v_mul_f32_e32 v220, v196, v220
	v_mul_f32_e32 v221, v197, v221
	v_mul_f32_e32 v222, v198, v222
	v_mul_f32_e32 v223, v199, v223
	v_mul_f32_e32 v224, v200, v224
	v_mul_f32_e32 v225, v201, v225
	v_mul_f32_e32 v226, v202, v226
	v_mul_f32_e32 v227, v203, v227
	v_cvt_pk_bf16_f32 v196, v220, v221
	v_cvt_pk_bf16_f32 v197, v222, v223
	v_cvt_pk_bf16_f32 v198, v224, v225
	v_cvt_pk_bf16_f32 v199, v226, v227
	global_store_dwordx4 v26, v[196:199], s[54:55]
	s_add_u32 s54, s54, 0x1000
	s_addc_u32 s55, s55, 0
	s_waitcnt vmcnt(15)
	v_lshlrev_b32_e32 v172, 16, v148
	v_and_b32_e32 v173, 0xffff0000, v148
	v_lshlrev_b32_e32 v174, 16, v149
	v_and_b32_e32 v175, 0xffff0000, v149
	v_lshlrev_b32_e32 v176, 16, v150
	v_and_b32_e32 v177, 0xffff0000, v150
	v_lshlrev_b32_e32 v178, 16, v151
	v_and_b32_e32 v179, 0xffff0000, v151
	v_pk_fma_f32 v[180:181], v[44:45], v[172:173], v[180:181]
	v_pk_fma_f32 v[182:183], v[46:47], v[174:175], v[182:183]
	v_pk_fma_f32 v[184:185], v[48:49], v[176:177], v[184:185]
	v_pk_fma_f32 v[186:187], v[50:51], v[178:179], v[186:187]
	v_pk_fma_f32 v[212:213], v[52:53], v[172:173], v[212:213]
	v_pk_fma_f32 v[214:215], v[54:55], v[174:175], v[214:215]
	v_pk_fma_f32 v[216:217], v[56:57], v[176:177], v[216:217]
	v_pk_fma_f32 v[218:219], v[58:59], v[178:179], v[218:219]
	v_pk_fma_f32 v[204:205], v[60:61], v[172:173], v[204:205]
	v_pk_fma_f32 v[206:207], v[62:63], v[174:175], v[206:207]
	v_pk_fma_f32 v[208:209], v[64:65], v[176:177], v[208:209]
	v_pk_fma_f32 v[210:211], v[66:67], v[178:179], v[210:211]
	v_mul_f32_e32 v220, 0xbfb8aa3b, v204
	v_mul_f32_e32 v221, 0xbfb8aa3b, v205
	v_mul_f32_e32 v222, 0xbfb8aa3b, v206
	v_mul_f32_e32 v223, 0xbfb8aa3b, v207
	v_mul_f32_e32 v224, 0xbfb8aa3b, v208
	v_mul_f32_e32 v225, 0xbfb8aa3b, v209
	v_mul_f32_e32 v226, 0xbfb8aa3b, v210
	v_mul_f32_e32 v227, 0xbfb8aa3b, v211
	v_exp_f32_e32 v220, v220
	v_exp_f32_e32 v221, v221
	v_exp_f32_e32 v222, v222
	v_exp_f32_e32 v223, v223
	v_exp_f32_e32 v224, v224
	v_exp_f32_e32 v225, v225
	v_exp_f32_e32 v226, v226
	v_exp_f32_e32 v227, v227
	v_add_f32_e32 v220, 1.0, v220
	v_add_f32_e32 v221, 1.0, v221
	v_add_f32_e32 v222, 1.0, v222
	v_add_f32_e32 v223, 1.0, v223
	v_add_f32_e32 v224, 1.0, v224
	v_add_f32_e32 v225, 1.0, v225
	v_add_f32_e32 v226, 1.0, v226
	v_add_f32_e32 v227, 1.0, v227
	v_rcp_f32_e32 v220, v220
	v_rcp_f32_e32 v221, v221
	v_rcp_f32_e32 v222, v222
	v_rcp_f32_e32 v223, v223
	v_rcp_f32_e32 v224, v224
	v_rcp_f32_e32 v225, v225
	v_rcp_f32_e32 v226, v226
	v_rcp_f32_e32 v227, v227
	v_mul_f32_e32 v220, v204, v220
	v_mul_f32_e32 v221, v205, v221
	v_mul_f32_e32 v222, v206, v222
	v_mul_f32_e32 v223, v207, v223
	v_mul_f32_e32 v224, v208, v224
	v_mul_f32_e32 v225, v209, v225
	v_mul_f32_e32 v226, v210, v226
	v_mul_f32_e32 v227, v211, v227
	v_cvt_pk_bf16_f32 v204, v220, v221
	v_cvt_pk_bf16_f32 v205, v222, v223
	v_cvt_pk_bf16_f32 v206, v224, v225
	v_cvt_pk_bf16_f32 v207, v226, v227
	global_store_dwordx4 v26, v[204:207], s[54:55]
	s_add_u32 s54, s54, 0x1000
	s_addc_u32 s55, s55, 0
	s_waitcnt vmcnt(15)
	v_and_b32_e32 v152, s63, v152
	v_and_b32_e32 v153, s63, v153
	v_and_b32_e32 v154, s63, v154
	v_and_b32_e32 v155, s63, v155
	v_lshlrev_b32_e32 v172, 16, v152
	v_and_b32_e32 v173, 0xffff0000, v152
	v_lshlrev_b32_e32 v174, 16, v153
	v_and_b32_e32 v175, 0xffff0000, v153
	v_lshlrev_b32_e32 v176, 16, v154
	v_and_b32_e32 v177, 0xffff0000, v154
	v_lshlrev_b32_e32 v178, 16, v155
	v_and_b32_e32 v179, 0xffff0000, v155
	v_pk_fma_f32 v[180:181], v[52:53], v[172:173], v[180:181]
	v_pk_fma_f32 v[182:183], v[54:55], v[174:175], v[182:183]
	v_pk_fma_f32 v[184:185], v[56:57], v[176:177], v[184:185]
	v_pk_fma_f32 v[186:187], v[58:59], v[178:179], v[186:187]
	v_pk_fma_f32 v[212:213], v[60:61], v[172:173], v[212:213]
	v_pk_fma_f32 v[214:215], v[62:63], v[174:175], v[214:215]
	v_pk_fma_f32 v[216:217], v[64:65], v[176:177], v[216:217]
	v_pk_fma_f32 v[218:219], v[66:67], v[178:179], v[218:219]
	v_mul_f32_e32 v220, 0xbfb8aa3b, v212
	v_mul_f32_e32 v221, 0xbfb8aa3b, v213
	v_mul_f32_e32 v222, 0xbfb8aa3b, v214
	v_mul_f32_e32 v223, 0xbfb8aa3b, v215
	v_mul_f32_e32 v224, 0xbfb8aa3b, v216
	v_mul_f32_e32 v225, 0xbfb8aa3b, v217
	v_mul_f32_e32 v226, 0xbfb8aa3b, v218
	v_mul_f32_e32 v227, 0xbfb8aa3b, v219
	v_exp_f32_e32 v220, v220
	v_exp_f32_e32 v221, v221
	v_exp_f32_e32 v222, v222
	v_exp_f32_e32 v223, v223
	v_exp_f32_e32 v224, v224
	v_exp_f32_e32 v225, v225
	v_exp_f32_e32 v226, v226
	v_exp_f32_e32 v227, v227
	v_add_f32_e32 v220, 1.0, v220
	v_add_f32_e32 v221, 1.0, v221
	v_add_f32_e32 v222, 1.0, v222
	v_add_f32_e32 v223, 1.0, v223
	v_add_f32_e32 v224, 1.0, v224
	v_add_f32_e32 v225, 1.0, v225
	v_add_f32_e32 v226, 1.0, v226
	v_add_f32_e32 v227, 1.0, v227
	v_rcp_f32_e32 v220, v220
	v_rcp_f32_e32 v221, v221
	v_rcp_f32_e32 v222, v222
	v_rcp_f32_e32 v223, v223
	v_rcp_f32_e32 v224, v224
	v_rcp_f32_e32 v225, v225
	v_rcp_f32_e32 v226, v226
	v_rcp_f32_e32 v227, v227
	v_mul_f32_e32 v220, v212, v220
	v_mul_f32_e32 v221, v213, v221
	v_mul_f32_e32 v222, v214, v222
	v_mul_f32_e32 v223, v215, v223
	v_mul_f32_e32 v224, v216, v224
	v_mul_f32_e32 v225, v217, v225
	v_mul_f32_e32 v226, v218, v226
	v_mul_f32_e32 v227, v219, v227
	v_cvt_pk_bf16_f32 v212, v220, v221
	v_cvt_pk_bf16_f32 v213, v222, v223
	v_cvt_pk_bf16_f32 v214, v224, v225
	v_cvt_pk_bf16_f32 v215, v226, v227
	global_store_dwordx4 v26, v[212:215], s[54:55]
	s_add_u32 s54, s54, 0x1000
	s_addc_u32 s55, s55, 0
	s_waitcnt vmcnt(15)
	v_and_b32_e32 v156, s63, v156
	v_and_b32_e32 v157, s63, v157
	v_and_b32_e32 v158, s63, v158
	v_and_b32_e32 v159, s63, v159
	v_lshlrev_b32_e32 v172, 16, v156
	v_and_b32_e32 v173, 0xffff0000, v156
	v_lshlrev_b32_e32 v174, 16, v157
	v_and_b32_e32 v175, 0xffff0000, v157
	v_lshlrev_b32_e32 v176, 16, v158
	v_and_b32_e32 v177, 0xffff0000, v158
	v_lshlrev_b32_e32 v178, 16, v159
	v_and_b32_e32 v179, 0xffff0000, v159
	v_pk_fma_f32 v[180:181], v[60:61], v[172:173], v[180:181]
	v_pk_fma_f32 v[182:183], v[62:63], v[174:175], v[182:183]
	v_pk_fma_f32 v[184:185], v[64:65], v[176:177], v[184:185]
	v_pk_fma_f32 v[186:187], v[66:67], v[178:179], v[186:187]
	v_mul_f32_e32 v220, 0xbfb8aa3b, v180
	v_mul_f32_e32 v221, 0xbfb8aa3b, v181
	v_mul_f32_e32 v222, 0xbfb8aa3b, v182
	v_mul_f32_e32 v223, 0xbfb8aa3b, v183
	v_mul_f32_e32 v224, 0xbfb8aa3b, v184
	v_mul_f32_e32 v225, 0xbfb8aa3b, v185
	v_mul_f32_e32 v226, 0xbfb8aa3b, v186
	v_mul_f32_e32 v227, 0xbfb8aa3b, v187
	v_exp_f32_e32 v220, v220
	v_exp_f32_e32 v221, v221
	v_exp_f32_e32 v222, v222
	v_exp_f32_e32 v223, v223
	v_exp_f32_e32 v224, v224
	v_exp_f32_e32 v225, v225
	v_exp_f32_e32 v226, v226
	v_exp_f32_e32 v227, v227
	v_add_f32_e32 v220, 1.0, v220
	v_add_f32_e32 v221, 1.0, v221
	v_add_f32_e32 v222, 1.0, v222
	v_add_f32_e32 v223, 1.0, v223
	v_add_f32_e32 v224, 1.0, v224
	v_add_f32_e32 v225, 1.0, v225
	v_add_f32_e32 v226, 1.0, v226
	v_add_f32_e32 v227, 1.0, v227
	v_rcp_f32_e32 v220, v220
	v_rcp_f32_e32 v221, v221
	v_rcp_f32_e32 v222, v222
	v_rcp_f32_e32 v223, v223
	v_rcp_f32_e32 v224, v224
	v_rcp_f32_e32 v225, v225
	v_rcp_f32_e32 v226, v226
	v_rcp_f32_e32 v227, v227
	v_mul_f32_e32 v220, v180, v220
	v_mul_f32_e32 v221, v181, v221
	v_mul_f32_e32 v222, v182, v222
	v_mul_f32_e32 v223, v183, v223
	v_mul_f32_e32 v224, v184, v224
	v_mul_f32_e32 v225, v185, v225
	v_mul_f32_e32 v226, v186, v226
	v_mul_f32_e32 v227, v187, v227
	v_cvt_pk_bf16_f32 v180, v220, v221
	v_cvt_pk_bf16_f32 v181, v222, v223
	v_cvt_pk_bf16_f32 v182, v224, v225
	v_cvt_pk_bf16_f32 v183, v226, v227
	global_store_dwordx4 v26, v[180:183], s[54:55]
	s_add_u32 s54, s54, 0x1000
	s_addc_u32 s55, s55, 0
	s_add_u32 s3, s3, s64
	s_branch .Lcv3_rb
.Lcv3_end:
.LBB0_486:
	s_or_b64 exec, exec, s[18:19]
	s_mov_b32 s3, 0x40000
	v_cmp_gt_i32_e32 vcc, s3, v8
	s_and_saveexec_b64 s[4:5], vcc
	s_cbranch_execz .LBB0_491
	s_load_dwordx2 s[8:9], s[16:17], 0x78
	v_and_b32_e32 v0, 31, v162
	v_mov_b32_e32 v1, 0
	v_ashrrev_i32_e32 v9, 31, v8
	v_lshlrev_b32_e32 v0, 2, v0
	s_waitcnt lgkmcnt(0)
	v_lshl_add_u64 v[0:1], s[8:9], 0, v[0:1]
	v_lshl_add_u64 v[2:3], v[8:9], 2, s[14:15]
	s_mov_b64 s[8:9], 0x1247a100
	s_ashr_i32 s13, s12, 31
	v_lshl_add_u64 v[2:3], v[2:3], 0, s[8:9]
	s_lshl_b64 s[8:9], s[12:13], 2
	s_mov_b64 s[10:11], 0
	s_mov_b32 s3, 0x41a00000
	s_mov_b32 s13, 0x3f2aaaab
	v_mov_b32_e32 v6, 0x3ecc95a3
	s_mov_b32 s16, 0x3f317218
	s_mov_b32 s17, 0x7f800000
	s_mov_b32 s18, 0x33800000
	s_mov_b32 s19, 0x3ffff
	v_mov_b32_e32 v4, 0x3f317218
	v_mov_b32_e32 v7, 0x7f800000
	v_mov_b32_e32 v9, 0x7fc00000
	v_mov_b32_e32 v10, 0xff800000
	s_branch .LBB0_489

.LBB0_836:
	s_lshl_b32 s6, s38, 7
	s_and_b32 s39, s6, 0x1f80
	s_lshl_b32 s6, s38, 1
	s_and_b32 s30, s6, 0xffffff80
	s_lshl_b32 s6, s39, 12
	v_lshl_add_u64 v[102:103], v[98:99], 0, s[6:7]
	v_add_co_u32_e32 v38, vcc, 0x20000, v102
	s_ashr_i32 s31, s30, 31
	s_nop 0
	v_addc_co_u32_e32 v39, vcc, 0, v103, vcc
	v_add_co_u32_e32 v44, vcc, 0x40000, v102
	s_lshl_b64 s[40:41], s[30:31], 12
	s_nop 0
	v_addc_co_u32_e32 v45, vcc, 0, v103, vcc
	v_add_co_u32_e32 v46, vcc, 0x60000, v102
	v_lshl_add_u64 v[104:105], v[100:101], 0, s[40:41]
	s_nop 0
	v_addc_co_u32_e32 v47, vcc, 0, v103, vcc
	v_add_co_u32_e32 v48, vcc, s35, v104
	s_nop 0
	v_addc_co_u32_e32 v49, vcc, 0, v105, vcc
	v_add_co_u32_e32 v50, vcc, s36, v104
	v_addc_co_u32_e32 v51, vcc, 0, v105, vcc
	v_add_co_u32_e32 v52, vcc, s37, v104
	v_addc_co_u32_e32 v53, vcc, 0, v105, vcc
	s_mov_b32 s31, -2
	v_mov_b32_e32 v8, 0
	v_mov_b32_e32 v9, v97
	v_mov_b32_e32 v10, v97
	v_mov_b32_e32 v11, v97
	v_mov_b32_e32 v24, 0
	v_mov_b32_e32 v25, v97
	v_mov_b32_e32 v26, v97
	v_mov_b32_e32 v27, v97
	v_mov_b32_e32 v36, 0
	v_mov_b32_e32 v37, v97
	v_mov_b32_e32 v38, v97
	v_lshl_add_u64 v[106:107], v[102:103], 0, s[8:9]
	v_lshl_add_u64 v[108:109], v[102:103], 0, s[10:11]
	v_lshl_add_u64 v[110:111], v[102:103], 0, s[12:13]
	v_lshl_add_u64 v[118:119], v[102:103], 0, s[14:15]
	v_lshl_add_u64 v[120:121], v[102:103], 0, s[16:17]
	v_lshl_add_u64 v[122:123], v[102:103], 0, s[18:19]
	v_lshl_add_u64 v[124:125], v[102:103], 0, s[20:21]
	v_lshl_add_u64 v[112:113], v[104:105], 0, s[8:9]
	v_lshl_add_u64 v[114:115], v[104:105], 0, s[10:11]
	v_lshl_add_u64 v[116:117], v[104:105], 0, s[12:13]
	v_lshl_add_u64 v[130:131], v[104:105], 0, s[14:15]
	v_lshl_add_u64 v[132:133], v[104:105], 0, s[16:17]
	v_lshl_add_u64 v[134:135], v[104:105], 0, s[18:19]
	v_lshl_add_u64 v[126:127], v[104:105], 0, s[20:21]
	v_mov_b32_e32 v39, v97
	v_mov_b32_e32 v48, 0
	v_mov_b32_e32 v49, v97
	v_mov_b32_e32 v50, v97
	v_mov_b32_e32 v51, v97
	v_mov_b32_e32 v52, 0
	v_mov_b32_e32 v53, v97
	v_mov_b32_e32 v54, v97
	v_mov_b32_e32 v55, v97
	v_mov_b32_e32 v56, 0
	v_mov_b32_e32 v57, v97
	v_mov_b32_e32 v58, v97
	v_mov_b32_e32 v59, v97
	v_mov_b32_e32 v44, 0
	v_mov_b32_e32 v45, v97
	v_mov_b32_e32 v46, v97
	v_mov_b32_e32 v47, v97
	v_mov_b32_e32 v60, 0
	v_mov_b32_e32 v61, v97
	v_mov_b32_e32 v62, v97
	v_mov_b32_e32 v63, v97
	v_mov_b32_e32 v0, 0
	v_mov_b32_e32 v1, v97
	v_mov_b32_e32 v2, v97
	v_mov_b32_e32 v3, v97
	v_mov_b32_e32 v16, 0
	v_mov_b32_e32 v17, v97
	v_mov_b32_e32 v18, v97
	v_mov_b32_e32 v19, v97
	v_mov_b32_e32 v32, 0
	v_mov_b32_e32 v33, v97
	v_mov_b32_e32 v34, v97
	v_mov_b32_e32 v35, v97
	v_mov_b32_e32 v4, 0
	v_mov_b32_e32 v5, v97
	v_mov_b32_e32 v6, v97
	v_mov_b32_e32 v7, v97
	v_mov_b32_e32 v20, 0
	v_mov_b32_e32 v21, v97
	v_mov_b32_e32 v22, v97
	v_mov_b32_e32 v23, v97
	v_mov_b32_e32 v40, 0
	v_mov_b32_e32 v41, v97
	v_mov_b32_e32 v42, v97
	v_mov_b32_e32 v43, v97
	v_mov_b32_e32 v12, 0
	v_mov_b32_e32 v13, v97
	v_mov_b32_e32 v14, v97
	v_mov_b32_e32 v15, v97
	v_mov_b32_e32 v28, 0
	v_mov_b32_e32 v29, v97
	v_mov_b32_e32 v30, v97
	v_mov_b32_e32 v31, v97
	v_readfirstlane_b32 s40, v102
	v_readfirstlane_b32 s41, v103
	v_readfirstlane_b32 s48, v104
	v_readfirstlane_b32 s49, v105
	v_readfirstlane_b32 s6, v247
	s_nop 3
	s_mul_i32 s32, s6, 0x8000
	s_sub_u32 s40, s40, s32
	s_subb_u32 s41, s41, 0
	s_sub_u32 s48, s48, s32
	s_subb_u32 s49, s49, 0
	s_lshl_b32 s6, s6, 12
	s_add_u32 m0, s6, 0x0
	v_mov_b32_e32 v60, 0
	global_load_lds_dwordx4 v248, s[40:41]
	v_mov_b32_e32 v61, 0
	s_add_u32 m0, s6, 0x400
	v_mov_b32_e32 v62, 0
	global_load_lds_dwordx4 v249, s[40:41]
	v_mov_b32_e32 v63, 0
	s_add_u32 m0, s6, 0x800
	v_mov_b32_e32 v44, 0
	global_load_lds_dwordx4 v250, s[40:41]
	v_mov_b32_e32 v45, 0
	s_add_u32 m0, s6, 0xc00
	v_mov_b32_e32 v46, 0
	global_load_lds_dwordx4 v251, s[40:41]
	v_mov_b32_e32 v47, 0
	s_add_u32 m0, s6, 0x8000
	v_mov_b32_e32 v28, 0
	global_load_lds_dwordx4 v248, s[48:49]
	v_mov_b32_e32 v29, 0
	s_add_u32 m0, s6, 0x8400
	v_mov_b32_e32 v30, 0
	global_load_lds_dwordx4 v249, s[48:49]
	v_mov_b32_e32 v31, 0
	s_add_u32 m0, s6, 0x8800
	v_mov_b32_e32 v12, 0
	global_load_lds_dwordx4 v250, s[48:49]
	v_mov_b32_e32 v13, 0
	s_add_u32 m0, s6, 0x8c00
	v_mov_b32_e32 v14, 0
	global_load_lds_dwordx4 v251, s[48:49]
	v_mov_b32_e32 v15, 0
	s_add_u32 s40, s40, 0x80
	s_addc_u32 s41, s41, 0
	s_add_u32 s48, s48, 0x80
	s_addc_u32 s49, s49, 0
	s_add_u32 m0, s6, 0x4000
	v_mov_b32_e32 v56, 0
	global_load_lds_dwordx4 v248, s[40:41]
	v_mov_b32_e32 v57, 0
	s_add_u32 m0, s6, 0x4400
	v_mov_b32_e32 v58, 0
	global_load_lds_dwordx4 v249, s[40:41]
	v_mov_b32_e32 v59, 0
	s_add_u32 m0, s6, 0x4800
	v_mov_b32_e32 v40, 0
	global_load_lds_dwordx4 v250, s[40:41]
	v_mov_b32_e32 v41, 0
	s_add_u32 m0, s6, 0x4c00
	v_mov_b32_e32 v42, 0
	global_load_lds_dwordx4 v251, s[40:41]
	v_mov_b32_e32 v43, 0
	s_add_u32 m0, s6, 0xc000
	v_mov_b32_e32 v20, 0
	global_load_lds_dwordx4 v248, s[48:49]
	v_mov_b32_e32 v21, 0
	s_add_u32 m0, s6, 0xc400
	v_mov_b32_e32 v22, 0
	global_load_lds_dwordx4 v249, s[48:49]
	v_mov_b32_e32 v23, 0
	s_add_u32 m0, s6, 0xc800
	v_mov_b32_e32 v4, 0
	global_load_lds_dwordx4 v250, s[48:49]
	v_mov_b32_e32 v5, 0
	s_add_u32 m0, s6, 0xcc00
	v_mov_b32_e32 v6, 0
	global_load_lds_dwordx4 v251, s[48:49]
	v_mov_b32_e32 v7, 0
	s_add_u32 s40, s40, 0x80
	s_addc_u32 s41, s41, 0
	s_add_u32 s48, s48, 0x80
	s_addc_u32 s49, s49, 0
	v_mov_b32_e32 v52, 0
	v_mov_b32_e32 v53, 0
	v_mov_b32_e32 v54, 0
	v_mov_b32_e32 v55, 0
	v_mov_b32_e32 v32, 0
	v_mov_b32_e32 v33, 0
	v_mov_b32_e32 v34, 0
	v_mov_b32_e32 v35, 0
	v_mov_b32_e32 v16, 0
	v_mov_b32_e32 v17, 0
	v_mov_b32_e32 v18, 0
	v_mov_b32_e32 v19, 0
	v_mov_b32_e32 v0, 0
	v_mov_b32_e32 v1, 0
	v_mov_b32_e32 v2, 0
	v_mov_b32_e32 v3, 0
	v_mov_b32_e32 v48, 0
	v_mov_b32_e32 v49, 0
	v_mov_b32_e32 v50, 0
	v_mov_b32_e32 v51, 0
	v_mov_b32_e32 v36, 0
	v_mov_b32_e32 v37, 0
	v_mov_b32_e32 v38, 0
	v_mov_b32_e32 v39, 0
	v_mov_b32_e32 v24, 0
	v_mov_b32_e32 v25, 0
	v_mov_b32_e32 v26, 0
	v_mov_b32_e32 v27, 0
	v_mov_b32_e32 v8, 0
	v_mov_b32_e32 v9, 0
	v_mov_b32_e32 v10, 0
	v_mov_b32_e32 v11, 0
	s_waitcnt vmcnt(8)
	s_barrier
	ds_read_b128 v[64:67], v252 offset:0
	ds_read_b128 v[104:107], v254 offset:32768
	ds_read_b128 v[108:111], v254 offset:34816
	ds_read_b128 v[112:115], v254 offset:36864
	ds_read_b128 v[116:119], v254 offset:38912
	ds_read_b128 v[68:71], v252 offset:2048
	ds_read_b128 v[72:75], v252 offset:4096
	ds_read_b128 v[76:79], v252 offset:6144
	ds_read_b128 v[80:83], v253 offset:0
	ds_read_b128 v[120:123], v255 offset:32768
	ds_read_b128 v[124:127], v255 offset:34816
	ds_read_b128 v[132:135], v255 offset:36864
	ds_read_b128 v[136:139], v255 offset:38912
	s_waitcnt lgkmcnt(11)
	v_mfma_f32_16x16x32_bf16 v[60:63], v[64:67], v[104:107], v[60:63]
	s_waitcnt lgkmcnt(10)
	v_mfma_f32_16x16x32_bf16 v[44:47], v[64:67], v[108:111], v[44:47]
	s_waitcnt lgkmcnt(9)
	v_mfma_f32_16x16x32_bf16 v[28:31], v[64:67], v[112:115], v[28:31]
	s_waitcnt lgkmcnt(8)
	v_mfma_f32_16x16x32_bf16 v[12:15], v[64:67], v[116:119], v[12:15]
	ds_read_b128 v[84:87], v253 offset:2048
	ds_read_b128 v[88:91], v253 offset:4096
	ds_read_b128 v[92:95], v253 offset:6144
	s_waitcnt lgkmcnt(10)
	v_mfma_f32_16x16x32_bf16 v[56:59], v[68:71], v[104:107], v[56:59]
	v_mfma_f32_16x16x32_bf16 v[40:43], v[68:71], v[108:111], v[40:43]
	v_mfma_f32_16x16x32_bf16 v[20:23], v[68:71], v[112:115], v[20:23]
	v_mfma_f32_16x16x32_bf16 v[4:7], v[68:71], v[116:119], v[4:7]
	s_waitcnt lgkmcnt(0)
	s_barrier
	s_add_u32 m0, s6, 0x0
	v_mfma_f32_16x16x32_bf16 v[52:55], v[72:75], v[104:107], v[52:55]
	global_load_lds_dwordx4 v248, s[40:41]
	s_add_u32 m0, s6, 0x400
	v_mfma_f32_16x16x32_bf16 v[32:35], v[72:75], v[108:111], v[32:35]
	global_load_lds_dwordx4 v249, s[40:41]
	s_add_u32 m0, s6, 0x800
	v_mfma_f32_16x16x32_bf16 v[16:19], v[72:75], v[112:115], v[16:19]
	global_load_lds_dwordx4 v250, s[40:41]
	s_add_u32 m0, s6, 0xc00
	v_mfma_f32_16x16x32_bf16 v[0:3], v[72:75], v[116:119], v[0:3]
	global_load_lds_dwordx4 v251, s[40:41]
	s_add_u32 m0, s6, 0x8000
	v_mfma_f32_16x16x32_bf16 v[48:51], v[76:79], v[104:107], v[48:51]
	global_load_lds_dwordx4 v248, s[48:49]
	s_add_u32 m0, s6, 0x8400
	v_mfma_f32_16x16x32_bf16 v[36:39], v[76:79], v[108:111], v[36:39]
	global_load_lds_dwordx4 v249, s[48:49]
	s_add_u32 m0, s6, 0x8800
	v_mfma_f32_16x16x32_bf16 v[24:27], v[76:79], v[112:115], v[24:27]
	global_load_lds_dwordx4 v250, s[48:49]
	s_add_u32 m0, s6, 0x8c00
	v_mfma_f32_16x16x32_bf16 v[8:11], v[76:79], v[116:119], v[8:11]
	global_load_lds_dwordx4 v251, s[48:49]
	s_add_u32 s40, s40, 0x80
	s_addc_u32 s41, s41, 0
	s_add_u32 s48, s48, 0x80
	s_addc_u32 s49, s49, 0
	s_waitcnt vmcnt(8)
	s_barrier
	ds_read_b128 v[64:67], v252 offset:16384
	ds_read_b128 v[104:107], v254 offset:49152
	ds_read_b128 v[108:111], v254 offset:51200
	ds_read_b128 v[112:115], v254 offset:53248
	ds_read_b128 v[116:119], v254 offset:55296
	ds_read_b128 v[68:71], v252 offset:18432
	ds_read_b128 v[72:75], v252 offset:20480
	ds_read_b128 v[76:79], v252 offset:22528
	v_mfma_f32_16x16x32_bf16 v[60:63], v[80:83], v[120:123], v[60:63]
	v_mfma_f32_16x16x32_bf16 v[44:47], v[80:83], v[124:127], v[44:47]
	v_mfma_f32_16x16x32_bf16 v[28:31], v[80:83], v[132:135], v[28:31]
	v_mfma_f32_16x16x32_bf16 v[12:15], v[80:83], v[136:139], v[12:15]
	v_mfma_f32_16x16x32_bf16 v[56:59], v[84:87], v[120:123], v[56:59]
	v_mfma_f32_16x16x32_bf16 v[40:43], v[84:87], v[124:127], v[40:43]
	v_mfma_f32_16x16x32_bf16 v[20:23], v[84:87], v[132:135], v[20:23]
	v_mfma_f32_16x16x32_bf16 v[4:7], v[84:87], v[136:139], v[4:7]
	v_mfma_f32_16x16x32_bf16 v[52:55], v[88:91], v[120:123], v[52:55]
	v_mfma_f32_16x16x32_bf16 v[32:35], v[88:91], v[124:127], v[32:35]
	v_mfma_f32_16x16x32_bf16 v[16:19], v[88:91], v[132:135], v[16:19]
	v_mfma_f32_16x16x32_bf16 v[0:3], v[88:91], v[136:139], v[0:3]
	v_mfma_f32_16x16x32_bf16 v[48:51], v[92:95], v[120:123], v[48:51]
	v_mfma_f32_16x16x32_bf16 v[36:39], v[92:95], v[124:127], v[36:39]
	v_mfma_f32_16x16x32_bf16 v[24:27], v[92:95], v[132:135], v[24:27]
	v_mfma_f32_16x16x32_bf16 v[8:11], v[92:95], v[136:139], v[8:11]
	ds_read_b128 v[80:83], v253 offset:16384
	ds_read_b128 v[120:123], v255 offset:49152
	ds_read_b128 v[124:127], v255 offset:51200
	ds_read_b128 v[132:135], v255 offset:53248
	ds_read_b128 v[136:139], v255 offset:55296
	ds_read_b128 v[84:87], v253 offset:18432
	ds_read_b128 v[88:91], v253 offset:20480
	ds_read_b128 v[92:95], v253 offset:22528
	s_waitcnt lgkmcnt(14)
	v_mfma_f32_16x16x32_bf16 v[60:63], v[64:67], v[104:107], v[60:63]
	s_waitcnt lgkmcnt(13)
	v_mfma_f32_16x16x32_bf16 v[44:47], v[64:67], v[108:111], v[44:47]
	s_waitcnt lgkmcnt(12)
	v_mfma_f32_16x16x32_bf16 v[28:31], v[64:67], v[112:115], v[28:31]
	s_waitcnt lgkmcnt(11)
	v_mfma_f32_16x16x32_bf16 v[12:15], v[64:67], v[116:119], v[12:15]
	s_waitcnt lgkmcnt(10)
	v_mfma_f32_16x16x32_bf16 v[56:59], v[68:71], v[104:107], v[56:59]
	v_mfma_f32_16x16x32_bf16 v[40:43], v[68:71], v[108:111], v[40:43]
	v_mfma_f32_16x16x32_bf16 v[20:23], v[68:71], v[112:115], v[20:23]
	v_mfma_f32_16x16x32_bf16 v[4:7], v[68:71], v[116:119], v[4:7]
	s_waitcnt lgkmcnt(0)
	s_barrier
	s_add_u32 m0, s6, 0x4000
	v_mfma_f32_16x16x32_bf16 v[52:55], v[72:75], v[104:107], v[52:55]
	global_load_lds_dwordx4 v248, s[40:41]
	s_add_u32 m0, s6, 0x4400
	v_mfma_f32_16x16x32_bf16 v[32:35], v[72:75], v[108:111], v[32:35]
	global_load_lds_dwordx4 v249, s[40:41]
	s_add_u32 m0, s6, 0x4800
	v_mfma_f32_16x16x32_bf16 v[16:19], v[72:75], v[112:115], v[16:19]
	global_load_lds_dwordx4 v250, s[40:41]
	s_add_u32 m0, s6, 0x4c00
	v_mfma_f32_16x16x32_bf16 v[0:3], v[72:75], v[116:119], v[0:3]
	global_load_lds_dwordx4 v251, s[40:41]
	s_add_u32 m0, s6, 0xc000
	v_mfma_f32_16x16x32_bf16 v[48:51], v[76:79], v[104:107], v[48:51]
	global_load_lds_dwordx4 v248, s[48:49]
	s_add_u32 m0, s6, 0xc400
	v_mfma_f32_16x16x32_bf16 v[36:39], v[76:79], v[108:111], v[36:39]
	global_load_lds_dwordx4 v249, s[48:49]
	s_add_u32 m0, s6, 0xc800
	v_mfma_f32_16x16x32_bf16 v[24:27], v[76:79], v[112:115], v[24:27]
	global_load_lds_dwordx4 v250, s[48:49]
	s_add_u32 m0, s6, 0xcc00
	v_mfma_f32_16x16x32_bf16 v[8:11], v[76:79], v[116:119], v[8:11]
	global_load_lds_dwordx4 v251, s[48:49]
	s_add_u32 s40, s40, 0x80
	s_addc_u32 s41, s41, 0
	s_add_u32 s48, s48, 0x80
	s_addc_u32 s49, s49, 0
	s_mov_b32 s31, 14
.Lg6_loop:
	s_waitcnt vmcnt(8)
	s_barrier
	ds_read_b128 v[64:67], v252 offset:0
	ds_read_b128 v[104:107], v254 offset:32768
	ds_read_b128 v[108:111], v254 offset:34816
	ds_read_b128 v[112:115], v254 offset:36864
	ds_read_b128 v[116:119], v254 offset:38912
	ds_read_b128 v[68:71], v252 offset:2048
	ds_read_b128 v[72:75], v252 offset:4096
	ds_read_b128 v[76:79], v252 offset:6144
	v_mfma_f32_16x16x32_bf16 v[60:63], v[80:83], v[120:123], v[60:63]
	v_mfma_f32_16x16x32_bf16 v[44:47], v[80:83], v[124:127], v[44:47]
	v_mfma_f32_16x16x32_bf16 v[28:31], v[80:83], v[132:135], v[28:31]
	v_mfma_f32_16x16x32_bf16 v[12:15], v[80:83], v[136:139], v[12:15]
	v_mfma_f32_16x16x32_bf16 v[56:59], v[84:87], v[120:123], v[56:59]
	v_mfma_f32_16x16x32_bf16 v[40:43], v[84:87], v[124:127], v[40:43]
	v_mfma_f32_16x16x32_bf16 v[20:23], v[84:87], v[132:135], v[20:23]
	v_mfma_f32_16x16x32_bf16 v[4:7], v[84:87], v[136:139], v[4:7]
	v_mfma_f32_16x16x32_bf16 v[52:55], v[88:91], v[120:123], v[52:55]
	v_mfma_f32_16x16x32_bf16 v[32:35], v[88:91], v[124:127], v[32:35]
	v_mfma_f32_16x16x32_bf16 v[16:19], v[88:91], v[132:135], v[16:19]
	v_mfma_f32_16x16x32_bf16 v[0:3], v[88:91], v[136:139], v[0:3]
	v_mfma_f32_16x16x32_bf16 v[48:51], v[92:95], v[120:123], v[48:51]
	v_mfma_f32_16x16x32_bf16 v[36:39], v[92:95], v[124:127], v[36:39]
	v_mfma_f32_16x16x32_bf16 v[24:27], v[92:95], v[132:135], v[24:27]
	v_mfma_f32_16x16x32_bf16 v[8:11], v[92:95], v[136:139], v[8:11]
	ds_read_b128 v[80:83], v253 offset:0
	ds_read_b128 v[120:123], v255 offset:32768
	ds_read_b128 v[124:127], v255 offset:34816
	ds_read_b128 v[132:135], v255 offset:36864
	ds_read_b128 v[136:139], v255 offset:38912
	ds_read_b128 v[84:87], v253 offset:2048
	ds_read_b128 v[88:91], v253 offset:4096
	ds_read_b128 v[92:95], v253 offset:6144
	s_waitcnt lgkmcnt(14)
	v_mfma_f32_16x16x32_bf16 v[60:63], v[64:67], v[104:107], v[60:63]
	s_waitcnt lgkmcnt(13)
	v_mfma_f32_16x16x32_bf16 v[44:47], v[64:67], v[108:111], v[44:47]
	s_waitcnt lgkmcnt(12)
	v_mfma_f32_16x16x32_bf16 v[28:31], v[64:67], v[112:115], v[28:31]
	s_waitcnt lgkmcnt(11)
	v_mfma_f32_16x16x32_bf16 v[12:15], v[64:67], v[116:119], v[12:15]
	s_waitcnt lgkmcnt(10)
	v_mfma_f32_16x16x32_bf16 v[56:59], v[68:71], v[104:107], v[56:59]
	v_mfma_f32_16x16x32_bf16 v[40:43], v[68:71], v[108:111], v[40:43]
	v_mfma_f32_16x16x32_bf16 v[20:23], v[68:71], v[112:115], v[20:23]
	v_mfma_f32_16x16x32_bf16 v[4:7], v[68:71], v[116:119], v[4:7]
	s_waitcnt lgkmcnt(0)
	s_barrier
	s_add_u32 m0, s6, 0x0
	v_mfma_f32_16x16x32_bf16 v[52:55], v[72:75], v[104:107], v[52:55]
	global_load_lds_dwordx4 v248, s[40:41]
	s_add_u32 m0, s6, 0x400
	v_mfma_f32_16x16x32_bf16 v[32:35], v[72:75], v[108:111], v[32:35]
	global_load_lds_dwordx4 v249, s[40:41]
	s_add_u32 m0, s6, 0x800
	v_mfma_f32_16x16x32_bf16 v[16:19], v[72:75], v[112:115], v[16:19]
	global_load_lds_dwordx4 v250, s[40:41]
	s_add_u32 m0, s6, 0xc00
	v_mfma_f32_16x16x32_bf16 v[0:3], v[72:75], v[116:119], v[0:3]
	global_load_lds_dwordx4 v251, s[40:41]
	s_add_u32 m0, s6, 0x8000
	v_mfma_f32_16x16x32_bf16 v[48:51], v[76:79], v[104:107], v[48:51]
	global_load_lds_dwordx4 v248, s[48:49]
	s_add_u32 m0, s6, 0x8400
	v_mfma_f32_16x16x32_bf16 v[36:39], v[76:79], v[108:111], v[36:39]
	global_load_lds_dwordx4 v249, s[48:49]
	s_add_u32 m0, s6, 0x8800
	v_mfma_f32_16x16x32_bf16 v[24:27], v[76:79], v[112:115], v[24:27]
	global_load_lds_dwordx4 v250, s[48:49]
	s_add_u32 m0, s6, 0x8c00
	v_mfma_f32_16x16x32_bf16 v[8:11], v[76:79], v[116:119], v[8:11]
	global_load_lds_dwordx4 v251, s[48:49]
	s_add_u32 s40, s40, 0x80
	s_addc_u32 s41, s41, 0
	s_add_u32 s48, s48, 0x80
	s_addc_u32 s49, s49, 0
	s_waitcnt vmcnt(8)
	s_barrier
	ds_read_b128 v[64:67], v252 offset:16384
	ds_read_b128 v[104:107], v254 offset:49152
	ds_read_b128 v[108:111], v254 offset:51200
	ds_read_b128 v[112:115], v254 offset:53248
	ds_read_b128 v[116:119], v254 offset:55296
	ds_read_b128 v[68:71], v252 offset:18432
	ds_read_b128 v[72:75], v252 offset:20480
	ds_read_b128 v[76:79], v252 offset:22528
	v_mfma_f32_16x16x32_bf16 v[60:63], v[80:83], v[120:123], v[60:63]
	v_mfma_f32_16x16x32_bf16 v[44:47], v[80:83], v[124:127], v[44:47]
	v_mfma_f32_16x16x32_bf16 v[28:31], v[80:83], v[132:135], v[28:31]
	v_mfma_f32_16x16x32_bf16 v[12:15], v[80:83], v[136:139], v[12:15]
	v_mfma_f32_16x16x32_bf16 v[56:59], v[84:87], v[120:123], v[56:59]
	v_mfma_f32_16x16x32_bf16 v[40:43], v[84:87], v[124:127], v[40:43]
	v_mfma_f32_16x16x32_bf16 v[20:23], v[84:87], v[132:135], v[20:23]
	v_mfma_f32_16x16x32_bf16 v[4:7], v[84:87], v[136:139], v[4:7]
	v_mfma_f32_16x16x32_bf16 v[52:55], v[88:91], v[120:123], v[52:55]
	v_mfma_f32_16x16x32_bf16 v[32:35], v[88:91], v[124:127], v[32:35]
	v_mfma_f32_16x16x32_bf16 v[16:19], v[88:91], v[132:135], v[16:19]
	v_mfma_f32_16x16x32_bf16 v[0:3], v[88:91], v[136:139], v[0:3]
	v_mfma_f32_16x16x32_bf16 v[48:51], v[92:95], v[120:123], v[48:51]
	v_mfma_f32_16x16x32_bf16 v[36:39], v[92:95], v[124:127], v[36:39]
	v_mfma_f32_16x16x32_bf16 v[24:27], v[92:95], v[132:135], v[24:27]
	v_mfma_f32_16x16x32_bf16 v[8:11], v[92:95], v[136:139], v[8:11]
	ds_read_b128 v[80:83], v253 offset:16384
	ds_read_b128 v[120:123], v255 offset:49152
	ds_read_b128 v[124:127], v255 offset:51200
	ds_read_b128 v[132:135], v255 offset:53248
	ds_read_b128 v[136:139], v255 offset:55296
	ds_read_b128 v[84:87], v253 offset:18432
	ds_read_b128 v[88:91], v253 offset:20480
	ds_read_b128 v[92:95], v253 offset:22528
	s_waitcnt lgkmcnt(14)
	v_mfma_f32_16x16x32_bf16 v[60:63], v[64:67], v[104:107], v[60:63]
	s_waitcnt lgkmcnt(13)
	v_mfma_f32_16x16x32_bf16 v[44:47], v[64:67], v[108:111], v[44:47]
	s_waitcnt lgkmcnt(12)
	v_mfma_f32_16x16x32_bf16 v[28:31], v[64:67], v[112:115], v[28:31]
	s_waitcnt lgkmcnt(11)
	v_mfma_f32_16x16x32_bf16 v[12:15], v[64:67], v[116:119], v[12:15]
	s_waitcnt lgkmcnt(10)
	v_mfma_f32_16x16x32_bf16 v[56:59], v[68:71], v[104:107], v[56:59]
	v_mfma_f32_16x16x32_bf16 v[40:43], v[68:71], v[108:111], v[40:43]
	v_mfma_f32_16x16x32_bf16 v[20:23], v[68:71], v[112:115], v[20:23]
	v_mfma_f32_16x16x32_bf16 v[4:7], v[68:71], v[116:119], v[4:7]
	s_waitcnt lgkmcnt(0)
	s_barrier
	s_add_u32 m0, s6, 0x4000
	v_mfma_f32_16x16x32_bf16 v[52:55], v[72:75], v[104:107], v[52:55]
	global_load_lds_dwordx4 v248, s[40:41]
	s_add_u32 m0, s6, 0x4400
	v_mfma_f32_16x16x32_bf16 v[32:35], v[72:75], v[108:111], v[32:35]
	global_load_lds_dwordx4 v249, s[40:41]
	s_add_u32 m0, s6, 0x4800
	v_mfma_f32_16x16x32_bf16 v[16:19], v[72:75], v[112:115], v[16:19]
	global_load_lds_dwordx4 v250, s[40:41]
	s_add_u32 m0, s6, 0x4c00
	v_mfma_f32_16x16x32_bf16 v[0:3], v[72:75], v[116:119], v[0:3]
	global_load_lds_dwordx4 v251, s[40:41]
	s_add_u32 m0, s6, 0xc000
	v_mfma_f32_16x16x32_bf16 v[48:51], v[76:79], v[104:107], v[48:51]
	global_load_lds_dwordx4 v248, s[48:49]
	s_add_u32 m0, s6, 0xc400
	v_mfma_f32_16x16x32_bf16 v[36:39], v[76:79], v[108:111], v[36:39]
	global_load_lds_dwordx4 v249, s[48:49]
	s_add_u32 m0, s6, 0xc800
	v_mfma_f32_16x16x32_bf16 v[24:27], v[76:79], v[112:115], v[24:27]
	global_load_lds_dwordx4 v250, s[48:49]
	s_add_u32 m0, s6, 0xcc00
	v_mfma_f32_16x16x32_bf16 v[8:11], v[76:79], v[116:119], v[8:11]
	global_load_lds_dwordx4 v251, s[48:49]
	s_add_u32 s40, s40, 0x80
	s_addc_u32 s41, s41, 0
	s_add_u32 s48, s48, 0x80
	s_addc_u32 s49, s49, 0
	s_sub_u32 s31, s31, 1
	s_cmp_lg_u32 s31, 0
	s_cbranch_scc1 .Lg6_loop
	s_waitcnt vmcnt(8)
	s_barrier
	ds_read_b128 v[64:67], v252 offset:0
	ds_read_b128 v[104:107], v254 offset:32768
	ds_read_b128 v[108:111], v254 offset:34816
	ds_read_b128 v[112:115], v254 offset:36864
	ds_read_b128 v[116:119], v254 offset:38912
	ds_read_b128 v[68:71], v252 offset:2048
	ds_read_b128 v[72:75], v252 offset:4096
	ds_read_b128 v[76:79], v252 offset:6144
	v_mfma_f32_16x16x32_bf16 v[60:63], v[80:83], v[120:123], v[60:63]
	v_mfma_f32_16x16x32_bf16 v[44:47], v[80:83], v[124:127], v[44:47]
	v_mfma_f32_16x16x32_bf16 v[28:31], v[80:83], v[132:135], v[28:31]
	v_mfma_f32_16x16x32_bf16 v[12:15], v[80:83], v[136:139], v[12:15]
	v_mfma_f32_16x16x32_bf16 v[56:59], v[84:87], v[120:123], v[56:59]
	v_mfma_f32_16x16x32_bf16 v[40:43], v[84:87], v[124:127], v[40:43]
	v_mfma_f32_16x16x32_bf16 v[20:23], v[84:87], v[132:135], v[20:23]
	v_mfma_f32_16x16x32_bf16 v[4:7], v[84:87], v[136:139], v[4:7]
	v_mfma_f32_16x16x32_bf16 v[52:55], v[88:91], v[120:123], v[52:55]
	v_mfma_f32_16x16x32_bf16 v[32:35], v[88:91], v[124:127], v[32:35]
	v_mfma_f32_16x16x32_bf16 v[16:19], v[88:91], v[132:135], v[16:19]
	v_mfma_f32_16x16x32_bf16 v[0:3], v[88:91], v[136:139], v[0:3]
	v_mfma_f32_16x16x32_bf16 v[48:51], v[92:95], v[120:123], v[48:51]
	v_mfma_f32_16x16x32_bf16 v[36:39], v[92:95], v[124:127], v[36:39]
	v_mfma_f32_16x16x32_bf16 v[24:27], v[92:95], v[132:135], v[24:27]
	v_mfma_f32_16x16x32_bf16 v[8:11], v[92:95], v[136:139], v[8:11]
	ds_read_b128 v[80:83], v253 offset:0
	ds_read_b128 v[120:123], v255 offset:32768
	ds_read_b128 v[124:127], v255 offset:34816
	ds_read_b128 v[132:135], v255 offset:36864
	ds_read_b128 v[136:139], v255 offset:38912
	ds_read_b128 v[84:87], v253 offset:2048
	ds_read_b128 v[88:91], v253 offset:4096
	ds_read_b128 v[92:95], v253 offset:6144
	s_waitcnt lgkmcnt(14)
	v_mfma_f32_16x16x32_bf16 v[60:63], v[64:67], v[104:107], v[60:63]
	s_waitcnt lgkmcnt(13)
	v_mfma_f32_16x16x32_bf16 v[44:47], v[64:67], v[108:111], v[44:47]
	s_waitcnt lgkmcnt(12)
	v_mfma_f32_16x16x32_bf16 v[28:31], v[64:67], v[112:115], v[28:31]
	s_waitcnt lgkmcnt(11)
	v_mfma_f32_16x16x32_bf16 v[12:15], v[64:67], v[116:119], v[12:15]
	s_waitcnt lgkmcnt(10)
	v_mfma_f32_16x16x32_bf16 v[56:59], v[68:71], v[104:107], v[56:59]
	v_mfma_f32_16x16x32_bf16 v[40:43], v[68:71], v[108:111], v[40:43]
	v_mfma_f32_16x16x32_bf16 v[20:23], v[68:71], v[112:115], v[20:23]
	v_mfma_f32_16x16x32_bf16 v[4:7], v[68:71], v[116:119], v[4:7]
	s_waitcnt lgkmcnt(0)
	s_barrier
	v_mfma_f32_16x16x32_bf16 v[52:55], v[72:75], v[104:107], v[52:55]
	v_mfma_f32_16x16x32_bf16 v[32:35], v[72:75], v[108:111], v[32:35]
	v_mfma_f32_16x16x32_bf16 v[16:19], v[72:75], v[112:115], v[16:19]
	v_mfma_f32_16x16x32_bf16 v[0:3], v[72:75], v[116:119], v[0:3]
	v_mfma_f32_16x16x32_bf16 v[48:51], v[76:79], v[104:107], v[48:51]
	v_mfma_f32_16x16x32_bf16 v[36:39], v[76:79], v[108:111], v[36:39]
	v_mfma_f32_16x16x32_bf16 v[24:27], v[76:79], v[112:115], v[24:27]
	v_mfma_f32_16x16x32_bf16 v[8:11], v[76:79], v[116:119], v[8:11]
	s_waitcnt vmcnt(0)
	s_barrier
	ds_read_b128 v[64:67], v252 offset:16384
	ds_read_b128 v[104:107], v254 offset:49152
	ds_read_b128 v[108:111], v254 offset:51200
	ds_read_b128 v[112:115], v254 offset:53248
	ds_read_b128 v[116:119], v254 offset:55296
	ds_read_b128 v[68:71], v252 offset:18432
	ds_read_b128 v[72:75], v252 offset:20480
	ds_read_b128 v[76:79], v252 offset:22528
	v_mfma_f32_16x16x32_bf16 v[60:63], v[80:83], v[120:123], v[60:63]
	v_mfma_f32_16x16x32_bf16 v[44:47], v[80:83], v[124:127], v[44:47]
	v_mfma_f32_16x16x32_bf16 v[28:31], v[80:83], v[132:135], v[28:31]
	v_mfma_f32_16x16x32_bf16 v[12:15], v[80:83], v[136:139], v[12:15]
	v_mfma_f32_16x16x32_bf16 v[56:59], v[84:87], v[120:123], v[56:59]
	v_mfma_f32_16x16x32_bf16 v[40:43], v[84:87], v[124:127], v[40:43]
	v_mfma_f32_16x16x32_bf16 v[20:23], v[84:87], v[132:135], v[20:23]
	v_mfma_f32_16x16x32_bf16 v[4:7], v[84:87], v[136:139], v[4:7]
	v_mfma_f32_16x16x32_bf16 v[52:55], v[88:91], v[120:123], v[52:55]
	v_mfma_f32_16x16x32_bf16 v[32:35], v[88:91], v[124:127], v[32:35]
	v_mfma_f32_16x16x32_bf16 v[16:19], v[88:91], v[132:135], v[16:19]
	v_mfma_f32_16x16x32_bf16 v[0:3], v[88:91], v[136:139], v[0:3]
	v_mfma_f32_16x16x32_bf16 v[48:51], v[92:95], v[120:123], v[48:51]
	v_mfma_f32_16x16x32_bf16 v[36:39], v[92:95], v[124:127], v[36:39]
	v_mfma_f32_16x16x32_bf16 v[24:27], v[92:95], v[132:135], v[24:27]
	v_mfma_f32_16x16x32_bf16 v[8:11], v[92:95], v[136:139], v[8:11]
	ds_read_b128 v[80:83], v253 offset:16384
	ds_read_b128 v[120:123], v255 offset:49152
	ds_read_b128 v[124:127], v255 offset:51200
	ds_read_b128 v[132:135], v255 offset:53248
	ds_read_b128 v[136:139], v255 offset:55296
	ds_read_b128 v[84:87], v253 offset:18432
	ds_read_b128 v[88:91], v253 offset:20480
	ds_read_b128 v[92:95], v253 offset:22528
	s_waitcnt lgkmcnt(14)
	v_mfma_f32_16x16x32_bf16 v[60:63], v[64:67], v[104:107], v[60:63]
	s_waitcnt lgkmcnt(13)
	v_mfma_f32_16x16x32_bf16 v[44:47], v[64:67], v[108:111], v[44:47]
	s_waitcnt lgkmcnt(12)
	v_mfma_f32_16x16x32_bf16 v[28:31], v[64:67], v[112:115], v[28:31]
	s_waitcnt lgkmcnt(11)
	v_mfma_f32_16x16x32_bf16 v[12:15], v[64:67], v[116:119], v[12:15]
	s_waitcnt lgkmcnt(10)
	v_mfma_f32_16x16x32_bf16 v[56:59], v[68:71], v[104:107], v[56:59]
	v_mfma_f32_16x16x32_bf16 v[40:43], v[68:71], v[108:111], v[40:43]
	v_mfma_f32_16x16x32_bf16 v[20:23], v[68:71], v[112:115], v[20:23]
	v_mfma_f32_16x16x32_bf16 v[4:7], v[68:71], v[116:119], v[4:7]
	s_waitcnt lgkmcnt(0)
	s_barrier
	v_mfma_f32_16x16x32_bf16 v[52:55], v[72:75], v[104:107], v[52:55]
	v_mfma_f32_16x16x32_bf16 v[32:35], v[72:75], v[108:111], v[32:35]
	v_mfma_f32_16x16x32_bf16 v[16:19], v[72:75], v[112:115], v[16:19]
	v_mfma_f32_16x16x32_bf16 v[0:3], v[72:75], v[116:119], v[0:3]
	v_mfma_f32_16x16x32_bf16 v[48:51], v[76:79], v[104:107], v[48:51]
	v_mfma_f32_16x16x32_bf16 v[36:39], v[76:79], v[108:111], v[36:39]
	v_mfma_f32_16x16x32_bf16 v[24:27], v[76:79], v[112:115], v[24:27]
	v_mfma_f32_16x16x32_bf16 v[8:11], v[76:79], v[116:119], v[8:11]
	v_mfma_f32_16x16x32_bf16 v[60:63], v[80:83], v[120:123], v[60:63]
	v_mfma_f32_16x16x32_bf16 v[44:47], v[80:83], v[124:127], v[44:47]
	v_mfma_f32_16x16x32_bf16 v[28:31], v[80:83], v[132:135], v[28:31]
	v_mfma_f32_16x16x32_bf16 v[12:15], v[80:83], v[136:139], v[12:15]
	v_mfma_f32_16x16x32_bf16 v[56:59], v[84:87], v[120:123], v[56:59]
	v_mfma_f32_16x16x32_bf16 v[40:43], v[84:87], v[124:127], v[40:43]
	v_mfma_f32_16x16x32_bf16 v[20:23], v[84:87], v[132:135], v[20:23]
	v_mfma_f32_16x16x32_bf16 v[4:7], v[84:87], v[136:139], v[4:7]
	v_mfma_f32_16x16x32_bf16 v[52:55], v[88:91], v[120:123], v[52:55]
	v_mfma_f32_16x16x32_bf16 v[32:35], v[88:91], v[124:127], v[32:35]
	v_mfma_f32_16x16x32_bf16 v[16:19], v[88:91], v[132:135], v[16:19]
	v_mfma_f32_16x16x32_bf16 v[0:3], v[88:91], v[136:139], v[0:3]
	v_mfma_f32_16x16x32_bf16 v[48:51], v[92:95], v[120:123], v[48:51]
	v_mfma_f32_16x16x32_bf16 v[36:39], v[92:95], v[124:127], v[36:39]
	v_mfma_f32_16x16x32_bf16 v[24:27], v[92:95], v[132:135], v[24:27]
	v_mfma_f32_16x16x32_bf16 v[8:11], v[92:95], v[136:139], v[8:11]
	s_nop 7
	s_nop 1
	v_sub_co_u32_e32 v64, vcc, s39, v150
	s_nop 0
	v_readfirstlane_b32 s6, v64
	s_lshr_b32 s6, s6, 10
	s_add_i32 s6, s6, 1
	s_and_b64 s[40:41], vcc, exec
	s_cselect_b32 s6, 0, s6
	s_mul_hi_u32 s31, s6, 0x6000
	s_mulk_i32 s6, 0x6000
	v_or_b32_e32 v64, s30, v148
	s_add_u32 s40, s2, s6
	v_ashrrev_i32_e32 v65, 31, v64
	s_addc_u32 s41, s3, s31
	v_add_lshl_u32 v94, v149, s39, 12
	v_lshlrev_b64 v[66:67], 2, v[64:65]
	v_lshl_add_u64 v[102:103], s[40:41], 0, v[66:67]
	v_lshl_add_u64 v[136:137], s[4:5], 0, v[66:67]
	v_mov_b32_e32 v95, v97
	v_or_b32_e32 v66, 0x1000, v94
	v_mov_b32_e32 v67, v97
	v_lshl_add_u64 v[104:105], v[136:137], 0, v[94:95]
	global_load_dword v65, v[102:103], off
	global_load_dword v151, v[104:105], off
	v_lshl_add_u64 v[106:107], v[136:137], 0, v[66:67]
	v_or_b32_e32 v68, 0x2000, v94
	v_mov_b32_e32 v69, v97
	v_or_b32_e32 v70, 0x3000, v94
	v_mov_b32_e32 v71, v97
	v_or_b32_e32 v72, 0x10000, v94
	v_mov_b32_e32 v73, v97
	global_load_dword v152, v[106:107], off
	v_lshl_add_u64 v[108:109], v[136:137], 0, v[68:69]
	v_lshl_add_u64 v[110:111], v[136:137], 0, v[70:71]
	v_lshl_add_u64 v[112:113], v[136:137], 0, v[72:73]
	v_or_b32_e32 v74, 0x11000, v94
	v_mov_b32_e32 v75, v97
	global_load_dword v153, v[108:109], off
	global_load_dword v154, v[110:111], off
	global_load_dword v155, v[112:113], off
	v_lshl_add_u64 v[114:115], v[136:137], 0, v[74:75]
	v_or_b32_e32 v76, 0x12000, v94
	v_mov_b32_e32 v77, v97
	v_or_b32_e32 v78, 0x13000, v94
	v_mov_b32_e32 v79, v97
	v_or_b32_e32 v80, 0x20000, v94
	v_mov_b32_e32 v81, v97
	global_load_dword v156, v[114:115], off
	v_or_b32_e32 v96, 0x30000, v94
	v_lshl_add_u64 v[116:117], v[136:137], 0, v[76:77]
	v_lshl_add_u64 v[118:119], v[136:137], 0, v[78:79]
	v_lshl_add_u64 v[120:121], v[136:137], 0, v[80:81]
	v_or_b32_e32 v82, 0x21000, v94
	v_mov_b32_e32 v83, v97
	global_load_dword v157, v[116:117], off
	global_load_dword v158, v[118:119], off
	global_load_dword v159, v[120:121], off
	v_lshl_add_u64 v[122:123], v[136:137], 0, v[82:83]
	v_or_b32_e32 v84, 0x22000, v94
	v_mov_b32_e32 v85, v97
	v_or_b32_e32 v86, 0x23000, v94
	v_mov_b32_e32 v87, v97
	v_lshl_add_u64 v[130:131], v[136:137], 0, v[96:97]
	v_lshl_add_u64 v[124:125], v[136:137], 0, v[84:85]
	v_lshl_add_u64 v[126:127], v[136:137], 0, v[86:87]
	global_load_dword v160, v[122:123], off
	global_load_dword v161, v[124:125], off
	global_load_dword v170, v[126:127], off
	global_load_dword v171, v[130:131], off
	v_or_b32_e32 v88, 0x31000, v94
	v_mov_b32_e32 v89, v97
	v_lshl_add_u64 v[132:133], v[136:137], 0, v[88:89]
	v_or_b32_e32 v90, 0x32000, v94
	v_mov_b32_e32 v91, v97
	v_or_b32_e32 v92, 0x33000, v94
	v_mov_b32_e32 v93, v97
	v_lshl_add_u64 v[134:135], v[136:137], 0, v[90:91]
	v_lshl_add_u64 v[136:137], v[136:137], 0, v[92:93]
	global_load_dword v172, v[132:133], off
	global_load_dword v173, v[134:135], off
	global_load_dword v174, v[136:137], off
	v_or_b32_e32 v138, 16, v64
	v_ashrrev_i32_e32 v139, 31, v138
	v_lshlrev_b64 v[138:139], 2, v[138:139]
	v_lshl_add_u64 v[94:95], s[4:5], 0, v[94:95]
	global_load_dword v175, v[102:103], off offset:64
	v_lshl_add_u64 v[142:143], s[4:5], 0, v[138:139]
	v_lshl_add_u64 v[138:139], v[94:95], 0, v[138:139]
	v_add_f32_e32 v60, 0, v60
	v_lshl_add_u64 v[140:141], v[142:143], 0, v[66:67]
	global_load_dword v176, v[138:139], off
	global_load_dword v177, v[140:141], off
	global_load_dword v178, v[102:103], off offset:128
	global_load_dword v179, v[102:103], off offset:192
	v_lshl_add_u64 v[102:103], v[142:143], 0, v[68:69]
	global_load_dword v180, v[102:103], off
	v_add_f32_e32 v56, 0, v56
	v_add_f32_e32 v58, 0, v58
	v_add_f32_e32 v52, 0, v52
	v_add_f32_e32 v48, 0, v48
	v_add_f32_e32 v44, 0, v44
	v_add_f32_e32 v50, 0, v50
	v_add_f32_e32 v32, 0, v32
	v_add_f32_e32 v34, 0, v34
	v_add_f32_e32 v40, 0, v40
	v_add_f32_e32 v38, 0, v38
	v_add_f32_e32 v36, 0, v36
	v_add_f32_e32 v28, 0, v28
	v_add_f32_e32 v30, 0, v30
	v_add_f32_e32 v20, 0, v20
	s_waitcnt vmcnt(21)
	v_fmac_f32_e32 v151, v60, v65
	v_add_f32_e32 v60, 0, v61
	global_store_dword v[104:105], v151, off
	v_lshl_add_u64 v[104:105], v[142:143], 0, v[72:73]
	v_add_f32_e32 v16, 0, v16
	v_add_f32_e32 v0, 0, v0
	v_add_f32_e32 v12, 0, v12
	v_add_f32_e32 v4, 0, v4
	s_waitcnt vmcnt(21)
	v_fmac_f32_e32 v152, v60, v65
	v_add_f32_e32 v60, 0, v62
	v_add_f32_e32 v62, 0, v63
	global_store_dword v[106:107], v152, off
	v_lshl_add_u64 v[106:107], v[142:143], 0, v[76:77]
	global_load_dword v152, v[104:105], off
	s_waitcnt vmcnt(22)
	v_fmac_f32_e32 v153, v60, v65
	global_store_dword v[108:109], v153, off
	s_waitcnt vmcnt(21)
	v_fmac_f32_e32 v155, v56, v65
	v_add_f32_e32 v56, 0, v57
	v_lshl_add_u64 v[108:109], v[142:143], 0, v[80:81]
	v_lshl_add_u64 v[60:61], v[142:143], 0, v[70:71]
	global_store_dword v[112:113], v155, off
	v_add_f32_e32 v112, 0, v59
	v_fmac_f32_e32 v154, v62, v65
	global_store_dword v[110:111], v154, off
	s_waitcnt vmcnt(22)
	v_fmac_f32_e32 v156, v56, v65
	global_store_dword v[114:115], v156, off
	global_load_dword v156, v[108:109], off
	v_lshl_add_u64 v[62:63], v[142:143], 0, v[74:75]
	global_load_dword v151, v[60:61], off
	global_load_dword v154, v[106:107], off
	v_lshl_add_u64 v[110:111], v[142:143], 0, v[82:83]
	s_waitcnt vmcnt(25)
	v_fmac_f32_e32 v157, v58, v65
	v_lshl_add_u64 v[58:59], v[142:143], 0, v[84:85]
	s_waitcnt vmcnt(23)
	v_fmac_f32_e32 v159, v52, v65
	v_add_f32_e32 v52, 0, v53
	global_store_dword v[116:117], v157, off
	global_load_dword v157, v[58:59], off
	v_fmac_f32_e32 v158, v112, v65
	v_lshl_add_u64 v[112:113], v[142:143], 0, v[86:87]
	global_load_dword v182, v[112:113], off
	s_waitcnt vmcnt(25)
	v_fmac_f32_e32 v160, v52, v65
	v_add_f32_e32 v52, 0, v54
	s_waitcnt vmcnt(24)
	v_fmac_f32_e32 v161, v52, v65
	s_waitcnt vmcnt(22)
	v_fmac_f32_e32 v171, v48, v65
	v_add_f32_e32 v48, 0, v49
	v_lshl_add_u64 v[52:53], v[142:143], 0, v[90:91]
	v_lshl_add_u64 v[114:115], v[142:143], 0, v[96:97]
	global_store_dword v[120:121], v159, off
	global_load_dword v120, v[52:53], off
	v_lshl_add_u64 v[56:57], v[142:143], 0, v[78:79]
	global_load_dword v181, v[110:111], off
	global_load_dword v155, v[56:57], off
	s_waitcnt vmcnt(25)
	v_fmac_f32_e32 v172, v48, v65
	v_lshl_add_u64 v[48:49], v[142:143], 0, v[92:93]
	global_load_dword v121, v[48:49], off
	s_waitcnt vmcnt(25)
	v_fmac_f32_e32 v173, v50, v65
	global_store_dword v[118:119], v158, off
	global_load_dword v118, v[114:115], off
	v_add_f32_e32 v50, 0, v51
	global_load_dword v153, v[62:63], off
	s_waitcnt vmcnt(25)
	v_fmac_f32_e32 v176, v44, v175
	v_add_f32_e32 v44, 0, v45
	s_waitcnt vmcnt(24)
	v_fmac_f32_e32 v177, v44, v175
	v_add_f32_e32 v44, 0, v46
	v_add_f32_e32 v54, 0, v55
	s_waitcnt vmcnt(21)
	v_fmac_f32_e32 v180, v44, v175
	v_or_b32_e32 v44, 32, v64
	v_ashrrev_i32_e32 v45, 31, v44
	v_lshlrev_b64 v[44:45], 2, v[44:45]
	v_fmac_f32_e32 v174, v50, v65
	v_lshl_add_u64 v[50:51], v[94:95], 0, v[44:45]
	v_lshl_add_u64 v[44:45], s[4:5], 0, v[44:45]
	v_fmac_f32_e32 v170, v54, v65
	v_lshl_add_u64 v[54:55], v[44:45], 0, v[78:79]
	v_add_f32_e32 v46, 0, v47
	v_lshl_add_u64 v[116:117], v[142:143], 0, v[88:89]
	global_load_dword v119, v[116:117], off
	v_or_b32_e32 v64, 48, v64
	global_store_dword v[102:103], v180, off
	v_ashrrev_i32_e32 v65, 31, v64
	v_lshlrev_b64 v[64:65], 2, v[64:65]
	global_store_dword v[122:123], v160, off
	global_store_dword v[124:125], v161, off
	global_store_dword v[126:127], v170, off
	global_store_dword v[130:131], v171, off
	global_store_dword v[132:133], v172, off
	global_store_dword v[134:135], v173, off
	global_store_dword v[136:137], v174, off
	global_store_dword v[138:139], v176, off
	global_store_dword v[140:141], v177, off
	v_lshl_add_u64 v[94:95], v[94:95], 0, v[64:65]
	v_lshl_add_u64 v[64:65], s[4:5], 0, v[64:65]
	v_add_f32_e32 v21, 0, v21
	s_waitcnt vmcnt(29)
	v_fmac_f32_e32 v152, v40, v175
	v_add_f32_e32 v40, 0, v41
	global_store_dword v[104:105], v152, off
	s_add_i32 s38, s38, s34
	s_cmpk_gt_i32 s38, 0x1ff
	s_waitcnt vmcnt(25)
	v_fmac_f32_e32 v156, v32, v175
	global_store_dword v[108:109], v156, off
	global_load_dword v109, v[54:55], off
	s_waitcnt vmcnt(26)
	v_fmac_f32_e32 v151, v46, v175
	v_lshl_add_u64 v[46:47], v[44:45], 0, v[66:67]
	global_load_dword v102, v[50:51], off
	global_load_dword v103, v[46:47], off
	v_add_f32_e32 v32, 0, v33
	global_store_dword v[60:61], v151, off
	v_lshl_add_u64 v[60:61], v[44:45], 0, v[88:89]
	s_waitcnt vmcnt(26)
	v_fmac_f32_e32 v157, v34, v175
	global_store_dword v[58:59], v157, off
	v_add_f32_e32 v34, 0, v35
	v_add_f32_e32 v58, 0, v39
	s_waitcnt vmcnt(26)
	v_fmac_f32_e32 v182, v34, v175
	global_store_dword v[112:113], v182, off
	v_lshl_add_u64 v[34:35], v[44:45], 0, v[72:73]
	v_lshl_add_u64 v[66:67], v[64:65], 0, v[66:67]
	s_waitcnt vmcnt(25)
	v_fmac_f32_e32 v120, v38, v175
	global_store_dword v[52:53], v120, off
	s_waitcnt vmcnt(25)
	v_fmac_f32_e32 v181, v32, v175
	v_lshl_add_u64 v[52:53], v[44:45], 0, v[82:83]
	global_store_dword v[110:111], v181, off
	v_lshl_add_u64 v[32:33], v[44:45], 0, v[70:71]
	s_waitcnt vmcnt(24)
	v_fmac_f32_e32 v121, v58, v175
	v_lshl_add_u64 v[58:59], v[44:45], 0, v[86:87]
	global_load_dword v113, v[58:59], off
	global_load_dword v111, v[52:53], off
	s_waitcnt vmcnt(24)
	v_fmac_f32_e32 v118, v36, v175
	s_waitcnt vmcnt(23)
	v_fmac_f32_e32 v153, v40, v175
	v_add_f32_e32 v40, 0, v42
	v_add_f32_e32 v42, 0, v43
	v_fmac_f32_e32 v155, v42, v175
	global_store_dword v[56:57], v155, off
	v_lshl_add_u64 v[56:57], v[44:45], 0, v[80:81]
	global_store_dword v[114:115], v118, off
	global_load_dword v110, v[56:57], off
	global_load_dword v105, v[32:33], off
	v_add_f32_e32 v36, 0, v37
	global_load_dword v115, v[60:61], off
	v_fmac_f32_e32 v154, v40, v175
	v_lshl_add_u64 v[40:41], v[44:45], 0, v[68:69]
	global_load_dword v104, v[40:41], off
	v_lshl_add_u64 v[42:43], v[44:45], 0, v[76:77]
	global_store_dword v[106:107], v154, off
	global_load_dword v106, v[34:35], off
	s_waitcnt vmcnt(30)
	v_fmac_f32_e32 v119, v36, v175
	global_store_dword v[48:49], v121, off
	v_lshl_add_u64 v[48:49], v[44:45], 0, v[96:97]
	global_store_dword v[62:63], v153, off
	v_lshl_add_u64 v[36:37], v[44:45], 0, v[74:75]
	global_store_dword v[116:117], v119, off
	v_lshl_add_u64 v[38:39], v[44:45], 0, v[84:85]
	global_load_dword v114, v[48:49], off
	v_lshl_add_u64 v[62:63], v[44:45], 0, v[90:91]
	global_load_dword v107, v[36:37], off
	global_load_dword v108, v[42:43], off
	global_load_dword v112, v[38:39], off
	v_lshl_add_u64 v[44:45], v[44:45], 0, v[92:93]
	global_load_dword v116, v[62:63], off
	global_load_dword v117, v[44:45], off
	v_lshl_add_u64 v[68:69], v[64:65], 0, v[68:69]
	global_load_dword v120, v[68:69], off
	global_load_dword v118, v[94:95], off
	global_load_dword v119, v[66:67], off
	s_waitcnt vmcnt(28)
	v_fmac_f32_e32 v102, v28, v178
	global_store_dword v[50:51], v102, off
	v_lshl_add_u64 v[50:51], v[64:65], 0, v[70:71]
	v_add_f32_e32 v70, 0, v29
	v_lshl_add_u64 v[28:29], v[64:65], 0, v[72:73]
	s_waitcnt vmcnt(28)
	v_fmac_f32_e32 v103, v70, v178
	v_lshl_add_u64 v[70:71], v[64:65], 0, v[74:75]
	v_lshl_add_u64 v[72:73], v[64:65], 0, v[78:79]
	v_lshl_add_u64 v[74:75], v[64:65], 0, v[80:81]
	global_load_dword v122, v[70:71], off
	global_load_dword v123, v[72:73], off
	global_load_dword v124, v[74:75], off
	global_load_dword v102, v[50:51], off
	global_load_dword v121, v[28:29], off
	v_lshl_add_u64 v[78:79], v[64:65], 0, v[88:89]
	global_store_dword v[46:47], v103, off
	v_lshl_add_u64 v[46:47], v[64:65], 0, v[76:77]
	global_load_dword v103, v[46:47], off
	v_add_f32_e32 v76, 0, v31
	v_lshl_add_u64 v[80:81], v[64:65], 0, v[90:91]
	s_waitcnt vmcnt(25)
	v_fmac_f32_e32 v110, v16, v178
	s_waitcnt vmcnt(24)
	v_fmac_f32_e32 v105, v76, v178
	v_lshl_add_u64 v[76:77], v[64:65], 0, v[86:87]
	global_store_dword v[32:33], v105, off
	v_lshl_add_u64 v[32:33], v[64:65], 0, v[96:97]
	global_load_dword v86, v[78:79], off
	s_waitcnt vmcnt(24)
	v_fmac_f32_e32 v104, v30, v178
	global_store_dword v[40:41], v104, off
	v_lshl_add_u64 v[40:41], v[64:65], 0, v[82:83]
	global_load_dword v82, v[40:41], off
	v_lshl_add_u64 v[30:31], v[64:65], 0, v[84:85]
	global_load_dword v83, v[30:31], off
	global_load_dword v85, v[32:33], off
	global_load_dword v84, v[76:77], off
	s_waitcnt vmcnt(27)
	v_fmac_f32_e32 v106, v20, v178
	global_load_dword v20, v[80:81], off
	v_add_f32_e32 v16, 0, v17
	global_store_dword v[34:35], v106, off
	v_lshl_add_u64 v[34:35], v[64:65], 0, v[92:93]
	global_load_dword v64, v[34:35], off
	v_fmac_f32_e32 v111, v16, v178
	v_add_f32_e32 v16, 0, v18
	s_waitcnt vmcnt(23)
	v_fmac_f32_e32 v112, v16, v178
	v_add_f32_e32 v16, 0, v19
	v_fmac_f32_e32 v113, v16, v178
	v_add_f32_e32 v16, 0, v24
	v_fmac_f32_e32 v114, v16, v178
	v_add_f32_e32 v16, 0, v25
	s_waitcnt vmcnt(19)
	v_fmac_f32_e32 v118, v12, v179
	v_add_f32_e32 v12, 0, v13
	v_fmac_f32_e32 v107, v21, v178
	v_add_f32_e32 v21, 0, v22
	v_fmac_f32_e32 v115, v16, v178
	v_add_f32_e32 v16, 0, v26
	s_waitcnt vmcnt(18)
	v_fmac_f32_e32 v119, v12, v179
	v_add_f32_e32 v12, 0, v14
	v_fmac_f32_e32 v108, v21, v178
	v_add_f32_e32 v21, 0, v23
	v_fmac_f32_e32 v116, v16, v178
	v_add_f32_e32 v16, 0, v27
	v_fmac_f32_e32 v120, v12, v179
	v_add_f32_e32 v12, 0, v15
	v_fmac_f32_e32 v109, v21, v178
	v_fmac_f32_e32 v117, v16, v178
	global_store_dword v[36:37], v107, off
	global_store_dword v[42:43], v108, off
	global_store_dword v[54:55], v109, off
	global_store_dword v[56:57], v110, off
	global_store_dword v[52:53], v111, off
	global_store_dword v[38:39], v112, off
	global_store_dword v[58:59], v113, off
	global_store_dword v[48:49], v114, off
	global_store_dword v[60:61], v115, off
	global_store_dword v[62:63], v116, off
	global_store_dword v[44:45], v117, off
	global_store_dword v[94:95], v118, off
	s_waitcnt vmcnt(26)
	v_fmac_f32_e32 v124, v0, v179
	v_add_f32_e32 v0, 0, v1
	s_waitcnt vmcnt(24)
	v_fmac_f32_e32 v121, v4, v179
	v_add_f32_e32 v4, 0, v5
	v_fmac_f32_e32 v122, v4, v179
	v_add_f32_e32 v4, 0, v6
	s_waitcnt vmcnt(22)
	v_fmac_f32_e32 v103, v4, v179
	v_add_f32_e32 v4, 0, v7
	v_fmac_f32_e32 v102, v12, v179
	v_fmac_f32_e32 v123, v4, v179
	global_store_dword v[66:67], v119, off
	global_store_dword v[68:69], v120, off
	global_store_dword v[50:51], v102, off
	global_store_dword v[28:29], v121, off
	global_store_dword v[70:71], v122, off
	global_store_dword v[46:47], v103, off
	global_store_dword v[72:73], v123, off
	global_store_dword v[74:75], v124, off
	s_waitcnt vmcnt(26)
	v_fmac_f32_e32 v82, v0, v179
	v_add_f32_e32 v0, 0, v2
	s_waitcnt vmcnt(25)
	v_fmac_f32_e32 v83, v0, v179
	v_add_f32_e32 v0, 0, v3
	s_waitcnt vmcnt(23)
	v_fmac_f32_e32 v84, v0, v179
	v_add_f32_e32 v0, 0, v8
	v_fmac_f32_e32 v85, v0, v179
	v_add_f32_e32 v0, 0, v9
	v_fmac_f32_e32 v86, v0, v179
	v_add_f32_e32 v0, 0, v10
	s_waitcnt vmcnt(22)
	v_fmac_f32_e32 v20, v0, v179
	v_add_f32_e32 v0, 0, v11
	s_waitcnt vmcnt(20)
	v_fmac_f32_e32 v64, v0, v179
	global_store_dword v[40:41], v82, off
	global_store_dword v[30:31], v83, off
	global_store_dword v[76:77], v84, off
	global_store_dword v[32:33], v85, off
	global_store_dword v[78:79], v86, off
	global_store_dword v[80:81], v20, off
	global_store_dword v[34:35], v64, off
	s_cbranch_scc0 .LBB0_836

.LBB0_958:
	s_lshl_b32 s8, s3, 11
	s_and_b32 s8, s8, 0xfc0000
	s_add_i32 s51, s55, s2
	s_cmpk_gt_i32 s51, 0xaff
	v_lshl_add_u64 v[116:117], v[106:107], 0, s[8:9]
	s_cselect_b64 s[26:27], -1, 0
	s_lshl_b32 s8, s51, 18
	s_and_b32 s8, s8, 0xfc0000
	s_add_u32 s8, s4, s8
	s_addc_u32 s59, s5, 0
	s_ashr_i32 s30, s51, 6
	s_ashr_i32 s31, s30, 31
	s_lshl_b64 s[30:31], s[30:31], 18
	s_add_u32 s62, s6, s30
	s_addc_u32 s63, s7, s31
	s_cmpk_lt_i32 s51, 0xb00
	s_cselect_b64 vcc, -1, 0
	s_and_b64 s[30:31], vcc, exec
	s_cselect_b32 s31, s59, 0
	s_cselect_b32 s30, s8, 0
	v_lshl_add_u64 v[2:3], s[30:31], 0, v[108:109]
	v_lshl_add_u64 v[0:1], v[112:113], 0, s[24:25]
	s_cselect_b32 s63, s63, 0
	s_cselect_b32 s62, s62, 0
	v_lshl_add_u64 v[2:3], v[2:3], 0, v[110:111]
	v_cndmask_b32_e32 v129, v1, v3, vcc
	v_cndmask_b32_e32 v96, v0, v2, vcc
	v_lshl_add_u64 v[0:1], s[62:63], 0, v[108:109]
	v_lshl_add_u64 v[0:1], v[0:1], 0, v[110:111]
	v_lshl_add_u64 v[2:3], v[114:115], 0, s[24:25]
	v_cndmask_b32_e32 v132, v2, v0, vcc
	v_mov_b32_e32 v0, 0
	v_lshl_add_u64 v[136:137], v[112:113], 0, s[10:11]
	v_lshl_add_u64 v[118:119], v[112:113], 0, s[12:13]
	v_lshl_add_u64 v[140:141], v[112:113], 0, s[14:15]
	v_lshl_add_u64 v[120:121], v[112:113], 0, s[16:17]
	v_lshl_add_u64 v[142:143], v[112:113], 0, s[18:19]
	v_lshl_add_u64 v[122:123], v[112:113], 0, s[20:21]
	v_lshl_add_u64 v[144:145], v[112:113], 0, s[22:23]
	v_lshl_add_u64 v[138:139], v[114:115], 0, s[10:11]
	v_lshl_add_u64 v[124:125], v[114:115], 0, s[12:13]
	v_lshl_add_u64 v[146:147], v[114:115], 0, s[14:15]
	v_lshl_add_u64 v[126:127], v[114:115], 0, s[16:17]
	v_lshl_add_u64 v[148:149], v[114:115], 0, s[18:19]
	v_lshl_add_u64 v[130:131], v[114:115], 0, s[20:21]
	v_lshl_add_u64 v[150:151], v[114:115], 0, s[22:23]
	v_cndmask_b32_e32 v133, v3, v1, vcc
	v_lshl_add_u64 v[134:135], v[104:105], 0, s[28:29]
	s_mov_b32 s28, -2
	v_mov_b32_e32 v1, v0
	v_mov_b32_e32 v2, v0
	v_mov_b32_e32 v3, v0
	v_mov_b32_e32 v16, v0
	v_mov_b32_e32 v17, v0
	v_mov_b32_e32 v18, v0
	v_mov_b32_e32 v19, v0
	v_mov_b32_e32 v4, v0
	v_mov_b32_e32 v5, v0
	v_mov_b32_e32 v6, v0
	v_mov_b32_e32 v7, v0
	v_mov_b32_e32 v20, v0
	v_mov_b32_e32 v21, v0
	v_mov_b32_e32 v22, v0
	v_mov_b32_e32 v23, v0
	v_mov_b32_e32 v12, v0
	v_mov_b32_e32 v13, v0
	v_mov_b32_e32 v14, v0
	v_mov_b32_e32 v15, v0
	v_mov_b32_e32 v24, v0
	v_mov_b32_e32 v25, v0
	v_mov_b32_e32 v26, v0
	v_mov_b32_e32 v27, v0
	v_mov_b32_e32 v8, v0
	v_mov_b32_e32 v9, v0
	v_mov_b32_e32 v10, v0
	v_mov_b32_e32 v11, v0
	v_mov_b32_e32 v32, v0
	v_mov_b32_e32 v33, v0
	v_mov_b32_e32 v34, v0
	v_mov_b32_e32 v35, v0
	v_mov_b32_e32 v64, v0
	v_mov_b32_e32 v65, v0
	v_mov_b32_e32 v66, v0
	v_mov_b32_e32 v67, v0
	v_mov_b32_e32 v72, v0
	v_mov_b32_e32 v73, v0
	v_mov_b32_e32 v74, v0
	v_mov_b32_e32 v75, v0
	v_mov_b32_e32 v68, v0
	v_mov_b32_e32 v69, v0
	v_mov_b32_e32 v70, v0
	v_mov_b32_e32 v71, v0
	v_mov_b32_e32 v76, v0
	v_mov_b32_e32 v77, v0
	v_mov_b32_e32 v78, v0
	v_mov_b32_e32 v79, v0
	v_mov_b32_e32 v80, v0
	v_mov_b32_e32 v81, v0
	v_mov_b32_e32 v82, v0
	v_mov_b32_e32 v83, v0
	v_mov_b32_e32 v88, v0
	v_mov_b32_e32 v89, v0
	v_mov_b32_e32 v90, v0
	v_mov_b32_e32 v91, v0
	v_mov_b32_e32 v84, v0
	v_mov_b32_e32 v85, v0
	v_mov_b32_e32 v86, v0
	v_mov_b32_e32 v87, v0
	v_mov_b32_e32 v92, v0
	v_mov_b32_e32 v93, v0
	v_mov_b32_e32 v94, v0
	v_mov_b32_e32 v95, v0
	v_readfirstlane_b32 s30, v112
	v_readfirstlane_b32 s31, v113
	v_readfirstlane_b32 s62, v114
	v_readfirstlane_b32 s63, v115
	v_readfirstlane_b32 s8, v247
	s_nop 3
	s_mul_i32 s59, s8, 0x4000
	s_sub_u32 s30, s30, s59
	s_subb_u32 s31, s31, 0
	s_sub_u32 s62, s62, s59
	s_subb_u32 s63, s63, 0
	s_lshl_b32 s8, s8, 12
	s_add_u32 m0, s8, 0x0
	v_mov_b32_e32 v92, 0
	global_load_lds_dwordx4 v248, s[30:31]
	v_mov_b32_e32 v93, 0
	s_add_u32 m0, s8, 0x400
	v_mov_b32_e32 v94, 0
	global_load_lds_dwordx4 v249, s[30:31]
	v_mov_b32_e32 v95, 0
	s_add_u32 m0, s8, 0x800
	v_mov_b32_e32 v84, 0
	global_load_lds_dwordx4 v250, s[30:31]
	v_mov_b32_e32 v85, 0
	s_add_u32 m0, s8, 0xc00
	v_mov_b32_e32 v86, 0
	global_load_lds_dwordx4 v251, s[30:31]
	v_mov_b32_e32 v87, 0
	s_add_u32 m0, s8, 0x8000
	v_mov_b32_e32 v88, 0
	global_load_lds_dwordx4 v248, s[62:63]
	v_mov_b32_e32 v89, 0
	s_add_u32 m0, s8, 0x8400
	v_mov_b32_e32 v90, 0
	global_load_lds_dwordx4 v249, s[62:63]
	v_mov_b32_e32 v91, 0
	s_add_u32 m0, s8, 0x8800
	v_mov_b32_e32 v80, 0
	global_load_lds_dwordx4 v250, s[62:63]
	v_mov_b32_e32 v81, 0
	s_add_u32 m0, s8, 0x8c00
	v_mov_b32_e32 v82, 0
	global_load_lds_dwordx4 v251, s[62:63]
	v_mov_b32_e32 v83, 0
	s_add_u32 s30, s30, 0x80
	s_addc_u32 s31, s31, 0
	s_add_u32 s62, s62, 0x80
	s_addc_u32 s63, s63, 0
	s_add_u32 m0, s8, 0x4000
	v_mov_b32_e32 v76, 0
	global_load_lds_dwordx4 v248, s[30:31]
	v_mov_b32_e32 v77, 0
	s_add_u32 m0, s8, 0x4400
	v_mov_b32_e32 v78, 0
	global_load_lds_dwordx4 v249, s[30:31]
	v_mov_b32_e32 v79, 0
	s_add_u32 m0, s8, 0x4800
	v_mov_b32_e32 v68, 0
	global_load_lds_dwordx4 v250, s[30:31]
	v_mov_b32_e32 v69, 0
	s_add_u32 m0, s8, 0x4c00
	v_mov_b32_e32 v70, 0
	global_load_lds_dwordx4 v251, s[30:31]
	v_mov_b32_e32 v71, 0
	s_add_u32 m0, s8, 0xc000
	v_mov_b32_e32 v72, 0
	global_load_lds_dwordx4 v248, s[62:63]
	v_mov_b32_e32 v73, 0
	s_add_u32 m0, s8, 0xc400
	v_mov_b32_e32 v74, 0
	global_load_lds_dwordx4 v249, s[62:63]
	v_mov_b32_e32 v75, 0
	s_add_u32 m0, s8, 0xc800
	v_mov_b32_e32 v64, 0
	global_load_lds_dwordx4 v250, s[62:63]
	v_mov_b32_e32 v65, 0
	s_add_u32 m0, s8, 0xcc00
	v_mov_b32_e32 v66, 0
	global_load_lds_dwordx4 v251, s[62:63]
	v_mov_b32_e32 v67, 0
	s_add_u32 s30, s30, 0x80
	s_addc_u32 s31, s31, 0
	s_add_u32 s62, s62, 0x80
	s_addc_u32 s63, s63, 0
	v_mov_b32_e32 v32, 0
	v_mov_b32_e32 v33, 0
	v_mov_b32_e32 v34, 0
	v_mov_b32_e32 v35, 0
	v_mov_b32_e32 v8, 0
	v_mov_b32_e32 v9, 0
	v_mov_b32_e32 v10, 0
	v_mov_b32_e32 v11, 0
	v_mov_b32_e32 v24, 0
	v_mov_b32_e32 v25, 0
	v_mov_b32_e32 v26, 0
	v_mov_b32_e32 v27, 0
	v_mov_b32_e32 v12, 0
	v_mov_b32_e32 v13, 0
	v_mov_b32_e32 v14, 0
	v_mov_b32_e32 v15, 0
	v_mov_b32_e32 v20, 0
	v_mov_b32_e32 v21, 0
	v_mov_b32_e32 v22, 0
	v_mov_b32_e32 v23, 0
	v_mov_b32_e32 v4, 0
	v_mov_b32_e32 v5, 0
	v_mov_b32_e32 v6, 0
	v_mov_b32_e32 v7, 0
	v_mov_b32_e32 v16, 0
	v_mov_b32_e32 v17, 0
	v_mov_b32_e32 v18, 0
	v_mov_b32_e32 v19, 0
	v_mov_b32_e32 v0, 0
	v_mov_b32_e32 v1, 0
	v_mov_b32_e32 v2, 0
	v_mov_b32_e32 v3, 0
	s_waitcnt vmcnt(8)
	s_barrier
	ds_read_b128 v[28:31], v252 offset:0
	ds_read_b128 v[112:115], v254 offset:32768
	ds_read_b128 v[116:119], v254 offset:34816
	ds_read_b128 v[120:123], v254 offset:36864
	ds_read_b128 v[124:127], v254 offset:38912
	ds_read_b128 v[36:39], v252 offset:2048
	ds_read_b128 v[40:43], v252 offset:4096
	ds_read_b128 v[44:47], v252 offset:6144
	ds_read_b128 v[48:51], v253 offset:0
	ds_read_b128 v[132:135], v255 offset:32768
	ds_read_b128 v[136:139], v255 offset:34816
	ds_read_b128 v[140:143], v255 offset:36864
	ds_read_b128 v[144:147], v255 offset:38912
	s_waitcnt lgkmcnt(11)
	v_mfma_f32_16x16x32_bf16 v[92:95], v[28:31], v[112:115], v[92:95]
	s_waitcnt lgkmcnt(10)
	v_mfma_f32_16x16x32_bf16 v[84:87], v[28:31], v[116:119], v[84:87]
	s_waitcnt lgkmcnt(9)
	v_mfma_f32_16x16x32_bf16 v[88:91], v[28:31], v[120:123], v[88:91]
	s_waitcnt lgkmcnt(8)
	v_mfma_f32_16x16x32_bf16 v[80:83], v[28:31], v[124:127], v[80:83]
	ds_read_b128 v[52:55], v253 offset:2048
	ds_read_b128 v[56:59], v253 offset:4096
	ds_read_b128 v[60:63], v253 offset:6144
	s_waitcnt lgkmcnt(10)
	v_mfma_f32_16x16x32_bf16 v[76:79], v[36:39], v[112:115], v[76:79]
	v_mfma_f32_16x16x32_bf16 v[68:71], v[36:39], v[116:119], v[68:71]
	v_mfma_f32_16x16x32_bf16 v[72:75], v[36:39], v[120:123], v[72:75]
	v_mfma_f32_16x16x32_bf16 v[64:67], v[36:39], v[124:127], v[64:67]
	s_waitcnt lgkmcnt(0)
	s_barrier
	s_add_u32 m0, s8, 0x0
	v_mfma_f32_16x16x32_bf16 v[32:35], v[40:43], v[112:115], v[32:35]
	global_load_lds_dwordx4 v248, s[30:31]
	s_add_u32 m0, s8, 0x400
	v_mfma_f32_16x16x32_bf16 v[8:11], v[40:43], v[116:119], v[8:11]
	global_load_lds_dwordx4 v249, s[30:31]
	s_add_u32 m0, s8, 0x800
	v_mfma_f32_16x16x32_bf16 v[24:27], v[40:43], v[120:123], v[24:27]
	global_load_lds_dwordx4 v250, s[30:31]
	s_add_u32 m0, s8, 0xc00
	v_mfma_f32_16x16x32_bf16 v[12:15], v[40:43], v[124:127], v[12:15]
	global_load_lds_dwordx4 v251, s[30:31]
	s_add_u32 m0, s8, 0x8000
	v_mfma_f32_16x16x32_bf16 v[20:23], v[44:47], v[112:115], v[20:23]
	global_load_lds_dwordx4 v248, s[62:63]
	s_add_u32 m0, s8, 0x8400
	v_mfma_f32_16x16x32_bf16 v[4:7], v[44:47], v[116:119], v[4:7]
	global_load_lds_dwordx4 v249, s[62:63]
	s_add_u32 m0, s8, 0x8800
	v_mfma_f32_16x16x32_bf16 v[16:19], v[44:47], v[120:123], v[16:19]
	global_load_lds_dwordx4 v250, s[62:63]
	s_add_u32 m0, s8, 0x8c00
	v_mfma_f32_16x16x32_bf16 v[0:3], v[44:47], v[124:127], v[0:3]
	global_load_lds_dwordx4 v251, s[62:63]
	s_add_u32 s30, s30, 0x80
	s_addc_u32 s31, s31, 0
	s_add_u32 s62, s62, 0x80
	s_addc_u32 s63, s63, 0
	s_waitcnt vmcnt(8)
	s_barrier
	ds_read_b128 v[28:31], v252 offset:16384
	ds_read_b128 v[112:115], v254 offset:49152
	ds_read_b128 v[116:119], v254 offset:51200
	ds_read_b128 v[120:123], v254 offset:53248
	ds_read_b128 v[124:127], v254 offset:55296
	ds_read_b128 v[36:39], v252 offset:18432
	ds_read_b128 v[40:43], v252 offset:20480
	ds_read_b128 v[44:47], v252 offset:22528
	v_mfma_f32_16x16x32_bf16 v[92:95], v[48:51], v[132:135], v[92:95]
	v_mfma_f32_16x16x32_bf16 v[84:87], v[48:51], v[136:139], v[84:87]
	v_mfma_f32_16x16x32_bf16 v[88:91], v[48:51], v[140:143], v[88:91]
	v_mfma_f32_16x16x32_bf16 v[80:83], v[48:51], v[144:147], v[80:83]
	v_mfma_f32_16x16x32_bf16 v[76:79], v[52:55], v[132:135], v[76:79]
	v_mfma_f32_16x16x32_bf16 v[68:71], v[52:55], v[136:139], v[68:71]
	v_mfma_f32_16x16x32_bf16 v[72:75], v[52:55], v[140:143], v[72:75]
	v_mfma_f32_16x16x32_bf16 v[64:67], v[52:55], v[144:147], v[64:67]
	v_mfma_f32_16x16x32_bf16 v[32:35], v[56:59], v[132:135], v[32:35]
	v_mfma_f32_16x16x32_bf16 v[8:11], v[56:59], v[136:139], v[8:11]
	v_mfma_f32_16x16x32_bf16 v[24:27], v[56:59], v[140:143], v[24:27]
	v_mfma_f32_16x16x32_bf16 v[12:15], v[56:59], v[144:147], v[12:15]
	v_mfma_f32_16x16x32_bf16 v[20:23], v[60:63], v[132:135], v[20:23]
	v_mfma_f32_16x16x32_bf16 v[4:7], v[60:63], v[136:139], v[4:7]
	v_mfma_f32_16x16x32_bf16 v[16:19], v[60:63], v[140:143], v[16:19]
	v_mfma_f32_16x16x32_bf16 v[0:3], v[60:63], v[144:147], v[0:3]
	ds_read_b128 v[48:51], v253 offset:16384
	ds_read_b128 v[132:135], v255 offset:49152
	ds_read_b128 v[136:139], v255 offset:51200
	ds_read_b128 v[140:143], v255 offset:53248
	ds_read_b128 v[144:147], v255 offset:55296
	ds_read_b128 v[52:55], v253 offset:18432
	ds_read_b128 v[56:59], v253 offset:20480
	ds_read_b128 v[60:63], v253 offset:22528
	s_waitcnt lgkmcnt(14)
	v_mfma_f32_16x16x32_bf16 v[92:95], v[28:31], v[112:115], v[92:95]
	s_waitcnt lgkmcnt(13)
	v_mfma_f32_16x16x32_bf16 v[84:87], v[28:31], v[116:119], v[84:87]
	s_waitcnt lgkmcnt(12)
	v_mfma_f32_16x16x32_bf16 v[88:91], v[28:31], v[120:123], v[88:91]
	s_waitcnt lgkmcnt(11)
	v_mfma_f32_16x16x32_bf16 v[80:83], v[28:31], v[124:127], v[80:83]
	s_waitcnt lgkmcnt(10)
	v_mfma_f32_16x16x32_bf16 v[76:79], v[36:39], v[112:115], v[76:79]
	v_mfma_f32_16x16x32_bf16 v[68:71], v[36:39], v[116:119], v[68:71]
	v_mfma_f32_16x16x32_bf16 v[72:75], v[36:39], v[120:123], v[72:75]
	v_mfma_f32_16x16x32_bf16 v[64:67], v[36:39], v[124:127], v[64:67]
	s_waitcnt lgkmcnt(0)
	s_barrier
	s_add_u32 m0, s8, 0x4000
	v_mfma_f32_16x16x32_bf16 v[32:35], v[40:43], v[112:115], v[32:35]
	global_load_lds_dwordx4 v248, s[30:31]
	s_add_u32 m0, s8, 0x4400
	v_mfma_f32_16x16x32_bf16 v[8:11], v[40:43], v[116:119], v[8:11]
	global_load_lds_dwordx4 v249, s[30:31]
	s_add_u32 m0, s8, 0x4800
	v_mfma_f32_16x16x32_bf16 v[24:27], v[40:43], v[120:123], v[24:27]
	global_load_lds_dwordx4 v250, s[30:31]
	s_add_u32 m0, s8, 0x4c00
	v_mfma_f32_16x16x32_bf16 v[12:15], v[40:43], v[124:127], v[12:15]
	global_load_lds_dwordx4 v251, s[30:31]
	s_add_u32 m0, s8, 0xc000
	v_mfma_f32_16x16x32_bf16 v[20:23], v[44:47], v[112:115], v[20:23]
	global_load_lds_dwordx4 v248, s[62:63]
	s_add_u32 m0, s8, 0xc400
	v_mfma_f32_16x16x32_bf16 v[4:7], v[44:47], v[116:119], v[4:7]
	global_load_lds_dwordx4 v249, s[62:63]
	s_add_u32 m0, s8, 0xc800
	v_mfma_f32_16x16x32_bf16 v[16:19], v[44:47], v[120:123], v[16:19]
	global_load_lds_dwordx4 v250, s[62:63]
	s_add_u32 m0, s8, 0xcc00
	v_mfma_f32_16x16x32_bf16 v[0:3], v[44:47], v[124:127], v[0:3]
	global_load_lds_dwordx4 v251, s[62:63]
	s_add_u32 s30, s30, 0x80
	s_addc_u32 s31, s31, 0
	s_add_u32 s62, s62, 0x80
	s_addc_u32 s63, s63, 0
	s_mov_b32 s32, 6
.Lg8_loop:
	s_waitcnt vmcnt(8)
	s_barrier
	ds_read_b128 v[28:31], v252 offset:0
	ds_read_b128 v[112:115], v254 offset:32768
	ds_read_b128 v[116:119], v254 offset:34816
	ds_read_b128 v[120:123], v254 offset:36864
	ds_read_b128 v[124:127], v254 offset:38912
	ds_read_b128 v[36:39], v252 offset:2048
	ds_read_b128 v[40:43], v252 offset:4096
	ds_read_b128 v[44:47], v252 offset:6144
	v_mfma_f32_16x16x32_bf16 v[92:95], v[48:51], v[132:135], v[92:95]
	v_mfma_f32_16x16x32_bf16 v[84:87], v[48:51], v[136:139], v[84:87]
	v_mfma_f32_16x16x32_bf16 v[88:91], v[48:51], v[140:143], v[88:91]
	v_mfma_f32_16x16x32_bf16 v[80:83], v[48:51], v[144:147], v[80:83]
	v_mfma_f32_16x16x32_bf16 v[76:79], v[52:55], v[132:135], v[76:79]
	v_mfma_f32_16x16x32_bf16 v[68:71], v[52:55], v[136:139], v[68:71]
	v_mfma_f32_16x16x32_bf16 v[72:75], v[52:55], v[140:143], v[72:75]
	v_mfma_f32_16x16x32_bf16 v[64:67], v[52:55], v[144:147], v[64:67]
	v_mfma_f32_16x16x32_bf16 v[32:35], v[56:59], v[132:135], v[32:35]
	v_mfma_f32_16x16x32_bf16 v[8:11], v[56:59], v[136:139], v[8:11]
	v_mfma_f32_16x16x32_bf16 v[24:27], v[56:59], v[140:143], v[24:27]
	v_mfma_f32_16x16x32_bf16 v[12:15], v[56:59], v[144:147], v[12:15]
	v_mfma_f32_16x16x32_bf16 v[20:23], v[60:63], v[132:135], v[20:23]
	v_mfma_f32_16x16x32_bf16 v[4:7], v[60:63], v[136:139], v[4:7]
	v_mfma_f32_16x16x32_bf16 v[16:19], v[60:63], v[140:143], v[16:19]
	v_mfma_f32_16x16x32_bf16 v[0:3], v[60:63], v[144:147], v[0:3]
	ds_read_b128 v[48:51], v253 offset:0
	ds_read_b128 v[132:135], v255 offset:32768
	ds_read_b128 v[136:139], v255 offset:34816
	ds_read_b128 v[140:143], v255 offset:36864
	ds_read_b128 v[144:147], v255 offset:38912
	ds_read_b128 v[52:55], v253 offset:2048
	ds_read_b128 v[56:59], v253 offset:4096
	ds_read_b128 v[60:63], v253 offset:6144
	s_waitcnt lgkmcnt(14)
	v_mfma_f32_16x16x32_bf16 v[92:95], v[28:31], v[112:115], v[92:95]
	s_waitcnt lgkmcnt(13)
	v_mfma_f32_16x16x32_bf16 v[84:87], v[28:31], v[116:119], v[84:87]
	s_waitcnt lgkmcnt(12)
	v_mfma_f32_16x16x32_bf16 v[88:91], v[28:31], v[120:123], v[88:91]
	s_waitcnt lgkmcnt(11)
	v_mfma_f32_16x16x32_bf16 v[80:83], v[28:31], v[124:127], v[80:83]
	s_waitcnt lgkmcnt(10)
	v_mfma_f32_16x16x32_bf16 v[76:79], v[36:39], v[112:115], v[76:79]
	v_mfma_f32_16x16x32_bf16 v[68:71], v[36:39], v[116:119], v[68:71]
	v_mfma_f32_16x16x32_bf16 v[72:75], v[36:39], v[120:123], v[72:75]
	v_mfma_f32_16x16x32_bf16 v[64:67], v[36:39], v[124:127], v[64:67]
	s_waitcnt lgkmcnt(0)
	s_barrier
	s_add_u32 m0, s8, 0x0
	v_mfma_f32_16x16x32_bf16 v[32:35], v[40:43], v[112:115], v[32:35]
	global_load_lds_dwordx4 v248, s[30:31]
	s_add_u32 m0, s8, 0x400
	v_mfma_f32_16x16x32_bf16 v[8:11], v[40:43], v[116:119], v[8:11]
	global_load_lds_dwordx4 v249, s[30:31]
	s_add_u32 m0, s8, 0x800
	v_mfma_f32_16x16x32_bf16 v[24:27], v[40:43], v[120:123], v[24:27]
	global_load_lds_dwordx4 v250, s[30:31]
	s_add_u32 m0, s8, 0xc00
	v_mfma_f32_16x16x32_bf16 v[12:15], v[40:43], v[124:127], v[12:15]
	global_load_lds_dwordx4 v251, s[30:31]
	s_add_u32 m0, s8, 0x8000
	v_mfma_f32_16x16x32_bf16 v[20:23], v[44:47], v[112:115], v[20:23]
	global_load_lds_dwordx4 v248, s[62:63]
	s_add_u32 m0, s8, 0x8400
	v_mfma_f32_16x16x32_bf16 v[4:7], v[44:47], v[116:119], v[4:7]
	global_load_lds_dwordx4 v249, s[62:63]
	s_add_u32 m0, s8, 0x8800
	v_mfma_f32_16x16x32_bf16 v[16:19], v[44:47], v[120:123], v[16:19]
	global_load_lds_dwordx4 v250, s[62:63]
	s_add_u32 m0, s8, 0x8c00
	v_mfma_f32_16x16x32_bf16 v[0:3], v[44:47], v[124:127], v[0:3]
	global_load_lds_dwordx4 v251, s[62:63]
	s_add_u32 s30, s30, 0x80
	s_addc_u32 s31, s31, 0
	s_add_u32 s62, s62, 0x80
	s_addc_u32 s63, s63, 0
	s_waitcnt vmcnt(8)
	s_barrier
	ds_read_b128 v[28:31], v252 offset:16384
	ds_read_b128 v[112:115], v254 offset:49152
	ds_read_b128 v[116:119], v254 offset:51200
	ds_read_b128 v[120:123], v254 offset:53248
	ds_read_b128 v[124:127], v254 offset:55296
	ds_read_b128 v[36:39], v252 offset:18432
	ds_read_b128 v[40:43], v252 offset:20480
	ds_read_b128 v[44:47], v252 offset:22528
	v_mfma_f32_16x16x32_bf16 v[92:95], v[48:51], v[132:135], v[92:95]
	v_mfma_f32_16x16x32_bf16 v[84:87], v[48:51], v[136:139], v[84:87]
	v_mfma_f32_16x16x32_bf16 v[88:91], v[48:51], v[140:143], v[88:91]
	v_mfma_f32_16x16x32_bf16 v[80:83], v[48:51], v[144:147], v[80:83]
	v_mfma_f32_16x16x32_bf16 v[76:79], v[52:55], v[132:135], v[76:79]
	v_mfma_f32_16x16x32_bf16 v[68:71], v[52:55], v[136:139], v[68:71]
	v_mfma_f32_16x16x32_bf16 v[72:75], v[52:55], v[140:143], v[72:75]
	v_mfma_f32_16x16x32_bf16 v[64:67], v[52:55], v[144:147], v[64:67]
	v_mfma_f32_16x16x32_bf16 v[32:35], v[56:59], v[132:135], v[32:35]
	v_mfma_f32_16x16x32_bf16 v[8:11], v[56:59], v[136:139], v[8:11]
	v_mfma_f32_16x16x32_bf16 v[24:27], v[56:59], v[140:143], v[24:27]
	v_mfma_f32_16x16x32_bf16 v[12:15], v[56:59], v[144:147], v[12:15]
	v_mfma_f32_16x16x32_bf16 v[20:23], v[60:63], v[132:135], v[20:23]
	v_mfma_f32_16x16x32_bf16 v[4:7], v[60:63], v[136:139], v[4:7]
	v_mfma_f32_16x16x32_bf16 v[16:19], v[60:63], v[140:143], v[16:19]
	v_mfma_f32_16x16x32_bf16 v[0:3], v[60:63], v[144:147], v[0:3]
	ds_read_b128 v[48:51], v253 offset:16384
	ds_read_b128 v[132:135], v255 offset:49152
	ds_read_b128 v[136:139], v255 offset:51200
	ds_read_b128 v[140:143], v255 offset:53248
	ds_read_b128 v[144:147], v255 offset:55296
	ds_read_b128 v[52:55], v253 offset:18432
	ds_read_b128 v[56:59], v253 offset:20480
	ds_read_b128 v[60:63], v253 offset:22528
	s_waitcnt lgkmcnt(14)
	v_mfma_f32_16x16x32_bf16 v[92:95], v[28:31], v[112:115], v[92:95]
	s_waitcnt lgkmcnt(13)
	v_mfma_f32_16x16x32_bf16 v[84:87], v[28:31], v[116:119], v[84:87]
	s_waitcnt lgkmcnt(12)
	v_mfma_f32_16x16x32_bf16 v[88:91], v[28:31], v[120:123], v[88:91]
	s_waitcnt lgkmcnt(11)
	v_mfma_f32_16x16x32_bf16 v[80:83], v[28:31], v[124:127], v[80:83]
	s_waitcnt lgkmcnt(10)
	v_mfma_f32_16x16x32_bf16 v[76:79], v[36:39], v[112:115], v[76:79]
	v_mfma_f32_16x16x32_bf16 v[68:71], v[36:39], v[116:119], v[68:71]
	v_mfma_f32_16x16x32_bf16 v[72:75], v[36:39], v[120:123], v[72:75]
	v_mfma_f32_16x16x32_bf16 v[64:67], v[36:39], v[124:127], v[64:67]
	s_waitcnt lgkmcnt(0)
	s_barrier
	s_add_u32 m0, s8, 0x4000
	v_mfma_f32_16x16x32_bf16 v[32:35], v[40:43], v[112:115], v[32:35]
	global_load_lds_dwordx4 v248, s[30:31]
	s_add_u32 m0, s8, 0x4400
	v_mfma_f32_16x16x32_bf16 v[8:11], v[40:43], v[116:119], v[8:11]
	global_load_lds_dwordx4 v249, s[30:31]
	s_add_u32 m0, s8, 0x4800
	v_mfma_f32_16x16x32_bf16 v[24:27], v[40:43], v[120:123], v[24:27]
	global_load_lds_dwordx4 v250, s[30:31]
	s_add_u32 m0, s8, 0x4c00
	v_mfma_f32_16x16x32_bf16 v[12:15], v[40:43], v[124:127], v[12:15]
	global_load_lds_dwordx4 v251, s[30:31]
	s_add_u32 m0, s8, 0xc000
	v_mfma_f32_16x16x32_bf16 v[20:23], v[44:47], v[112:115], v[20:23]
	global_load_lds_dwordx4 v248, s[62:63]
	s_add_u32 m0, s8, 0xc400
	v_mfma_f32_16x16x32_bf16 v[4:7], v[44:47], v[116:119], v[4:7]
	global_load_lds_dwordx4 v249, s[62:63]
	s_add_u32 m0, s8, 0xc800
	v_mfma_f32_16x16x32_bf16 v[16:19], v[44:47], v[120:123], v[16:19]
	global_load_lds_dwordx4 v250, s[62:63]
	s_add_u32 m0, s8, 0xcc00
	v_mfma_f32_16x16x32_bf16 v[0:3], v[44:47], v[124:127], v[0:3]
	global_load_lds_dwordx4 v251, s[62:63]
	s_add_u32 s30, s30, 0x80
	s_addc_u32 s31, s31, 0
	s_add_u32 s62, s62, 0x80
	s_addc_u32 s63, s63, 0
	s_sub_u32 s32, s32, 1
	s_cmp_lg_u32 s32, 0
	s_cbranch_scc1 .Lg8_loop
	s_waitcnt vmcnt(8)
	s_barrier
	ds_read_b128 v[28:31], v252 offset:0
	ds_read_b128 v[112:115], v254 offset:32768
	ds_read_b128 v[116:119], v254 offset:34816
	ds_read_b128 v[120:123], v254 offset:36864
	ds_read_b128 v[124:127], v254 offset:38912
	ds_read_b128 v[36:39], v252 offset:2048
	ds_read_b128 v[40:43], v252 offset:4096
	ds_read_b128 v[44:47], v252 offset:6144
	v_mfma_f32_16x16x32_bf16 v[92:95], v[48:51], v[132:135], v[92:95]
	v_mfma_f32_16x16x32_bf16 v[84:87], v[48:51], v[136:139], v[84:87]
	v_mfma_f32_16x16x32_bf16 v[88:91], v[48:51], v[140:143], v[88:91]
	v_mfma_f32_16x16x32_bf16 v[80:83], v[48:51], v[144:147], v[80:83]
	v_mfma_f32_16x16x32_bf16 v[76:79], v[52:55], v[132:135], v[76:79]
	v_mfma_f32_16x16x32_bf16 v[68:71], v[52:55], v[136:139], v[68:71]
	v_mfma_f32_16x16x32_bf16 v[72:75], v[52:55], v[140:143], v[72:75]
	v_mfma_f32_16x16x32_bf16 v[64:67], v[52:55], v[144:147], v[64:67]
	v_mfma_f32_16x16x32_bf16 v[32:35], v[56:59], v[132:135], v[32:35]
	v_mfma_f32_16x16x32_bf16 v[8:11], v[56:59], v[136:139], v[8:11]
	v_mfma_f32_16x16x32_bf16 v[24:27], v[56:59], v[140:143], v[24:27]
	v_mfma_f32_16x16x32_bf16 v[12:15], v[56:59], v[144:147], v[12:15]
	v_mfma_f32_16x16x32_bf16 v[20:23], v[60:63], v[132:135], v[20:23]
	v_mfma_f32_16x16x32_bf16 v[4:7], v[60:63], v[136:139], v[4:7]
	v_mfma_f32_16x16x32_bf16 v[16:19], v[60:63], v[140:143], v[16:19]
	v_mfma_f32_16x16x32_bf16 v[0:3], v[60:63], v[144:147], v[0:3]
	ds_read_b128 v[48:51], v253 offset:0
	ds_read_b128 v[132:135], v255 offset:32768
	ds_read_b128 v[136:139], v255 offset:34816
	ds_read_b128 v[140:143], v255 offset:36864
	ds_read_b128 v[144:147], v255 offset:38912
	ds_read_b128 v[52:55], v253 offset:2048
	ds_read_b128 v[56:59], v253 offset:4096
	ds_read_b128 v[60:63], v253 offset:6144
	s_waitcnt lgkmcnt(14)
	v_mfma_f32_16x16x32_bf16 v[92:95], v[28:31], v[112:115], v[92:95]
	s_waitcnt lgkmcnt(13)
	v_mfma_f32_16x16x32_bf16 v[84:87], v[28:31], v[116:119], v[84:87]
	s_waitcnt lgkmcnt(12)
	v_mfma_f32_16x16x32_bf16 v[88:91], v[28:31], v[120:123], v[88:91]
	s_waitcnt lgkmcnt(11)
	v_mfma_f32_16x16x32_bf16 v[80:83], v[28:31], v[124:127], v[80:83]
	s_waitcnt lgkmcnt(10)
	v_mfma_f32_16x16x32_bf16 v[76:79], v[36:39], v[112:115], v[76:79]
	v_mfma_f32_16x16x32_bf16 v[68:71], v[36:39], v[116:119], v[68:71]
	v_mfma_f32_16x16x32_bf16 v[72:75], v[36:39], v[120:123], v[72:75]
	v_mfma_f32_16x16x32_bf16 v[64:67], v[36:39], v[124:127], v[64:67]
	s_waitcnt lgkmcnt(0)
	s_barrier
	v_mfma_f32_16x16x32_bf16 v[32:35], v[40:43], v[112:115], v[32:35]
	v_mfma_f32_16x16x32_bf16 v[8:11], v[40:43], v[116:119], v[8:11]
	v_mfma_f32_16x16x32_bf16 v[24:27], v[40:43], v[120:123], v[24:27]
	v_mfma_f32_16x16x32_bf16 v[12:15], v[40:43], v[124:127], v[12:15]
	v_mfma_f32_16x16x32_bf16 v[20:23], v[44:47], v[112:115], v[20:23]
	v_mfma_f32_16x16x32_bf16 v[4:7], v[44:47], v[116:119], v[4:7]
	v_mfma_f32_16x16x32_bf16 v[16:19], v[44:47], v[120:123], v[16:19]
	v_mfma_f32_16x16x32_bf16 v[0:3], v[44:47], v[124:127], v[0:3]
	s_waitcnt vmcnt(0)
	s_barrier
	ds_read_b128 v[28:31], v252 offset:16384
	ds_read_b128 v[112:115], v254 offset:49152
	ds_read_b128 v[116:119], v254 offset:51200
	ds_read_b128 v[120:123], v254 offset:53248
	ds_read_b128 v[124:127], v254 offset:55296
	ds_read_b128 v[36:39], v252 offset:18432
	ds_read_b128 v[40:43], v252 offset:20480
	ds_read_b128 v[44:47], v252 offset:22528
	v_mfma_f32_16x16x32_bf16 v[92:95], v[48:51], v[132:135], v[92:95]
	v_mfma_f32_16x16x32_bf16 v[84:87], v[48:51], v[136:139], v[84:87]
	v_mfma_f32_16x16x32_bf16 v[88:91], v[48:51], v[140:143], v[88:91]
	v_mfma_f32_16x16x32_bf16 v[80:83], v[48:51], v[144:147], v[80:83]
	v_mfma_f32_16x16x32_bf16 v[76:79], v[52:55], v[132:135], v[76:79]
	v_mfma_f32_16x16x32_bf16 v[68:71], v[52:55], v[136:139], v[68:71]
	v_mfma_f32_16x16x32_bf16 v[72:75], v[52:55], v[140:143], v[72:75]
	v_mfma_f32_16x16x32_bf16 v[64:67], v[52:55], v[144:147], v[64:67]
	v_mfma_f32_16x16x32_bf16 v[32:35], v[56:59], v[132:135], v[32:35]
	v_mfma_f32_16x16x32_bf16 v[8:11], v[56:59], v[136:139], v[8:11]
	v_mfma_f32_16x16x32_bf16 v[24:27], v[56:59], v[140:143], v[24:27]
	v_mfma_f32_16x16x32_bf16 v[12:15], v[56:59], v[144:147], v[12:15]
	v_mfma_f32_16x16x32_bf16 v[20:23], v[60:63], v[132:135], v[20:23]
	v_mfma_f32_16x16x32_bf16 v[4:7], v[60:63], v[136:139], v[4:7]
	v_mfma_f32_16x16x32_bf16 v[16:19], v[60:63], v[140:143], v[16:19]
	v_mfma_f32_16x16x32_bf16 v[0:3], v[60:63], v[144:147], v[0:3]
	ds_read_b128 v[48:51], v253 offset:16384
	ds_read_b128 v[132:135], v255 offset:49152
	ds_read_b128 v[136:139], v255 offset:51200
	ds_read_b128 v[140:143], v255 offset:53248
	ds_read_b128 v[144:147], v255 offset:55296
	ds_read_b128 v[52:55], v253 offset:18432
	ds_read_b128 v[56:59], v253 offset:20480
	ds_read_b128 v[60:63], v253 offset:22528
	s_waitcnt lgkmcnt(14)
	v_mfma_f32_16x16x32_bf16 v[92:95], v[28:31], v[112:115], v[92:95]
	s_waitcnt lgkmcnt(13)
	v_mfma_f32_16x16x32_bf16 v[84:87], v[28:31], v[116:119], v[84:87]
	s_waitcnt lgkmcnt(12)
	v_mfma_f32_16x16x32_bf16 v[88:91], v[28:31], v[120:123], v[88:91]
	s_waitcnt lgkmcnt(11)
	v_mfma_f32_16x16x32_bf16 v[80:83], v[28:31], v[124:127], v[80:83]
	s_waitcnt lgkmcnt(10)
	v_mfma_f32_16x16x32_bf16 v[76:79], v[36:39], v[112:115], v[76:79]
	v_mfma_f32_16x16x32_bf16 v[68:71], v[36:39], v[116:119], v[68:71]
	v_mfma_f32_16x16x32_bf16 v[72:75], v[36:39], v[120:123], v[72:75]
	v_mfma_f32_16x16x32_bf16 v[64:67], v[36:39], v[124:127], v[64:67]
	s_waitcnt lgkmcnt(0)
	s_barrier
	v_mfma_f32_16x16x32_bf16 v[32:35], v[40:43], v[112:115], v[32:35]
	v_mfma_f32_16x16x32_bf16 v[8:11], v[40:43], v[116:119], v[8:11]
	v_mfma_f32_16x16x32_bf16 v[24:27], v[40:43], v[120:123], v[24:27]
	v_mfma_f32_16x16x32_bf16 v[12:15], v[40:43], v[124:127], v[12:15]
	v_mfma_f32_16x16x32_bf16 v[20:23], v[44:47], v[112:115], v[20:23]
	v_mfma_f32_16x16x32_bf16 v[4:7], v[44:47], v[116:119], v[4:7]
	v_mfma_f32_16x16x32_bf16 v[16:19], v[44:47], v[120:123], v[16:19]
	v_mfma_f32_16x16x32_bf16 v[0:3], v[44:47], v[124:127], v[0:3]
	v_mfma_f32_16x16x32_bf16 v[92:95], v[48:51], v[132:135], v[92:95]
	v_mfma_f32_16x16x32_bf16 v[84:87], v[48:51], v[136:139], v[84:87]
	v_mfma_f32_16x16x32_bf16 v[88:91], v[48:51], v[140:143], v[88:91]
	v_mfma_f32_16x16x32_bf16 v[80:83], v[48:51], v[144:147], v[80:83]
	v_mfma_f32_16x16x32_bf16 v[76:79], v[52:55], v[132:135], v[76:79]
	v_mfma_f32_16x16x32_bf16 v[68:71], v[52:55], v[136:139], v[68:71]
	v_mfma_f32_16x16x32_bf16 v[72:75], v[52:55], v[140:143], v[72:75]
	v_mfma_f32_16x16x32_bf16 v[64:67], v[52:55], v[144:147], v[64:67]
	v_mfma_f32_16x16x32_bf16 v[32:35], v[56:59], v[132:135], v[32:35]
	v_mfma_f32_16x16x32_bf16 v[8:11], v[56:59], v[136:139], v[8:11]
	v_mfma_f32_16x16x32_bf16 v[24:27], v[56:59], v[140:143], v[24:27]
	v_mfma_f32_16x16x32_bf16 v[12:15], v[56:59], v[144:147], v[12:15]
	v_mfma_f32_16x16x32_bf16 v[20:23], v[60:63], v[132:135], v[20:23]
	v_mfma_f32_16x16x32_bf16 v[4:7], v[60:63], v[136:139], v[4:7]
	v_mfma_f32_16x16x32_bf16 v[16:19], v[60:63], v[140:143], v[16:19]
	v_mfma_f32_16x16x32_bf16 v[0:3], v[60:63], v[144:147], v[0:3]
	s_nop 7
	s_nop 1
	v_mul_f32_e32 v28, 0xbfb8aa3b, v92
	v_exp_f32_e32 v30, v28
	v_mul_f32_e32 v36, 0xbfb8aa3b, v93
	v_exp_f32_e32 v36, v36
	s_and_b32 s8, s55, 0xffffffc0
	v_add_f32_e32 v30, 1.0, v30
	v_rcp_f32_e32 v30, v30
	v_add_f32_e32 v36, 1.0, v36
	v_or_b32_e32 v28, s8, v157
	v_rcp_f32_e32 v36, v36
	v_add_u32_e32 v31, s54, v158
	v_ashrrev_i32_e32 v29, 31, v28
	v_mul_f32_e32 v30, v92, v30
	v_lshl_add_u64 v[28:29], v[28:29], 1, v[102:103]
	v_mul_f32_e32 v30, v88, v30
	v_mul_u32_u24_e32 v96, 0x1600, v31
	v_cvt_pk_bf16_f32 v30, v30, s0
	v_lshl_add_u64 v[28:29], v[28:29], 0, v[96:97]
	global_store_short v[28:29], v30, off
	v_mul_f32_e32 v30, v93, v36
	v_mul_f32_e32 v30, v89, v30
	v_cvt_pk_bf16_f32 v36, v30, s0
	v_mul_f32_e32 v30, 0xbfb8aa3b, v94
	v_exp_f32_e32 v37, v30
	v_add_co_u32_e32 v30, vcc, s37, v28
	s_add_i32 s3, s3, s34
	s_nop 0
	v_addc_co_u32_e32 v31, vcc, 0, v29, vcc
	global_store_short v[30:31], v36, off offset:1536
	v_mul_f32_e32 v36, 0xbfb8aa3b, v95
	v_exp_f32_e32 v36, v36
	v_add_f32_e32 v37, 1.0, v37
	v_rcp_f32_e32 v37, v37
	s_mov_b64 s[30:31], -1
	v_add_f32_e32 v36, 1.0, v36
	v_rcp_f32_e32 v39, v36
	v_mul_f32_e32 v37, v94, v37
	v_mul_f32_e32 v37, v90, v37
	v_add_co_u32_e32 v36, vcc, s38, v28
	v_cvt_pk_bf16_f32 v38, v37, s0
	s_nop 0
	v_addc_co_u32_e32 v37, vcc, 0, v29, vcc
	global_store_short v[36:37], v38, off offset:3072
	v_mul_f32_e32 v38, v95, v39
	v_mul_f32_e32 v38, v91, v38
	v_cvt_pk_bf16_f32 v40, v38, s0
	v_mul_f32_e32 v38, 0xbfb8aa3b, v84
	v_exp_f32_e32 v41, v38
	v_add_co_u32_e32 v38, vcc, s39, v28
	s_mov_b32 s55, s51
	s_nop 0
	v_addc_co_u32_e32 v39, vcc, 0, v29, vcc
	global_store_short v[38:39], v40, off offset:512
	v_mul_f32_e32 v40, 0xbfb8aa3b, v85
	v_exp_f32_e32 v40, v40
	v_add_f32_e32 v41, 1.0, v41
	v_rcp_f32_e32 v41, v41
	v_add_f32_e32 v40, 1.0, v40
	v_rcp_f32_e32 v40, v40
	v_mul_f32_e32 v41, v84, v41
	v_mul_f32_e32 v41, v80, v41
	v_cvt_pk_bf16_f32 v41, v41, s0
	global_store_short v[28:29], v41, off offset:32
	v_mul_f32_e32 v41, 0xbfb8aa3b, v86
	v_mul_f32_e32 v40, v85, v40
	v_exp_f32_e32 v41, v41
	v_mul_f32_e32 v40, v81, v40
	v_cvt_pk_bf16_f32 v40, v40, s0
	global_store_short v[30:31], v40, off offset:1568
	v_mul_f32_e32 v30, 0xbfb8aa3b, v87
	v_exp_f32_e32 v30, v30
	v_add_f32_e32 v41, 1.0, v41
	v_rcp_f32_e32 v41, v41
	v_add_f32_e32 v30, 1.0, v30
	v_rcp_f32_e32 v30, v30
	v_mul_f32_e32 v31, v86, v41
	v_mul_f32_e32 v31, v82, v31
	v_cvt_pk_bf16_f32 v31, v31, s0
	global_store_short v[36:37], v31, off offset:3104
	v_mul_f32_e32 v31, 0xbfb8aa3b, v76
	v_mul_f32_e32 v30, v87, v30
	v_exp_f32_e32 v31, v31
	v_mul_f32_e32 v30, v83, v30
	v_cvt_pk_bf16_f32 v30, v30, s0
	global_store_short v[38:39], v30, off offset:544
	v_mul_f32_e32 v30, 0xbfb8aa3b, v77
	v_exp_f32_e32 v30, v30
	v_add_f32_e32 v31, 1.0, v31
	v_rcp_f32_e32 v31, v31
	v_add_f32_e32 v30, 1.0, v30
	v_rcp_f32_e32 v37, v30
	v_mul_f32_e32 v31, v76, v31
	v_mul_f32_e32 v31, v72, v31
	v_add_co_u32_e32 v30, vcc, s40, v28
	v_cvt_pk_bf16_f32 v36, v31, s0
	s_nop 0
	v_addc_co_u32_e32 v31, vcc, 0, v29, vcc
	global_store_short v[30:31], v36, off
	v_mul_f32_e32 v36, v77, v37
	v_mul_f32_e32 v36, v73, v36
	v_cvt_pk_bf16_f32 v38, v36, s0
	v_mul_f32_e32 v36, 0xbfb8aa3b, v78
	v_exp_f32_e32 v39, v36
	v_add_co_u32_e32 v36, vcc, s41, v28
	v_add_f32_e32 v39, 1.0, v39
	s_nop 0
	v_addc_co_u32_e32 v37, vcc, 0, v29, vcc
	global_store_short v[36:37], v38, off offset:1536
	v_mul_f32_e32 v38, 0xbfb8aa3b, v79
	v_exp_f32_e32 v38, v38
	v_rcp_f32_e32 v39, v39
	v_add_f32_e32 v38, 1.0, v38
	v_rcp_f32_e32 v41, v38
	v_mul_f32_e32 v39, v78, v39
	v_mul_f32_e32 v39, v74, v39
	v_add_co_u32_e32 v38, vcc, s42, v28
	v_cvt_pk_bf16_f32 v40, v39, s0
	s_nop 0
	v_addc_co_u32_e32 v39, vcc, 0, v29, vcc
	global_store_short v[38:39], v40, off offset:3072
	v_mul_f32_e32 v40, v79, v41
	v_mul_f32_e32 v40, v75, v40
	v_cvt_pk_bf16_f32 v42, v40, s0
	v_mul_f32_e32 v40, 0xbfb8aa3b, v68
	v_exp_f32_e32 v43, v40
	v_add_co_u32_e32 v40, vcc, s43, v28
	v_add_f32_e32 v43, 1.0, v43
	s_nop 0
	v_addc_co_u32_e32 v41, vcc, 0, v29, vcc
	v_rcp_f32_e32 v43, v43
	global_store_short v[40:41], v42, off offset:512
	v_mul_f32_e32 v42, 0xbfb8aa3b, v69
	v_exp_f32_e32 v42, v42
	v_mul_f32_e32 v43, v68, v43
	v_mul_f32_e32 v43, v64, v43
	v_cvt_pk_bf16_f32 v43, v43, s0
	v_add_f32_e32 v42, 1.0, v42
	v_rcp_f32_e32 v42, v42
	global_store_short v[30:31], v43, off offset:32
	v_mul_f32_e32 v30, 0xbfb8aa3b, v70
	v_exp_f32_e32 v30, v30
	v_mul_f32_e32 v31, v69, v42
	v_mul_f32_e32 v31, v65, v31
	v_cvt_pk_bf16_f32 v31, v31, s0
	v_add_f32_e32 v30, 1.0, v30
	v_rcp_f32_e32 v30, v30
	global_store_short v[36:37], v31, off offset:1568
	v_mul_f32_e32 v31, 0xbfb8aa3b, v71
	v_exp_f32_e32 v31, v31
	v_mul_f32_e32 v30, v70, v30
	v_mul_f32_e32 v30, v66, v30
	v_cvt_pk_bf16_f32 v30, v30, s0
	v_add_f32_e32 v31, 1.0, v31
	v_rcp_f32_e32 v31, v31
	global_store_short v[38:39], v30, off offset:3104
	v_mul_f32_e32 v30, 0xbfb8aa3b, v32
	v_exp_f32_e32 v30, v30
	v_mul_f32_e32 v31, v71, v31
	v_mul_f32_e32 v31, v67, v31
	v_cvt_pk_bf16_f32 v31, v31, s0
	v_add_f32_e32 v30, 1.0, v30
	v_rcp_f32_e32 v30, v30
	global_store_short v[40:41], v31, off offset:544
	v_mul_f32_e32 v31, 0xbfb8aa3b, v33
	v_exp_f32_e32 v31, v31
	v_mul_f32_e32 v30, v32, v30
	v_mul_f32_e32 v24, v24, v30
	v_cvt_pk_bf16_f32 v24, v24, s0
	v_add_f32_e32 v30, 1.0, v31
	v_rcp_f32_e32 v32, v30
	v_add_co_u32_e32 v30, vcc, s44, v28
	s_nop 1
	v_addc_co_u32_e32 v31, vcc, 0, v29, vcc
	global_store_short v[30:31], v24, off
	v_mul_f32_e32 v24, v33, v32
	v_mul_f32_e32 v24, v25, v24
	v_cvt_pk_bf16_f32 v32, v24, s0
	v_mul_f32_e32 v24, 0xbfb8aa3b, v34
	v_exp_f32_e32 v33, v24
	v_add_co_u32_e32 v24, vcc, s45, v28
	v_add_f32_e32 v33, 1.0, v33
	s_nop 0
	v_addc_co_u32_e32 v25, vcc, 0, v29, vcc
	global_store_short v[24:25], v32, off offset:1536
	v_mul_f32_e32 v32, 0xbfb8aa3b, v35
	v_exp_f32_e32 v32, v32
	v_rcp_f32_e32 v33, v33
	v_add_f32_e32 v32, 1.0, v32
	v_mul_f32_e32 v33, v34, v33
	v_rcp_f32_e32 v34, v32
	v_mul_f32_e32 v26, v26, v33
	v_add_co_u32_e32 v32, vcc, s46, v28
	v_cvt_pk_bf16_f32 v26, v26, s0
	s_nop 0
	v_addc_co_u32_e32 v33, vcc, 0, v29, vcc
	global_store_short v[32:33], v26, off offset:3072
	v_mul_f32_e32 v26, v35, v34
	v_mul_f32_e32 v26, v27, v26
	v_cvt_pk_bf16_f32 v34, v26, s0
	v_mul_f32_e32 v26, 0xbfb8aa3b, v8
	v_exp_f32_e32 v35, v26
	v_add_co_u32_e32 v26, vcc, s36, v28
	v_add_f32_e32 v35, 1.0, v35
	s_nop 0
	v_addc_co_u32_e32 v27, vcc, 0, v29, vcc
	v_rcp_f32_e32 v35, v35
	global_store_short v[26:27], v34, off offset:512
	v_mul_f32_e32 v34, 0xbfb8aa3b, v9
	v_exp_f32_e32 v34, v34
	v_mul_f32_e32 v8, v8, v35
	v_mul_f32_e32 v8, v12, v8
	v_cvt_pk_bf16_f32 v8, v8, s0
	v_add_f32_e32 v12, 1.0, v34
	v_rcp_f32_e32 v12, v12
	global_store_short v[30:31], v8, off offset:32
	v_mul_f32_e32 v8, 0xbfb8aa3b, v10
	v_exp_f32_e32 v8, v8
	v_mul_f32_e32 v9, v9, v12
	v_mul_f32_e32 v9, v13, v9
	v_cvt_pk_bf16_f32 v9, v9, s0
	v_add_f32_e32 v8, 1.0, v8
	v_rcp_f32_e32 v8, v8
	global_store_short v[24:25], v9, off offset:1568
	v_mul_f32_e32 v9, 0xbfb8aa3b, v11
	v_exp_f32_e32 v9, v9
	v_mul_f32_e32 v8, v10, v8
	v_mul_f32_e32 v8, v14, v8
	v_cvt_pk_bf16_f32 v8, v8, s0
	v_add_f32_e32 v9, 1.0, v9
	v_rcp_f32_e32 v9, v9
	global_store_short v[32:33], v8, off offset:3104
	v_mul_f32_e32 v8, 0xbfb8aa3b, v20
	v_exp_f32_e32 v8, v8
	v_mul_f32_e32 v9, v11, v9
	v_mul_f32_e32 v9, v15, v9
	v_cvt_pk_bf16_f32 v9, v9, s0
	v_add_f32_e32 v8, 1.0, v8
	v_rcp_f32_e32 v8, v8
	global_store_short v[26:27], v9, off offset:544
	v_mul_f32_e32 v9, 0xbfb8aa3b, v21
	v_exp_f32_e32 v9, v9
	v_mul_f32_e32 v8, v20, v8
	v_mul_f32_e32 v8, v16, v8
	v_cvt_pk_bf16_f32 v10, v8, s0
	v_add_f32_e32 v8, 1.0, v9
	v_rcp_f32_e32 v11, v8
	v_add_co_u32_e32 v8, vcc, s47, v28
	s_nop 1
	v_addc_co_u32_e32 v9, vcc, 0, v29, vcc
	global_store_short v[8:9], v10, off
	v_mul_f32_e32 v10, v21, v11
	v_mul_f32_e32 v10, v17, v10
	v_cvt_pk_bf16_f32 v12, v10, s0
	v_mul_f32_e32 v10, 0xbfb8aa3b, v22
	v_exp_f32_e32 v13, v10
	v_add_co_u32_e32 v10, vcc, s48, v28
	v_add_f32_e32 v13, 1.0, v13
	s_nop 0
	v_addc_co_u32_e32 v11, vcc, 0, v29, vcc
	global_store_short v[10:11], v12, off offset:1536
	v_mul_f32_e32 v12, 0xbfb8aa3b, v23
	v_exp_f32_e32 v12, v12
	v_rcp_f32_e32 v13, v13
	v_add_f32_e32 v12, 1.0, v12
	v_rcp_f32_e32 v15, v12
	v_mul_f32_e32 v13, v22, v13
	v_mul_f32_e32 v13, v18, v13
	v_add_co_u32_e32 v12, vcc, s49, v28
	v_cvt_pk_bf16_f32 v14, v13, s0
	s_nop 0
	v_addc_co_u32_e32 v13, vcc, 0, v29, vcc
	global_store_short v[12:13], v14, off offset:3072
	v_mul_f32_e32 v14, v23, v15
	v_mul_f32_e32 v14, v19, v14
	v_cvt_pk_bf16_f32 v16, v14, s0
	v_mul_f32_e32 v14, 0xbfb8aa3b, v4
	v_exp_f32_e32 v17, v14
	v_add_co_u32_e32 v14, vcc, s50, v28
	v_add_f32_e32 v17, 1.0, v17
	s_nop 0
	v_addc_co_u32_e32 v15, vcc, 0, v29, vcc
	v_rcp_f32_e32 v17, v17
	global_store_short v[14:15], v16, off offset:512
	v_mul_f32_e32 v16, 0xbfb8aa3b, v5
	v_exp_f32_e32 v16, v16
	v_mul_f32_e32 v4, v4, v17
	v_mul_f32_e32 v0, v0, v4
	v_cvt_pk_bf16_f32 v0, v0, s0
	v_add_f32_e32 v4, 1.0, v16
	v_rcp_f32_e32 v4, v4
	v_mul_f32_e32 v16, 0xbfb8aa3b, v6
	v_exp_f32_e32 v16, v16
	global_store_short v[8:9], v0, off offset:32
	v_mul_f32_e32 v0, v5, v4
	v_mul_f32_e32 v0, v1, v0
	v_add_f32_e32 v1, 1.0, v16
	v_mul_f32_e32 v4, 0xbfb8aa3b, v7
	v_rcp_f32_e32 v1, v1
	v_exp_f32_e32 v4, v4
	v_cvt_pk_bf16_f32 v0, v0, s0
	global_store_short v[10:11], v0, off offset:1568
	v_mul_f32_e32 v0, v6, v1
	v_add_f32_e32 v1, 1.0, v4
	v_rcp_f32_e32 v1, v1
	v_mul_f32_e32 v0, v2, v0
	v_cvt_pk_bf16_f32 v0, v0, s0
	global_store_short v[12:13], v0, off offset:3104
	v_mul_f32_e32 v0, v7, v1
	v_mul_f32_e32 v0, v3, v0
	v_cvt_pk_bf16_f32 v0, v0, s0
	s_andn2_b64 vcc, exec, s[26:27]
	global_store_short v[14:15], v0, off offset:544
	s_cbranch_vccnz .LBB0_954

.LBB0_1018:
	s_lshl_b32 s6, s36, 7
	s_and_b32 s37, s6, 0x1f80
	s_lshl_b32 s6, s36, 1
	s_and_b32 s38, s6, 0xffffff80
	s_mul_i32 s6, s37, 0x1600
	v_lshl_add_u64 v[102:103], v[98:99], 0, s[6:7]
	v_add_co_u32_e32 v38, vcc, 0x2c000, v102
	v_mad_i64_i32 v[104:105], s[40:41], s38, v150, v[100:101]
	s_nop 0
	v_addc_co_u32_e32 v39, vcc, 0, v103, vcc
	v_add_co_u32_e32 v44, vcc, 0x58000, v102
	s_nop 0
	v_addc_co_u32_e32 v45, vcc, 0, v103, vcc
	v_add_co_u32_e32 v46, vcc, 0x84000, v102
	v_addc_co_u32_e32 v47, vcc, 0, v103, vcc
	v_add_co_u32_e32 v48, vcc, s31, v104
	v_addc_co_u32_e32 v49, vcc, 0, v105, vcc
	v_add_co_u32_e32 v50, vcc, s34, v104
	s_nop 0
	v_addc_co_u32_e32 v51, vcc, 0, v105, vcc
	v_add_co_u32_e32 v52, vcc, s35, v104
	s_nop 0
	v_addc_co_u32_e32 v53, vcc, 0, v105, vcc
	s_mov_b32 s39, -2
	v_mov_b32_e32 v8, 0
	v_mov_b32_e32 v9, v97
	v_mov_b32_e32 v10, v97
	v_mov_b32_e32 v11, v97
	v_mov_b32_e32 v24, 0
	v_mov_b32_e32 v25, v97
	v_mov_b32_e32 v26, v97
	v_mov_b32_e32 v27, v97
	v_mov_b32_e32 v36, 0
	v_mov_b32_e32 v37, v97
	v_mov_b32_e32 v38, v97
	v_mov_b32_e32 v39, v97
	v_lshl_add_u64 v[106:107], v[104:105], 0, s[8:9]
	v_lshl_add_u64 v[108:109], v[104:105], 0, s[10:11]
	v_lshl_add_u64 v[110:111], v[104:105], 0, s[12:13]
	v_lshl_add_u64 v[120:121], v[104:105], 0, s[14:15]
	v_lshl_add_u64 v[122:123], v[104:105], 0, s[16:17]
	v_lshl_add_u64 v[124:125], v[104:105], 0, s[18:19]
	v_lshl_add_u64 v[118:119], v[104:105], 0, s[20:21]
	v_lshl_add_u64 v[112:113], v[102:103], 0, s[8:9]
	v_lshl_add_u64 v[114:115], v[102:103], 0, s[10:11]
	v_lshl_add_u64 v[116:117], v[102:103], 0, s[12:13]
	v_lshl_add_u64 v[126:127], v[102:103], 0, s[14:15]
	v_lshl_add_u64 v[130:131], v[102:103], 0, s[16:17]
	v_lshl_add_u64 v[132:133], v[102:103], 0, s[18:19]
	v_lshl_add_u64 v[134:135], v[102:103], 0, s[20:21]
	v_mov_b32_e32 v48, 0
	v_mov_b32_e32 v49, v97
	v_mov_b32_e32 v50, v97
	v_mov_b32_e32 v51, v97
	v_mov_b32_e32 v52, 0
	v_mov_b32_e32 v53, v97
	v_mov_b32_e32 v54, v97
	v_mov_b32_e32 v55, v97
	v_mov_b32_e32 v56, 0
	v_mov_b32_e32 v57, v97
	v_mov_b32_e32 v58, v97
	v_mov_b32_e32 v59, v97
	v_mov_b32_e32 v44, 0
	v_mov_b32_e32 v45, v97
	v_mov_b32_e32 v46, v97
	v_mov_b32_e32 v47, v97
	v_mov_b32_e32 v60, 0
	v_mov_b32_e32 v61, v97
	v_mov_b32_e32 v62, v97
	v_mov_b32_e32 v63, v97
	v_mov_b32_e32 v0, 0
	v_mov_b32_e32 v1, v97
	v_mov_b32_e32 v2, v97
	v_mov_b32_e32 v3, v97
	v_mov_b32_e32 v16, 0
	v_mov_b32_e32 v17, v97
	v_mov_b32_e32 v18, v97
	v_mov_b32_e32 v19, v97
	v_mov_b32_e32 v32, 0
	v_mov_b32_e32 v33, v97
	v_mov_b32_e32 v34, v97
	v_mov_b32_e32 v35, v97
	v_mov_b32_e32 v4, 0
	v_mov_b32_e32 v5, v97
	v_mov_b32_e32 v6, v97
	v_mov_b32_e32 v7, v97
	v_mov_b32_e32 v20, 0
	v_mov_b32_e32 v21, v97
	v_mov_b32_e32 v22, v97
	v_mov_b32_e32 v23, v97
	v_mov_b32_e32 v40, 0
	v_mov_b32_e32 v41, v97
	v_mov_b32_e32 v42, v97
	v_mov_b32_e32 v43, v97
	v_mov_b32_e32 v12, 0
	v_mov_b32_e32 v13, v97
	v_mov_b32_e32 v14, v97
	v_mov_b32_e32 v15, v97
	v_mov_b32_e32 v28, 0
	v_mov_b32_e32 v29, v97
	v_mov_b32_e32 v30, v97
	v_mov_b32_e32 v31, v97
	v_readfirstlane_b32 s40, v102
	v_readfirstlane_b32 s41, v103
	v_readfirstlane_b32 s48, v104
	v_readfirstlane_b32 s49, v105
	v_readfirstlane_b32 s6, v247
	s_nop 3
	s_mul_i32 s39, s6, 0xb000
	s_sub_u32 s40, s40, s39
	s_subb_u32 s41, s41, 0
	s_sub_u32 s48, s48, s39
	s_subb_u32 s49, s49, 0
	s_lshl_b32 s6, s6, 12
	s_add_u32 m0, s6, 0x0
	v_mov_b32_e32 v60, 0
	global_load_lds_dwordx4 v248, s[40:41]
	v_mov_b32_e32 v61, 0
	s_add_u32 m0, s6, 0x400
	v_mov_b32_e32 v62, 0
	global_load_lds_dwordx4 v249, s[40:41]
	v_mov_b32_e32 v63, 0
	s_add_u32 m0, s6, 0x800
	v_mov_b32_e32 v44, 0
	global_load_lds_dwordx4 v250, s[40:41]
	v_mov_b32_e32 v45, 0
	s_add_u32 m0, s6, 0xc00
	v_mov_b32_e32 v46, 0
	global_load_lds_dwordx4 v251, s[40:41]
	v_mov_b32_e32 v47, 0
	s_add_u32 m0, s6, 0x8000
	v_mov_b32_e32 v28, 0
	global_load_lds_dwordx4 v248, s[48:49]
	v_mov_b32_e32 v29, 0
	s_add_u32 m0, s6, 0x8400
	v_mov_b32_e32 v30, 0
	global_load_lds_dwordx4 v249, s[48:49]
	v_mov_b32_e32 v31, 0
	s_add_u32 m0, s6, 0x8800
	v_mov_b32_e32 v12, 0
	global_load_lds_dwordx4 v250, s[48:49]
	v_mov_b32_e32 v13, 0
	s_add_u32 m0, s6, 0x8c00
	v_mov_b32_e32 v14, 0
	global_load_lds_dwordx4 v251, s[48:49]
	v_mov_b32_e32 v15, 0
	s_add_u32 s40, s40, 0x80
	s_addc_u32 s41, s41, 0
	s_add_u32 s48, s48, 0x80
	s_addc_u32 s49, s49, 0
	s_add_u32 m0, s6, 0x4000
	v_mov_b32_e32 v56, 0
	global_load_lds_dwordx4 v248, s[40:41]
	v_mov_b32_e32 v57, 0
	s_add_u32 m0, s6, 0x4400
	v_mov_b32_e32 v58, 0
	global_load_lds_dwordx4 v249, s[40:41]
	v_mov_b32_e32 v59, 0
	s_add_u32 m0, s6, 0x4800
	v_mov_b32_e32 v40, 0
	global_load_lds_dwordx4 v250, s[40:41]
	v_mov_b32_e32 v41, 0
	s_add_u32 m0, s6, 0x4c00
	v_mov_b32_e32 v42, 0
	global_load_lds_dwordx4 v251, s[40:41]
	v_mov_b32_e32 v43, 0
	s_add_u32 m0, s6, 0xc000
	v_mov_b32_e32 v20, 0
	global_load_lds_dwordx4 v248, s[48:49]
	v_mov_b32_e32 v21, 0
	s_add_u32 m0, s6, 0xc400
	v_mov_b32_e32 v22, 0
	global_load_lds_dwordx4 v249, s[48:49]
	v_mov_b32_e32 v23, 0
	s_add_u32 m0, s6, 0xc800
	v_mov_b32_e32 v4, 0
	global_load_lds_dwordx4 v250, s[48:49]
	v_mov_b32_e32 v5, 0
	s_add_u32 m0, s6, 0xcc00
	v_mov_b32_e32 v6, 0
	global_load_lds_dwordx4 v251, s[48:49]
	v_mov_b32_e32 v7, 0
	s_add_u32 s40, s40, 0x80
	s_addc_u32 s41, s41, 0
	s_add_u32 s48, s48, 0x80
	s_addc_u32 s49, s49, 0
	v_mov_b32_e32 v52, 0
	v_mov_b32_e32 v53, 0
	v_mov_b32_e32 v54, 0
	v_mov_b32_e32 v55, 0
	v_mov_b32_e32 v32, 0
	v_mov_b32_e32 v33, 0
	v_mov_b32_e32 v34, 0
	v_mov_b32_e32 v35, 0
	v_mov_b32_e32 v16, 0
	v_mov_b32_e32 v17, 0
	v_mov_b32_e32 v18, 0
	v_mov_b32_e32 v19, 0
	v_mov_b32_e32 v0, 0
	v_mov_b32_e32 v1, 0
	v_mov_b32_e32 v2, 0
	v_mov_b32_e32 v3, 0
	v_mov_b32_e32 v48, 0
	v_mov_b32_e32 v49, 0
	v_mov_b32_e32 v50, 0
	v_mov_b32_e32 v51, 0
	v_mov_b32_e32 v36, 0
	v_mov_b32_e32 v37, 0
	v_mov_b32_e32 v38, 0
	v_mov_b32_e32 v39, 0
	v_mov_b32_e32 v24, 0
	v_mov_b32_e32 v25, 0
	v_mov_b32_e32 v26, 0
	v_mov_b32_e32 v27, 0
	v_mov_b32_e32 v8, 0
	v_mov_b32_e32 v9, 0
	v_mov_b32_e32 v10, 0
	v_mov_b32_e32 v11, 0
	s_waitcnt vmcnt(8)
	s_barrier
	ds_read_b128 v[64:67], v252 offset:0
	ds_read_b128 v[104:107], v254 offset:32768
	ds_read_b128 v[108:111], v254 offset:34816
	ds_read_b128 v[112:115], v254 offset:36864
	ds_read_b128 v[116:119], v254 offset:38912
	ds_read_b128 v[68:71], v252 offset:2048
	ds_read_b128 v[72:75], v252 offset:4096
	ds_read_b128 v[76:79], v252 offset:6144
	ds_read_b128 v[80:83], v253 offset:0
	ds_read_b128 v[120:123], v255 offset:32768
	ds_read_b128 v[124:127], v255 offset:34816
	ds_read_b128 v[132:135], v255 offset:36864
	ds_read_b128 v[136:139], v255 offset:38912
	s_waitcnt lgkmcnt(11)
	v_mfma_f32_16x16x32_bf16 v[60:63], v[64:67], v[104:107], v[60:63]
	s_waitcnt lgkmcnt(10)
	v_mfma_f32_16x16x32_bf16 v[44:47], v[64:67], v[108:111], v[44:47]
	s_waitcnt lgkmcnt(9)
	v_mfma_f32_16x16x32_bf16 v[28:31], v[64:67], v[112:115], v[28:31]
	s_waitcnt lgkmcnt(8)
	v_mfma_f32_16x16x32_bf16 v[12:15], v[64:67], v[116:119], v[12:15]
	ds_read_b128 v[84:87], v253 offset:2048
	ds_read_b128 v[88:91], v253 offset:4096
	ds_read_b128 v[92:95], v253 offset:6144
	s_waitcnt lgkmcnt(10)
	v_mfma_f32_16x16x32_bf16 v[56:59], v[68:71], v[104:107], v[56:59]
	v_mfma_f32_16x16x32_bf16 v[40:43], v[68:71], v[108:111], v[40:43]
	v_mfma_f32_16x16x32_bf16 v[20:23], v[68:71], v[112:115], v[20:23]
	v_mfma_f32_16x16x32_bf16 v[4:7], v[68:71], v[116:119], v[4:7]
	s_waitcnt lgkmcnt(0)
	s_barrier
	s_add_u32 m0, s6, 0x0
	v_mfma_f32_16x16x32_bf16 v[52:55], v[72:75], v[104:107], v[52:55]
	global_load_lds_dwordx4 v248, s[40:41]
	s_add_u32 m0, s6, 0x400
	v_mfma_f32_16x16x32_bf16 v[32:35], v[72:75], v[108:111], v[32:35]
	global_load_lds_dwordx4 v249, s[40:41]
	s_add_u32 m0, s6, 0x800
	v_mfma_f32_16x16x32_bf16 v[16:19], v[72:75], v[112:115], v[16:19]
	global_load_lds_dwordx4 v250, s[40:41]
	s_add_u32 m0, s6, 0xc00
	v_mfma_f32_16x16x32_bf16 v[0:3], v[72:75], v[116:119], v[0:3]
	global_load_lds_dwordx4 v251, s[40:41]
	s_add_u32 m0, s6, 0x8000
	v_mfma_f32_16x16x32_bf16 v[48:51], v[76:79], v[104:107], v[48:51]
	global_load_lds_dwordx4 v248, s[48:49]
	s_add_u32 m0, s6, 0x8400
	v_mfma_f32_16x16x32_bf16 v[36:39], v[76:79], v[108:111], v[36:39]
	global_load_lds_dwordx4 v249, s[48:49]
	s_add_u32 m0, s6, 0x8800
	v_mfma_f32_16x16x32_bf16 v[24:27], v[76:79], v[112:115], v[24:27]
	global_load_lds_dwordx4 v250, s[48:49]
	s_add_u32 m0, s6, 0x8c00
	v_mfma_f32_16x16x32_bf16 v[8:11], v[76:79], v[116:119], v[8:11]
	global_load_lds_dwordx4 v251, s[48:49]
	s_add_u32 s40, s40, 0x80
	s_addc_u32 s41, s41, 0
	s_add_u32 s48, s48, 0x80
	s_addc_u32 s49, s49, 0
	s_waitcnt vmcnt(8)
	s_barrier
	ds_read_b128 v[64:67], v252 offset:16384
	ds_read_b128 v[104:107], v254 offset:49152
	ds_read_b128 v[108:111], v254 offset:51200
	ds_read_b128 v[112:115], v254 offset:53248
	ds_read_b128 v[116:119], v254 offset:55296
	ds_read_b128 v[68:71], v252 offset:18432
	ds_read_b128 v[72:75], v252 offset:20480
	ds_read_b128 v[76:79], v252 offset:22528
	v_mfma_f32_16x16x32_bf16 v[60:63], v[80:83], v[120:123], v[60:63]
	v_mfma_f32_16x16x32_bf16 v[44:47], v[80:83], v[124:127], v[44:47]
	v_mfma_f32_16x16x32_bf16 v[28:31], v[80:83], v[132:135], v[28:31]
	v_mfma_f32_16x16x32_bf16 v[12:15], v[80:83], v[136:139], v[12:15]
	v_mfma_f32_16x16x32_bf16 v[56:59], v[84:87], v[120:123], v[56:59]
	v_mfma_f32_16x16x32_bf16 v[40:43], v[84:87], v[124:127], v[40:43]
	v_mfma_f32_16x16x32_bf16 v[20:23], v[84:87], v[132:135], v[20:23]
	v_mfma_f32_16x16x32_bf16 v[4:7], v[84:87], v[136:139], v[4:7]
	v_mfma_f32_16x16x32_bf16 v[52:55], v[88:91], v[120:123], v[52:55]
	v_mfma_f32_16x16x32_bf16 v[32:35], v[88:91], v[124:127], v[32:35]
	v_mfma_f32_16x16x32_bf16 v[16:19], v[88:91], v[132:135], v[16:19]
	v_mfma_f32_16x16x32_bf16 v[0:3], v[88:91], v[136:139], v[0:3]
	v_mfma_f32_16x16x32_bf16 v[48:51], v[92:95], v[120:123], v[48:51]
	v_mfma_f32_16x16x32_bf16 v[36:39], v[92:95], v[124:127], v[36:39]
	v_mfma_f32_16x16x32_bf16 v[24:27], v[92:95], v[132:135], v[24:27]
	v_mfma_f32_16x16x32_bf16 v[8:11], v[92:95], v[136:139], v[8:11]
	ds_read_b128 v[80:83], v253 offset:16384
	ds_read_b128 v[120:123], v255 offset:49152
	ds_read_b128 v[124:127], v255 offset:51200
	ds_read_b128 v[132:135], v255 offset:53248
	ds_read_b128 v[136:139], v255 offset:55296
	ds_read_b128 v[84:87], v253 offset:18432
	ds_read_b128 v[88:91], v253 offset:20480
	ds_read_b128 v[92:95], v253 offset:22528
	s_waitcnt lgkmcnt(14)
	v_mfma_f32_16x16x32_bf16 v[60:63], v[64:67], v[104:107], v[60:63]
	s_waitcnt lgkmcnt(13)
	v_mfma_f32_16x16x32_bf16 v[44:47], v[64:67], v[108:111], v[44:47]
	s_waitcnt lgkmcnt(12)
	v_mfma_f32_16x16x32_bf16 v[28:31], v[64:67], v[112:115], v[28:31]
	s_waitcnt lgkmcnt(11)
	v_mfma_f32_16x16x32_bf16 v[12:15], v[64:67], v[116:119], v[12:15]
	s_waitcnt lgkmcnt(10)
	v_mfma_f32_16x16x32_bf16 v[56:59], v[68:71], v[104:107], v[56:59]
	v_mfma_f32_16x16x32_bf16 v[40:43], v[68:71], v[108:111], v[40:43]
	v_mfma_f32_16x16x32_bf16 v[20:23], v[68:71], v[112:115], v[20:23]
	v_mfma_f32_16x16x32_bf16 v[4:7], v[68:71], v[116:119], v[4:7]
	s_waitcnt lgkmcnt(0)
	s_barrier
	s_add_u32 m0, s6, 0x4000
	v_mfma_f32_16x16x32_bf16 v[52:55], v[72:75], v[104:107], v[52:55]
	global_load_lds_dwordx4 v248, s[40:41]
	s_add_u32 m0, s6, 0x4400
	v_mfma_f32_16x16x32_bf16 v[32:35], v[72:75], v[108:111], v[32:35]
	global_load_lds_dwordx4 v249, s[40:41]
	s_add_u32 m0, s6, 0x4800
	v_mfma_f32_16x16x32_bf16 v[16:19], v[72:75], v[112:115], v[16:19]
	global_load_lds_dwordx4 v250, s[40:41]
	s_add_u32 m0, s6, 0x4c00
	v_mfma_f32_16x16x32_bf16 v[0:3], v[72:75], v[116:119], v[0:3]
	global_load_lds_dwordx4 v251, s[40:41]
	s_add_u32 m0, s6, 0xc000
	v_mfma_f32_16x16x32_bf16 v[48:51], v[76:79], v[104:107], v[48:51]
	global_load_lds_dwordx4 v248, s[48:49]
	s_add_u32 m0, s6, 0xc400
	v_mfma_f32_16x16x32_bf16 v[36:39], v[76:79], v[108:111], v[36:39]
	global_load_lds_dwordx4 v249, s[48:49]
	s_add_u32 m0, s6, 0xc800
	v_mfma_f32_16x16x32_bf16 v[24:27], v[76:79], v[112:115], v[24:27]
	global_load_lds_dwordx4 v250, s[48:49]
	s_add_u32 m0, s6, 0xcc00
	v_mfma_f32_16x16x32_bf16 v[8:11], v[76:79], v[116:119], v[8:11]
	global_load_lds_dwordx4 v251, s[48:49]
	s_add_u32 s40, s40, 0x80
	s_addc_u32 s41, s41, 0
	s_add_u32 s48, s48, 0x80
	s_addc_u32 s49, s49, 0
	s_mov_b32 s32, 20
.Lg9_loop:
	s_waitcnt vmcnt(8)
	s_barrier
	ds_read_b128 v[64:67], v252 offset:0
	ds_read_b128 v[104:107], v254 offset:32768
	ds_read_b128 v[108:111], v254 offset:34816
	ds_read_b128 v[112:115], v254 offset:36864
	ds_read_b128 v[116:119], v254 offset:38912
	ds_read_b128 v[68:71], v252 offset:2048
	ds_read_b128 v[72:75], v252 offset:4096
	ds_read_b128 v[76:79], v252 offset:6144
	v_mfma_f32_16x16x32_bf16 v[60:63], v[80:83], v[120:123], v[60:63]
	v_mfma_f32_16x16x32_bf16 v[44:47], v[80:83], v[124:127], v[44:47]
	v_mfma_f32_16x16x32_bf16 v[28:31], v[80:83], v[132:135], v[28:31]
	v_mfma_f32_16x16x32_bf16 v[12:15], v[80:83], v[136:139], v[12:15]
	v_mfma_f32_16x16x32_bf16 v[56:59], v[84:87], v[120:123], v[56:59]
	v_mfma_f32_16x16x32_bf16 v[40:43], v[84:87], v[124:127], v[40:43]
	v_mfma_f32_16x16x32_bf16 v[20:23], v[84:87], v[132:135], v[20:23]
	v_mfma_f32_16x16x32_bf16 v[4:7], v[84:87], v[136:139], v[4:7]
	v_mfma_f32_16x16x32_bf16 v[52:55], v[88:91], v[120:123], v[52:55]
	v_mfma_f32_16x16x32_bf16 v[32:35], v[88:91], v[124:127], v[32:35]
	v_mfma_f32_16x16x32_bf16 v[16:19], v[88:91], v[132:135], v[16:19]
	v_mfma_f32_16x16x32_bf16 v[0:3], v[88:91], v[136:139], v[0:3]
	v_mfma_f32_16x16x32_bf16 v[48:51], v[92:95], v[120:123], v[48:51]
	v_mfma_f32_16x16x32_bf16 v[36:39], v[92:95], v[124:127], v[36:39]
	v_mfma_f32_16x16x32_bf16 v[24:27], v[92:95], v[132:135], v[24:27]
	v_mfma_f32_16x16x32_bf16 v[8:11], v[92:95], v[136:139], v[8:11]
	ds_read_b128 v[80:83], v253 offset:0
	ds_read_b128 v[120:123], v255 offset:32768
	ds_read_b128 v[124:127], v255 offset:34816
	ds_read_b128 v[132:135], v255 offset:36864
	ds_read_b128 v[136:139], v255 offset:38912
	ds_read_b128 v[84:87], v253 offset:2048
	ds_read_b128 v[88:91], v253 offset:4096
	ds_read_b128 v[92:95], v253 offset:6144
	s_waitcnt lgkmcnt(14)
	v_mfma_f32_16x16x32_bf16 v[60:63], v[64:67], v[104:107], v[60:63]
	s_waitcnt lgkmcnt(13)
	v_mfma_f32_16x16x32_bf16 v[44:47], v[64:67], v[108:111], v[44:47]
	s_waitcnt lgkmcnt(12)
	v_mfma_f32_16x16x32_bf16 v[28:31], v[64:67], v[112:115], v[28:31]
	s_waitcnt lgkmcnt(11)
	v_mfma_f32_16x16x32_bf16 v[12:15], v[64:67], v[116:119], v[12:15]
	s_waitcnt lgkmcnt(10)
	v_mfma_f32_16x16x32_bf16 v[56:59], v[68:71], v[104:107], v[56:59]
	v_mfma_f32_16x16x32_bf16 v[40:43], v[68:71], v[108:111], v[40:43]
	v_mfma_f32_16x16x32_bf16 v[20:23], v[68:71], v[112:115], v[20:23]
	v_mfma_f32_16x16x32_bf16 v[4:7], v[68:71], v[116:119], v[4:7]
	s_waitcnt lgkmcnt(0)
	s_barrier
	s_add_u32 m0, s6, 0x0
	v_mfma_f32_16x16x32_bf16 v[52:55], v[72:75], v[104:107], v[52:55]
	global_load_lds_dwordx4 v248, s[40:41]
	s_add_u32 m0, s6, 0x400
	v_mfma_f32_16x16x32_bf16 v[32:35], v[72:75], v[108:111], v[32:35]
	global_load_lds_dwordx4 v249, s[40:41]
	s_add_u32 m0, s6, 0x800
	v_mfma_f32_16x16x32_bf16 v[16:19], v[72:75], v[112:115], v[16:19]
	global_load_lds_dwordx4 v250, s[40:41]
	s_add_u32 m0, s6, 0xc00
	v_mfma_f32_16x16x32_bf16 v[0:3], v[72:75], v[116:119], v[0:3]
	global_load_lds_dwordx4 v251, s[40:41]
	s_add_u32 m0, s6, 0x8000
	v_mfma_f32_16x16x32_bf16 v[48:51], v[76:79], v[104:107], v[48:51]
	global_load_lds_dwordx4 v248, s[48:49]
	s_add_u32 m0, s6, 0x8400
	v_mfma_f32_16x16x32_bf16 v[36:39], v[76:79], v[108:111], v[36:39]
	global_load_lds_dwordx4 v249, s[48:49]
	s_add_u32 m0, s6, 0x8800
	v_mfma_f32_16x16x32_bf16 v[24:27], v[76:79], v[112:115], v[24:27]
	global_load_lds_dwordx4 v250, s[48:49]
	s_add_u32 m0, s6, 0x8c00
	v_mfma_f32_16x16x32_bf16 v[8:11], v[76:79], v[116:119], v[8:11]
	global_load_lds_dwordx4 v251, s[48:49]
	s_add_u32 s40, s40, 0x80
	s_addc_u32 s41, s41, 0
	s_add_u32 s48, s48, 0x80
	s_addc_u32 s49, s49, 0
	s_waitcnt vmcnt(8)
	s_barrier
	ds_read_b128 v[64:67], v252 offset:16384
	ds_read_b128 v[104:107], v254 offset:49152
	ds_read_b128 v[108:111], v254 offset:51200
	ds_read_b128 v[112:115], v254 offset:53248
	ds_read_b128 v[116:119], v254 offset:55296
	ds_read_b128 v[68:71], v252 offset:18432
	ds_read_b128 v[72:75], v252 offset:20480
	ds_read_b128 v[76:79], v252 offset:22528
	v_mfma_f32_16x16x32_bf16 v[60:63], v[80:83], v[120:123], v[60:63]
	v_mfma_f32_16x16x32_bf16 v[44:47], v[80:83], v[124:127], v[44:47]
	v_mfma_f32_16x16x32_bf16 v[28:31], v[80:83], v[132:135], v[28:31]
	v_mfma_f32_16x16x32_bf16 v[12:15], v[80:83], v[136:139], v[12:15]
	v_mfma_f32_16x16x32_bf16 v[56:59], v[84:87], v[120:123], v[56:59]
	v_mfma_f32_16x16x32_bf16 v[40:43], v[84:87], v[124:127], v[40:43]
	v_mfma_f32_16x16x32_bf16 v[20:23], v[84:87], v[132:135], v[20:23]
	v_mfma_f32_16x16x32_bf16 v[4:7], v[84:87], v[136:139], v[4:7]
	v_mfma_f32_16x16x32_bf16 v[52:55], v[88:91], v[120:123], v[52:55]
	v_mfma_f32_16x16x32_bf16 v[32:35], v[88:91], v[124:127], v[32:35]
	v_mfma_f32_16x16x32_bf16 v[16:19], v[88:91], v[132:135], v[16:19]
	v_mfma_f32_16x16x32_bf16 v[0:3], v[88:91], v[136:139], v[0:3]
	v_mfma_f32_16x16x32_bf16 v[48:51], v[92:95], v[120:123], v[48:51]
	v_mfma_f32_16x16x32_bf16 v[36:39], v[92:95], v[124:127], v[36:39]
	v_mfma_f32_16x16x32_bf16 v[24:27], v[92:95], v[132:135], v[24:27]
	v_mfma_f32_16x16x32_bf16 v[8:11], v[92:95], v[136:139], v[8:11]
	ds_read_b128 v[80:83], v253 offset:16384
	ds_read_b128 v[120:123], v255 offset:49152
	ds_read_b128 v[124:127], v255 offset:51200
	ds_read_b128 v[132:135], v255 offset:53248
	ds_read_b128 v[136:139], v255 offset:55296
	ds_read_b128 v[84:87], v253 offset:18432
	ds_read_b128 v[88:91], v253 offset:20480
	ds_read_b128 v[92:95], v253 offset:22528
	s_waitcnt lgkmcnt(14)
	v_mfma_f32_16x16x32_bf16 v[60:63], v[64:67], v[104:107], v[60:63]
	s_waitcnt lgkmcnt(13)
	v_mfma_f32_16x16x32_bf16 v[44:47], v[64:67], v[108:111], v[44:47]
	s_waitcnt lgkmcnt(12)
	v_mfma_f32_16x16x32_bf16 v[28:31], v[64:67], v[112:115], v[28:31]
	s_waitcnt lgkmcnt(11)
	v_mfma_f32_16x16x32_bf16 v[12:15], v[64:67], v[116:119], v[12:15]
	s_waitcnt lgkmcnt(10)
	v_mfma_f32_16x16x32_bf16 v[56:59], v[68:71], v[104:107], v[56:59]
	v_mfma_f32_16x16x32_bf16 v[40:43], v[68:71], v[108:111], v[40:43]
	v_mfma_f32_16x16x32_bf16 v[20:23], v[68:71], v[112:115], v[20:23]
	v_mfma_f32_16x16x32_bf16 v[4:7], v[68:71], v[116:119], v[4:7]
	s_waitcnt lgkmcnt(0)
	s_barrier
	s_add_u32 m0, s6, 0x4000
	v_mfma_f32_16x16x32_bf16 v[52:55], v[72:75], v[104:107], v[52:55]
	global_load_lds_dwordx4 v248, s[40:41]
	s_add_u32 m0, s6, 0x4400
	v_mfma_f32_16x16x32_bf16 v[32:35], v[72:75], v[108:111], v[32:35]
	global_load_lds_dwordx4 v249, s[40:41]
	s_add_u32 m0, s6, 0x4800
	v_mfma_f32_16x16x32_bf16 v[16:19], v[72:75], v[112:115], v[16:19]
	global_load_lds_dwordx4 v250, s[40:41]
	s_add_u32 m0, s6, 0x4c00
	v_mfma_f32_16x16x32_bf16 v[0:3], v[72:75], v[116:119], v[0:3]
	global_load_lds_dwordx4 v251, s[40:41]
	s_add_u32 m0, s6, 0xc000
	v_mfma_f32_16x16x32_bf16 v[48:51], v[76:79], v[104:107], v[48:51]
	global_load_lds_dwordx4 v248, s[48:49]
	s_add_u32 m0, s6, 0xc400
	v_mfma_f32_16x16x32_bf16 v[36:39], v[76:79], v[108:111], v[36:39]
	global_load_lds_dwordx4 v249, s[48:49]
	s_add_u32 m0, s6, 0xc800
	v_mfma_f32_16x16x32_bf16 v[24:27], v[76:79], v[112:115], v[24:27]
	global_load_lds_dwordx4 v250, s[48:49]
	s_add_u32 m0, s6, 0xcc00
	v_mfma_f32_16x16x32_bf16 v[8:11], v[76:79], v[116:119], v[8:11]
	global_load_lds_dwordx4 v251, s[48:49]
	s_add_u32 s40, s40, 0x80
	s_addc_u32 s41, s41, 0
	s_add_u32 s48, s48, 0x80
	s_addc_u32 s49, s49, 0
	s_sub_u32 s32, s32, 1
	s_cmp_lg_u32 s32, 0
	s_cbranch_scc1 .Lg9_loop
	s_waitcnt vmcnt(8)
	s_barrier
	ds_read_b128 v[64:67], v252 offset:0
	ds_read_b128 v[104:107], v254 offset:32768
	ds_read_b128 v[108:111], v254 offset:34816
	ds_read_b128 v[112:115], v254 offset:36864
	ds_read_b128 v[116:119], v254 offset:38912
	ds_read_b128 v[68:71], v252 offset:2048
	ds_read_b128 v[72:75], v252 offset:4096
	ds_read_b128 v[76:79], v252 offset:6144
	v_mfma_f32_16x16x32_bf16 v[60:63], v[80:83], v[120:123], v[60:63]
	v_mfma_f32_16x16x32_bf16 v[44:47], v[80:83], v[124:127], v[44:47]
	v_mfma_f32_16x16x32_bf16 v[28:31], v[80:83], v[132:135], v[28:31]
	v_mfma_f32_16x16x32_bf16 v[12:15], v[80:83], v[136:139], v[12:15]
	v_mfma_f32_16x16x32_bf16 v[56:59], v[84:87], v[120:123], v[56:59]
	v_mfma_f32_16x16x32_bf16 v[40:43], v[84:87], v[124:127], v[40:43]
	v_mfma_f32_16x16x32_bf16 v[20:23], v[84:87], v[132:135], v[20:23]
	v_mfma_f32_16x16x32_bf16 v[4:7], v[84:87], v[136:139], v[4:7]
	v_mfma_f32_16x16x32_bf16 v[52:55], v[88:91], v[120:123], v[52:55]
	v_mfma_f32_16x16x32_bf16 v[32:35], v[88:91], v[124:127], v[32:35]
	v_mfma_f32_16x16x32_bf16 v[16:19], v[88:91], v[132:135], v[16:19]
	v_mfma_f32_16x16x32_bf16 v[0:3], v[88:91], v[136:139], v[0:3]
	v_mfma_f32_16x16x32_bf16 v[48:51], v[92:95], v[120:123], v[48:51]
	v_mfma_f32_16x16x32_bf16 v[36:39], v[92:95], v[124:127], v[36:39]
	v_mfma_f32_16x16x32_bf16 v[24:27], v[92:95], v[132:135], v[24:27]
	v_mfma_f32_16x16x32_bf16 v[8:11], v[92:95], v[136:139], v[8:11]
	ds_read_b128 v[80:83], v253 offset:0
	ds_read_b128 v[120:123], v255 offset:32768
	ds_read_b128 v[124:127], v255 offset:34816
	ds_read_b128 v[132:135], v255 offset:36864
	ds_read_b128 v[136:139], v255 offset:38912
	ds_read_b128 v[84:87], v253 offset:2048
	ds_read_b128 v[88:91], v253 offset:4096
	ds_read_b128 v[92:95], v253 offset:6144
	s_waitcnt lgkmcnt(14)
	v_mfma_f32_16x16x32_bf16 v[60:63], v[64:67], v[104:107], v[60:63]
	s_waitcnt lgkmcnt(13)
	v_mfma_f32_16x16x32_bf16 v[44:47], v[64:67], v[108:111], v[44:47]
	s_waitcnt lgkmcnt(12)
	v_mfma_f32_16x16x32_bf16 v[28:31], v[64:67], v[112:115], v[28:31]
	s_waitcnt lgkmcnt(11)
	v_mfma_f32_16x16x32_bf16 v[12:15], v[64:67], v[116:119], v[12:15]
	s_waitcnt lgkmcnt(10)
	v_mfma_f32_16x16x32_bf16 v[56:59], v[68:71], v[104:107], v[56:59]
	v_mfma_f32_16x16x32_bf16 v[40:43], v[68:71], v[108:111], v[40:43]
	v_mfma_f32_16x16x32_bf16 v[20:23], v[68:71], v[112:115], v[20:23]
	v_mfma_f32_16x16x32_bf16 v[4:7], v[68:71], v[116:119], v[4:7]
	s_waitcnt lgkmcnt(0)
	s_barrier
	v_mfma_f32_16x16x32_bf16 v[52:55], v[72:75], v[104:107], v[52:55]
	v_mfma_f32_16x16x32_bf16 v[32:35], v[72:75], v[108:111], v[32:35]
	v_mfma_f32_16x16x32_bf16 v[16:19], v[72:75], v[112:115], v[16:19]
	v_mfma_f32_16x16x32_bf16 v[0:3], v[72:75], v[116:119], v[0:3]
	v_mfma_f32_16x16x32_bf16 v[48:51], v[76:79], v[104:107], v[48:51]
	v_mfma_f32_16x16x32_bf16 v[36:39], v[76:79], v[108:111], v[36:39]
	v_mfma_f32_16x16x32_bf16 v[24:27], v[76:79], v[112:115], v[24:27]
	v_mfma_f32_16x16x32_bf16 v[8:11], v[76:79], v[116:119], v[8:11]
	s_waitcnt vmcnt(0)
	s_barrier
	ds_read_b128 v[64:67], v252 offset:16384
	ds_read_b128 v[104:107], v254 offset:49152
	ds_read_b128 v[108:111], v254 offset:51200
	ds_read_b128 v[112:115], v254 offset:53248
	ds_read_b128 v[116:119], v254 offset:55296
	ds_read_b128 v[68:71], v252 offset:18432
	ds_read_b128 v[72:75], v252 offset:20480
	ds_read_b128 v[76:79], v252 offset:22528
	v_mfma_f32_16x16x32_bf16 v[60:63], v[80:83], v[120:123], v[60:63]
	v_mfma_f32_16x16x32_bf16 v[44:47], v[80:83], v[124:127], v[44:47]
	v_mfma_f32_16x16x32_bf16 v[28:31], v[80:83], v[132:135], v[28:31]
	v_mfma_f32_16x16x32_bf16 v[12:15], v[80:83], v[136:139], v[12:15]
	v_mfma_f32_16x16x32_bf16 v[56:59], v[84:87], v[120:123], v[56:59]
	v_mfma_f32_16x16x32_bf16 v[40:43], v[84:87], v[124:127], v[40:43]
	v_mfma_f32_16x16x32_bf16 v[20:23], v[84:87], v[132:135], v[20:23]
	v_mfma_f32_16x16x32_bf16 v[4:7], v[84:87], v[136:139], v[4:7]
	v_mfma_f32_16x16x32_bf16 v[52:55], v[88:91], v[120:123], v[52:55]
	v_mfma_f32_16x16x32_bf16 v[32:35], v[88:91], v[124:127], v[32:35]
	v_mfma_f32_16x16x32_bf16 v[16:19], v[88:91], v[132:135], v[16:19]
	v_mfma_f32_16x16x32_bf16 v[0:3], v[88:91], v[136:139], v[0:3]
	v_mfma_f32_16x16x32_bf16 v[48:51], v[92:95], v[120:123], v[48:51]
	v_mfma_f32_16x16x32_bf16 v[36:39], v[92:95], v[124:127], v[36:39]
	v_mfma_f32_16x16x32_bf16 v[24:27], v[92:95], v[132:135], v[24:27]
	v_mfma_f32_16x16x32_bf16 v[8:11], v[92:95], v[136:139], v[8:11]
	ds_read_b128 v[80:83], v253 offset:16384
	ds_read_b128 v[120:123], v255 offset:49152
	ds_read_b128 v[124:127], v255 offset:51200
	ds_read_b128 v[132:135], v255 offset:53248
	ds_read_b128 v[136:139], v255 offset:55296
	ds_read_b128 v[84:87], v253 offset:18432
	ds_read_b128 v[88:91], v253 offset:20480
	ds_read_b128 v[92:95], v253 offset:22528
	s_waitcnt lgkmcnt(14)
	v_mfma_f32_16x16x32_bf16 v[60:63], v[64:67], v[104:107], v[60:63]
	s_waitcnt lgkmcnt(13)
	v_mfma_f32_16x16x32_bf16 v[44:47], v[64:67], v[108:111], v[44:47]
	s_waitcnt lgkmcnt(12)
	v_mfma_f32_16x16x32_bf16 v[28:31], v[64:67], v[112:115], v[28:31]
	s_waitcnt lgkmcnt(11)
	v_mfma_f32_16x16x32_bf16 v[12:15], v[64:67], v[116:119], v[12:15]
	s_waitcnt lgkmcnt(10)
	v_mfma_f32_16x16x32_bf16 v[56:59], v[68:71], v[104:107], v[56:59]
	v_mfma_f32_16x16x32_bf16 v[40:43], v[68:71], v[108:111], v[40:43]
	v_mfma_f32_16x16x32_bf16 v[20:23], v[68:71], v[112:115], v[20:23]
	v_mfma_f32_16x16x32_bf16 v[4:7], v[68:71], v[116:119], v[4:7]
	s_waitcnt lgkmcnt(0)
	s_barrier
	v_mfma_f32_16x16x32_bf16 v[52:55], v[72:75], v[104:107], v[52:55]
	v_mfma_f32_16x16x32_bf16 v[32:35], v[72:75], v[108:111], v[32:35]
	v_mfma_f32_16x16x32_bf16 v[16:19], v[72:75], v[112:115], v[16:19]
	v_mfma_f32_16x16x32_bf16 v[0:3], v[72:75], v[116:119], v[0:3]
	v_mfma_f32_16x16x32_bf16 v[48:51], v[76:79], v[104:107], v[48:51]
	v_mfma_f32_16x16x32_bf16 v[36:39], v[76:79], v[108:111], v[36:39]
	v_mfma_f32_16x16x32_bf16 v[24:27], v[76:79], v[112:115], v[24:27]
	v_mfma_f32_16x16x32_bf16 v[8:11], v[76:79], v[116:119], v[8:11]
	v_mfma_f32_16x16x32_bf16 v[60:63], v[80:83], v[120:123], v[60:63]
	v_mfma_f32_16x16x32_bf16 v[44:47], v[80:83], v[124:127], v[44:47]
	v_mfma_f32_16x16x32_bf16 v[28:31], v[80:83], v[132:135], v[28:31]
	v_mfma_f32_16x16x32_bf16 v[12:15], v[80:83], v[136:139], v[12:15]
	v_mfma_f32_16x16x32_bf16 v[56:59], v[84:87], v[120:123], v[56:59]
	v_mfma_f32_16x16x32_bf16 v[40:43], v[84:87], v[124:127], v[40:43]
	v_mfma_f32_16x16x32_bf16 v[20:23], v[84:87], v[132:135], v[20:23]
	v_mfma_f32_16x16x32_bf16 v[4:7], v[84:87], v[136:139], v[4:7]
	v_mfma_f32_16x16x32_bf16 v[52:55], v[88:91], v[120:123], v[52:55]
	v_mfma_f32_16x16x32_bf16 v[32:35], v[88:91], v[124:127], v[32:35]
	v_mfma_f32_16x16x32_bf16 v[16:19], v[88:91], v[132:135], v[16:19]
	v_mfma_f32_16x16x32_bf16 v[0:3], v[88:91], v[136:139], v[0:3]
	v_mfma_f32_16x16x32_bf16 v[48:51], v[92:95], v[120:123], v[48:51]
	v_mfma_f32_16x16x32_bf16 v[36:39], v[92:95], v[124:127], v[36:39]
	v_mfma_f32_16x16x32_bf16 v[24:27], v[92:95], v[132:135], v[24:27]
	v_mfma_f32_16x16x32_bf16 v[8:11], v[92:95], v[136:139], v[8:11]
	s_nop 7
	s_nop 1
	v_sub_co_u32_e32 v64, vcc, s37, v151
	s_nop 0
	v_readfirstlane_b32 s6, v64
	s_lshr_b32 s6, s6, 10
	s_add_i32 s6, s6, 1
	s_and_b64 s[40:41], vcc, exec
	s_cselect_b32 s6, 0, s6
	s_mul_hi_u32 s39, s6, 0x6000
	s_mulk_i32 s6, 0x6000
	v_or_b32_e32 v64, s38, v148
	s_add_u32 s40, s2, s6
	v_ashrrev_i32_e32 v65, 31, v64
	s_addc_u32 s41, s3, s39
	v_add_lshl_u32 v94, v149, s37, 12
	v_lshlrev_b64 v[66:67], 2, v[64:65]
	v_lshl_add_u64 v[102:103], s[40:41], 0, v[66:67]
	v_lshl_add_u64 v[136:137], s[4:5], 0, v[66:67]
	v_mov_b32_e32 v95, v97
	v_or_b32_e32 v66, 0x1000, v94
	v_mov_b32_e32 v67, v97
	v_lshl_add_u64 v[104:105], v[136:137], 0, v[94:95]
	global_load_dword v65, v[102:103], off
	global_load_dword v152, v[104:105], off
	v_lshl_add_u64 v[106:107], v[136:137], 0, v[66:67]
	v_or_b32_e32 v68, 0x2000, v94
	v_mov_b32_e32 v69, v97
	v_or_b32_e32 v70, 0x3000, v94
	v_mov_b32_e32 v71, v97
	v_or_b32_e32 v72, 0x10000, v94
	v_mov_b32_e32 v73, v97
	global_load_dword v153, v[106:107], off
	v_lshl_add_u64 v[108:109], v[136:137], 0, v[68:69]
	v_lshl_add_u64 v[110:111], v[136:137], 0, v[70:71]
	v_lshl_add_u64 v[112:113], v[136:137], 0, v[72:73]
	v_or_b32_e32 v74, 0x11000, v94
	v_mov_b32_e32 v75, v97
	global_load_dword v154, v[108:109], off
	global_load_dword v155, v[110:111], off
	global_load_dword v156, v[112:113], off
	v_lshl_add_u64 v[114:115], v[136:137], 0, v[74:75]
	v_or_b32_e32 v76, 0x12000, v94
	v_mov_b32_e32 v77, v97
	v_or_b32_e32 v78, 0x13000, v94
	v_mov_b32_e32 v79, v97
	v_or_b32_e32 v80, 0x20000, v94
	v_mov_b32_e32 v81, v97
	global_load_dword v157, v[114:115], off
	v_or_b32_e32 v96, 0x30000, v94
	v_lshl_add_u64 v[116:117], v[136:137], 0, v[76:77]
	v_lshl_add_u64 v[118:119], v[136:137], 0, v[78:79]
	v_lshl_add_u64 v[120:121], v[136:137], 0, v[80:81]
	v_or_b32_e32 v82, 0x21000, v94
	v_mov_b32_e32 v83, v97
	global_load_dword v158, v[116:117], off
	global_load_dword v159, v[118:119], off
	global_load_dword v160, v[120:121], off
	v_lshl_add_u64 v[122:123], v[136:137], 0, v[82:83]
	v_or_b32_e32 v84, 0x22000, v94
	v_mov_b32_e32 v85, v97
	v_or_b32_e32 v86, 0x23000, v94
	v_mov_b32_e32 v87, v97
	v_lshl_add_u64 v[130:131], v[136:137], 0, v[96:97]
	v_lshl_add_u64 v[124:125], v[136:137], 0, v[84:85]
	v_lshl_add_u64 v[126:127], v[136:137], 0, v[86:87]
	global_load_dword v161, v[122:123], off
	global_load_dword v170, v[124:125], off
	global_load_dword v171, v[126:127], off
	global_load_dword v172, v[130:131], off
	v_or_b32_e32 v88, 0x31000, v94
	v_mov_b32_e32 v89, v97
	v_lshl_add_u64 v[132:133], v[136:137], 0, v[88:89]
	v_or_b32_e32 v90, 0x32000, v94
	v_mov_b32_e32 v91, v97
	v_or_b32_e32 v92, 0x33000, v94
	v_mov_b32_e32 v93, v97
	v_lshl_add_u64 v[134:135], v[136:137], 0, v[90:91]
	v_lshl_add_u64 v[136:137], v[136:137], 0, v[92:93]
	global_load_dword v173, v[132:133], off
	global_load_dword v174, v[134:135], off
	global_load_dword v175, v[136:137], off
	v_or_b32_e32 v138, 16, v64
	v_ashrrev_i32_e32 v139, 31, v138
	v_lshlrev_b64 v[138:139], 2, v[138:139]
	v_lshl_add_u64 v[94:95], s[4:5], 0, v[94:95]
	global_load_dword v176, v[102:103], off offset:64
	v_lshl_add_u64 v[142:143], s[4:5], 0, v[138:139]
	v_lshl_add_u64 v[138:139], v[94:95], 0, v[138:139]
	v_add_f32_e32 v60, 0, v60
	v_lshl_add_u64 v[140:141], v[142:143], 0, v[66:67]
	global_load_dword v177, v[138:139], off
	global_load_dword v178, v[140:141], off
	global_load_dword v179, v[102:103], off offset:128
	global_load_dword v180, v[102:103], off offset:192
	v_lshl_add_u64 v[102:103], v[142:143], 0, v[68:69]
	global_load_dword v181, v[102:103], off
	v_add_f32_e32 v56, 0, v56
	v_add_f32_e32 v58, 0, v58
	v_add_f32_e32 v52, 0, v52
	v_add_f32_e32 v48, 0, v48
	v_add_f32_e32 v44, 0, v44
	v_add_f32_e32 v50, 0, v50
	v_add_f32_e32 v32, 0, v32
	v_add_f32_e32 v34, 0, v34
	v_add_f32_e32 v40, 0, v40
	v_add_f32_e32 v38, 0, v38
	v_add_f32_e32 v36, 0, v36
	v_add_f32_e32 v28, 0, v28
	v_add_f32_e32 v30, 0, v30
	v_add_f32_e32 v20, 0, v20
	s_waitcnt vmcnt(21)
	v_fmac_f32_e32 v152, v60, v65
	v_add_f32_e32 v60, 0, v61
	global_store_dword v[104:105], v152, off
	v_lshl_add_u64 v[104:105], v[142:143], 0, v[72:73]
	v_add_f32_e32 v16, 0, v16
	v_add_f32_e32 v0, 0, v0
	v_add_f32_e32 v12, 0, v12
	v_add_f32_e32 v4, 0, v4
	s_waitcnt vmcnt(21)
	v_fmac_f32_e32 v153, v60, v65
	v_add_f32_e32 v60, 0, v62
	v_add_f32_e32 v62, 0, v63
	global_store_dword v[106:107], v153, off
	v_lshl_add_u64 v[106:107], v[142:143], 0, v[76:77]
	global_load_dword v153, v[104:105], off
	s_waitcnt vmcnt(22)
	v_fmac_f32_e32 v154, v60, v65
	global_store_dword v[108:109], v154, off
	s_waitcnt vmcnt(21)
	v_fmac_f32_e32 v156, v56, v65
	v_add_f32_e32 v56, 0, v57
	v_lshl_add_u64 v[108:109], v[142:143], 0, v[80:81]
	v_lshl_add_u64 v[60:61], v[142:143], 0, v[70:71]
	global_store_dword v[112:113], v156, off
	v_add_f32_e32 v112, 0, v59
	v_fmac_f32_e32 v155, v62, v65
	global_store_dword v[110:111], v155, off
	s_waitcnt vmcnt(22)
	v_fmac_f32_e32 v157, v56, v65
	global_store_dword v[114:115], v157, off
	global_load_dword v157, v[108:109], off
	v_lshl_add_u64 v[62:63], v[142:143], 0, v[74:75]
	global_load_dword v152, v[60:61], off
	global_load_dword v155, v[106:107], off
	v_lshl_add_u64 v[110:111], v[142:143], 0, v[82:83]
	s_waitcnt vmcnt(25)
	v_fmac_f32_e32 v158, v58, v65
	v_lshl_add_u64 v[58:59], v[142:143], 0, v[84:85]
	s_waitcnt vmcnt(23)
	v_fmac_f32_e32 v160, v52, v65
	v_add_f32_e32 v52, 0, v53
	global_store_dword v[116:117], v158, off
	global_load_dword v158, v[58:59], off
	v_fmac_f32_e32 v159, v112, v65
	v_lshl_add_u64 v[112:113], v[142:143], 0, v[86:87]
	global_load_dword v183, v[112:113], off
	s_waitcnt vmcnt(25)
	v_fmac_f32_e32 v161, v52, v65
	v_add_f32_e32 v52, 0, v54
	s_waitcnt vmcnt(24)
	v_fmac_f32_e32 v170, v52, v65
	s_waitcnt vmcnt(22)
	v_fmac_f32_e32 v172, v48, v65
	v_add_f32_e32 v48, 0, v49
	v_lshl_add_u64 v[52:53], v[142:143], 0, v[90:91]
	v_lshl_add_u64 v[114:115], v[142:143], 0, v[96:97]
	global_store_dword v[120:121], v160, off
	global_load_dword v120, v[52:53], off
	v_lshl_add_u64 v[56:57], v[142:143], 0, v[78:79]
	global_load_dword v182, v[110:111], off
	global_load_dword v156, v[56:57], off
	s_waitcnt vmcnt(25)
	v_fmac_f32_e32 v173, v48, v65
	v_lshl_add_u64 v[48:49], v[142:143], 0, v[92:93]
	global_load_dword v121, v[48:49], off
	s_waitcnt vmcnt(25)
	v_fmac_f32_e32 v174, v50, v65
	global_store_dword v[118:119], v159, off
	global_load_dword v118, v[114:115], off
	v_add_f32_e32 v50, 0, v51
	global_load_dword v154, v[62:63], off
	s_waitcnt vmcnt(25)
	v_fmac_f32_e32 v177, v44, v176
	v_add_f32_e32 v44, 0, v45
	s_waitcnt vmcnt(24)
	v_fmac_f32_e32 v178, v44, v176
	v_add_f32_e32 v44, 0, v46
	v_add_f32_e32 v54, 0, v55
	s_waitcnt vmcnt(21)
	v_fmac_f32_e32 v181, v44, v176
	v_or_b32_e32 v44, 32, v64
	v_ashrrev_i32_e32 v45, 31, v44
	v_lshlrev_b64 v[44:45], 2, v[44:45]
	v_fmac_f32_e32 v175, v50, v65
	v_lshl_add_u64 v[50:51], v[94:95], 0, v[44:45]
	v_lshl_add_u64 v[44:45], s[4:5], 0, v[44:45]
	v_fmac_f32_e32 v171, v54, v65
	v_lshl_add_u64 v[54:55], v[44:45], 0, v[78:79]
	v_add_f32_e32 v46, 0, v47
	v_lshl_add_u64 v[116:117], v[142:143], 0, v[88:89]
	global_load_dword v119, v[116:117], off
	v_or_b32_e32 v64, 48, v64
	global_store_dword v[102:103], v181, off
	v_ashrrev_i32_e32 v65, 31, v64
	v_lshlrev_b64 v[64:65], 2, v[64:65]
	global_store_dword v[122:123], v161, off
	global_store_dword v[124:125], v170, off
	global_store_dword v[126:127], v171, off
	global_store_dword v[130:131], v172, off
	global_store_dword v[132:133], v173, off
	global_store_dword v[134:135], v174, off
	global_store_dword v[136:137], v175, off
	global_store_dword v[138:139], v177, off
	global_store_dword v[140:141], v178, off
	v_lshl_add_u64 v[94:95], v[94:95], 0, v[64:65]
	v_lshl_add_u64 v[64:65], s[4:5], 0, v[64:65]
	v_add_f32_e32 v21, 0, v21
	s_waitcnt vmcnt(29)
	v_fmac_f32_e32 v153, v40, v176
	v_add_f32_e32 v40, 0, v41
	global_store_dword v[104:105], v153, off
	s_add_i32 s36, s36, s30
	s_cmpk_gt_i32 s36, 0x1ff
	s_waitcnt vmcnt(25)
	v_fmac_f32_e32 v157, v32, v176
	global_store_dword v[108:109], v157, off
	global_load_dword v109, v[54:55], off
	s_waitcnt vmcnt(26)
	v_fmac_f32_e32 v152, v46, v176
	v_lshl_add_u64 v[46:47], v[44:45], 0, v[66:67]
	global_load_dword v102, v[50:51], off
	global_load_dword v103, v[46:47], off
	v_add_f32_e32 v32, 0, v33
	global_store_dword v[60:61], v152, off
	v_lshl_add_u64 v[60:61], v[44:45], 0, v[88:89]
	s_waitcnt vmcnt(26)
	v_fmac_f32_e32 v158, v34, v176
	global_store_dword v[58:59], v158, off
	v_add_f32_e32 v34, 0, v35
	v_add_f32_e32 v58, 0, v39
	s_waitcnt vmcnt(26)
	v_fmac_f32_e32 v183, v34, v176
	global_store_dword v[112:113], v183, off
	v_lshl_add_u64 v[34:35], v[44:45], 0, v[72:73]
	v_lshl_add_u64 v[66:67], v[64:65], 0, v[66:67]
	s_waitcnt vmcnt(25)
	v_fmac_f32_e32 v120, v38, v176
	global_store_dword v[52:53], v120, off
	s_waitcnt vmcnt(25)
	v_fmac_f32_e32 v182, v32, v176
	v_lshl_add_u64 v[52:53], v[44:45], 0, v[82:83]
	global_store_dword v[110:111], v182, off
	v_lshl_add_u64 v[32:33], v[44:45], 0, v[70:71]
	s_waitcnt vmcnt(24)
	v_fmac_f32_e32 v121, v58, v176
	v_lshl_add_u64 v[58:59], v[44:45], 0, v[86:87]
	global_load_dword v113, v[58:59], off
	global_load_dword v111, v[52:53], off
	s_waitcnt vmcnt(24)
	v_fmac_f32_e32 v118, v36, v176
	s_waitcnt vmcnt(23)
	v_fmac_f32_e32 v154, v40, v176
	v_add_f32_e32 v40, 0, v42
	v_add_f32_e32 v42, 0, v43
	v_fmac_f32_e32 v156, v42, v176
	global_store_dword v[56:57], v156, off
	v_lshl_add_u64 v[56:57], v[44:45], 0, v[80:81]
	global_store_dword v[114:115], v118, off
	global_load_dword v110, v[56:57], off
	global_load_dword v105, v[32:33], off
	v_add_f32_e32 v36, 0, v37
	global_load_dword v115, v[60:61], off
	v_fmac_f32_e32 v155, v40, v176
	v_lshl_add_u64 v[40:41], v[44:45], 0, v[68:69]
	global_load_dword v104, v[40:41], off
	v_lshl_add_u64 v[42:43], v[44:45], 0, v[76:77]
	global_store_dword v[106:107], v155, off
	global_load_dword v106, v[34:35], off
	s_waitcnt vmcnt(30)
	v_fmac_f32_e32 v119, v36, v176
	global_store_dword v[48:49], v121, off
	v_lshl_add_u64 v[48:49], v[44:45], 0, v[96:97]
	global_store_dword v[62:63], v154, off
	v_lshl_add_u64 v[36:37], v[44:45], 0, v[74:75]
	global_store_dword v[116:117], v119, off
	v_lshl_add_u64 v[38:39], v[44:45], 0, v[84:85]
	global_load_dword v114, v[48:49], off
	v_lshl_add_u64 v[62:63], v[44:45], 0, v[90:91]
	global_load_dword v107, v[36:37], off
	global_load_dword v108, v[42:43], off
	global_load_dword v112, v[38:39], off
	v_lshl_add_u64 v[44:45], v[44:45], 0, v[92:93]
	global_load_dword v116, v[62:63], off
	global_load_dword v117, v[44:45], off
	v_lshl_add_u64 v[68:69], v[64:65], 0, v[68:69]
	global_load_dword v120, v[68:69], off
	global_load_dword v118, v[94:95], off
	global_load_dword v119, v[66:67], off
	s_waitcnt vmcnt(28)
	v_fmac_f32_e32 v102, v28, v179
	global_store_dword v[50:51], v102, off
	v_lshl_add_u64 v[50:51], v[64:65], 0, v[70:71]
	v_add_f32_e32 v70, 0, v29
	v_lshl_add_u64 v[28:29], v[64:65], 0, v[72:73]
	s_waitcnt vmcnt(28)
	v_fmac_f32_e32 v103, v70, v179
	v_lshl_add_u64 v[70:71], v[64:65], 0, v[74:75]
	v_lshl_add_u64 v[72:73], v[64:65], 0, v[78:79]
	v_lshl_add_u64 v[74:75], v[64:65], 0, v[80:81]
	global_load_dword v122, v[70:71], off
	global_load_dword v123, v[72:73], off
	global_load_dword v124, v[74:75], off
	global_load_dword v102, v[50:51], off
	global_load_dword v121, v[28:29], off
	v_lshl_add_u64 v[78:79], v[64:65], 0, v[88:89]
	global_store_dword v[46:47], v103, off
	v_lshl_add_u64 v[46:47], v[64:65], 0, v[76:77]
	global_load_dword v103, v[46:47], off
	v_add_f32_e32 v76, 0, v31
	v_lshl_add_u64 v[80:81], v[64:65], 0, v[90:91]
	s_waitcnt vmcnt(25)
	v_fmac_f32_e32 v110, v16, v179
	s_waitcnt vmcnt(24)
	v_fmac_f32_e32 v105, v76, v179
	v_lshl_add_u64 v[76:77], v[64:65], 0, v[86:87]
	global_store_dword v[32:33], v105, off
	v_lshl_add_u64 v[32:33], v[64:65], 0, v[96:97]
	global_load_dword v86, v[78:79], off
	s_waitcnt vmcnt(24)
	v_fmac_f32_e32 v104, v30, v179
	global_store_dword v[40:41], v104, off
	v_lshl_add_u64 v[40:41], v[64:65], 0, v[82:83]
	global_load_dword v82, v[40:41], off
	v_lshl_add_u64 v[30:31], v[64:65], 0, v[84:85]
	global_load_dword v83, v[30:31], off
	global_load_dword v85, v[32:33], off
	global_load_dword v84, v[76:77], off
	s_waitcnt vmcnt(27)
	v_fmac_f32_e32 v106, v20, v179
	global_load_dword v20, v[80:81], off
	v_add_f32_e32 v16, 0, v17
	global_store_dword v[34:35], v106, off
	v_lshl_add_u64 v[34:35], v[64:65], 0, v[92:93]
	global_load_dword v64, v[34:35], off
	v_fmac_f32_e32 v111, v16, v179
	v_add_f32_e32 v16, 0, v18
	s_waitcnt vmcnt(23)
	v_fmac_f32_e32 v112, v16, v179
	v_add_f32_e32 v16, 0, v19
	v_fmac_f32_e32 v113, v16, v179
	v_add_f32_e32 v16, 0, v24
	v_fmac_f32_e32 v114, v16, v179
	v_add_f32_e32 v16, 0, v25
	s_waitcnt vmcnt(19)
	v_fmac_f32_e32 v118, v12, v180
	v_add_f32_e32 v12, 0, v13
	v_fmac_f32_e32 v107, v21, v179
	v_add_f32_e32 v21, 0, v22
	v_fmac_f32_e32 v115, v16, v179
	v_add_f32_e32 v16, 0, v26
	s_waitcnt vmcnt(18)
	v_fmac_f32_e32 v119, v12, v180
	v_add_f32_e32 v12, 0, v14
	v_fmac_f32_e32 v108, v21, v179
	v_add_f32_e32 v21, 0, v23
	v_fmac_f32_e32 v116, v16, v179
	v_add_f32_e32 v16, 0, v27
	v_fmac_f32_e32 v120, v12, v180
	v_add_f32_e32 v12, 0, v15
	v_fmac_f32_e32 v109, v21, v179
	v_fmac_f32_e32 v117, v16, v179
	global_store_dword v[36:37], v107, off
	global_store_dword v[42:43], v108, off
	global_store_dword v[54:55], v109, off
	global_store_dword v[56:57], v110, off
	global_store_dword v[52:53], v111, off
	global_store_dword v[38:39], v112, off
	global_store_dword v[58:59], v113, off
	global_store_dword v[48:49], v114, off
	global_store_dword v[60:61], v115, off
	global_store_dword v[62:63], v116, off
	global_store_dword v[44:45], v117, off
	global_store_dword v[94:95], v118, off
	s_waitcnt vmcnt(26)
	v_fmac_f32_e32 v124, v0, v180
	v_add_f32_e32 v0, 0, v1
	s_waitcnt vmcnt(24)
	v_fmac_f32_e32 v121, v4, v180
	v_add_f32_e32 v4, 0, v5
	v_fmac_f32_e32 v122, v4, v180
	v_add_f32_e32 v4, 0, v6
	s_waitcnt vmcnt(22)
	v_fmac_f32_e32 v103, v4, v180
	v_add_f32_e32 v4, 0, v7
	v_fmac_f32_e32 v102, v12, v180
	v_fmac_f32_e32 v123, v4, v180
	global_store_dword v[66:67], v119, off
	global_store_dword v[68:69], v120, off
	global_store_dword v[50:51], v102, off
	global_store_dword v[28:29], v121, off
	global_store_dword v[70:71], v122, off
	global_store_dword v[46:47], v103, off
	global_store_dword v[72:73], v123, off
	global_store_dword v[74:75], v124, off
	s_waitcnt vmcnt(26)
	v_fmac_f32_e32 v82, v0, v180
	v_add_f32_e32 v0, 0, v2
	s_waitcnt vmcnt(25)
	v_fmac_f32_e32 v83, v0, v180
	v_add_f32_e32 v0, 0, v3
	s_waitcnt vmcnt(23)
	v_fmac_f32_e32 v84, v0, v180
	v_add_f32_e32 v0, 0, v8
	v_fmac_f32_e32 v85, v0, v180
	v_add_f32_e32 v0, 0, v9
	v_fmac_f32_e32 v86, v0, v180
	v_add_f32_e32 v0, 0, v10
	s_waitcnt vmcnt(22)
	v_fmac_f32_e32 v20, v0, v180
	v_add_f32_e32 v0, 0, v11
	s_waitcnt vmcnt(20)
	v_fmac_f32_e32 v64, v0, v180
	global_store_dword v[40:41], v82, off
	global_store_dword v[30:31], v83, off
	global_store_dword v[76:77], v84, off
	global_store_dword v[32:33], v85, off
	global_store_dword v[78:79], v86, off
	global_store_dword v[80:81], v20, off
	global_store_dword v[34:35], v64, off
	s_cbranch_scc0 .LBB0_1018

.LBB0_1264:
	s_lshl_b32 s4, s42, 7
	s_and_b32 s43, s4, 0x1f80
	s_lshl_b32 s12, s43, 11
	v_lshl_add_u64 v[102:103], v[98:99], 0, s[12:13]
	v_add_co_u32_e32 v40, vcc, 0x10000, v102
	s_lshl_b32 s4, s42, 1
	s_nop 0
	v_addc_co_u32_e32 v41, vcc, 0, v103, vcc
	s_and_b32 s4, s4, 0xffffff80
	v_add_co_u32_e32 v42, vcc, 0x20000, v102
	s_ashr_i32 s5, s4, 31
	s_nop 0
	v_addc_co_u32_e32 v43, vcc, 0, v103, vcc
	s_lshl_b64 s[44:45], s[4:5], 11
	v_add_co_u32_e32 v46, vcc, 0x30000, v102
	v_lshl_add_u64 v[104:105], v[100:101], 0, s[44:45]
	s_nop 0
	v_addc_co_u32_e32 v47, vcc, 0, v103, vcc
	v_add_co_u32_e32 v48, vcc, s39, v104
	s_nop 0
	v_addc_co_u32_e32 v49, vcc, 0, v105, vcc
	v_add_co_u32_e32 v50, vcc, s40, v104
	v_addc_co_u32_e32 v51, vcc, 0, v105, vcc
	v_add_co_u32_e32 v52, vcc, s41, v104
	v_addc_co_u32_e32 v53, vcc, 0, v105, vcc
	s_mov_b32 s5, -2
	v_mov_b32_e32 v12, v97
	v_mov_b32_e32 v13, v97
	v_mov_b32_e32 v14, v97
	v_mov_b32_e32 v15, v97
	v_mov_b32_e32 v28, v97
	v_mov_b32_e32 v29, v97
	v_mov_b32_e32 v30, v97
	v_mov_b32_e32 v31, v97
	v_mov_b32_e32 v44, v97
	v_mov_b32_e32 v45, v97
	v_mov_b32_e32 v46, v97
	v_lshl_add_u64 v[106:107], v[102:103], 0, s[14:15]
	v_lshl_add_u64 v[108:109], v[102:103], 0, s[16:17]
	v_lshl_add_u64 v[110:111], v[102:103], 0, s[18:19]
	v_lshl_add_u64 v[118:119], v[102:103], 0, s[20:21]
	v_lshl_add_u64 v[120:121], v[102:103], 0, s[22:23]
	v_lshl_add_u64 v[122:123], v[102:103], 0, s[24:25]
	v_lshl_add_u64 v[124:125], v[102:103], 0, s[26:27]
	v_lshl_add_u64 v[112:113], v[104:105], 0, s[14:15]
	v_lshl_add_u64 v[114:115], v[104:105], 0, s[16:17]
	v_lshl_add_u64 v[116:117], v[104:105], 0, s[18:19]
	v_lshl_add_u64 v[130:131], v[104:105], 0, s[20:21]
	v_lshl_add_u64 v[132:133], v[104:105], 0, s[22:23]
	v_lshl_add_u64 v[134:135], v[104:105], 0, s[24:25]
	v_lshl_add_u64 v[126:127], v[104:105], 0, s[26:27]
	v_mov_b32_e32 v47, v97
	v_mov_b32_e32 v52, v97
	v_mov_b32_e32 v53, v97
	v_mov_b32_e32 v54, v97
	v_mov_b32_e32 v55, v97
	v_mov_b32_e32 v48, v97
	v_mov_b32_e32 v49, v97
	v_mov_b32_e32 v50, v97
	v_mov_b32_e32 v51, v97
	v_mov_b32_e32 v56, v97
	v_mov_b32_e32 v57, v97
	v_mov_b32_e32 v58, v97
	v_mov_b32_e32 v59, v97
	v_mov_b32_e32 v40, v97
	v_mov_b32_e32 v41, v97
	v_mov_b32_e32 v42, v97
	v_mov_b32_e32 v43, v97
	v_mov_b32_e32 v60, v97
	v_mov_b32_e32 v61, v97
	v_mov_b32_e32 v62, v97
	v_mov_b32_e32 v63, v97
	v_mov_b32_e32 v4, v97
	v_mov_b32_e32 v5, v97
	v_mov_b32_e32 v6, v97
	v_mov_b32_e32 v7, v97
	v_mov_b32_e32 v16, v97
	v_mov_b32_e32 v17, v97
	v_mov_b32_e32 v18, v97
	v_mov_b32_e32 v19, v97
	v_mov_b32_e32 v32, v97
	v_mov_b32_e32 v33, v97
	v_mov_b32_e32 v34, v97
	v_mov_b32_e32 v35, v97
	v_mov_b32_e32 v0, v97
	v_mov_b32_e32 v1, v97
	v_mov_b32_e32 v2, v97
	v_mov_b32_e32 v3, v97
	v_mov_b32_e32 v20, v97
	v_mov_b32_e32 v21, v97
	v_mov_b32_e32 v22, v97
	v_mov_b32_e32 v23, v97
	v_mov_b32_e32 v36, v97
	v_mov_b32_e32 v37, v97
	v_mov_b32_e32 v38, v97
	v_mov_b32_e32 v39, v97
	v_mov_b32_e32 v8, v97
	v_mov_b32_e32 v9, v97
	v_mov_b32_e32 v10, v97
	v_mov_b32_e32 v11, v97
	v_mov_b32_e32 v24, v97
	v_mov_b32_e32 v25, v97
	v_mov_b32_e32 v26, v97
	v_mov_b32_e32 v27, v97
	v_readfirstlane_b32 s44, v102
	v_readfirstlane_b32 s45, v103
	v_readfirstlane_b32 s48, v104
	v_readfirstlane_b32 s49, v105
	v_readfirstlane_b32 s5, v247
	s_nop 3
	s_mul_i32 s32, s5, 0x4000
	s_sub_u32 s44, s44, s32
	s_subb_u32 s45, s45, 0
	s_sub_u32 s48, s48, s32
	s_subb_u32 s49, s49, 0
	s_lshl_b32 s5, s5, 12
	s_add_u32 m0, s5, 0x0
	v_mov_b32_e32 v60, 0
	global_load_lds_dwordx4 v248, s[44:45]
	v_mov_b32_e32 v61, 0
	s_add_u32 m0, s5, 0x400
	v_mov_b32_e32 v62, 0
	global_load_lds_dwordx4 v249, s[44:45]
	v_mov_b32_e32 v63, 0
	s_add_u32 m0, s5, 0x800
	v_mov_b32_e32 v40, 0
	global_load_lds_dwordx4 v250, s[44:45]
	v_mov_b32_e32 v41, 0
	s_add_u32 m0, s5, 0xc00
	v_mov_b32_e32 v42, 0
	global_load_lds_dwordx4 v251, s[44:45]
	v_mov_b32_e32 v43, 0
	s_add_u32 m0, s5, 0x8000
	v_mov_b32_e32 v24, 0
	global_load_lds_dwordx4 v248, s[48:49]
	v_mov_b32_e32 v25, 0
	s_add_u32 m0, s5, 0x8400
	v_mov_b32_e32 v26, 0
	global_load_lds_dwordx4 v249, s[48:49]
	v_mov_b32_e32 v27, 0
	s_add_u32 m0, s5, 0x8800
	v_mov_b32_e32 v8, 0
	global_load_lds_dwordx4 v250, s[48:49]
	v_mov_b32_e32 v9, 0
	s_add_u32 m0, s5, 0x8c00
	v_mov_b32_e32 v10, 0
	global_load_lds_dwordx4 v251, s[48:49]
	v_mov_b32_e32 v11, 0
	s_add_u32 s44, s44, 0x80
	s_addc_u32 s45, s45, 0
	s_add_u32 s48, s48, 0x80
	s_addc_u32 s49, s49, 0
	s_add_u32 m0, s5, 0x4000
	v_mov_b32_e32 v56, 0
	global_load_lds_dwordx4 v248, s[44:45]
	v_mov_b32_e32 v57, 0
	s_add_u32 m0, s5, 0x4400
	v_mov_b32_e32 v58, 0
	global_load_lds_dwordx4 v249, s[44:45]
	v_mov_b32_e32 v59, 0
	s_add_u32 m0, s5, 0x4800
	v_mov_b32_e32 v36, 0
	global_load_lds_dwordx4 v250, s[44:45]
	v_mov_b32_e32 v37, 0
	s_add_u32 m0, s5, 0x4c00
	v_mov_b32_e32 v38, 0
	global_load_lds_dwordx4 v251, s[44:45]
	v_mov_b32_e32 v39, 0
	s_add_u32 m0, s5, 0xc000
	v_mov_b32_e32 v20, 0
	global_load_lds_dwordx4 v248, s[48:49]
	v_mov_b32_e32 v21, 0
	s_add_u32 m0, s5, 0xc400
	v_mov_b32_e32 v22, 0
	global_load_lds_dwordx4 v249, s[48:49]
	v_mov_b32_e32 v23, 0
	s_add_u32 m0, s5, 0xc800
	v_mov_b32_e32 v0, 0
	global_load_lds_dwordx4 v250, s[48:49]
	v_mov_b32_e32 v1, 0
	s_add_u32 m0, s5, 0xcc00
	v_mov_b32_e32 v2, 0
	global_load_lds_dwordx4 v251, s[48:49]
	v_mov_b32_e32 v3, 0
	s_add_u32 s44, s44, 0x80
	s_addc_u32 s45, s45, 0
	s_add_u32 s48, s48, 0x80
	s_addc_u32 s49, s49, 0
	v_mov_b32_e32 v48, 0
	v_mov_b32_e32 v49, 0
	v_mov_b32_e32 v50, 0
	v_mov_b32_e32 v51, 0
	v_mov_b32_e32 v32, 0
	v_mov_b32_e32 v33, 0
	v_mov_b32_e32 v34, 0
	v_mov_b32_e32 v35, 0
	v_mov_b32_e32 v16, 0
	v_mov_b32_e32 v17, 0
	v_mov_b32_e32 v18, 0
	v_mov_b32_e32 v19, 0
	v_mov_b32_e32 v4, 0
	v_mov_b32_e32 v5, 0
	v_mov_b32_e32 v6, 0
	v_mov_b32_e32 v7, 0
	v_mov_b32_e32 v52, 0
	v_mov_b32_e32 v53, 0
	v_mov_b32_e32 v54, 0
	v_mov_b32_e32 v55, 0
	v_mov_b32_e32 v44, 0
	v_mov_b32_e32 v45, 0
	v_mov_b32_e32 v46, 0
	v_mov_b32_e32 v47, 0
	v_mov_b32_e32 v28, 0
	v_mov_b32_e32 v29, 0
	v_mov_b32_e32 v30, 0
	v_mov_b32_e32 v31, 0
	v_mov_b32_e32 v12, 0
	v_mov_b32_e32 v13, 0
	v_mov_b32_e32 v14, 0
	v_mov_b32_e32 v15, 0
	s_waitcnt vmcnt(8)
	s_barrier
	ds_read_b128 v[64:67], v252 offset:0
	ds_read_b128 v[104:107], v254 offset:32768
	ds_read_b128 v[108:111], v254 offset:34816
	ds_read_b128 v[112:115], v254 offset:36864
	ds_read_b128 v[116:119], v254 offset:38912
	ds_read_b128 v[68:71], v252 offset:2048
	ds_read_b128 v[72:75], v252 offset:4096
	ds_read_b128 v[76:79], v252 offset:6144
	ds_read_b128 v[80:83], v253 offset:0
	ds_read_b128 v[120:123], v255 offset:32768
	ds_read_b128 v[124:127], v255 offset:34816
	ds_read_b128 v[132:135], v255 offset:36864
	ds_read_b128 v[136:139], v255 offset:38912
	s_waitcnt lgkmcnt(11)
	v_mfma_f32_16x16x32_bf16 v[60:63], v[64:67], v[104:107], v[60:63]
	s_waitcnt lgkmcnt(10)
	v_mfma_f32_16x16x32_bf16 v[40:43], v[64:67], v[108:111], v[40:43]
	s_waitcnt lgkmcnt(9)
	v_mfma_f32_16x16x32_bf16 v[24:27], v[64:67], v[112:115], v[24:27]
	s_waitcnt lgkmcnt(8)
	v_mfma_f32_16x16x32_bf16 v[8:11], v[64:67], v[116:119], v[8:11]
	ds_read_b128 v[84:87], v253 offset:2048
	ds_read_b128 v[88:91], v253 offset:4096
	ds_read_b128 v[92:95], v253 offset:6144
	s_waitcnt lgkmcnt(10)
	v_mfma_f32_16x16x32_bf16 v[56:59], v[68:71], v[104:107], v[56:59]
	v_mfma_f32_16x16x32_bf16 v[36:39], v[68:71], v[108:111], v[36:39]
	v_mfma_f32_16x16x32_bf16 v[20:23], v[68:71], v[112:115], v[20:23]
	v_mfma_f32_16x16x32_bf16 v[0:3], v[68:71], v[116:119], v[0:3]
	s_waitcnt lgkmcnt(0)
	s_barrier
	s_add_u32 m0, s5, 0x0
	v_mfma_f32_16x16x32_bf16 v[48:51], v[72:75], v[104:107], v[48:51]
	global_load_lds_dwordx4 v248, s[44:45]
	s_add_u32 m0, s5, 0x400
	v_mfma_f32_16x16x32_bf16 v[32:35], v[72:75], v[108:111], v[32:35]
	global_load_lds_dwordx4 v249, s[44:45]
	s_add_u32 m0, s5, 0x800
	v_mfma_f32_16x16x32_bf16 v[16:19], v[72:75], v[112:115], v[16:19]
	global_load_lds_dwordx4 v250, s[44:45]
	s_add_u32 m0, s5, 0xc00
	v_mfma_f32_16x16x32_bf16 v[4:7], v[72:75], v[116:119], v[4:7]
	global_load_lds_dwordx4 v251, s[44:45]
	s_add_u32 m0, s5, 0x8000
	v_mfma_f32_16x16x32_bf16 v[52:55], v[76:79], v[104:107], v[52:55]
	global_load_lds_dwordx4 v248, s[48:49]
	s_add_u32 m0, s5, 0x8400
	v_mfma_f32_16x16x32_bf16 v[44:47], v[76:79], v[108:111], v[44:47]
	global_load_lds_dwordx4 v249, s[48:49]
	s_add_u32 m0, s5, 0x8800
	v_mfma_f32_16x16x32_bf16 v[28:31], v[76:79], v[112:115], v[28:31]
	global_load_lds_dwordx4 v250, s[48:49]
	s_add_u32 m0, s5, 0x8c00
	v_mfma_f32_16x16x32_bf16 v[12:15], v[76:79], v[116:119], v[12:15]
	global_load_lds_dwordx4 v251, s[48:49]
	s_add_u32 s44, s44, 0x80
	s_addc_u32 s45, s45, 0
	s_add_u32 s48, s48, 0x80
	s_addc_u32 s49, s49, 0
	s_waitcnt vmcnt(8)
	s_barrier
	ds_read_b128 v[64:67], v252 offset:16384
	ds_read_b128 v[104:107], v254 offset:49152
	ds_read_b128 v[108:111], v254 offset:51200
	ds_read_b128 v[112:115], v254 offset:53248
	ds_read_b128 v[116:119], v254 offset:55296
	ds_read_b128 v[68:71], v252 offset:18432
	ds_read_b128 v[72:75], v252 offset:20480
	ds_read_b128 v[76:79], v252 offset:22528
	v_mfma_f32_16x16x32_bf16 v[60:63], v[80:83], v[120:123], v[60:63]
	v_mfma_f32_16x16x32_bf16 v[40:43], v[80:83], v[124:127], v[40:43]
	v_mfma_f32_16x16x32_bf16 v[24:27], v[80:83], v[132:135], v[24:27]
	v_mfma_f32_16x16x32_bf16 v[8:11], v[80:83], v[136:139], v[8:11]
	v_mfma_f32_16x16x32_bf16 v[56:59], v[84:87], v[120:123], v[56:59]
	v_mfma_f32_16x16x32_bf16 v[36:39], v[84:87], v[124:127], v[36:39]
	v_mfma_f32_16x16x32_bf16 v[20:23], v[84:87], v[132:135], v[20:23]
	v_mfma_f32_16x16x32_bf16 v[0:3], v[84:87], v[136:139], v[0:3]
	v_mfma_f32_16x16x32_bf16 v[48:51], v[88:91], v[120:123], v[48:51]
	v_mfma_f32_16x16x32_bf16 v[32:35], v[88:91], v[124:127], v[32:35]
	v_mfma_f32_16x16x32_bf16 v[16:19], v[88:91], v[132:135], v[16:19]
	v_mfma_f32_16x16x32_bf16 v[4:7], v[88:91], v[136:139], v[4:7]
	v_mfma_f32_16x16x32_bf16 v[52:55], v[92:95], v[120:123], v[52:55]
	v_mfma_f32_16x16x32_bf16 v[44:47], v[92:95], v[124:127], v[44:47]
	v_mfma_f32_16x16x32_bf16 v[28:31], v[92:95], v[132:135], v[28:31]
	v_mfma_f32_16x16x32_bf16 v[12:15], v[92:95], v[136:139], v[12:15]
	ds_read_b128 v[80:83], v253 offset:16384
	ds_read_b128 v[120:123], v255 offset:49152
	ds_read_b128 v[124:127], v255 offset:51200
	ds_read_b128 v[132:135], v255 offset:53248
	ds_read_b128 v[136:139], v255 offset:55296
	ds_read_b128 v[84:87], v253 offset:18432
	ds_read_b128 v[88:91], v253 offset:20480
	ds_read_b128 v[92:95], v253 offset:22528
	s_waitcnt lgkmcnt(14)
	v_mfma_f32_16x16x32_bf16 v[60:63], v[64:67], v[104:107], v[60:63]
	s_waitcnt lgkmcnt(13)
	v_mfma_f32_16x16x32_bf16 v[40:43], v[64:67], v[108:111], v[40:43]
	s_waitcnt lgkmcnt(12)
	v_mfma_f32_16x16x32_bf16 v[24:27], v[64:67], v[112:115], v[24:27]
	s_waitcnt lgkmcnt(11)
	v_mfma_f32_16x16x32_bf16 v[8:11], v[64:67], v[116:119], v[8:11]
	s_waitcnt lgkmcnt(10)
	v_mfma_f32_16x16x32_bf16 v[56:59], v[68:71], v[104:107], v[56:59]
	v_mfma_f32_16x16x32_bf16 v[36:39], v[68:71], v[108:111], v[36:39]
	v_mfma_f32_16x16x32_bf16 v[20:23], v[68:71], v[112:115], v[20:23]
	v_mfma_f32_16x16x32_bf16 v[0:3], v[68:71], v[116:119], v[0:3]
	s_waitcnt lgkmcnt(0)
	s_barrier
	s_add_u32 m0, s5, 0x4000
	v_mfma_f32_16x16x32_bf16 v[48:51], v[72:75], v[104:107], v[48:51]
	global_load_lds_dwordx4 v248, s[44:45]
	s_add_u32 m0, s5, 0x4400
	v_mfma_f32_16x16x32_bf16 v[32:35], v[72:75], v[108:111], v[32:35]
	global_load_lds_dwordx4 v249, s[44:45]
	s_add_u32 m0, s5, 0x4800
	v_mfma_f32_16x16x32_bf16 v[16:19], v[72:75], v[112:115], v[16:19]
	global_load_lds_dwordx4 v250, s[44:45]
	s_add_u32 m0, s5, 0x4c00
	v_mfma_f32_16x16x32_bf16 v[4:7], v[72:75], v[116:119], v[4:7]
	global_load_lds_dwordx4 v251, s[44:45]
	s_add_u32 m0, s5, 0xc000
	v_mfma_f32_16x16x32_bf16 v[52:55], v[76:79], v[104:107], v[52:55]
	global_load_lds_dwordx4 v248, s[48:49]
	s_add_u32 m0, s5, 0xc400
	v_mfma_f32_16x16x32_bf16 v[44:47], v[76:79], v[108:111], v[44:47]
	global_load_lds_dwordx4 v249, s[48:49]
	s_add_u32 m0, s5, 0xc800
	v_mfma_f32_16x16x32_bf16 v[28:31], v[76:79], v[112:115], v[28:31]
	global_load_lds_dwordx4 v250, s[48:49]
	s_add_u32 m0, s5, 0xcc00
	v_mfma_f32_16x16x32_bf16 v[12:15], v[76:79], v[116:119], v[12:15]
	global_load_lds_dwordx4 v251, s[48:49]
	s_add_u32 s44, s44, 0x80
	s_addc_u32 s45, s45, 0
	s_add_u32 s48, s48, 0x80
	s_addc_u32 s49, s49, 0
	s_mov_b32 s12, 6
.Lg13_loop:
	s_waitcnt vmcnt(8)
	s_barrier
	ds_read_b128 v[64:67], v252 offset:0
	ds_read_b128 v[104:107], v254 offset:32768
	ds_read_b128 v[108:111], v254 offset:34816
	ds_read_b128 v[112:115], v254 offset:36864
	ds_read_b128 v[116:119], v254 offset:38912
	ds_read_b128 v[68:71], v252 offset:2048
	ds_read_b128 v[72:75], v252 offset:4096
	ds_read_b128 v[76:79], v252 offset:6144
	v_mfma_f32_16x16x32_bf16 v[60:63], v[80:83], v[120:123], v[60:63]
	v_mfma_f32_16x16x32_bf16 v[40:43], v[80:83], v[124:127], v[40:43]
	v_mfma_f32_16x16x32_bf16 v[24:27], v[80:83], v[132:135], v[24:27]
	v_mfma_f32_16x16x32_bf16 v[8:11], v[80:83], v[136:139], v[8:11]
	v_mfma_f32_16x16x32_bf16 v[56:59], v[84:87], v[120:123], v[56:59]
	v_mfma_f32_16x16x32_bf16 v[36:39], v[84:87], v[124:127], v[36:39]
	v_mfma_f32_16x16x32_bf16 v[20:23], v[84:87], v[132:135], v[20:23]
	v_mfma_f32_16x16x32_bf16 v[0:3], v[84:87], v[136:139], v[0:3]
	v_mfma_f32_16x16x32_bf16 v[48:51], v[88:91], v[120:123], v[48:51]
	v_mfma_f32_16x16x32_bf16 v[32:35], v[88:91], v[124:127], v[32:35]
	v_mfma_f32_16x16x32_bf16 v[16:19], v[88:91], v[132:135], v[16:19]
	v_mfma_f32_16x16x32_bf16 v[4:7], v[88:91], v[136:139], v[4:7]
	v_mfma_f32_16x16x32_bf16 v[52:55], v[92:95], v[120:123], v[52:55]
	v_mfma_f32_16x16x32_bf16 v[44:47], v[92:95], v[124:127], v[44:47]
	v_mfma_f32_16x16x32_bf16 v[28:31], v[92:95], v[132:135], v[28:31]
	v_mfma_f32_16x16x32_bf16 v[12:15], v[92:95], v[136:139], v[12:15]
	ds_read_b128 v[80:83], v253 offset:0
	ds_read_b128 v[120:123], v255 offset:32768
	ds_read_b128 v[124:127], v255 offset:34816
	ds_read_b128 v[132:135], v255 offset:36864
	ds_read_b128 v[136:139], v255 offset:38912
	ds_read_b128 v[84:87], v253 offset:2048
	ds_read_b128 v[88:91], v253 offset:4096
	ds_read_b128 v[92:95], v253 offset:6144
	s_waitcnt lgkmcnt(14)
	v_mfma_f32_16x16x32_bf16 v[60:63], v[64:67], v[104:107], v[60:63]
	s_waitcnt lgkmcnt(13)
	v_mfma_f32_16x16x32_bf16 v[40:43], v[64:67], v[108:111], v[40:43]
	s_waitcnt lgkmcnt(12)
	v_mfma_f32_16x16x32_bf16 v[24:27], v[64:67], v[112:115], v[24:27]
	s_waitcnt lgkmcnt(11)
	v_mfma_f32_16x16x32_bf16 v[8:11], v[64:67], v[116:119], v[8:11]
	s_waitcnt lgkmcnt(10)
	v_mfma_f32_16x16x32_bf16 v[56:59], v[68:71], v[104:107], v[56:59]
	v_mfma_f32_16x16x32_bf16 v[36:39], v[68:71], v[108:111], v[36:39]
	v_mfma_f32_16x16x32_bf16 v[20:23], v[68:71], v[112:115], v[20:23]
	v_mfma_f32_16x16x32_bf16 v[0:3], v[68:71], v[116:119], v[0:3]
	s_waitcnt lgkmcnt(0)
	s_barrier
	s_add_u32 m0, s5, 0x0
	v_mfma_f32_16x16x32_bf16 v[48:51], v[72:75], v[104:107], v[48:51]
	global_load_lds_dwordx4 v248, s[44:45]
	s_add_u32 m0, s5, 0x400
	v_mfma_f32_16x16x32_bf16 v[32:35], v[72:75], v[108:111], v[32:35]
	global_load_lds_dwordx4 v249, s[44:45]
	s_add_u32 m0, s5, 0x800
	v_mfma_f32_16x16x32_bf16 v[16:19], v[72:75], v[112:115], v[16:19]
	global_load_lds_dwordx4 v250, s[44:45]
	s_add_u32 m0, s5, 0xc00
	v_mfma_f32_16x16x32_bf16 v[4:7], v[72:75], v[116:119], v[4:7]
	global_load_lds_dwordx4 v251, s[44:45]
	s_add_u32 m0, s5, 0x8000
	v_mfma_f32_16x16x32_bf16 v[52:55], v[76:79], v[104:107], v[52:55]
	global_load_lds_dwordx4 v248, s[48:49]
	s_add_u32 m0, s5, 0x8400
	v_mfma_f32_16x16x32_bf16 v[44:47], v[76:79], v[108:111], v[44:47]
	global_load_lds_dwordx4 v249, s[48:49]
	s_add_u32 m0, s5, 0x8800
	v_mfma_f32_16x16x32_bf16 v[28:31], v[76:79], v[112:115], v[28:31]
	global_load_lds_dwordx4 v250, s[48:49]
	s_add_u32 m0, s5, 0x8c00
	v_mfma_f32_16x16x32_bf16 v[12:15], v[76:79], v[116:119], v[12:15]
	global_load_lds_dwordx4 v251, s[48:49]
	s_add_u32 s44, s44, 0x80
	s_addc_u32 s45, s45, 0
	s_add_u32 s48, s48, 0x80
	s_addc_u32 s49, s49, 0
	s_waitcnt vmcnt(8)
	s_barrier
	ds_read_b128 v[64:67], v252 offset:16384
	ds_read_b128 v[104:107], v254 offset:49152
	ds_read_b128 v[108:111], v254 offset:51200
	ds_read_b128 v[112:115], v254 offset:53248
	ds_read_b128 v[116:119], v254 offset:55296
	ds_read_b128 v[68:71], v252 offset:18432
	ds_read_b128 v[72:75], v252 offset:20480
	ds_read_b128 v[76:79], v252 offset:22528
	v_mfma_f32_16x16x32_bf16 v[60:63], v[80:83], v[120:123], v[60:63]
	v_mfma_f32_16x16x32_bf16 v[40:43], v[80:83], v[124:127], v[40:43]
	v_mfma_f32_16x16x32_bf16 v[24:27], v[80:83], v[132:135], v[24:27]
	v_mfma_f32_16x16x32_bf16 v[8:11], v[80:83], v[136:139], v[8:11]
	v_mfma_f32_16x16x32_bf16 v[56:59], v[84:87], v[120:123], v[56:59]
	v_mfma_f32_16x16x32_bf16 v[36:39], v[84:87], v[124:127], v[36:39]
	v_mfma_f32_16x16x32_bf16 v[20:23], v[84:87], v[132:135], v[20:23]
	v_mfma_f32_16x16x32_bf16 v[0:3], v[84:87], v[136:139], v[0:3]
	v_mfma_f32_16x16x32_bf16 v[48:51], v[88:91], v[120:123], v[48:51]
	v_mfma_f32_16x16x32_bf16 v[32:35], v[88:91], v[124:127], v[32:35]
	v_mfma_f32_16x16x32_bf16 v[16:19], v[88:91], v[132:135], v[16:19]
	v_mfma_f32_16x16x32_bf16 v[4:7], v[88:91], v[136:139], v[4:7]
	v_mfma_f32_16x16x32_bf16 v[52:55], v[92:95], v[120:123], v[52:55]
	v_mfma_f32_16x16x32_bf16 v[44:47], v[92:95], v[124:127], v[44:47]
	v_mfma_f32_16x16x32_bf16 v[28:31], v[92:95], v[132:135], v[28:31]
	v_mfma_f32_16x16x32_bf16 v[12:15], v[92:95], v[136:139], v[12:15]
	ds_read_b128 v[80:83], v253 offset:16384
	ds_read_b128 v[120:123], v255 offset:49152
	ds_read_b128 v[124:127], v255 offset:51200
	ds_read_b128 v[132:135], v255 offset:53248
	ds_read_b128 v[136:139], v255 offset:55296
	ds_read_b128 v[84:87], v253 offset:18432
	ds_read_b128 v[88:91], v253 offset:20480
	ds_read_b128 v[92:95], v253 offset:22528
	s_waitcnt lgkmcnt(14)
	v_mfma_f32_16x16x32_bf16 v[60:63], v[64:67], v[104:107], v[60:63]
	s_waitcnt lgkmcnt(13)
	v_mfma_f32_16x16x32_bf16 v[40:43], v[64:67], v[108:111], v[40:43]
	s_waitcnt lgkmcnt(12)
	v_mfma_f32_16x16x32_bf16 v[24:27], v[64:67], v[112:115], v[24:27]
	s_waitcnt lgkmcnt(11)
	v_mfma_f32_16x16x32_bf16 v[8:11], v[64:67], v[116:119], v[8:11]
	s_waitcnt lgkmcnt(10)
	v_mfma_f32_16x16x32_bf16 v[56:59], v[68:71], v[104:107], v[56:59]
	v_mfma_f32_16x16x32_bf16 v[36:39], v[68:71], v[108:111], v[36:39]
	v_mfma_f32_16x16x32_bf16 v[20:23], v[68:71], v[112:115], v[20:23]
	v_mfma_f32_16x16x32_bf16 v[0:3], v[68:71], v[116:119], v[0:3]
	s_waitcnt lgkmcnt(0)
	s_barrier
	s_add_u32 m0, s5, 0x4000
	v_mfma_f32_16x16x32_bf16 v[48:51], v[72:75], v[104:107], v[48:51]
	global_load_lds_dwordx4 v248, s[44:45]
	s_add_u32 m0, s5, 0x4400
	v_mfma_f32_16x16x32_bf16 v[32:35], v[72:75], v[108:111], v[32:35]
	global_load_lds_dwordx4 v249, s[44:45]
	s_add_u32 m0, s5, 0x4800
	v_mfma_f32_16x16x32_bf16 v[16:19], v[72:75], v[112:115], v[16:19]
	global_load_lds_dwordx4 v250, s[44:45]
	s_add_u32 m0, s5, 0x4c00
	v_mfma_f32_16x16x32_bf16 v[4:7], v[72:75], v[116:119], v[4:7]
	global_load_lds_dwordx4 v251, s[44:45]
	s_add_u32 m0, s5, 0xc000
	v_mfma_f32_16x16x32_bf16 v[52:55], v[76:79], v[104:107], v[52:55]
	global_load_lds_dwordx4 v248, s[48:49]
	s_add_u32 m0, s5, 0xc400
	v_mfma_f32_16x16x32_bf16 v[44:47], v[76:79], v[108:111], v[44:47]
	global_load_lds_dwordx4 v249, s[48:49]
	s_add_u32 m0, s5, 0xc800
	v_mfma_f32_16x16x32_bf16 v[28:31], v[76:79], v[112:115], v[28:31]
	global_load_lds_dwordx4 v250, s[48:49]
	s_add_u32 m0, s5, 0xcc00
	v_mfma_f32_16x16x32_bf16 v[12:15], v[76:79], v[116:119], v[12:15]
	global_load_lds_dwordx4 v251, s[48:49]
	s_add_u32 s44, s44, 0x80
	s_addc_u32 s45, s45, 0
	s_add_u32 s48, s48, 0x80
	s_addc_u32 s49, s49, 0
	s_sub_u32 s12, s12, 1
	s_cmp_lg_u32 s12, 0
	s_cbranch_scc1 .Lg13_loop
	s_waitcnt vmcnt(8)
	s_barrier
	ds_read_b128 v[64:67], v252 offset:0
	ds_read_b128 v[104:107], v254 offset:32768
	ds_read_b128 v[108:111], v254 offset:34816
	ds_read_b128 v[112:115], v254 offset:36864
	ds_read_b128 v[116:119], v254 offset:38912
	ds_read_b128 v[68:71], v252 offset:2048
	ds_read_b128 v[72:75], v252 offset:4096
	ds_read_b128 v[76:79], v252 offset:6144
	v_mfma_f32_16x16x32_bf16 v[60:63], v[80:83], v[120:123], v[60:63]
	v_mfma_f32_16x16x32_bf16 v[40:43], v[80:83], v[124:127], v[40:43]
	v_mfma_f32_16x16x32_bf16 v[24:27], v[80:83], v[132:135], v[24:27]
	v_mfma_f32_16x16x32_bf16 v[8:11], v[80:83], v[136:139], v[8:11]
	v_mfma_f32_16x16x32_bf16 v[56:59], v[84:87], v[120:123], v[56:59]
	v_mfma_f32_16x16x32_bf16 v[36:39], v[84:87], v[124:127], v[36:39]
	v_mfma_f32_16x16x32_bf16 v[20:23], v[84:87], v[132:135], v[20:23]
	v_mfma_f32_16x16x32_bf16 v[0:3], v[84:87], v[136:139], v[0:3]
	v_mfma_f32_16x16x32_bf16 v[48:51], v[88:91], v[120:123], v[48:51]
	v_mfma_f32_16x16x32_bf16 v[32:35], v[88:91], v[124:127], v[32:35]
	v_mfma_f32_16x16x32_bf16 v[16:19], v[88:91], v[132:135], v[16:19]
	v_mfma_f32_16x16x32_bf16 v[4:7], v[88:91], v[136:139], v[4:7]
	v_mfma_f32_16x16x32_bf16 v[52:55], v[92:95], v[120:123], v[52:55]
	v_mfma_f32_16x16x32_bf16 v[44:47], v[92:95], v[124:127], v[44:47]
	v_mfma_f32_16x16x32_bf16 v[28:31], v[92:95], v[132:135], v[28:31]
	v_mfma_f32_16x16x32_bf16 v[12:15], v[92:95], v[136:139], v[12:15]
	ds_read_b128 v[80:83], v253 offset:0
	ds_read_b128 v[120:123], v255 offset:32768
	ds_read_b128 v[124:127], v255 offset:34816
	ds_read_b128 v[132:135], v255 offset:36864
	ds_read_b128 v[136:139], v255 offset:38912
	ds_read_b128 v[84:87], v253 offset:2048
	ds_read_b128 v[88:91], v253 offset:4096
	ds_read_b128 v[92:95], v253 offset:6144
	s_waitcnt lgkmcnt(14)
	v_mfma_f32_16x16x32_bf16 v[60:63], v[64:67], v[104:107], v[60:63]
	s_waitcnt lgkmcnt(13)
	v_mfma_f32_16x16x32_bf16 v[40:43], v[64:67], v[108:111], v[40:43]
	s_waitcnt lgkmcnt(12)
	v_mfma_f32_16x16x32_bf16 v[24:27], v[64:67], v[112:115], v[24:27]
	s_waitcnt lgkmcnt(11)
	v_mfma_f32_16x16x32_bf16 v[8:11], v[64:67], v[116:119], v[8:11]
	s_waitcnt lgkmcnt(10)
	v_mfma_f32_16x16x32_bf16 v[56:59], v[68:71], v[104:107], v[56:59]
	v_mfma_f32_16x16x32_bf16 v[36:39], v[68:71], v[108:111], v[36:39]
	v_mfma_f32_16x16x32_bf16 v[20:23], v[68:71], v[112:115], v[20:23]
	v_mfma_f32_16x16x32_bf16 v[0:3], v[68:71], v[116:119], v[0:3]
	s_waitcnt lgkmcnt(0)
	s_barrier
	v_mfma_f32_16x16x32_bf16 v[48:51], v[72:75], v[104:107], v[48:51]
	v_mfma_f32_16x16x32_bf16 v[32:35], v[72:75], v[108:111], v[32:35]
	v_mfma_f32_16x16x32_bf16 v[16:19], v[72:75], v[112:115], v[16:19]
	v_mfma_f32_16x16x32_bf16 v[4:7], v[72:75], v[116:119], v[4:7]
	v_mfma_f32_16x16x32_bf16 v[52:55], v[76:79], v[104:107], v[52:55]
	v_mfma_f32_16x16x32_bf16 v[44:47], v[76:79], v[108:111], v[44:47]
	v_mfma_f32_16x16x32_bf16 v[28:31], v[76:79], v[112:115], v[28:31]
	v_mfma_f32_16x16x32_bf16 v[12:15], v[76:79], v[116:119], v[12:15]
	s_waitcnt vmcnt(0)
	s_barrier
	ds_read_b128 v[64:67], v252 offset:16384
	ds_read_b128 v[104:107], v254 offset:49152
	ds_read_b128 v[108:111], v254 offset:51200
	ds_read_b128 v[112:115], v254 offset:53248
	ds_read_b128 v[116:119], v254 offset:55296
	ds_read_b128 v[68:71], v252 offset:18432
	ds_read_b128 v[72:75], v252 offset:20480
	ds_read_b128 v[76:79], v252 offset:22528
	v_mfma_f32_16x16x32_bf16 v[60:63], v[80:83], v[120:123], v[60:63]
	v_mfma_f32_16x16x32_bf16 v[40:43], v[80:83], v[124:127], v[40:43]
	v_mfma_f32_16x16x32_bf16 v[24:27], v[80:83], v[132:135], v[24:27]
	v_mfma_f32_16x16x32_bf16 v[8:11], v[80:83], v[136:139], v[8:11]
	v_mfma_f32_16x16x32_bf16 v[56:59], v[84:87], v[120:123], v[56:59]
	v_mfma_f32_16x16x32_bf16 v[36:39], v[84:87], v[124:127], v[36:39]
	v_mfma_f32_16x16x32_bf16 v[20:23], v[84:87], v[132:135], v[20:23]
	v_mfma_f32_16x16x32_bf16 v[0:3], v[84:87], v[136:139], v[0:3]
	v_mfma_f32_16x16x32_bf16 v[48:51], v[88:91], v[120:123], v[48:51]
	v_mfma_f32_16x16x32_bf16 v[32:35], v[88:91], v[124:127], v[32:35]
	v_mfma_f32_16x16x32_bf16 v[16:19], v[88:91], v[132:135], v[16:19]
	v_mfma_f32_16x16x32_bf16 v[4:7], v[88:91], v[136:139], v[4:7]
	v_mfma_f32_16x16x32_bf16 v[52:55], v[92:95], v[120:123], v[52:55]
	v_mfma_f32_16x16x32_bf16 v[44:47], v[92:95], v[124:127], v[44:47]
	v_mfma_f32_16x16x32_bf16 v[28:31], v[92:95], v[132:135], v[28:31]
	v_mfma_f32_16x16x32_bf16 v[12:15], v[92:95], v[136:139], v[12:15]
	ds_read_b128 v[80:83], v253 offset:16384
	ds_read_b128 v[120:123], v255 offset:49152
	ds_read_b128 v[124:127], v255 offset:51200
	ds_read_b128 v[132:135], v255 offset:53248
	ds_read_b128 v[136:139], v255 offset:55296
	ds_read_b128 v[84:87], v253 offset:18432
	ds_read_b128 v[88:91], v253 offset:20480
	ds_read_b128 v[92:95], v253 offset:22528
	s_waitcnt lgkmcnt(14)
	v_mfma_f32_16x16x32_bf16 v[60:63], v[64:67], v[104:107], v[60:63]
	s_waitcnt lgkmcnt(13)
	v_mfma_f32_16x16x32_bf16 v[40:43], v[64:67], v[108:111], v[40:43]
	s_waitcnt lgkmcnt(12)
	v_mfma_f32_16x16x32_bf16 v[24:27], v[64:67], v[112:115], v[24:27]
	s_waitcnt lgkmcnt(11)
	v_mfma_f32_16x16x32_bf16 v[8:11], v[64:67], v[116:119], v[8:11]
	s_waitcnt lgkmcnt(10)
	v_mfma_f32_16x16x32_bf16 v[56:59], v[68:71], v[104:107], v[56:59]
	v_mfma_f32_16x16x32_bf16 v[36:39], v[68:71], v[108:111], v[36:39]
	v_mfma_f32_16x16x32_bf16 v[20:23], v[68:71], v[112:115], v[20:23]
	v_mfma_f32_16x16x32_bf16 v[0:3], v[68:71], v[116:119], v[0:3]
	s_waitcnt lgkmcnt(0)
	s_barrier
	v_mfma_f32_16x16x32_bf16 v[48:51], v[72:75], v[104:107], v[48:51]
	v_mfma_f32_16x16x32_bf16 v[32:35], v[72:75], v[108:111], v[32:35]
	v_mfma_f32_16x16x32_bf16 v[16:19], v[72:75], v[112:115], v[16:19]
	v_mfma_f32_16x16x32_bf16 v[4:7], v[72:75], v[116:119], v[4:7]
	v_mfma_f32_16x16x32_bf16 v[52:55], v[76:79], v[104:107], v[52:55]
	v_mfma_f32_16x16x32_bf16 v[44:47], v[76:79], v[108:111], v[44:47]
	v_mfma_f32_16x16x32_bf16 v[28:31], v[76:79], v[112:115], v[28:31]
	v_mfma_f32_16x16x32_bf16 v[12:15], v[76:79], v[116:119], v[12:15]
	v_mfma_f32_16x16x32_bf16 v[60:63], v[80:83], v[120:123], v[60:63]
	v_mfma_f32_16x16x32_bf16 v[40:43], v[80:83], v[124:127], v[40:43]
	v_mfma_f32_16x16x32_bf16 v[24:27], v[80:83], v[132:135], v[24:27]
	v_mfma_f32_16x16x32_bf16 v[8:11], v[80:83], v[136:139], v[8:11]
	v_mfma_f32_16x16x32_bf16 v[56:59], v[84:87], v[120:123], v[56:59]
	v_mfma_f32_16x16x32_bf16 v[36:39], v[84:87], v[124:127], v[36:39]
	v_mfma_f32_16x16x32_bf16 v[20:23], v[84:87], v[132:135], v[20:23]
	v_mfma_f32_16x16x32_bf16 v[0:3], v[84:87], v[136:139], v[0:3]
	v_mfma_f32_16x16x32_bf16 v[48:51], v[88:91], v[120:123], v[48:51]
	v_mfma_f32_16x16x32_bf16 v[32:35], v[88:91], v[124:127], v[32:35]
	v_mfma_f32_16x16x32_bf16 v[16:19], v[88:91], v[132:135], v[16:19]
	v_mfma_f32_16x16x32_bf16 v[4:7], v[88:91], v[136:139], v[4:7]
	v_mfma_f32_16x16x32_bf16 v[52:55], v[92:95], v[120:123], v[52:55]
	v_mfma_f32_16x16x32_bf16 v[44:47], v[92:95], v[124:127], v[44:47]
	v_mfma_f32_16x16x32_bf16 v[28:31], v[92:95], v[132:135], v[28:31]
	v_mfma_f32_16x16x32_bf16 v[12:15], v[92:95], v[136:139], v[12:15]
	s_nop 7
	s_nop 1
	v_sub_co_u32_e32 v64, vcc, s43, v142
	s_nop 0
	v_readfirstlane_b32 s5, v64
	s_lshr_b32 s5, s5, 10
	s_add_i32 s5, s5, 1
	s_and_b64 s[44:45], vcc, exec
	s_cselect_b32 s5, 0, s5
	s_mul_hi_u32 s12, s5, 0x6000
	s_mulk_i32 s5, 0x6000
	s_add_u32 s44, s2, s5
	v_or_b32_e32 v64, s4, v140
	s_addc_u32 s45, s3, s12
	v_ashrrev_i32_e32 v65, 31, v64
	v_lshl_add_u64 v[66:67], v[64:65], 2, s[44:45]
	global_load_dword v107, v[66:67], off
	s_waitcnt vmcnt(7)
	v_cndmask_b32_e64 v68, 0, 1, s[10:11]
	v_mov_b32_e32 v106, 0
	v_cmp_ne_u32_e64 s[4:5], 1, v68
	s_andn2_b64 vcc, exec, s[10:11]
	v_lshl_add_u64 v[68:69], v[64:65], 2, s[6:7]
	v_mov_b32_e32 v108, 0
	s_cbranch_vccnz .LBB0_1268
	global_load_dword v108, v[68:69], off

.LBB0_1581:
	s_and_b32 s8, s68, 0xffffff80
	s_ashr_i32 s9, s8, 31
	s_lshl_b32 s7, s70, 11
	s_lshl_b64 s[8:9], s[8:9], 11
	s_and_b32 s22, s7, 0xfc0000
	s_add_i32 s2, s2, s3
	s_cmpk_gt_i32 s2, 0xc3f
	s_cselect_b64 s[62:63], -1, 0
	s_lshl_b32 s7, s2, 18
	s_and_b32 s7, s7, 0xfc0000
	s_add_u32 s7, s18, s7
	v_lshl_add_u64 v[126:127], v[114:115], 0, s[8:9]
	s_addc_u32 s10, s19, 0
	s_ashr_i32 s8, s2, 6
	s_ashr_i32 s9, s8, 31
	s_lshl_b64 s[8:9], s[8:9], 18
	v_lshl_add_u64 v[130:131], v[116:117], 0, s[22:23]
	s_add_u32 s22, s20, s8
	s_addc_u32 s11, s21, s9
	s_cmpk_lt_i32 s2, 0xc40
	s_cselect_b64 vcc, -1, 0
	s_and_b64 s[8:9], vcc, exec
	s_cselect_b32 s9, s10, 0
	s_cselect_b32 s8, s7, 0
	v_lshl_add_u64 v[2:3], s[8:9], 0, v[118:119]
	v_lshl_add_u64 v[0:1], v[122:123], 0, s[46:47]
	s_cselect_b32 s11, s11, 0
	s_cselect_b32 s10, s22, 0
	v_lshl_add_u64 v[2:3], v[2:3], 0, v[120:121]
	v_cndmask_b32_e32 v97, v1, v3, vcc
	v_cndmask_b32_e32 v98, v0, v2, vcc
	v_lshl_add_u64 v[0:1], s[10:11], 0, v[118:119]
	v_lshl_add_u64 v[0:1], v[0:1], 0, v[120:121]
	v_lshl_add_u64 v[2:3], v[124:125], 0, s[46:47]
	v_cndmask_b32_e32 v144, v2, v0, vcc
	v_mov_b32_e32 v0, 0
	v_lshl_add_u64 v[146:147], v[122:123], 0, s[30:31]
	v_lshl_add_u64 v[132:133], v[122:123], 0, s[34:35]
	v_lshl_add_u64 v[150:151], v[122:123], 0, s[36:37]
	v_lshl_add_u64 v[134:135], v[122:123], 0, s[38:39]
	v_lshl_add_u64 v[152:153], v[122:123], 0, s[40:41]
	v_lshl_add_u64 v[136:137], v[122:123], 0, s[42:43]
	v_lshl_add_u64 v[154:155], v[122:123], 0, s[44:45]
	v_lshl_add_u64 v[148:149], v[124:125], 0, s[30:31]
	v_lshl_add_u64 v[138:139], v[124:125], 0, s[34:35]
	v_lshl_add_u64 v[156:157], v[124:125], 0, s[36:37]
	v_lshl_add_u64 v[140:141], v[124:125], 0, s[38:39]
	v_lshl_add_u64 v[158:159], v[124:125], 0, s[40:41]
	v_lshl_add_u64 v[142:143], v[124:125], 0, s[42:43]
	v_lshl_add_u64 v[160:161], v[124:125], 0, s[44:45]
	v_cndmask_b32_e32 v129, v3, v1, vcc
	s_mov_b32 s7, -2
	v_mov_b32_e32 v1, v0
	v_mov_b32_e32 v2, v0
	v_mov_b32_e32 v3, v0
	v_mov_b32_e32 v20, v0
	v_mov_b32_e32 v21, v0
	v_mov_b32_e32 v22, v0
	v_mov_b32_e32 v23, v0
	v_mov_b32_e32 v24, v0
	v_mov_b32_e32 v25, v0
	v_mov_b32_e32 v26, v0
	v_mov_b32_e32 v27, v0
	v_mov_b32_e32 v32, v0
	v_mov_b32_e32 v33, v0
	v_mov_b32_e32 v34, v0
	v_mov_b32_e32 v35, v0
	v_mov_b32_e32 v8, v0
	v_mov_b32_e32 v9, v0
	v_mov_b32_e32 v10, v0
	v_mov_b32_e32 v11, v0
	v_mov_b32_e32 v4, v0
	v_mov_b32_e32 v5, v0
	v_mov_b32_e32 v6, v0
	v_mov_b32_e32 v7, v0
	v_mov_b32_e32 v12, v0
	v_mov_b32_e32 v13, v0
	v_mov_b32_e32 v14, v0
	v_mov_b32_e32 v15, v0
	v_mov_b32_e32 v16, v0
	v_mov_b32_e32 v17, v0
	v_mov_b32_e32 v18, v0
	v_mov_b32_e32 v19, v0
	v_mov_b32_e32 v28, v0
	v_mov_b32_e32 v29, v0
	v_mov_b32_e32 v30, v0
	v_mov_b32_e32 v31, v0
	v_mov_b32_e32 v36, v0
	v_mov_b32_e32 v37, v0
	v_mov_b32_e32 v38, v0
	v_mov_b32_e32 v39, v0
	v_mov_b32_e32 v40, v0
	v_mov_b32_e32 v41, v0
	v_mov_b32_e32 v42, v0
	v_mov_b32_e32 v43, v0
	v_mov_b32_e32 v44, v0
	v_mov_b32_e32 v45, v0
	v_mov_b32_e32 v46, v0
	v_mov_b32_e32 v47, v0
	v_mov_b32_e32 v48, v0
	v_mov_b32_e32 v49, v0
	v_mov_b32_e32 v50, v0
	v_mov_b32_e32 v51, v0
	v_mov_b32_e32 v52, v0
	v_mov_b32_e32 v53, v0
	v_mov_b32_e32 v54, v0
	v_mov_b32_e32 v55, v0
	v_mov_b32_e32 v56, v0
	v_mov_b32_e32 v57, v0
	v_mov_b32_e32 v58, v0
	v_mov_b32_e32 v59, v0
	v_mov_b32_e32 v60, v0
	v_mov_b32_e32 v61, v0
	v_mov_b32_e32 v62, v0
	v_mov_b32_e32 v63, v0
	v_readfirstlane_b32 s8, v122
	v_readfirstlane_b32 s9, v123
	v_readfirstlane_b32 s64, v124
	v_readfirstlane_b32 s65, v125
	v_readfirstlane_b32 s7, v247
	s_nop 3
	s_mul_i32 s66, s7, 0x4000
	s_sub_u32 s8, s8, s66
	s_subb_u32 s9, s9, 0
	s_sub_u32 s64, s64, s66
	s_subb_u32 s65, s65, 0
	s_lshl_b32 s7, s7, 12
	s_add_u32 m0, s7, 0x0
	v_mov_b32_e32 v60, 0
	global_load_lds_dwordx4 v248, s[8:9]
	v_mov_b32_e32 v61, 0
	s_add_u32 m0, s7, 0x400
	v_mov_b32_e32 v62, 0
	global_load_lds_dwordx4 v249, s[8:9]
	v_mov_b32_e32 v63, 0
	s_add_u32 m0, s7, 0x800
	v_mov_b32_e32 v56, 0
	global_load_lds_dwordx4 v250, s[8:9]
	v_mov_b32_e32 v57, 0
	s_add_u32 m0, s7, 0xc00
	v_mov_b32_e32 v58, 0
	global_load_lds_dwordx4 v251, s[8:9]
	v_mov_b32_e32 v59, 0
	s_add_u32 m0, s7, 0x8000
	v_mov_b32_e32 v52, 0
	global_load_lds_dwordx4 v248, s[64:65]
	v_mov_b32_e32 v53, 0
	s_add_u32 m0, s7, 0x8400
	v_mov_b32_e32 v54, 0
	global_load_lds_dwordx4 v249, s[64:65]
	v_mov_b32_e32 v55, 0
	s_add_u32 m0, s7, 0x8800
	v_mov_b32_e32 v48, 0
	global_load_lds_dwordx4 v250, s[64:65]
	v_mov_b32_e32 v49, 0
	s_add_u32 m0, s7, 0x8c00
	v_mov_b32_e32 v50, 0
	global_load_lds_dwordx4 v251, s[64:65]
	v_mov_b32_e32 v51, 0
	s_add_u32 s8, s8, 0x80
	s_addc_u32 s9, s9, 0
	s_add_u32 s64, s64, 0x80
	s_addc_u32 s65, s65, 0
	s_add_u32 m0, s7, 0x4000
	v_mov_b32_e32 v44, 0
	global_load_lds_dwordx4 v248, s[8:9]
	v_mov_b32_e32 v45, 0
	s_add_u32 m0, s7, 0x4400
	v_mov_b32_e32 v46, 0
	global_load_lds_dwordx4 v249, s[8:9]
	v_mov_b32_e32 v47, 0
	s_add_u32 m0, s7, 0x4800
	v_mov_b32_e32 v40, 0
	global_load_lds_dwordx4 v250, s[8:9]
	v_mov_b32_e32 v41, 0
	s_add_u32 m0, s7, 0x4c00
	v_mov_b32_e32 v42, 0
	global_load_lds_dwordx4 v251, s[8:9]
	v_mov_b32_e32 v43, 0
	s_add_u32 m0, s7, 0xc000
	v_mov_b32_e32 v36, 0
	global_load_lds_dwordx4 v248, s[64:65]
	v_mov_b32_e32 v37, 0
	s_add_u32 m0, s7, 0xc400
	v_mov_b32_e32 v38, 0
	global_load_lds_dwordx4 v249, s[64:65]
	v_mov_b32_e32 v39, 0
	s_add_u32 m0, s7, 0xc800
	v_mov_b32_e32 v28, 0
	global_load_lds_dwordx4 v250, s[64:65]
	v_mov_b32_e32 v29, 0
	s_add_u32 m0, s7, 0xcc00
	v_mov_b32_e32 v30, 0
	global_load_lds_dwordx4 v251, s[64:65]
	v_mov_b32_e32 v31, 0
	s_add_u32 s8, s8, 0x80
	s_addc_u32 s9, s9, 0
	s_add_u32 s64, s64, 0x80
	s_addc_u32 s65, s65, 0
	v_mov_b32_e32 v16, 0
	v_mov_b32_e32 v17, 0
	v_mov_b32_e32 v18, 0
	v_mov_b32_e32 v19, 0
	v_mov_b32_e32 v12, 0
	v_mov_b32_e32 v13, 0
	v_mov_b32_e32 v14, 0
	v_mov_b32_e32 v15, 0
	v_mov_b32_e32 v4, 0
	v_mov_b32_e32 v5, 0
	v_mov_b32_e32 v6, 0
	v_mov_b32_e32 v7, 0
	v_mov_b32_e32 v8, 0
	v_mov_b32_e32 v9, 0
	v_mov_b32_e32 v10, 0
	v_mov_b32_e32 v11, 0
	v_mov_b32_e32 v32, 0
	v_mov_b32_e32 v33, 0
	v_mov_b32_e32 v34, 0
	v_mov_b32_e32 v35, 0
	v_mov_b32_e32 v24, 0
	v_mov_b32_e32 v25, 0
	v_mov_b32_e32 v26, 0
	v_mov_b32_e32 v27, 0
	v_mov_b32_e32 v20, 0
	v_mov_b32_e32 v21, 0
	v_mov_b32_e32 v22, 0
	v_mov_b32_e32 v23, 0
	v_mov_b32_e32 v0, 0
	v_mov_b32_e32 v1, 0
	v_mov_b32_e32 v2, 0
	v_mov_b32_e32 v3, 0
	s_waitcnt vmcnt(8)
	s_barrier
	ds_read_b128 v[80:83], v252 offset:0
	ds_read_b128 v[144:147], v254 offset:32768
	ds_read_b128 v[148:151], v254 offset:34816
	ds_read_b128 v[152:155], v254 offset:36864
	ds_read_b128 v[156:159], v254 offset:38912
	ds_read_b128 v[84:87], v252 offset:2048
	ds_read_b128 v[88:91], v252 offset:4096
	ds_read_b128 v[92:95], v252 offset:6144
	ds_read_b128 v[124:127], v253 offset:0
	ds_read_b128 v[180:183], v255 offset:32768
	ds_read_b128 v[184:187], v255 offset:34816
	ds_read_b128 v[188:191], v255 offset:36864
	ds_read_b128 v[192:195], v255 offset:38912
	s_waitcnt lgkmcnt(11)
	v_mfma_f32_16x16x32_bf16 v[60:63], v[80:83], v[144:147], v[60:63]
	s_waitcnt lgkmcnt(10)
	v_mfma_f32_16x16x32_bf16 v[56:59], v[80:83], v[148:151], v[56:59]
	s_waitcnt lgkmcnt(9)
	v_mfma_f32_16x16x32_bf16 v[52:55], v[80:83], v[152:155], v[52:55]
	s_waitcnt lgkmcnt(8)
	v_mfma_f32_16x16x32_bf16 v[48:51], v[80:83], v[156:159], v[48:51]
	ds_read_b128 v[132:135], v253 offset:2048
	ds_read_b128 v[136:139], v253 offset:4096
	ds_read_b128 v[140:143], v253 offset:6144
	s_waitcnt lgkmcnt(10)
	v_mfma_f32_16x16x32_bf16 v[44:47], v[84:87], v[144:147], v[44:47]
	v_mfma_f32_16x16x32_bf16 v[40:43], v[84:87], v[148:151], v[40:43]
	v_mfma_f32_16x16x32_bf16 v[36:39], v[84:87], v[152:155], v[36:39]
	v_mfma_f32_16x16x32_bf16 v[28:31], v[84:87], v[156:159], v[28:31]
	s_waitcnt lgkmcnt(0)
	s_barrier
	s_add_u32 m0, s7, 0x0
	v_mfma_f32_16x16x32_bf16 v[16:19], v[88:91], v[144:147], v[16:19]
	global_load_lds_dwordx4 v248, s[8:9]
	s_add_u32 m0, s7, 0x400
	v_mfma_f32_16x16x32_bf16 v[12:15], v[88:91], v[148:151], v[12:15]
	global_load_lds_dwordx4 v249, s[8:9]
	s_add_u32 m0, s7, 0x800
	v_mfma_f32_16x16x32_bf16 v[4:7], v[88:91], v[152:155], v[4:7]
	global_load_lds_dwordx4 v250, s[8:9]
	s_add_u32 m0, s7, 0xc00
	v_mfma_f32_16x16x32_bf16 v[8:11], v[88:91], v[156:159], v[8:11]
	global_load_lds_dwordx4 v251, s[8:9]
	s_add_u32 m0, s7, 0x8000
	v_mfma_f32_16x16x32_bf16 v[32:35], v[92:95], v[144:147], v[32:35]
	global_load_lds_dwordx4 v248, s[64:65]
	s_add_u32 m0, s7, 0x8400
	v_mfma_f32_16x16x32_bf16 v[24:27], v[92:95], v[148:151], v[24:27]
	global_load_lds_dwordx4 v249, s[64:65]
	s_add_u32 m0, s7, 0x8800
	v_mfma_f32_16x16x32_bf16 v[20:23], v[92:95], v[152:155], v[20:23]
	global_load_lds_dwordx4 v250, s[64:65]
	s_add_u32 m0, s7, 0x8c00
	v_mfma_f32_16x16x32_bf16 v[0:3], v[92:95], v[156:159], v[0:3]
	global_load_lds_dwordx4 v251, s[64:65]
	s_add_u32 s8, s8, 0x80
	s_addc_u32 s9, s9, 0
	s_add_u32 s64, s64, 0x80
	s_addc_u32 s65, s65, 0
	s_waitcnt vmcnt(8)
	s_barrier
	ds_read_b128 v[80:83], v252 offset:16384
	ds_read_b128 v[144:147], v254 offset:49152
	ds_read_b128 v[148:151], v254 offset:51200
	ds_read_b128 v[152:155], v254 offset:53248
	ds_read_b128 v[156:159], v254 offset:55296
	ds_read_b128 v[84:87], v252 offset:18432
	ds_read_b128 v[88:91], v252 offset:20480
	ds_read_b128 v[92:95], v252 offset:22528
	v_mfma_f32_16x16x32_bf16 v[60:63], v[124:127], v[180:183], v[60:63]
	v_mfma_f32_16x16x32_bf16 v[56:59], v[124:127], v[184:187], v[56:59]
	v_mfma_f32_16x16x32_bf16 v[52:55], v[124:127], v[188:191], v[52:55]
	v_mfma_f32_16x16x32_bf16 v[48:51], v[124:127], v[192:195], v[48:51]
	v_mfma_f32_16x16x32_bf16 v[44:47], v[132:135], v[180:183], v[44:47]
	v_mfma_f32_16x16x32_bf16 v[40:43], v[132:135], v[184:187], v[40:43]
	v_mfma_f32_16x16x32_bf16 v[36:39], v[132:135], v[188:191], v[36:39]
	v_mfma_f32_16x16x32_bf16 v[28:31], v[132:135], v[192:195], v[28:31]
	v_mfma_f32_16x16x32_bf16 v[16:19], v[136:139], v[180:183], v[16:19]
	v_mfma_f32_16x16x32_bf16 v[12:15], v[136:139], v[184:187], v[12:15]
	v_mfma_f32_16x16x32_bf16 v[4:7], v[136:139], v[188:191], v[4:7]
	v_mfma_f32_16x16x32_bf16 v[8:11], v[136:139], v[192:195], v[8:11]
	v_mfma_f32_16x16x32_bf16 v[32:35], v[140:143], v[180:183], v[32:35]
	v_mfma_f32_16x16x32_bf16 v[24:27], v[140:143], v[184:187], v[24:27]
	v_mfma_f32_16x16x32_bf16 v[20:23], v[140:143], v[188:191], v[20:23]
	v_mfma_f32_16x16x32_bf16 v[0:3], v[140:143], v[192:195], v[0:3]
	ds_read_b128 v[124:127], v253 offset:16384
	ds_read_b128 v[180:183], v255 offset:49152
	ds_read_b128 v[184:187], v255 offset:51200
	ds_read_b128 v[188:191], v255 offset:53248
	ds_read_b128 v[192:195], v255 offset:55296
	ds_read_b128 v[132:135], v253 offset:18432
	ds_read_b128 v[136:139], v253 offset:20480
	ds_read_b128 v[140:143], v253 offset:22528
	s_waitcnt lgkmcnt(14)
	v_mfma_f32_16x16x32_bf16 v[60:63], v[80:83], v[144:147], v[60:63]
	s_waitcnt lgkmcnt(13)
	v_mfma_f32_16x16x32_bf16 v[56:59], v[80:83], v[148:151], v[56:59]
	s_waitcnt lgkmcnt(12)
	v_mfma_f32_16x16x32_bf16 v[52:55], v[80:83], v[152:155], v[52:55]
	s_waitcnt lgkmcnt(11)
	v_mfma_f32_16x16x32_bf16 v[48:51], v[80:83], v[156:159], v[48:51]
	s_waitcnt lgkmcnt(10)
	v_mfma_f32_16x16x32_bf16 v[44:47], v[84:87], v[144:147], v[44:47]
	v_mfma_f32_16x16x32_bf16 v[40:43], v[84:87], v[148:151], v[40:43]
	v_mfma_f32_16x16x32_bf16 v[36:39], v[84:87], v[152:155], v[36:39]
	v_mfma_f32_16x16x32_bf16 v[28:31], v[84:87], v[156:159], v[28:31]
	s_waitcnt lgkmcnt(0)
	s_barrier
	s_add_u32 m0, s7, 0x4000
	v_mfma_f32_16x16x32_bf16 v[16:19], v[88:91], v[144:147], v[16:19]
	global_load_lds_dwordx4 v248, s[8:9]
	s_add_u32 m0, s7, 0x4400
	v_mfma_f32_16x16x32_bf16 v[12:15], v[88:91], v[148:151], v[12:15]
	global_load_lds_dwordx4 v249, s[8:9]
	s_add_u32 m0, s7, 0x4800
	v_mfma_f32_16x16x32_bf16 v[4:7], v[88:91], v[152:155], v[4:7]
	global_load_lds_dwordx4 v250, s[8:9]
	s_add_u32 m0, s7, 0x4c00
	v_mfma_f32_16x16x32_bf16 v[8:11], v[88:91], v[156:159], v[8:11]
	global_load_lds_dwordx4 v251, s[8:9]
	s_add_u32 m0, s7, 0xc000
	v_mfma_f32_16x16x32_bf16 v[32:35], v[92:95], v[144:147], v[32:35]
	global_load_lds_dwordx4 v248, s[64:65]
	s_add_u32 m0, s7, 0xc400
	v_mfma_f32_16x16x32_bf16 v[24:27], v[92:95], v[148:151], v[24:27]
	global_load_lds_dwordx4 v249, s[64:65]
	s_add_u32 m0, s7, 0xc800
	v_mfma_f32_16x16x32_bf16 v[20:23], v[92:95], v[152:155], v[20:23]
	global_load_lds_dwordx4 v250, s[64:65]
	s_add_u32 m0, s7, 0xcc00
	v_mfma_f32_16x16x32_bf16 v[0:3], v[92:95], v[156:159], v[0:3]
	global_load_lds_dwordx4 v251, s[64:65]
	s_add_u32 s8, s8, 0x80
	s_addc_u32 s9, s9, 0
	s_add_u32 s64, s64, 0x80
	s_addc_u32 s65, s65, 0
	s_mov_b32 s32, 6
.Lg18_loop:
	s_waitcnt vmcnt(8)
	s_barrier
	ds_read_b128 v[80:83], v252 offset:0
	ds_read_b128 v[144:147], v254 offset:32768
	ds_read_b128 v[148:151], v254 offset:34816
	ds_read_b128 v[152:155], v254 offset:36864
	ds_read_b128 v[156:159], v254 offset:38912
	ds_read_b128 v[84:87], v252 offset:2048
	ds_read_b128 v[88:91], v252 offset:4096
	ds_read_b128 v[92:95], v252 offset:6144
	v_mfma_f32_16x16x32_bf16 v[60:63], v[124:127], v[180:183], v[60:63]
	v_mfma_f32_16x16x32_bf16 v[56:59], v[124:127], v[184:187], v[56:59]
	v_mfma_f32_16x16x32_bf16 v[52:55], v[124:127], v[188:191], v[52:55]
	v_mfma_f32_16x16x32_bf16 v[48:51], v[124:127], v[192:195], v[48:51]
	v_mfma_f32_16x16x32_bf16 v[44:47], v[132:135], v[180:183], v[44:47]
	v_mfma_f32_16x16x32_bf16 v[40:43], v[132:135], v[184:187], v[40:43]
	v_mfma_f32_16x16x32_bf16 v[36:39], v[132:135], v[188:191], v[36:39]
	v_mfma_f32_16x16x32_bf16 v[28:31], v[132:135], v[192:195], v[28:31]
	v_mfma_f32_16x16x32_bf16 v[16:19], v[136:139], v[180:183], v[16:19]
	v_mfma_f32_16x16x32_bf16 v[12:15], v[136:139], v[184:187], v[12:15]
	v_mfma_f32_16x16x32_bf16 v[4:7], v[136:139], v[188:191], v[4:7]
	v_mfma_f32_16x16x32_bf16 v[8:11], v[136:139], v[192:195], v[8:11]
	v_mfma_f32_16x16x32_bf16 v[32:35], v[140:143], v[180:183], v[32:35]
	v_mfma_f32_16x16x32_bf16 v[24:27], v[140:143], v[184:187], v[24:27]
	v_mfma_f32_16x16x32_bf16 v[20:23], v[140:143], v[188:191], v[20:23]
	v_mfma_f32_16x16x32_bf16 v[0:3], v[140:143], v[192:195], v[0:3]
	ds_read_b128 v[124:127], v253 offset:0
	ds_read_b128 v[180:183], v255 offset:32768
	ds_read_b128 v[184:187], v255 offset:34816
	ds_read_b128 v[188:191], v255 offset:36864
	ds_read_b128 v[192:195], v255 offset:38912
	ds_read_b128 v[132:135], v253 offset:2048
	ds_read_b128 v[136:139], v253 offset:4096
	ds_read_b128 v[140:143], v253 offset:6144
	s_waitcnt lgkmcnt(14)
	v_mfma_f32_16x16x32_bf16 v[60:63], v[80:83], v[144:147], v[60:63]
	s_waitcnt lgkmcnt(13)
	v_mfma_f32_16x16x32_bf16 v[56:59], v[80:83], v[148:151], v[56:59]
	s_waitcnt lgkmcnt(12)
	v_mfma_f32_16x16x32_bf16 v[52:55], v[80:83], v[152:155], v[52:55]
	s_waitcnt lgkmcnt(11)
	v_mfma_f32_16x16x32_bf16 v[48:51], v[80:83], v[156:159], v[48:51]
	s_waitcnt lgkmcnt(10)
	v_mfma_f32_16x16x32_bf16 v[44:47], v[84:87], v[144:147], v[44:47]
	v_mfma_f32_16x16x32_bf16 v[40:43], v[84:87], v[148:151], v[40:43]
	v_mfma_f32_16x16x32_bf16 v[36:39], v[84:87], v[152:155], v[36:39]
	v_mfma_f32_16x16x32_bf16 v[28:31], v[84:87], v[156:159], v[28:31]
	s_waitcnt lgkmcnt(0)
	s_barrier
	s_add_u32 m0, s7, 0x0
	v_mfma_f32_16x16x32_bf16 v[16:19], v[88:91], v[144:147], v[16:19]
	global_load_lds_dwordx4 v248, s[8:9]
	s_add_u32 m0, s7, 0x400
	v_mfma_f32_16x16x32_bf16 v[12:15], v[88:91], v[148:151], v[12:15]
	global_load_lds_dwordx4 v249, s[8:9]
	s_add_u32 m0, s7, 0x800
	v_mfma_f32_16x16x32_bf16 v[4:7], v[88:91], v[152:155], v[4:7]
	global_load_lds_dwordx4 v250, s[8:9]
	s_add_u32 m0, s7, 0xc00
	v_mfma_f32_16x16x32_bf16 v[8:11], v[88:91], v[156:159], v[8:11]
	global_load_lds_dwordx4 v251, s[8:9]
	s_add_u32 m0, s7, 0x8000
	v_mfma_f32_16x16x32_bf16 v[32:35], v[92:95], v[144:147], v[32:35]
	global_load_lds_dwordx4 v248, s[64:65]
	s_add_u32 m0, s7, 0x8400
	v_mfma_f32_16x16x32_bf16 v[24:27], v[92:95], v[148:151], v[24:27]
	global_load_lds_dwordx4 v249, s[64:65]
	s_add_u32 m0, s7, 0x8800
	v_mfma_f32_16x16x32_bf16 v[20:23], v[92:95], v[152:155], v[20:23]
	global_load_lds_dwordx4 v250, s[64:65]
	s_add_u32 m0, s7, 0x8c00
	v_mfma_f32_16x16x32_bf16 v[0:3], v[92:95], v[156:159], v[0:3]
	global_load_lds_dwordx4 v251, s[64:65]
	s_add_u32 s8, s8, 0x80
	s_addc_u32 s9, s9, 0
	s_add_u32 s64, s64, 0x80
	s_addc_u32 s65, s65, 0
	s_waitcnt vmcnt(8)
	s_barrier
	ds_read_b128 v[80:83], v252 offset:16384
	ds_read_b128 v[144:147], v254 offset:49152
	ds_read_b128 v[148:151], v254 offset:51200
	ds_read_b128 v[152:155], v254 offset:53248
	ds_read_b128 v[156:159], v254 offset:55296
	ds_read_b128 v[84:87], v252 offset:18432
	ds_read_b128 v[88:91], v252 offset:20480
	ds_read_b128 v[92:95], v252 offset:22528
	v_mfma_f32_16x16x32_bf16 v[60:63], v[124:127], v[180:183], v[60:63]
	v_mfma_f32_16x16x32_bf16 v[56:59], v[124:127], v[184:187], v[56:59]
	v_mfma_f32_16x16x32_bf16 v[52:55], v[124:127], v[188:191], v[52:55]
	v_mfma_f32_16x16x32_bf16 v[48:51], v[124:127], v[192:195], v[48:51]
	v_mfma_f32_16x16x32_bf16 v[44:47], v[132:135], v[180:183], v[44:47]
	v_mfma_f32_16x16x32_bf16 v[40:43], v[132:135], v[184:187], v[40:43]
	v_mfma_f32_16x16x32_bf16 v[36:39], v[132:135], v[188:191], v[36:39]
	v_mfma_f32_16x16x32_bf16 v[28:31], v[132:135], v[192:195], v[28:31]
	v_mfma_f32_16x16x32_bf16 v[16:19], v[136:139], v[180:183], v[16:19]
	v_mfma_f32_16x16x32_bf16 v[12:15], v[136:139], v[184:187], v[12:15]
	v_mfma_f32_16x16x32_bf16 v[4:7], v[136:139], v[188:191], v[4:7]
	v_mfma_f32_16x16x32_bf16 v[8:11], v[136:139], v[192:195], v[8:11]
	v_mfma_f32_16x16x32_bf16 v[32:35], v[140:143], v[180:183], v[32:35]
	v_mfma_f32_16x16x32_bf16 v[24:27], v[140:143], v[184:187], v[24:27]
	v_mfma_f32_16x16x32_bf16 v[20:23], v[140:143], v[188:191], v[20:23]
	v_mfma_f32_16x16x32_bf16 v[0:3], v[140:143], v[192:195], v[0:3]
	ds_read_b128 v[124:127], v253 offset:16384
	ds_read_b128 v[180:183], v255 offset:49152
	ds_read_b128 v[184:187], v255 offset:51200
	ds_read_b128 v[188:191], v255 offset:53248
	ds_read_b128 v[192:195], v255 offset:55296
	ds_read_b128 v[132:135], v253 offset:18432
	ds_read_b128 v[136:139], v253 offset:20480
	ds_read_b128 v[140:143], v253 offset:22528
	s_waitcnt lgkmcnt(14)
	v_mfma_f32_16x16x32_bf16 v[60:63], v[80:83], v[144:147], v[60:63]
	s_waitcnt lgkmcnt(13)
	v_mfma_f32_16x16x32_bf16 v[56:59], v[80:83], v[148:151], v[56:59]
	s_waitcnt lgkmcnt(12)
	v_mfma_f32_16x16x32_bf16 v[52:55], v[80:83], v[152:155], v[52:55]
	s_waitcnt lgkmcnt(11)
	v_mfma_f32_16x16x32_bf16 v[48:51], v[80:83], v[156:159], v[48:51]
	s_waitcnt lgkmcnt(10)
	v_mfma_f32_16x16x32_bf16 v[44:47], v[84:87], v[144:147], v[44:47]
	v_mfma_f32_16x16x32_bf16 v[40:43], v[84:87], v[148:151], v[40:43]
	v_mfma_f32_16x16x32_bf16 v[36:39], v[84:87], v[152:155], v[36:39]
	v_mfma_f32_16x16x32_bf16 v[28:31], v[84:87], v[156:159], v[28:31]
	s_waitcnt lgkmcnt(0)
	s_barrier
	s_add_u32 m0, s7, 0x4000
	v_mfma_f32_16x16x32_bf16 v[16:19], v[88:91], v[144:147], v[16:19]
	global_load_lds_dwordx4 v248, s[8:9]
	s_add_u32 m0, s7, 0x4400
	v_mfma_f32_16x16x32_bf16 v[12:15], v[88:91], v[148:151], v[12:15]
	global_load_lds_dwordx4 v249, s[8:9]
	s_add_u32 m0, s7, 0x4800
	v_mfma_f32_16x16x32_bf16 v[4:7], v[88:91], v[152:155], v[4:7]
	global_load_lds_dwordx4 v250, s[8:9]
	s_add_u32 m0, s7, 0x4c00
	v_mfma_f32_16x16x32_bf16 v[8:11], v[88:91], v[156:159], v[8:11]
	global_load_lds_dwordx4 v251, s[8:9]
	s_add_u32 m0, s7, 0xc000
	v_mfma_f32_16x16x32_bf16 v[32:35], v[92:95], v[144:147], v[32:35]
	global_load_lds_dwordx4 v248, s[64:65]
	s_add_u32 m0, s7, 0xc400
	v_mfma_f32_16x16x32_bf16 v[24:27], v[92:95], v[148:151], v[24:27]
	global_load_lds_dwordx4 v249, s[64:65]
	s_add_u32 m0, s7, 0xc800
	v_mfma_f32_16x16x32_bf16 v[20:23], v[92:95], v[152:155], v[20:23]
	global_load_lds_dwordx4 v250, s[64:65]
	s_add_u32 m0, s7, 0xcc00
	v_mfma_f32_16x16x32_bf16 v[0:3], v[92:95], v[156:159], v[0:3]
	global_load_lds_dwordx4 v251, s[64:65]
	s_add_u32 s8, s8, 0x80
	s_addc_u32 s9, s9, 0
	s_add_u32 s64, s64, 0x80
	s_addc_u32 s65, s65, 0
	s_sub_u32 s32, s32, 1
	s_cmp_lg_u32 s32, 0
	s_cbranch_scc1 .Lg18_loop
	s_waitcnt vmcnt(8)
	s_barrier
	ds_read_b128 v[80:83], v252 offset:0
	ds_read_b128 v[144:147], v254 offset:32768
	ds_read_b128 v[148:151], v254 offset:34816
	ds_read_b128 v[152:155], v254 offset:36864
	ds_read_b128 v[156:159], v254 offset:38912
	ds_read_b128 v[84:87], v252 offset:2048
	ds_read_b128 v[88:91], v252 offset:4096
	ds_read_b128 v[92:95], v252 offset:6144
	v_mfma_f32_16x16x32_bf16 v[60:63], v[124:127], v[180:183], v[60:63]
	v_mfma_f32_16x16x32_bf16 v[56:59], v[124:127], v[184:187], v[56:59]
	v_mfma_f32_16x16x32_bf16 v[52:55], v[124:127], v[188:191], v[52:55]
	v_mfma_f32_16x16x32_bf16 v[48:51], v[124:127], v[192:195], v[48:51]
	v_mfma_f32_16x16x32_bf16 v[44:47], v[132:135], v[180:183], v[44:47]
	v_mfma_f32_16x16x32_bf16 v[40:43], v[132:135], v[184:187], v[40:43]
	v_mfma_f32_16x16x32_bf16 v[36:39], v[132:135], v[188:191], v[36:39]
	v_mfma_f32_16x16x32_bf16 v[28:31], v[132:135], v[192:195], v[28:31]
	v_mfma_f32_16x16x32_bf16 v[16:19], v[136:139], v[180:183], v[16:19]
	v_mfma_f32_16x16x32_bf16 v[12:15], v[136:139], v[184:187], v[12:15]
	v_mfma_f32_16x16x32_bf16 v[4:7], v[136:139], v[188:191], v[4:7]
	v_mfma_f32_16x16x32_bf16 v[8:11], v[136:139], v[192:195], v[8:11]
	v_mfma_f32_16x16x32_bf16 v[32:35], v[140:143], v[180:183], v[32:35]
	v_mfma_f32_16x16x32_bf16 v[24:27], v[140:143], v[184:187], v[24:27]
	v_mfma_f32_16x16x32_bf16 v[20:23], v[140:143], v[188:191], v[20:23]
	v_mfma_f32_16x16x32_bf16 v[0:3], v[140:143], v[192:195], v[0:3]
	ds_read_b128 v[124:127], v253 offset:0
	ds_read_b128 v[180:183], v255 offset:32768
	ds_read_b128 v[184:187], v255 offset:34816
	ds_read_b128 v[188:191], v255 offset:36864
	ds_read_b128 v[192:195], v255 offset:38912
	ds_read_b128 v[132:135], v253 offset:2048
	ds_read_b128 v[136:139], v253 offset:4096
	ds_read_b128 v[140:143], v253 offset:6144
	s_waitcnt lgkmcnt(14)
	v_mfma_f32_16x16x32_bf16 v[60:63], v[80:83], v[144:147], v[60:63]
	s_waitcnt lgkmcnt(13)
	v_mfma_f32_16x16x32_bf16 v[56:59], v[80:83], v[148:151], v[56:59]
	s_waitcnt lgkmcnt(12)
	v_mfma_f32_16x16x32_bf16 v[52:55], v[80:83], v[152:155], v[52:55]
	s_waitcnt lgkmcnt(11)
	v_mfma_f32_16x16x32_bf16 v[48:51], v[80:83], v[156:159], v[48:51]
	s_waitcnt lgkmcnt(10)
	v_mfma_f32_16x16x32_bf16 v[44:47], v[84:87], v[144:147], v[44:47]
	v_mfma_f32_16x16x32_bf16 v[40:43], v[84:87], v[148:151], v[40:43]
	v_mfma_f32_16x16x32_bf16 v[36:39], v[84:87], v[152:155], v[36:39]
	v_mfma_f32_16x16x32_bf16 v[28:31], v[84:87], v[156:159], v[28:31]
	s_waitcnt lgkmcnt(0)
	s_barrier
	v_mfma_f32_16x16x32_bf16 v[16:19], v[88:91], v[144:147], v[16:19]
	v_mfma_f32_16x16x32_bf16 v[12:15], v[88:91], v[148:151], v[12:15]
	v_mfma_f32_16x16x32_bf16 v[4:7], v[88:91], v[152:155], v[4:7]
	v_mfma_f32_16x16x32_bf16 v[8:11], v[88:91], v[156:159], v[8:11]
	v_mfma_f32_16x16x32_bf16 v[32:35], v[92:95], v[144:147], v[32:35]
	v_mfma_f32_16x16x32_bf16 v[24:27], v[92:95], v[148:151], v[24:27]
	v_mfma_f32_16x16x32_bf16 v[20:23], v[92:95], v[152:155], v[20:23]
	v_mfma_f32_16x16x32_bf16 v[0:3], v[92:95], v[156:159], v[0:3]
	s_waitcnt vmcnt(0)
	s_barrier
	ds_read_b128 v[80:83], v252 offset:16384
	ds_read_b128 v[144:147], v254 offset:49152
	ds_read_b128 v[148:151], v254 offset:51200
	ds_read_b128 v[152:155], v254 offset:53248
	ds_read_b128 v[156:159], v254 offset:55296
	ds_read_b128 v[84:87], v252 offset:18432
	ds_read_b128 v[88:91], v252 offset:20480
	ds_read_b128 v[92:95], v252 offset:22528
	v_mfma_f32_16x16x32_bf16 v[60:63], v[124:127], v[180:183], v[60:63]
	v_mfma_f32_16x16x32_bf16 v[56:59], v[124:127], v[184:187], v[56:59]
	v_mfma_f32_16x16x32_bf16 v[52:55], v[124:127], v[188:191], v[52:55]
	v_mfma_f32_16x16x32_bf16 v[48:51], v[124:127], v[192:195], v[48:51]
	v_mfma_f32_16x16x32_bf16 v[44:47], v[132:135], v[180:183], v[44:47]
	v_mfma_f32_16x16x32_bf16 v[40:43], v[132:135], v[184:187], v[40:43]
	v_mfma_f32_16x16x32_bf16 v[36:39], v[132:135], v[188:191], v[36:39]
	v_mfma_f32_16x16x32_bf16 v[28:31], v[132:135], v[192:195], v[28:31]
	v_mfma_f32_16x16x32_bf16 v[16:19], v[136:139], v[180:183], v[16:19]
	v_mfma_f32_16x16x32_bf16 v[12:15], v[136:139], v[184:187], v[12:15]
	v_mfma_f32_16x16x32_bf16 v[4:7], v[136:139], v[188:191], v[4:7]
	v_mfma_f32_16x16x32_bf16 v[8:11], v[136:139], v[192:195], v[8:11]
	v_mfma_f32_16x16x32_bf16 v[32:35], v[140:143], v[180:183], v[32:35]
	v_mfma_f32_16x16x32_bf16 v[24:27], v[140:143], v[184:187], v[24:27]
	v_mfma_f32_16x16x32_bf16 v[20:23], v[140:143], v[188:191], v[20:23]
	v_mfma_f32_16x16x32_bf16 v[0:3], v[140:143], v[192:195], v[0:3]
	ds_read_b128 v[124:127], v253 offset:16384
	ds_read_b128 v[180:183], v255 offset:49152
	ds_read_b128 v[184:187], v255 offset:51200
	ds_read_b128 v[188:191], v255 offset:53248
	ds_read_b128 v[192:195], v255 offset:55296
	ds_read_b128 v[132:135], v253 offset:18432
	ds_read_b128 v[136:139], v253 offset:20480
	ds_read_b128 v[140:143], v253 offset:22528
	s_waitcnt lgkmcnt(14)
	v_mfma_f32_16x16x32_bf16 v[60:63], v[80:83], v[144:147], v[60:63]
	s_waitcnt lgkmcnt(13)
	v_mfma_f32_16x16x32_bf16 v[56:59], v[80:83], v[148:151], v[56:59]
	s_waitcnt lgkmcnt(12)
	v_mfma_f32_16x16x32_bf16 v[52:55], v[80:83], v[152:155], v[52:55]
	s_waitcnt lgkmcnt(11)
	v_mfma_f32_16x16x32_bf16 v[48:51], v[80:83], v[156:159], v[48:51]
	s_waitcnt lgkmcnt(10)
	v_mfma_f32_16x16x32_bf16 v[44:47], v[84:87], v[144:147], v[44:47]
	v_mfma_f32_16x16x32_bf16 v[40:43], v[84:87], v[148:151], v[40:43]
	v_mfma_f32_16x16x32_bf16 v[36:39], v[84:87], v[152:155], v[36:39]
	v_mfma_f32_16x16x32_bf16 v[28:31], v[84:87], v[156:159], v[28:31]
	s_waitcnt lgkmcnt(0)
	s_barrier
	v_mfma_f32_16x16x32_bf16 v[16:19], v[88:91], v[144:147], v[16:19]
	v_mfma_f32_16x16x32_bf16 v[12:15], v[88:91], v[148:151], v[12:15]
	v_mfma_f32_16x16x32_bf16 v[4:7], v[88:91], v[152:155], v[4:7]
	v_mfma_f32_16x16x32_bf16 v[8:11], v[88:91], v[156:159], v[8:11]
	v_mfma_f32_16x16x32_bf16 v[32:35], v[92:95], v[144:147], v[32:35]
	v_mfma_f32_16x16x32_bf16 v[24:27], v[92:95], v[148:151], v[24:27]
	v_mfma_f32_16x16x32_bf16 v[20:23], v[92:95], v[152:155], v[20:23]
	v_mfma_f32_16x16x32_bf16 v[0:3], v[92:95], v[156:159], v[0:3]
	v_mfma_f32_16x16x32_bf16 v[60:63], v[124:127], v[180:183], v[60:63]
	v_mfma_f32_16x16x32_bf16 v[56:59], v[124:127], v[184:187], v[56:59]
	v_mfma_f32_16x16x32_bf16 v[52:55], v[124:127], v[188:191], v[52:55]
	v_mfma_f32_16x16x32_bf16 v[48:51], v[124:127], v[192:195], v[48:51]
	v_mfma_f32_16x16x32_bf16 v[44:47], v[132:135], v[180:183], v[44:47]
	v_mfma_f32_16x16x32_bf16 v[40:43], v[132:135], v[184:187], v[40:43]
	v_mfma_f32_16x16x32_bf16 v[36:39], v[132:135], v[188:191], v[36:39]
	v_mfma_f32_16x16x32_bf16 v[28:31], v[132:135], v[192:195], v[28:31]
	v_mfma_f32_16x16x32_bf16 v[16:19], v[136:139], v[180:183], v[16:19]
	v_mfma_f32_16x16x32_bf16 v[12:15], v[136:139], v[184:187], v[12:15]
	v_mfma_f32_16x16x32_bf16 v[4:7], v[136:139], v[188:191], v[4:7]
	v_mfma_f32_16x16x32_bf16 v[8:11], v[136:139], v[192:195], v[8:11]
	v_mfma_f32_16x16x32_bf16 v[32:35], v[140:143], v[180:183], v[32:35]
	v_mfma_f32_16x16x32_bf16 v[24:27], v[140:143], v[184:187], v[24:27]
	v_mfma_f32_16x16x32_bf16 v[20:23], v[140:143], v[188:191], v[20:23]
	v_mfma_f32_16x16x32_bf16 v[0:3], v[140:143], v[192:195], v[0:3]
	s_nop 7
	s_nop 1
	v_add_u32_e32 v80, s12, v174
	v_or_b32_e32 v64, s6, v175
	s_cmpk_gt_i32 s6, 0x3ff
	s_mov_b64 s[6:7], -1
	s_cbranch_scc0 .LBB0_1789
	s_cmpk_gt_u32 s13, 0xbff
	s_cbranch_scc0 .LBB0_1786
	s_cmpk_gt_u32 s13, 0x13ff
	s_cbranch_scc0 .LBB0_1609
	s_cmpk_gt_u32 s13, 0x17ff
	s_cbranch_scc0 .LBB0_1590
	s_and_saveexec_b64 s[6:7], s[4:5]
	s_cbranch_execz .LBB0_1589
	v_lshlrev_b32_e32 v98, 7, v80
	v_lshl_add_u64 v[66:67], v[104:105], 0, v[98:99]
	global_store_dword v[66:67], v60, off
	global_store_dword v[66:67], v61, off offset:128
	global_store_dword v[66:67], v62, off offset:256
	global_store_dword v[66:67], v63, off offset:384
	global_store_dword v[66:67], v56, off offset:64
	global_store_dword v[66:67], v57, off offset:192
	global_store_dword v[66:67], v58, off offset:320
	global_store_dword v[66:67], v59, off offset:448
	global_store_dword v[66:67], v44, off offset:2048
	global_store_dword v[66:67], v45, off offset:2176
	global_store_dword v[66:67], v46, off offset:2304
	global_store_dword v[66:67], v47, off offset:2432
	global_store_dword v[66:67], v40, off offset:2112
	global_store_dword v[66:67], v41, off offset:2240
	global_store_dword v[66:67], v42, off offset:2368
	global_store_dword v[66:67], v43, off offset:2496
	v_or_b32_e32 v66, 0x1000, v98
	v_mov_b32_e32 v67, v99
	v_lshl_add_u64 v[68:69], v[104:105], 0, v[66:67]
	global_store_dword v[68:69], v16, off
	v_or_b32_e32 v68, 0x1080, v98
	v_mov_b32_e32 v69, v99
	v_lshl_add_u64 v[70:71], v[104:105], 0, v[68:69]
	global_store_dword v[70:71], v17, off
	v_or_b32_e32 v70, 0x1100, v98
	v_mov_b32_e32 v71, v99
	v_lshl_add_u64 v[66:67], v[106:107], 0, v[66:67]
	v_lshl_add_u64 v[72:73], v[104:105], 0, v[70:71]
	global_store_dword v[66:67], v12, off
	v_lshl_add_u64 v[66:67], v[106:107], 0, v[68:69]
	global_store_dword v[72:73], v18, off
	v_or_b32_e32 v72, 0x1180, v98
	v_mov_b32_e32 v73, v99
	global_store_dword v[66:67], v13, off
	v_lshl_add_u64 v[66:67], v[106:107], 0, v[70:71]
	global_store_dword v[66:67], v14, off
	v_lshl_add_u64 v[66:67], v[106:107], 0, v[72:73]
	global_store_dword v[66:67], v15, off
	v_or_b32_e32 v66, 0x1800, v98
	v_mov_b32_e32 v67, v99
	v_lshl_add_u64 v[68:69], v[104:105], 0, v[66:67]
	global_store_dword v[68:69], v32, off
	v_or_b32_e32 v68, 0x1880, v98
	v_mov_b32_e32 v69, v99
	v_lshl_add_u64 v[70:71], v[104:105], 0, v[68:69]
	v_lshl_add_u64 v[66:67], v[106:107], 0, v[66:67]
	global_store_dword v[70:71], v33, off
	v_or_b32_e32 v70, 0x1900, v98
	v_mov_b32_e32 v71, v99
	global_store_dword v[66:67], v24, off
	v_lshl_add_u64 v[66:67], v[106:107], 0, v[68:69]
	v_lshl_add_u64 v[74:75], v[104:105], 0, v[72:73]
	v_lshl_add_u64 v[72:73], v[104:105], 0, v[70:71]
	v_or_b32_e32 v98, 0x1980, v98
	global_store_dword v[66:67], v25, off
	v_lshl_add_u64 v[66:67], v[106:107], 0, v[70:71]
	global_store_dword v[72:73], v34, off
	v_lshl_add_u64 v[72:73], v[104:105], 0, v[98:99]
	global_store_dword v[66:67], v26, off
	v_lshl_add_u64 v[66:67], v[106:107], 0, v[98:99]
	global_store_dword v[74:75], v19, off
	global_store_dword v[72:73], v35, off
	global_store_dword v[66:67], v27, off

.LBB0_1845:
	s_cmp_gt_i32 s60, 19
	s_cselect_b64 s[2:3], -1, 0
	s_cmp_lt_i32 s61, 19
	s_cselect_b64 s[4:5], -1, 0
	s_or_b64 s[2:3], s[2:3], s[4:5]
	s_and_b64 vcc, exec, s[2:3]
	s_cbranch_vccnz .LBB0_1918
	s_mov_b64 s[12:13], s[0:1]
	s_load_dword s2, s[0:1], 0xf0
	s_load_dwordx2 s[10:11], s[12:13], 0xe0
	s_add_u32 s6, s0, 0xf0
	s_mov_b32 s3, 0x200000
	s_addc_u32 s7, s1, 0
	s_waitcnt lgkmcnt(0)
	s_lshl_b32 s8, s2, 8
	v_cmp_gt_i32_e32 vcc, s3, v128
	s_and_saveexec_b64 s[14:15], vcc
	s_cbranch_execz .LBB0_1859
	s_load_dwordx4 s[48:51], s[0:1], 0x68
	s_load_dword s64, s[0:1], 0xf0
	v_lshlrev_b32_e32 v25, 4, v162
	v_lshlrev_b32_e32 v26, 5, v162
	s_waitcnt lgkmcnt(0)
	s_add_u32 s48, s48, 0xa000
	s_addc_u32 s49, s49, 0
	s_add_u32 s50, s50, 0x2000
	s_addc_u32 s51, s51, 0
	global_load_dwordx4 v[28:31], v26, s[48:49]
	global_load_dwordx4 v[32:35], v26, s[48:49] offset:16
	s_add_u32 s48, s48, 0x2000
	s_addc_u32 s49, s49, 0
	global_load_dwordx4 v[36:39], v26, s[48:49]
	global_load_dwordx4 v[40:43], v26, s[48:49] offset:16
	s_add_u32 s48, s48, 0x2000
	s_addc_u32 s49, s49, 0
	global_load_dwordx4 v[44:47], v26, s[48:49]
	global_load_dwordx4 v[48:51], v26, s[48:49] offset:16
	s_add_u32 s48, s48, 0x2000
	s_addc_u32 s49, s49, 0
	global_load_dwordx4 v[52:55], v26, s[48:49]
	global_load_dwordx4 v[56:59], v26, s[48:49] offset:16
	s_add_u32 s48, s48, 0x2000
	s_addc_u32 s49, s49, 0
	global_load_dwordx4 v[60:63], v26, s[48:49]
	global_load_dwordx4 v[64:67], v26, s[48:49] offset:16
	global_load_dwordx4 v[68:71], v26, s[50:51]
	global_load_dwordx4 v[72:75], v26, s[50:51] offset:16
	s_mov_b32 s3, s58
.Lcv19_rb:
	s_cmp_lt_u32 s3, 0x200
	s_cbranch_scc0 .Lcv19_end
	s_lshl_b32 s32, s3, 4
	s_cmp_lt_u32 s32, 0x1000
	s_mov_b32 s59, 0x3ff
	s_cselect_b32 s59, 0xff, s59
	s_and_b32 s65, s32, s59
	s_cmp_lg_u32 s65, 0
	s_cselect_b32 s62, -1, 0
	s_add_u32 s65, s65, 15
	s_cmp_lg_u32 s65, s59
	s_cselect_b32 s63, -1, 0
	s_lshl_b32 s65, s32, 12
	s_add_u32 s4, s10, 0xab7a100
	s_addc_u32 s5, s11, 0
	s_add_u32 s4, s4, s65
	s_addc_u32 s5, s5, 0
	s_sub_u32 s4, s4, 0x2000
	s_subb_u32 s5, s5, 0
	s_add_u32 s54, s10, 0x1037a100
	s_addc_u32 s55, s11, 0
	s_add_u32 s54, s54, s65
	s_addc_u32 s55, s55, 0
	global_load_dwordx4 v[76:79], v25, s[4:5]
	s_add_u32 s4, s4, 0x1000
	s_addc_u32 s5, s5, 0
	global_load_dwordx4 v[80:83], v25, s[4:5]
	s_add_u32 s4, s4, 0x1000
	s_addc_u32 s5, s5, 0
	global_load_dwordx4 v[84:87], v25, s[4:5]
	s_add_u32 s4, s4, 0x1000
	s_addc_u32 s5, s5, 0
	global_load_dwordx4 v[88:91], v25, s[4:5]
	s_add_u32 s4, s4, 0x1000
	s_addc_u32 s5, s5, 0
	global_load_dwordx4 v[92:95], v25, s[4:5]
	s_add_u32 s4, s4, 0x1000
	s_addc_u32 s5, s5, 0
	global_load_dwordx4 v[96:99], v25, s[4:5]
	s_add_u32 s4, s4, 0x1000
	s_addc_u32 s5, s5, 0
	global_load_dwordx4 v[100:103], v25, s[4:5]
	s_add_u32 s4, s4, 0x1000
	s_addc_u32 s5, s5, 0
	global_load_dwordx4 v[104:107], v25, s[4:5]
	s_add_u32 s4, s4, 0x1000
	s_addc_u32 s5, s5, 0
	global_load_dwordx4 v[108:111], v25, s[4:5]
	s_add_u32 s4, s4, 0x1000
	s_addc_u32 s5, s5, 0
	global_load_dwordx4 v[112:115], v25, s[4:5]
	s_add_u32 s4, s4, 0x1000
	s_addc_u32 s5, s5, 0
	global_load_dwordx4 v[116:119], v25, s[4:5]
	s_add_u32 s4, s4, 0x1000
	s_addc_u32 s5, s5, 0
	global_load_dwordx4 v[120:123], v25, s[4:5]
	s_add_u32 s4, s4, 0x1000
	s_addc_u32 s5, s5, 0
	global_load_dwordx4 v[124:127], v25, s[4:5]
	s_add_u32 s4, s4, 0x1000
	s_addc_u32 s5, s5, 0
	global_load_dwordx4 v[132:135], v25, s[4:5]
	s_add_u32 s4, s4, 0x1000
	s_addc_u32 s5, s5, 0
	global_load_dwordx4 v[136:139], v25, s[4:5]
	s_add_u32 s4, s4, 0x1000
	s_addc_u32 s5, s5, 0
	global_load_dwordx4 v[140:143], v25, s[4:5]
	s_add_u32 s4, s4, 0x1000
	s_addc_u32 s5, s5, 0
	global_load_dwordx4 v[144:147], v25, s[4:5]
	s_add_u32 s4, s4, 0x1000
	s_addc_u32 s5, s5, 0
	global_load_dwordx4 v[148:151], v25, s[4:5]
	s_add_u32 s4, s4, 0x1000
	s_addc_u32 s5, s5, 0
	global_load_dwordx4 v[152:155], v25, s[4:5]
	s_add_u32 s4, s4, 0x1000
	s_addc_u32 s5, s5, 0
	global_load_dwordx4 v[156:159], v25, s[4:5]
	s_waitcnt vmcnt(19)
	v_and_b32_e32 v76, s62, v76
	v_and_b32_e32 v77, s62, v77
	v_and_b32_e32 v78, s62, v78
	v_and_b32_e32 v79, s62, v79
	v_lshlrev_b32_e32 v172, 16, v76
	v_and_b32_e32 v173, 0xffff0000, v76
	v_lshlrev_b32_e32 v174, 16, v77
	v_and_b32_e32 v175, 0xffff0000, v77
	v_lshlrev_b32_e32 v176, 16, v78
	v_and_b32_e32 v177, 0xffff0000, v78
	v_lshlrev_b32_e32 v178, 16, v79
	v_and_b32_e32 v179, 0xffff0000, v79
	v_pk_fma_f32 v[180:181], v[28:29], v[172:173], v[68:69]
	v_pk_fma_f32 v[182:183], v[30:31], v[174:175], v[70:71]
	v_pk_fma_f32 v[184:185], v[32:33], v[176:177], v[72:73]
	v_pk_fma_f32 v[186:187], v[34:35], v[178:179], v[74:75]
	s_waitcnt vmcnt(18)
	v_and_b32_e32 v80, s62, v80
	v_and_b32_e32 v81, s62, v81
	v_and_b32_e32 v82, s62, v82
	v_and_b32_e32 v83, s62, v83
	v_lshlrev_b32_e32 v172, 16, v80
	v_and_b32_e32 v173, 0xffff0000, v80
	v_lshlrev_b32_e32 v174, 16, v81
	v_and_b32_e32 v175, 0xffff0000, v81
	v_lshlrev_b32_e32 v176, 16, v82
	v_and_b32_e32 v177, 0xffff0000, v82
	v_lshlrev_b32_e32 v178, 16, v83
	v_and_b32_e32 v179, 0xffff0000, v83
	v_pk_fma_f32 v[188:189], v[28:29], v[172:173], v[68:69]
	v_pk_fma_f32 v[190:191], v[30:31], v[174:175], v[70:71]
	v_pk_fma_f32 v[192:193], v[32:33], v[176:177], v[72:73]
	v_pk_fma_f32 v[194:195], v[34:35], v[178:179], v[74:75]
	v_pk_fma_f32 v[180:181], v[36:37], v[172:173], v[180:181]
	v_pk_fma_f32 v[182:183], v[38:39], v[174:175], v[182:183]
	v_pk_fma_f32 v[184:185], v[40:41], v[176:177], v[184:185]
	v_pk_fma_f32 v[186:187], v[42:43], v[178:179], v[186:187]
	s_waitcnt vmcnt(17)
	v_lshlrev_b32_e32 v172, 16, v84
	v_and_b32_e32 v173, 0xffff0000, v84
	v_lshlrev_b32_e32 v174, 16, v85
	v_and_b32_e32 v175, 0xffff0000, v85
	v_lshlrev_b32_e32 v176, 16, v86
	v_and_b32_e32 v177, 0xffff0000, v86
	v_lshlrev_b32_e32 v178, 16, v87
	v_and_b32_e32 v179, 0xffff0000, v87
	v_pk_fma_f32 v[196:197], v[28:29], v[172:173], v[68:69]
	v_pk_fma_f32 v[198:199], v[30:31], v[174:175], v[70:71]
	v_pk_fma_f32 v[200:201], v[32:33], v[176:177], v[72:73]
	v_pk_fma_f32 v[202:203], v[34:35], v[178:179], v[74:75]
	v_pk_fma_f32 v[188:189], v[36:37], v[172:173], v[188:189]
	v_pk_fma_f32 v[190:191], v[38:39], v[174:175], v[190:191]
	v_pk_fma_f32 v[192:193], v[40:41], v[176:177], v[192:193]
	v_pk_fma_f32 v[194:195], v[42:43], v[178:179], v[194:195]
	v_pk_fma_f32 v[180:181], v[44:45], v[172:173], v[180:181]
	v_pk_fma_f32 v[182:183], v[46:47], v[174:175], v[182:183]
	v_pk_fma_f32 v[184:185], v[48:49], v[176:177], v[184:185]
	v_pk_fma_f32 v[186:187], v[50:51], v[178:179], v[186:187]
	s_waitcnt vmcnt(16)
	v_lshlrev_b32_e32 v172, 16, v88
	v_and_b32_e32 v173, 0xffff0000, v88
	v_lshlrev_b32_e32 v174, 16, v89
	v_and_b32_e32 v175, 0xffff0000, v89
	v_lshlrev_b32_e32 v176, 16, v90
	v_and_b32_e32 v177, 0xffff0000, v90
	v_lshlrev_b32_e32 v178, 16, v91
	v_and_b32_e32 v179, 0xffff0000, v91
	v_pk_fma_f32 v[204:205], v[28:29], v[172:173], v[68:69]
	v_pk_fma_f32 v[206:207], v[30:31], v[174:175], v[70:71]
	v_pk_fma_f32 v[208:209], v[32:33], v[176:177], v[72:73]
	v_pk_fma_f32 v[210:211], v[34:35], v[178:179], v[74:75]
	v_pk_fma_f32 v[196:197], v[36:37], v[172:173], v[196:197]
	v_pk_fma_f32 v[198:199], v[38:39], v[174:175], v[198:199]
	v_pk_fma_f32 v[200:201], v[40:41], v[176:177], v[200:201]
	v_pk_fma_f32 v[202:203], v[42:43], v[178:179], v[202:203]
	v_pk_fma_f32 v[188:189], v[44:45], v[172:173], v[188:189]
	v_pk_fma_f32 v[190:191], v[46:47], v[174:175], v[190:191]
	v_pk_fma_f32 v[192:193], v[48:49], v[176:177], v[192:193]
	v_pk_fma_f32 v[194:195], v[50:51], v[178:179], v[194:195]
	v_pk_fma_f32 v[180:181], v[52:53], v[172:173], v[180:181]
	v_pk_fma_f32 v[182:183], v[54:55], v[174:175], v[182:183]
	v_pk_fma_f32 v[184:185], v[56:57], v[176:177], v[184:185]
	v_pk_fma_f32 v[186:187], v[58:59], v[178:179], v[186:187]
	s_waitcnt vmcnt(15)
	v_lshlrev_b32_e32 v172, 16, v92
	v_and_b32_e32 v173, 0xffff0000, v92
	v_lshlrev_b32_e32 v174, 16, v93
	v_and_b32_e32 v175, 0xffff0000, v93
	v_lshlrev_b32_e32 v176, 16, v94
	v_and_b32_e32 v177, 0xffff0000, v94
	v_lshlrev_b32_e32 v178, 16, v95
	v_and_b32_e32 v179, 0xffff0000, v95
	v_pk_fma_f32 v[212:213], v[28:29], v[172:173], v[68:69]
	v_pk_fma_f32 v[214:215], v[30:31], v[174:175], v[70:71]
	v_pk_fma_f32 v[216:217], v[32:33], v[176:177], v[72:73]
	v_pk_fma_f32 v[218:219], v[34:35], v[178:179], v[74:75]
	v_pk_fma_f32 v[204:205], v[36:37], v[172:173], v[204:205]
	v_pk_fma_f32 v[206:207], v[38:39], v[174:175], v[206:207]
	v_pk_fma_f32 v[208:209], v[40:41], v[176:177], v[208:209]
	v_pk_fma_f32 v[210:211], v[42:43], v[178:179], v[210:211]
	v_pk_fma_f32 v[196:197], v[44:45], v[172:173], v[196:197]
	v_pk_fma_f32 v[198:199], v[46:47], v[174:175], v[198:199]
	v_pk_fma_f32 v[200:201], v[48:49], v[176:177], v[200:201]
	v_pk_fma_f32 v[202:203], v[50:51], v[178:179], v[202:203]
	v_pk_fma_f32 v[188:189], v[52:53], v[172:173], v[188:189]
	v_pk_fma_f32 v[190:191], v[54:55], v[174:175], v[190:191]
	v_pk_fma_f32 v[192:193], v[56:57], v[176:177], v[192:193]
	v_pk_fma_f32 v[194:195], v[58:59], v[178:179], v[194:195]
	v_pk_fma_f32 v[180:181], v[60:61], v[172:173], v[180:181]
	v_pk_fma_f32 v[182:183], v[62:63], v[174:175], v[182:183]
	v_pk_fma_f32 v[184:185], v[64:65], v[176:177], v[184:185]
	v_pk_fma_f32 v[186:187], v[66:67], v[178:179], v[186:187]
	v_mul_f32_e32 v220, 0xbfb8aa3b, v180
	v_mul_f32_e32 v221, 0xbfb8aa3b, v181
	v_mul_f32_e32 v222, 0xbfb8aa3b, v182
	v_mul_f32_e32 v223, 0xbfb8aa3b, v183
	v_mul_f32_e32 v224, 0xbfb8aa3b, v184
	v_mul_f32_e32 v225, 0xbfb8aa3b, v185
	v_mul_f32_e32 v226, 0xbfb8aa3b, v186
	v_mul_f32_e32 v227, 0xbfb8aa3b, v187
	v_exp_f32_e32 v220, v220
	v_exp_f32_e32 v221, v221
	v_exp_f32_e32 v222, v222
	v_exp_f32_e32 v223, v223
	v_exp_f32_e32 v224, v224
	v_exp_f32_e32 v225, v225
	v_exp_f32_e32 v226, v226
	v_exp_f32_e32 v227, v227
	v_add_f32_e32 v220, 1.0, v220
	v_add_f32_e32 v221, 1.0, v221
	v_add_f32_e32 v222, 1.0, v222
	v_add_f32_e32 v223, 1.0, v223
	v_add_f32_e32 v224, 1.0, v224
	v_add_f32_e32 v225, 1.0, v225
	v_add_f32_e32 v226, 1.0, v226
	v_add_f32_e32 v227, 1.0, v227
	v_rcp_f32_e32 v220, v220
	v_rcp_f32_e32 v221, v221
	v_rcp_f32_e32 v222, v222
	v_rcp_f32_e32 v223, v223
	v_rcp_f32_e32 v224, v224
	v_rcp_f32_e32 v225, v225
	v_rcp_f32_e32 v226, v226
	v_rcp_f32_e32 v227, v227
	v_mul_f32_e32 v220, v180, v220
	v_mul_f32_e32 v221, v181, v221
	v_mul_f32_e32 v222, v182, v222
	v_mul_f32_e32 v223, v183, v223
	v_mul_f32_e32 v224, v184, v224
	v_mul_f32_e32 v225, v185, v225
	v_mul_f32_e32 v226, v186, v226
	v_mul_f32_e32 v227, v187, v227
	v_cvt_pk_bf16_f32 v180, v220, v221
	v_cvt_pk_bf16_f32 v181, v222, v223
	v_cvt_pk_bf16_f32 v182, v224, v225
	v_cvt_pk_bf16_f32 v183, v226, v227
	global_store_dwordx4 v25, v[180:183], s[54:55]
	s_add_u32 s54, s54, 0x1000
	s_addc_u32 s55, s55, 0
	s_waitcnt vmcnt(15)
	v_lshlrev_b32_e32 v172, 16, v96
	v_and_b32_e32 v173, 0xffff0000, v96
	v_lshlrev_b32_e32 v174, 16, v97
	v_and_b32_e32 v175, 0xffff0000, v97
	v_lshlrev_b32_e32 v176, 16, v98
	v_and_b32_e32 v177, 0xffff0000, v98
	v_lshlrev_b32_e32 v178, 16, v99
	v_and_b32_e32 v179, 0xffff0000, v99
	v_pk_fma_f32 v[180:181], v[28:29], v[172:173], v[68:69]
	v_pk_fma_f32 v[182:183], v[30:31], v[174:175], v[70:71]
	v_pk_fma_f32 v[184:185], v[32:33], v[176:177], v[72:73]
	v_pk_fma_f32 v[186:187], v[34:35], v[178:179], v[74:75]
	v_pk_fma_f32 v[212:213], v[36:37], v[172:173], v[212:213]
	v_pk_fma_f32 v[214:215], v[38:39], v[174:175], v[214:215]
	v_pk_fma_f32 v[216:217], v[40:41], v[176:177], v[216:217]
	v_pk_fma_f32 v[218:219], v[42:43], v[178:179], v[218:219]
	v_pk_fma_f32 v[204:205], v[44:45], v[172:173], v[204:205]
	v_pk_fma_f32 v[206:207], v[46:47], v[174:175], v[206:207]
	v_pk_fma_f32 v[208:209], v[48:49], v[176:177], v[208:209]
	v_pk_fma_f32 v[210:211], v[50:51], v[178:179], v[210:211]
	v_pk_fma_f32 v[196:197], v[52:53], v[172:173], v[196:197]
	v_pk_fma_f32 v[198:199], v[54:55], v[174:175], v[198:199]
	v_pk_fma_f32 v[200:201], v[56:57], v[176:177], v[200:201]
	v_pk_fma_f32 v[202:203], v[58:59], v[178:179], v[202:203]
	v_pk_fma_f32 v[188:189], v[60:61], v[172:173], v[188:189]
	v_pk_fma_f32 v[190:191], v[62:63], v[174:175], v[190:191]
	v_pk_fma_f32 v[192:193], v[64:65], v[176:177], v[192:193]
	v_pk_fma_f32 v[194:195], v[66:67], v[178:179], v[194:195]
	v_mul_f32_e32 v220, 0xbfb8aa3b, v188
	v_mul_f32_e32 v221, 0xbfb8aa3b, v189
	v_mul_f32_e32 v222, 0xbfb8aa3b, v190
	v_mul_f32_e32 v223, 0xbfb8aa3b, v191
	v_mul_f32_e32 v224, 0xbfb8aa3b, v192
	v_mul_f32_e32 v225, 0xbfb8aa3b, v193
	v_mul_f32_e32 v226, 0xbfb8aa3b, v194
	v_mul_f32_e32 v227, 0xbfb8aa3b, v195
	v_exp_f32_e32 v220, v220
	v_exp_f32_e32 v221, v221
	v_exp_f32_e32 v222, v222
	v_exp_f32_e32 v223, v223
	v_exp_f32_e32 v224, v224
	v_exp_f32_e32 v225, v225
	v_exp_f32_e32 v226, v226
	v_exp_f32_e32 v227, v227
	v_add_f32_e32 v220, 1.0, v220
	v_add_f32_e32 v221, 1.0, v221
	v_add_f32_e32 v222, 1.0, v222
	v_add_f32_e32 v223, 1.0, v223
	v_add_f32_e32 v224, 1.0, v224
	v_add_f32_e32 v225, 1.0, v225
	v_add_f32_e32 v226, 1.0, v226
	v_add_f32_e32 v227, 1.0, v227
	v_rcp_f32_e32 v220, v220
	v_rcp_f32_e32 v221, v221
	v_rcp_f32_e32 v222, v222
	v_rcp_f32_e32 v223, v223
	v_rcp_f32_e32 v224, v224
	v_rcp_f32_e32 v225, v225
	v_rcp_f32_e32 v226, v226
	v_rcp_f32_e32 v227, v227
	v_mul_f32_e32 v220, v188, v220
	v_mul_f32_e32 v221, v189, v221
	v_mul_f32_e32 v222, v190, v222
	v_mul_f32_e32 v223, v191, v223
	v_mul_f32_e32 v224, v192, v224
	v_mul_f32_e32 v225, v193, v225
	v_mul_f32_e32 v226, v194, v226
	v_mul_f32_e32 v227, v195, v227
	v_cvt_pk_bf16_f32 v188, v220, v221
	v_cvt_pk_bf16_f32 v189, v222, v223
	v_cvt_pk_bf16_f32 v190, v224, v225
	v_cvt_pk_bf16_f32 v191, v226, v227
	global_store_dwordx4 v25, v[188:191], s[54:55]
	s_add_u32 s54, s54, 0x1000
	s_addc_u32 s55, s55, 0
	s_waitcnt vmcnt(15)
	v_lshlrev_b32_e32 v172, 16, v100
	v_and_b32_e32 v173, 0xffff0000, v100
	v_lshlrev_b32_e32 v174, 16, v101
	v_and_b32_e32 v175, 0xffff0000, v101
	v_lshlrev_b32_e32 v176, 16, v102
	v_and_b32_e32 v177, 0xffff0000, v102
	v_lshlrev_b32_e32 v178, 16, v103
	v_and_b32_e32 v179, 0xffff0000, v103
	v_pk_fma_f32 v[188:189], v[28:29], v[172:173], v[68:69]
	v_pk_fma_f32 v[190:191], v[30:31], v[174:175], v[70:71]
	v_pk_fma_f32 v[192:193], v[32:33], v[176:177], v[72:73]
	v_pk_fma_f32 v[194:195], v[34:35], v[178:179], v[74:75]
	v_pk_fma_f32 v[180:181], v[36:37], v[172:173], v[180:181]
	v_pk_fma_f32 v[182:183], v[38:39], v[174:175], v[182:183]
	v_pk_fma_f32 v[184:185], v[40:41], v[176:177], v[184:185]
	v_pk_fma_f32 v[186:187], v[42:43], v[178:179], v[186:187]
	v_pk_fma_f32 v[212:213], v[44:45], v[172:173], v[212:213]
	v_pk_fma_f32 v[214:215], v[46:47], v[174:175], v[214:215]
	v_pk_fma_f32 v[216:217], v[48:49], v[176:177], v[216:217]
	v_pk_fma_f32 v[218:219], v[50:51], v[178:179], v[218:219]
	v_pk_fma_f32 v[204:205], v[52:53], v[172:173], v[204:205]
	v_pk_fma_f32 v[206:207], v[54:55], v[174:175], v[206:207]
	v_pk_fma_f32 v[208:209], v[56:57], v[176:177], v[208:209]
	v_pk_fma_f32 v[210:211], v[58:59], v[178:179], v[210:211]
	v_pk_fma_f32 v[196:197], v[60:61], v[172:173], v[196:197]
	v_pk_fma_f32 v[198:199], v[62:63], v[174:175], v[198:199]
	v_pk_fma_f32 v[200:201], v[64:65], v[176:177], v[200:201]
	v_pk_fma_f32 v[202:203], v[66:67], v[178:179], v[202:203]
	v_mul_f32_e32 v220, 0xbfb8aa3b, v196
	v_mul_f32_e32 v221, 0xbfb8aa3b, v197
	v_mul_f32_e32 v222, 0xbfb8aa3b, v198
	v_mul_f32_e32 v223, 0xbfb8aa3b, v199
	v_mul_f32_e32 v224, 0xbfb8aa3b, v200
	v_mul_f32_e32 v225, 0xbfb8aa3b, v201
	v_mul_f32_e32 v226, 0xbfb8aa3b, v202
	v_mul_f32_e32 v227, 0xbfb8aa3b, v203
	v_exp_f32_e32 v220, v220
	v_exp_f32_e32 v221, v221
	v_exp_f32_e32 v222, v222
	v_exp_f32_e32 v223, v223
	v_exp_f32_e32 v224, v224
	v_exp_f32_e32 v225, v225
	v_exp_f32_e32 v226, v226
	v_exp_f32_e32 v227, v227
	v_add_f32_e32 v220, 1.0, v220
	v_add_f32_e32 v221, 1.0, v221
	v_add_f32_e32 v222, 1.0, v222
	v_add_f32_e32 v223, 1.0, v223
	v_add_f32_e32 v224, 1.0, v224
	v_add_f32_e32 v225, 1.0, v225
	v_add_f32_e32 v226, 1.0, v226
	v_add_f32_e32 v227, 1.0, v227
	v_rcp_f32_e32 v220, v220
	v_rcp_f32_e32 v221, v221
	v_rcp_f32_e32 v222, v222
	v_rcp_f32_e32 v223, v223
	v_rcp_f32_e32 v224, v224
	v_rcp_f32_e32 v225, v225
	v_rcp_f32_e32 v226, v226
	v_rcp_f32_e32 v227, v227
	v_mul_f32_e32 v220, v196, v220
	v_mul_f32_e32 v221, v197, v221
	v_mul_f32_e32 v222, v198, v222
	v_mul_f32_e32 v223, v199, v223
	v_mul_f32_e32 v224, v200, v224
	v_mul_f32_e32 v225, v201, v225
	v_mul_f32_e32 v226, v202, v226
	v_mul_f32_e32 v227, v203, v227
	v_cvt_pk_bf16_f32 v196, v220, v221
	v_cvt_pk_bf16_f32 v197, v222, v223
	v_cvt_pk_bf16_f32 v198, v224, v225
	v_cvt_pk_bf16_f32 v199, v226, v227
	global_store_dwordx4 v25, v[196:199], s[54:55]
	s_add_u32 s54, s54, 0x1000
	s_addc_u32 s55, s55, 0
	s_waitcnt vmcnt(15)
	v_lshlrev_b32_e32 v172, 16, v104
	v_and_b32_e32 v173, 0xffff0000, v104
	v_lshlrev_b32_e32 v174, 16, v105
	v_and_b32_e32 v175, 0xffff0000, v105
	v_lshlrev_b32_e32 v176, 16, v106
	v_and_b32_e32 v177, 0xffff0000, v106
	v_lshlrev_b32_e32 v178, 16, v107
	v_and_b32_e32 v179, 0xffff0000, v107
	v_pk_fma_f32 v[196:197], v[28:29], v[172:173], v[68:69]
	v_pk_fma_f32 v[198:199], v[30:31], v[174:175], v[70:71]
	v_pk_fma_f32 v[200:201], v[32:33], v[176:177], v[72:73]
	v_pk_fma_f32 v[202:203], v[34:35], v[178:179], v[74:75]
	v_pk_fma_f32 v[188:189], v[36:37], v[172:173], v[188:189]
	v_pk_fma_f32 v[190:191], v[38:39], v[174:175], v[190:191]
	v_pk_fma_f32 v[192:193], v[40:41], v[176:177], v[192:193]
	v_pk_fma_f32 v[194:195], v[42:43], v[178:179], v[194:195]
	v_pk_fma_f32 v[180:181], v[44:45], v[172:173], v[180:181]
	v_pk_fma_f32 v[182:183], v[46:47], v[174:175], v[182:183]
	v_pk_fma_f32 v[184:185], v[48:49], v[176:177], v[184:185]
	v_pk_fma_f32 v[186:187], v[50:51], v[178:179], v[186:187]
	v_pk_fma_f32 v[212:213], v[52:53], v[172:173], v[212:213]
	v_pk_fma_f32 v[214:215], v[54:55], v[174:175], v[214:215]
	v_pk_fma_f32 v[216:217], v[56:57], v[176:177], v[216:217]
	v_pk_fma_f32 v[218:219], v[58:59], v[178:179], v[218:219]
	v_pk_fma_f32 v[204:205], v[60:61], v[172:173], v[204:205]
	v_pk_fma_f32 v[206:207], v[62:63], v[174:175], v[206:207]
	v_pk_fma_f32 v[208:209], v[64:65], v[176:177], v[208:209]
	v_pk_fma_f32 v[210:211], v[66:67], v[178:179], v[210:211]
	v_mul_f32_e32 v220, 0xbfb8aa3b, v204
	v_mul_f32_e32 v221, 0xbfb8aa3b, v205
	v_mul_f32_e32 v222, 0xbfb8aa3b, v206
	v_mul_f32_e32 v223, 0xbfb8aa3b, v207
	v_mul_f32_e32 v224, 0xbfb8aa3b, v208
	v_mul_f32_e32 v225, 0xbfb8aa3b, v209
	v_mul_f32_e32 v226, 0xbfb8aa3b, v210
	v_mul_f32_e32 v227, 0xbfb8aa3b, v211
	v_exp_f32_e32 v220, v220
	v_exp_f32_e32 v221, v221
	v_exp_f32_e32 v222, v222
	v_exp_f32_e32 v223, v223
	v_exp_f32_e32 v224, v224
	v_exp_f32_e32 v225, v225
	v_exp_f32_e32 v226, v226
	v_exp_f32_e32 v227, v227
	v_add_f32_e32 v220, 1.0, v220
	v_add_f32_e32 v221, 1.0, v221
	v_add_f32_e32 v222, 1.0, v222
	v_add_f32_e32 v223, 1.0, v223
	v_add_f32_e32 v224, 1.0, v224
	v_add_f32_e32 v225, 1.0, v225
	v_add_f32_e32 v226, 1.0, v226
	v_add_f32_e32 v227, 1.0, v227
	v_rcp_f32_e32 v220, v220
	v_rcp_f32_e32 v221, v221
	v_rcp_f32_e32 v222, v222
	v_rcp_f32_e32 v223, v223
	v_rcp_f32_e32 v224, v224
	v_rcp_f32_e32 v225, v225
	v_rcp_f32_e32 v226, v226
	v_rcp_f32_e32 v227, v227
	v_mul_f32_e32 v220, v204, v220
	v_mul_f32_e32 v221, v205, v221
	v_mul_f32_e32 v222, v206, v222
	v_mul_f32_e32 v223, v207, v223
	v_mul_f32_e32 v224, v208, v224
	v_mul_f32_e32 v225, v209, v225
	v_mul_f32_e32 v226, v210, v226
	v_mul_f32_e32 v227, v211, v227
	v_cvt_pk_bf16_f32 v204, v220, v221
	v_cvt_pk_bf16_f32 v205, v222, v223
	v_cvt_pk_bf16_f32 v206, v224, v225
	v_cvt_pk_bf16_f32 v207, v226, v227
	global_store_dwordx4 v25, v[204:207], s[54:55]
	s_add_u32 s54, s54, 0x1000
	s_addc_u32 s55, s55, 0
	s_waitcnt vmcnt(15)
	v_lshlrev_b32_e32 v172, 16, v108
	v_and_b32_e32 v173, 0xffff0000, v108
	v_lshlrev_b32_e32 v174, 16, v109
	v_and_b32_e32 v175, 0xffff0000, v109
	v_lshlrev_b32_e32 v176, 16, v110
	v_and_b32_e32 v177, 0xffff0000, v110
	v_lshlrev_b32_e32 v178, 16, v111
	v_and_b32_e32 v179, 0xffff0000, v111
	v_pk_fma_f32 v[204:205], v[28:29], v[172:173], v[68:69]
	v_pk_fma_f32 v[206:207], v[30:31], v[174:175], v[70:71]
	v_pk_fma_f32 v[208:209], v[32:33], v[176:177], v[72:73]
	v_pk_fma_f32 v[210:211], v[34:35], v[178:179], v[74:75]
	v_pk_fma_f32 v[196:197], v[36:37], v[172:173], v[196:197]
	v_pk_fma_f32 v[198:199], v[38:39], v[174:175], v[198:199]
	v_pk_fma_f32 v[200:201], v[40:41], v[176:177], v[200:201]
	v_pk_fma_f32 v[202:203], v[42:43], v[178:179], v[202:203]
	v_pk_fma_f32 v[188:189], v[44:45], v[172:173], v[188:189]
	v_pk_fma_f32 v[190:191], v[46:47], v[174:175], v[190:191]
	v_pk_fma_f32 v[192:193], v[48:49], v[176:177], v[192:193]
	v_pk_fma_f32 v[194:195], v[50:51], v[178:179], v[194:195]
	v_pk_fma_f32 v[180:181], v[52:53], v[172:173], v[180:181]
	v_pk_fma_f32 v[182:183], v[54:55], v[174:175], v[182:183]
	v_pk_fma_f32 v[184:185], v[56:57], v[176:177], v[184:185]
	v_pk_fma_f32 v[186:187], v[58:59], v[178:179], v[186:187]
	v_pk_fma_f32 v[212:213], v[60:61], v[172:173], v[212:213]
	v_pk_fma_f32 v[214:215], v[62:63], v[174:175], v[214:215]
	v_pk_fma_f32 v[216:217], v[64:65], v[176:177], v[216:217]
	v_pk_fma_f32 v[218:219], v[66:67], v[178:179], v[218:219]
	v_mul_f32_e32 v220, 0xbfb8aa3b, v212
	v_mul_f32_e32 v221, 0xbfb8aa3b, v213
	v_mul_f32_e32 v222, 0xbfb8aa3b, v214
	v_mul_f32_e32 v223, 0xbfb8aa3b, v215
	v_mul_f32_e32 v224, 0xbfb8aa3b, v216
	v_mul_f32_e32 v225, 0xbfb8aa3b, v217
	v_mul_f32_e32 v226, 0xbfb8aa3b, v218
	v_mul_f32_e32 v227, 0xbfb8aa3b, v219
	v_exp_f32_e32 v220, v220
	v_exp_f32_e32 v221, v221
	v_exp_f32_e32 v222, v222
	v_exp_f32_e32 v223, v223
	v_exp_f32_e32 v224, v224
	v_exp_f32_e32 v225, v225
	v_exp_f32_e32 v226, v226
	v_exp_f32_e32 v227, v227
	v_add_f32_e32 v220, 1.0, v220
	v_add_f32_e32 v221, 1.0, v221
	v_add_f32_e32 v222, 1.0, v222
	v_add_f32_e32 v223, 1.0, v223
	v_add_f32_e32 v224, 1.0, v224
	v_add_f32_e32 v225, 1.0, v225
	v_add_f32_e32 v226, 1.0, v226
	v_add_f32_e32 v227, 1.0, v227
	v_rcp_f32_e32 v220, v220
	v_rcp_f32_e32 v221, v221
	v_rcp_f32_e32 v222, v222
	v_rcp_f32_e32 v223, v223
	v_rcp_f32_e32 v224, v224
	v_rcp_f32_e32 v225, v225
	v_rcp_f32_e32 v226, v226
	v_rcp_f32_e32 v227, v227
	v_mul_f32_e32 v220, v212, v220
	v_mul_f32_e32 v221, v213, v221
	v_mul_f32_e32 v222, v214, v222
	v_mul_f32_e32 v223, v215, v223
	v_mul_f32_e32 v224, v216, v224
	v_mul_f32_e32 v225, v217, v225
	v_mul_f32_e32 v226, v218, v226
	v_mul_f32_e32 v227, v219, v227
	v_cvt_pk_bf16_f32 v212, v220, v221
	v_cvt_pk_bf16_f32 v213, v222, v223
	v_cvt_pk_bf16_f32 v214, v224, v225
	v_cvt_pk_bf16_f32 v215, v226, v227
	global_store_dwordx4 v25, v[212:215], s[54:55]
	s_add_u32 s54, s54, 0x1000
	s_addc_u32 s55, s55, 0
	s_waitcnt vmcnt(15)
	v_lshlrev_b32_e32 v172, 16, v112
	v_and_b32_e32 v173, 0xffff0000, v112
	v_lshlrev_b32_e32 v174, 16, v113
	v_and_b32_e32 v175, 0xffff0000, v113
	v_lshlrev_b32_e32 v176, 16, v114
	v_and_b32_e32 v177, 0xffff0000, v114
	v_lshlrev_b32_e32 v178, 16, v115
	v_and_b32_e32 v179, 0xffff0000, v115
	v_pk_fma_f32 v[212:213], v[28:29], v[172:173], v[68:69]
	v_pk_fma_f32 v[214:215], v[30:31], v[174:175], v[70:71]
	v_pk_fma_f32 v[216:217], v[32:33], v[176:177], v[72:73]
	v_pk_fma_f32 v[218:219], v[34:35], v[178:179], v[74:75]
	v_pk_fma_f32 v[204:205], v[36:37], v[172:173], v[204:205]
	v_pk_fma_f32 v[206:207], v[38:39], v[174:175], v[206:207]
	v_pk_fma_f32 v[208:209], v[40:41], v[176:177], v[208:209]
	v_pk_fma_f32 v[210:211], v[42:43], v[178:179], v[210:211]
	v_pk_fma_f32 v[196:197], v[44:45], v[172:173], v[196:197]
	v_pk_fma_f32 v[198:199], v[46:47], v[174:175], v[198:199]
	v_pk_fma_f32 v[200:201], v[48:49], v[176:177], v[200:201]
	v_pk_fma_f32 v[202:203], v[50:51], v[178:179], v[202:203]
	v_pk_fma_f32 v[188:189], v[52:53], v[172:173], v[188:189]
	v_pk_fma_f32 v[190:191], v[54:55], v[174:175], v[190:191]
	v_pk_fma_f32 v[192:193], v[56:57], v[176:177], v[192:193]
	v_pk_fma_f32 v[194:195], v[58:59], v[178:179], v[194:195]
	v_pk_fma_f32 v[180:181], v[60:61], v[172:173], v[180:181]
	v_pk_fma_f32 v[182:183], v[62:63], v[174:175], v[182:183]
	v_pk_fma_f32 v[184:185], v[64:65], v[176:177], v[184:185]
	v_pk_fma_f32 v[186:187], v[66:67], v[178:179], v[186:187]
	v_mul_f32_e32 v220, 0xbfb8aa3b, v180
	v_mul_f32_e32 v221, 0xbfb8aa3b, v181
	v_mul_f32_e32 v222, 0xbfb8aa3b, v182
	v_mul_f32_e32 v223, 0xbfb8aa3b, v183
	v_mul_f32_e32 v224, 0xbfb8aa3b, v184
	v_mul_f32_e32 v225, 0xbfb8aa3b, v185
	v_mul_f32_e32 v226, 0xbfb8aa3b, v186
	v_mul_f32_e32 v227, 0xbfb8aa3b, v187
	v_exp_f32_e32 v220, v220
	v_exp_f32_e32 v221, v221
	v_exp_f32_e32 v222, v222
	v_exp_f32_e32 v223, v223
	v_exp_f32_e32 v224, v224
	v_exp_f32_e32 v225, v225
	v_exp_f32_e32 v226, v226
	v_exp_f32_e32 v227, v227
	v_add_f32_e32 v220, 1.0, v220
	v_add_f32_e32 v221, 1.0, v221
	v_add_f32_e32 v222, 1.0, v222
	v_add_f32_e32 v223, 1.0, v223
	v_add_f32_e32 v224, 1.0, v224
	v_add_f32_e32 v225, 1.0, v225
	v_add_f32_e32 v226, 1.0, v226
	v_add_f32_e32 v227, 1.0, v227
	v_rcp_f32_e32 v220, v220
	v_rcp_f32_e32 v221, v221
	v_rcp_f32_e32 v222, v222
	v_rcp_f32_e32 v223, v223
	v_rcp_f32_e32 v224, v224
	v_rcp_f32_e32 v225, v225
	v_rcp_f32_e32 v226, v226
	v_rcp_f32_e32 v227, v227
	v_mul_f32_e32 v220, v180, v220
	v_mul_f32_e32 v221, v181, v221
	v_mul_f32_e32 v222, v182, v222
	v_mul_f32_e32 v223, v183, v223
	v_mul_f32_e32 v224, v184, v224
	v_mul_f32_e32 v225, v185, v225
	v_mul_f32_e32 v226, v186, v226
	v_mul_f32_e32 v227, v187, v227
	v_cvt_pk_bf16_f32 v180, v220, v221
	v_cvt_pk_bf16_f32 v181, v222, v223
	v_cvt_pk_bf16_f32 v182, v224, v225
	v_cvt_pk_bf16_f32 v183, v226, v227
	global_store_dwordx4 v25, v[180:183], s[54:55]
	s_add_u32 s54, s54, 0x1000
	s_addc_u32 s55, s55, 0
	s_waitcnt vmcnt(15)
	v_lshlrev_b32_e32 v172, 16, v116
	v_and_b32_e32 v173, 0xffff0000, v116
	v_lshlrev_b32_e32 v174, 16, v117
	v_and_b32_e32 v175, 0xffff0000, v117
	v_lshlrev_b32_e32 v176, 16, v118
	v_and_b32_e32 v177, 0xffff0000, v118
	v_lshlrev_b32_e32 v178, 16, v119
	v_and_b32_e32 v179, 0xffff0000, v119
	v_pk_fma_f32 v[180:181], v[28:29], v[172:173], v[68:69]
	v_pk_fma_f32 v[182:183], v[30:31], v[174:175], v[70:71]
	v_pk_fma_f32 v[184:185], v[32:33], v[176:177], v[72:73]
	v_pk_fma_f32 v[186:187], v[34:35], v[178:179], v[74:75]
	v_pk_fma_f32 v[212:213], v[36:37], v[172:173], v[212:213]
	v_pk_fma_f32 v[214:215], v[38:39], v[174:175], v[214:215]
	v_pk_fma_f32 v[216:217], v[40:41], v[176:177], v[216:217]
	v_pk_fma_f32 v[218:219], v[42:43], v[178:179], v[218:219]
	v_pk_fma_f32 v[204:205], v[44:45], v[172:173], v[204:205]
	v_pk_fma_f32 v[206:207], v[46:47], v[174:175], v[206:207]
	v_pk_fma_f32 v[208:209], v[48:49], v[176:177], v[208:209]
	v_pk_fma_f32 v[210:211], v[50:51], v[178:179], v[210:211]
	v_pk_fma_f32 v[196:197], v[52:53], v[172:173], v[196:197]
	v_pk_fma_f32 v[198:199], v[54:55], v[174:175], v[198:199]
	v_pk_fma_f32 v[200:201], v[56:57], v[176:177], v[200:201]
	v_pk_fma_f32 v[202:203], v[58:59], v[178:179], v[202:203]
	v_pk_fma_f32 v[188:189], v[60:61], v[172:173], v[188:189]
	v_pk_fma_f32 v[190:191], v[62:63], v[174:175], v[190:191]
	v_pk_fma_f32 v[192:193], v[64:65], v[176:177], v[192:193]
	v_pk_fma_f32 v[194:195], v[66:67], v[178:179], v[194:195]
	v_mul_f32_e32 v220, 0xbfb8aa3b, v188
	v_mul_f32_e32 v221, 0xbfb8aa3b, v189
	v_mul_f32_e32 v222, 0xbfb8aa3b, v190
	v_mul_f32_e32 v223, 0xbfb8aa3b, v191
	v_mul_f32_e32 v224, 0xbfb8aa3b, v192
	v_mul_f32_e32 v225, 0xbfb8aa3b, v193
	v_mul_f32_e32 v226, 0xbfb8aa3b, v194
	v_mul_f32_e32 v227, 0xbfb8aa3b, v195
	v_exp_f32_e32 v220, v220
	v_exp_f32_e32 v221, v221
	v_exp_f32_e32 v222, v222
	v_exp_f32_e32 v223, v223
	v_exp_f32_e32 v224, v224
	v_exp_f32_e32 v225, v225
	v_exp_f32_e32 v226, v226
	v_exp_f32_e32 v227, v227
	v_add_f32_e32 v220, 1.0, v220
	v_add_f32_e32 v221, 1.0, v221
	v_add_f32_e32 v222, 1.0, v222
	v_add_f32_e32 v223, 1.0, v223
	v_add_f32_e32 v224, 1.0, v224
	v_add_f32_e32 v225, 1.0, v225
	v_add_f32_e32 v226, 1.0, v226
	v_add_f32_e32 v227, 1.0, v227
	v_rcp_f32_e32 v220, v220
	v_rcp_f32_e32 v221, v221
	v_rcp_f32_e32 v222, v222
	v_rcp_f32_e32 v223, v223
	v_rcp_f32_e32 v224, v224
	v_rcp_f32_e32 v225, v225
	v_rcp_f32_e32 v226, v226
	v_rcp_f32_e32 v227, v227
	v_mul_f32_e32 v220, v188, v220
	v_mul_f32_e32 v221, v189, v221
	v_mul_f32_e32 v222, v190, v222
	v_mul_f32_e32 v223, v191, v223
	v_mul_f32_e32 v224, v192, v224
	v_mul_f32_e32 v225, v193, v225
	v_mul_f32_e32 v226, v194, v226
	v_mul_f32_e32 v227, v195, v227
	v_cvt_pk_bf16_f32 v188, v220, v221
	v_cvt_pk_bf16_f32 v189, v222, v223
	v_cvt_pk_bf16_f32 v190, v224, v225
	v_cvt_pk_bf16_f32 v191, v226, v227
	global_store_dwordx4 v25, v[188:191], s[54:55]
	s_add_u32 s54, s54, 0x1000
	s_addc_u32 s55, s55, 0
	s_waitcnt vmcnt(15)
	v_lshlrev_b32_e32 v172, 16, v120
	v_and_b32_e32 v173, 0xffff0000, v120
	v_lshlrev_b32_e32 v174, 16, v121
	v_and_b32_e32 v175, 0xffff0000, v121
	v_lshlrev_b32_e32 v176, 16, v122
	v_and_b32_e32 v177, 0xffff0000, v122
	v_lshlrev_b32_e32 v178, 16, v123
	v_and_b32_e32 v179, 0xffff0000, v123
	v_pk_fma_f32 v[188:189], v[28:29], v[172:173], v[68:69]
	v_pk_fma_f32 v[190:191], v[30:31], v[174:175], v[70:71]
	v_pk_fma_f32 v[192:193], v[32:33], v[176:177], v[72:73]
	v_pk_fma_f32 v[194:195], v[34:35], v[178:179], v[74:75]
	v_pk_fma_f32 v[180:181], v[36:37], v[172:173], v[180:181]
	v_pk_fma_f32 v[182:183], v[38:39], v[174:175], v[182:183]
	v_pk_fma_f32 v[184:185], v[40:41], v[176:177], v[184:185]
	v_pk_fma_f32 v[186:187], v[42:43], v[178:179], v[186:187]
	v_pk_fma_f32 v[212:213], v[44:45], v[172:173], v[212:213]
	v_pk_fma_f32 v[214:215], v[46:47], v[174:175], v[214:215]
	v_pk_fma_f32 v[216:217], v[48:49], v[176:177], v[216:217]
	v_pk_fma_f32 v[218:219], v[50:51], v[178:179], v[218:219]
	v_pk_fma_f32 v[204:205], v[52:53], v[172:173], v[204:205]
	v_pk_fma_f32 v[206:207], v[54:55], v[174:175], v[206:207]
	v_pk_fma_f32 v[208:209], v[56:57], v[176:177], v[208:209]
	v_pk_fma_f32 v[210:211], v[58:59], v[178:179], v[210:211]
	v_pk_fma_f32 v[196:197], v[60:61], v[172:173], v[196:197]
	v_pk_fma_f32 v[198:199], v[62:63], v[174:175], v[198:199]
	v_pk_fma_f32 v[200:201], v[64:65], v[176:177], v[200:201]
	v_pk_fma_f32 v[202:203], v[66:67], v[178:179], v[202:203]
	v_mul_f32_e32 v220, 0xbfb8aa3b, v196
	v_mul_f32_e32 v221, 0xbfb8aa3b, v197
	v_mul_f32_e32 v222, 0xbfb8aa3b, v198
	v_mul_f32_e32 v223, 0xbfb8aa3b, v199
	v_mul_f32_e32 v224, 0xbfb8aa3b, v200
	v_mul_f32_e32 v225, 0xbfb8aa3b, v201
	v_mul_f32_e32 v226, 0xbfb8aa3b, v202
	v_mul_f32_e32 v227, 0xbfb8aa3b, v203
	v_exp_f32_e32 v220, v220
	v_exp_f32_e32 v221, v221
	v_exp_f32_e32 v222, v222
	v_exp_f32_e32 v223, v223
	v_exp_f32_e32 v224, v224
	v_exp_f32_e32 v225, v225
	v_exp_f32_e32 v226, v226
	v_exp_f32_e32 v227, v227
	v_add_f32_e32 v220, 1.0, v220
	v_add_f32_e32 v221, 1.0, v221
	v_add_f32_e32 v222, 1.0, v222
	v_add_f32_e32 v223, 1.0, v223
	v_add_f32_e32 v224, 1.0, v224
	v_add_f32_e32 v225, 1.0, v225
	v_add_f32_e32 v226, 1.0, v226
	v_add_f32_e32 v227, 1.0, v227
	v_rcp_f32_e32 v220, v220
	v_rcp_f32_e32 v221, v221
	v_rcp_f32_e32 v222, v222
	v_rcp_f32_e32 v223, v223
	v_rcp_f32_e32 v224, v224
	v_rcp_f32_e32 v225, v225
	v_rcp_f32_e32 v226, v226
	v_rcp_f32_e32 v227, v227
	v_mul_f32_e32 v220, v196, v220
	v_mul_f32_e32 v221, v197, v221
	v_mul_f32_e32 v222, v198, v222
	v_mul_f32_e32 v223, v199, v223
	v_mul_f32_e32 v224, v200, v224
	v_mul_f32_e32 v225, v201, v225
	v_mul_f32_e32 v226, v202, v226
	v_mul_f32_e32 v227, v203, v227
	v_cvt_pk_bf16_f32 v196, v220, v221
	v_cvt_pk_bf16_f32 v197, v222, v223
	v_cvt_pk_bf16_f32 v198, v224, v225
	v_cvt_pk_bf16_f32 v199, v226, v227
	global_store_dwordx4 v25, v[196:199], s[54:55]
	s_add_u32 s54, s54, 0x1000
	s_addc_u32 s55, s55, 0
	s_waitcnt vmcnt(15)
	v_lshlrev_b32_e32 v172, 16, v124
	v_and_b32_e32 v173, 0xffff0000, v124
	v_lshlrev_b32_e32 v174, 16, v125
	v_and_b32_e32 v175, 0xffff0000, v125
	v_lshlrev_b32_e32 v176, 16, v126
	v_and_b32_e32 v177, 0xffff0000, v126
	v_lshlrev_b32_e32 v178, 16, v127
	v_and_b32_e32 v179, 0xffff0000, v127
	v_pk_fma_f32 v[196:197], v[28:29], v[172:173], v[68:69]
	v_pk_fma_f32 v[198:199], v[30:31], v[174:175], v[70:71]
	v_pk_fma_f32 v[200:201], v[32:33], v[176:177], v[72:73]
	v_pk_fma_f32 v[202:203], v[34:35], v[178:179], v[74:75]
	v_pk_fma_f32 v[188:189], v[36:37], v[172:173], v[188:189]
	v_pk_fma_f32 v[190:191], v[38:39], v[174:175], v[190:191]
	v_pk_fma_f32 v[192:193], v[40:41], v[176:177], v[192:193]
	v_pk_fma_f32 v[194:195], v[42:43], v[178:179], v[194:195]
	v_pk_fma_f32 v[180:181], v[44:45], v[172:173], v[180:181]
	v_pk_fma_f32 v[182:183], v[46:47], v[174:175], v[182:183]
	v_pk_fma_f32 v[184:185], v[48:49], v[176:177], v[184:185]
	v_pk_fma_f32 v[186:187], v[50:51], v[178:179], v[186:187]
	v_pk_fma_f32 v[212:213], v[52:53], v[172:173], v[212:213]
	v_pk_fma_f32 v[214:215], v[54:55], v[174:175], v[214:215]
	v_pk_fma_f32 v[216:217], v[56:57], v[176:177], v[216:217]
	v_pk_fma_f32 v[218:219], v[58:59], v[178:179], v[218:219]
	v_pk_fma_f32 v[204:205], v[60:61], v[172:173], v[204:205]
	v_pk_fma_f32 v[206:207], v[62:63], v[174:175], v[206:207]
	v_pk_fma_f32 v[208:209], v[64:65], v[176:177], v[208:209]
	v_pk_fma_f32 v[210:211], v[66:67], v[178:179], v[210:211]
	v_mul_f32_e32 v220, 0xbfb8aa3b, v204
	v_mul_f32_e32 v221, 0xbfb8aa3b, v205
	v_mul_f32_e32 v222, 0xbfb8aa3b, v206
	v_mul_f32_e32 v223, 0xbfb8aa3b, v207
	v_mul_f32_e32 v224, 0xbfb8aa3b, v208
	v_mul_f32_e32 v225, 0xbfb8aa3b, v209
	v_mul_f32_e32 v226, 0xbfb8aa3b, v210
	v_mul_f32_e32 v227, 0xbfb8aa3b, v211
	v_exp_f32_e32 v220, v220
	v_exp_f32_e32 v221, v221
	v_exp_f32_e32 v222, v222
	v_exp_f32_e32 v223, v223
	v_exp_f32_e32 v224, v224
	v_exp_f32_e32 v225, v225
	v_exp_f32_e32 v226, v226
	v_exp_f32_e32 v227, v227
	v_add_f32_e32 v220, 1.0, v220
	v_add_f32_e32 v221, 1.0, v221
	v_add_f32_e32 v222, 1.0, v222
	v_add_f32_e32 v223, 1.0, v223
	v_add_f32_e32 v224, 1.0, v224
	v_add_f32_e32 v225, 1.0, v225
	v_add_f32_e32 v226, 1.0, v226
	v_add_f32_e32 v227, 1.0, v227
	v_rcp_f32_e32 v220, v220
	v_rcp_f32_e32 v221, v221
	v_rcp_f32_e32 v222, v222
	v_rcp_f32_e32 v223, v223
	v_rcp_f32_e32 v224, v224
	v_rcp_f32_e32 v225, v225
	v_rcp_f32_e32 v226, v226
	v_rcp_f32_e32 v227, v227
	v_mul_f32_e32 v220, v204, v220
	v_mul_f32_e32 v221, v205, v221
	v_mul_f32_e32 v222, v206, v222
	v_mul_f32_e32 v223, v207, v223
	v_mul_f32_e32 v224, v208, v224
	v_mul_f32_e32 v225, v209, v225
	v_mul_f32_e32 v226, v210, v226
	v_mul_f32_e32 v227, v211, v227
	v_cvt_pk_bf16_f32 v204, v220, v221
	v_cvt_pk_bf16_f32 v205, v222, v223
	v_cvt_pk_bf16_f32 v206, v224, v225
	v_cvt_pk_bf16_f32 v207, v226, v227
	global_store_dwordx4 v25, v[204:207], s[54:55]
	s_add_u32 s54, s54, 0x1000
	s_addc_u32 s55, s55, 0
	s_waitcnt vmcnt(15)
	v_lshlrev_b32_e32 v172, 16, v132
	v_and_b32_e32 v173, 0xffff0000, v132
	v_lshlrev_b32_e32 v174, 16, v133
	v_and_b32_e32 v175, 0xffff0000, v133
	v_lshlrev_b32_e32 v176, 16, v134
	v_and_b32_e32 v177, 0xffff0000, v134
	v_lshlrev_b32_e32 v178, 16, v135
	v_and_b32_e32 v179, 0xffff0000, v135
	v_pk_fma_f32 v[204:205], v[28:29], v[172:173], v[68:69]
	v_pk_fma_f32 v[206:207], v[30:31], v[174:175], v[70:71]
	v_pk_fma_f32 v[208:209], v[32:33], v[176:177], v[72:73]
	v_pk_fma_f32 v[210:211], v[34:35], v[178:179], v[74:75]
	v_pk_fma_f32 v[196:197], v[36:37], v[172:173], v[196:197]
	v_pk_fma_f32 v[198:199], v[38:39], v[174:175], v[198:199]
	v_pk_fma_f32 v[200:201], v[40:41], v[176:177], v[200:201]
	v_pk_fma_f32 v[202:203], v[42:43], v[178:179], v[202:203]
	v_pk_fma_f32 v[188:189], v[44:45], v[172:173], v[188:189]
	v_pk_fma_f32 v[190:191], v[46:47], v[174:175], v[190:191]
	v_pk_fma_f32 v[192:193], v[48:49], v[176:177], v[192:193]
	v_pk_fma_f32 v[194:195], v[50:51], v[178:179], v[194:195]
	v_pk_fma_f32 v[180:181], v[52:53], v[172:173], v[180:181]
	v_pk_fma_f32 v[182:183], v[54:55], v[174:175], v[182:183]
	v_pk_fma_f32 v[184:185], v[56:57], v[176:177], v[184:185]
	v_pk_fma_f32 v[186:187], v[58:59], v[178:179], v[186:187]
	v_pk_fma_f32 v[212:213], v[60:61], v[172:173], v[212:213]
	v_pk_fma_f32 v[214:215], v[62:63], v[174:175], v[214:215]
	v_pk_fma_f32 v[216:217], v[64:65], v[176:177], v[216:217]
	v_pk_fma_f32 v[218:219], v[66:67], v[178:179], v[218:219]
	v_mul_f32_e32 v220, 0xbfb8aa3b, v212
	v_mul_f32_e32 v221, 0xbfb8aa3b, v213
	v_mul_f32_e32 v222, 0xbfb8aa3b, v214
	v_mul_f32_e32 v223, 0xbfb8aa3b, v215
	v_mul_f32_e32 v224, 0xbfb8aa3b, v216
	v_mul_f32_e32 v225, 0xbfb8aa3b, v217
	v_mul_f32_e32 v226, 0xbfb8aa3b, v218
	v_mul_f32_e32 v227, 0xbfb8aa3b, v219
	v_exp_f32_e32 v220, v220
	v_exp_f32_e32 v221, v221
	v_exp_f32_e32 v222, v222
	v_exp_f32_e32 v223, v223
	v_exp_f32_e32 v224, v224
	v_exp_f32_e32 v225, v225
	v_exp_f32_e32 v226, v226
	v_exp_f32_e32 v227, v227
	v_add_f32_e32 v220, 1.0, v220
	v_add_f32_e32 v221, 1.0, v221
	v_add_f32_e32 v222, 1.0, v222
	v_add_f32_e32 v223, 1.0, v223
	v_add_f32_e32 v224, 1.0, v224
	v_add_f32_e32 v225, 1.0, v225
	v_add_f32_e32 v226, 1.0, v226
	v_add_f32_e32 v227, 1.0, v227
	v_rcp_f32_e32 v220, v220
	v_rcp_f32_e32 v221, v221
	v_rcp_f32_e32 v222, v222
	v_rcp_f32_e32 v223, v223
	v_rcp_f32_e32 v224, v224
	v_rcp_f32_e32 v225, v225
	v_rcp_f32_e32 v226, v226
	v_rcp_f32_e32 v227, v227
	v_mul_f32_e32 v220, v212, v220
	v_mul_f32_e32 v221, v213, v221
	v_mul_f32_e32 v222, v214, v222
	v_mul_f32_e32 v223, v215, v223
	v_mul_f32_e32 v224, v216, v224
	v_mul_f32_e32 v225, v217, v225
	v_mul_f32_e32 v226, v218, v226
	v_mul_f32_e32 v227, v219, v227
	v_cvt_pk_bf16_f32 v212, v220, v221
	v_cvt_pk_bf16_f32 v213, v222, v223
	v_cvt_pk_bf16_f32 v214, v224, v225
	v_cvt_pk_bf16_f32 v215, v226, v227
	global_store_dwordx4 v25, v[212:215], s[54:55]
	s_add_u32 s54, s54, 0x1000
	s_addc_u32 s55, s55, 0
	s_waitcnt vmcnt(15)
	v_lshlrev_b32_e32 v172, 16, v136
	v_and_b32_e32 v173, 0xffff0000, v136
	v_lshlrev_b32_e32 v174, 16, v137
	v_and_b32_e32 v175, 0xffff0000, v137
	v_lshlrev_b32_e32 v176, 16, v138
	v_and_b32_e32 v177, 0xffff0000, v138
	v_lshlrev_b32_e32 v178, 16, v139
	v_and_b32_e32 v179, 0xffff0000, v139
	v_pk_fma_f32 v[212:213], v[28:29], v[172:173], v[68:69]
	v_pk_fma_f32 v[214:215], v[30:31], v[174:175], v[70:71]
	v_pk_fma_f32 v[216:217], v[32:33], v[176:177], v[72:73]
	v_pk_fma_f32 v[218:219], v[34:35], v[178:179], v[74:75]
	v_pk_fma_f32 v[204:205], v[36:37], v[172:173], v[204:205]
	v_pk_fma_f32 v[206:207], v[38:39], v[174:175], v[206:207]
	v_pk_fma_f32 v[208:209], v[40:41], v[176:177], v[208:209]
	v_pk_fma_f32 v[210:211], v[42:43], v[178:179], v[210:211]
	v_pk_fma_f32 v[196:197], v[44:45], v[172:173], v[196:197]
	v_pk_fma_f32 v[198:199], v[46:47], v[174:175], v[198:199]
	v_pk_fma_f32 v[200:201], v[48:49], v[176:177], v[200:201]
	v_pk_fma_f32 v[202:203], v[50:51], v[178:179], v[202:203]
	v_pk_fma_f32 v[188:189], v[52:53], v[172:173], v[188:189]
	v_pk_fma_f32 v[190:191], v[54:55], v[174:175], v[190:191]
	v_pk_fma_f32 v[192:193], v[56:57], v[176:177], v[192:193]
	v_pk_fma_f32 v[194:195], v[58:59], v[178:179], v[194:195]
	v_pk_fma_f32 v[180:181], v[60:61], v[172:173], v[180:181]
	v_pk_fma_f32 v[182:183], v[62:63], v[174:175], v[182:183]
	v_pk_fma_f32 v[184:185], v[64:65], v[176:177], v[184:185]
	v_pk_fma_f32 v[186:187], v[66:67], v[178:179], v[186:187]
	v_mul_f32_e32 v220, 0xbfb8aa3b, v180
	v_mul_f32_e32 v221, 0xbfb8aa3b, v181
	v_mul_f32_e32 v222, 0xbfb8aa3b, v182
	v_mul_f32_e32 v223, 0xbfb8aa3b, v183
	v_mul_f32_e32 v224, 0xbfb8aa3b, v184
	v_mul_f32_e32 v225, 0xbfb8aa3b, v185
	v_mul_f32_e32 v226, 0xbfb8aa3b, v186
	v_mul_f32_e32 v227, 0xbfb8aa3b, v187
	v_exp_f32_e32 v220, v220
	v_exp_f32_e32 v221, v221
	v_exp_f32_e32 v222, v222
	v_exp_f32_e32 v223, v223
	v_exp_f32_e32 v224, v224
	v_exp_f32_e32 v225, v225
	v_exp_f32_e32 v226, v226
	v_exp_f32_e32 v227, v227
	v_add_f32_e32 v220, 1.0, v220
	v_add_f32_e32 v221, 1.0, v221
	v_add_f32_e32 v222, 1.0, v222
	v_add_f32_e32 v223, 1.0, v223
	v_add_f32_e32 v224, 1.0, v224
	v_add_f32_e32 v225, 1.0, v225
	v_add_f32_e32 v226, 1.0, v226
	v_add_f32_e32 v227, 1.0, v227
	v_rcp_f32_e32 v220, v220
	v_rcp_f32_e32 v221, v221
	v_rcp_f32_e32 v222, v222
	v_rcp_f32_e32 v223, v223
	v_rcp_f32_e32 v224, v224
	v_rcp_f32_e32 v225, v225
	v_rcp_f32_e32 v226, v226
	v_rcp_f32_e32 v227, v227
	v_mul_f32_e32 v220, v180, v220
	v_mul_f32_e32 v221, v181, v221
	v_mul_f32_e32 v222, v182, v222
	v_mul_f32_e32 v223, v183, v223
	v_mul_f32_e32 v224, v184, v224
	v_mul_f32_e32 v225, v185, v225
	v_mul_f32_e32 v226, v186, v226
	v_mul_f32_e32 v227, v187, v227
	v_cvt_pk_bf16_f32 v180, v220, v221
	v_cvt_pk_bf16_f32 v181, v222, v223
	v_cvt_pk_bf16_f32 v182, v224, v225
	v_cvt_pk_bf16_f32 v183, v226, v227
	global_store_dwordx4 v25, v[180:183], s[54:55]
	s_add_u32 s54, s54, 0x1000
	s_addc_u32 s55, s55, 0
	s_waitcnt vmcnt(15)
	v_lshlrev_b32_e32 v172, 16, v140
	v_and_b32_e32 v173, 0xffff0000, v140
	v_lshlrev_b32_e32 v174, 16, v141
	v_and_b32_e32 v175, 0xffff0000, v141
	v_lshlrev_b32_e32 v176, 16, v142
	v_and_b32_e32 v177, 0xffff0000, v142
	v_lshlrev_b32_e32 v178, 16, v143
	v_and_b32_e32 v179, 0xffff0000, v143
	v_pk_fma_f32 v[180:181], v[28:29], v[172:173], v[68:69]
	v_pk_fma_f32 v[182:183], v[30:31], v[174:175], v[70:71]
	v_pk_fma_f32 v[184:185], v[32:33], v[176:177], v[72:73]
	v_pk_fma_f32 v[186:187], v[34:35], v[178:179], v[74:75]
	v_pk_fma_f32 v[212:213], v[36:37], v[172:173], v[212:213]
	v_pk_fma_f32 v[214:215], v[38:39], v[174:175], v[214:215]
	v_pk_fma_f32 v[216:217], v[40:41], v[176:177], v[216:217]
	v_pk_fma_f32 v[218:219], v[42:43], v[178:179], v[218:219]
	v_pk_fma_f32 v[204:205], v[44:45], v[172:173], v[204:205]
	v_pk_fma_f32 v[206:207], v[46:47], v[174:175], v[206:207]
	v_pk_fma_f32 v[208:209], v[48:49], v[176:177], v[208:209]
	v_pk_fma_f32 v[210:211], v[50:51], v[178:179], v[210:211]
	v_pk_fma_f32 v[196:197], v[52:53], v[172:173], v[196:197]
	v_pk_fma_f32 v[198:199], v[54:55], v[174:175], v[198:199]
	v_pk_fma_f32 v[200:201], v[56:57], v[176:177], v[200:201]
	v_pk_fma_f32 v[202:203], v[58:59], v[178:179], v[202:203]
	v_pk_fma_f32 v[188:189], v[60:61], v[172:173], v[188:189]
	v_pk_fma_f32 v[190:191], v[62:63], v[174:175], v[190:191]
	v_pk_fma_f32 v[192:193], v[64:65], v[176:177], v[192:193]
	v_pk_fma_f32 v[194:195], v[66:67], v[178:179], v[194:195]
	v_mul_f32_e32 v220, 0xbfb8aa3b, v188
	v_mul_f32_e32 v221, 0xbfb8aa3b, v189
	v_mul_f32_e32 v222, 0xbfb8aa3b, v190
	v_mul_f32_e32 v223, 0xbfb8aa3b, v191
	v_mul_f32_e32 v224, 0xbfb8aa3b, v192
	v_mul_f32_e32 v225, 0xbfb8aa3b, v193
	v_mul_f32_e32 v226, 0xbfb8aa3b, v194
	v_mul_f32_e32 v227, 0xbfb8aa3b, v195
	v_exp_f32_e32 v220, v220
	v_exp_f32_e32 v221, v221
	v_exp_f32_e32 v222, v222
	v_exp_f32_e32 v223, v223
	v_exp_f32_e32 v224, v224
	v_exp_f32_e32 v225, v225
	v_exp_f32_e32 v226, v226
	v_exp_f32_e32 v227, v227
	v_add_f32_e32 v220, 1.0, v220
	v_add_f32_e32 v221, 1.0, v221
	v_add_f32_e32 v222, 1.0, v222
	v_add_f32_e32 v223, 1.0, v223
	v_add_f32_e32 v224, 1.0, v224
	v_add_f32_e32 v225, 1.0, v225
	v_add_f32_e32 v226, 1.0, v226
	v_add_f32_e32 v227, 1.0, v227
	v_rcp_f32_e32 v220, v220
	v_rcp_f32_e32 v221, v221
	v_rcp_f32_e32 v222, v222
	v_rcp_f32_e32 v223, v223
	v_rcp_f32_e32 v224, v224
	v_rcp_f32_e32 v225, v225
	v_rcp_f32_e32 v226, v226
	v_rcp_f32_e32 v227, v227
	v_mul_f32_e32 v220, v188, v220
	v_mul_f32_e32 v221, v189, v221
	v_mul_f32_e32 v222, v190, v222
	v_mul_f32_e32 v223, v191, v223
	v_mul_f32_e32 v224, v192, v224
	v_mul_f32_e32 v225, v193, v225
	v_mul_f32_e32 v226, v194, v226
	v_mul_f32_e32 v227, v195, v227
	v_cvt_pk_bf16_f32 v188, v220, v221
	v_cvt_pk_bf16_f32 v189, v222, v223
	v_cvt_pk_bf16_f32 v190, v224, v225
	v_cvt_pk_bf16_f32 v191, v226, v227
	global_store_dwordx4 v25, v[188:191], s[54:55]
	s_add_u32 s54, s54, 0x1000
	s_addc_u32 s55, s55, 0
	s_waitcnt vmcnt(15)
	v_lshlrev_b32_e32 v172, 16, v144
	v_and_b32_e32 v173, 0xffff0000, v144
	v_lshlrev_b32_e32 v174, 16, v145
	v_and_b32_e32 v175, 0xffff0000, v145
	v_lshlrev_b32_e32 v176, 16, v146
	v_and_b32_e32 v177, 0xffff0000, v146
	v_lshlrev_b32_e32 v178, 16, v147
	v_and_b32_e32 v179, 0xffff0000, v147
	v_pk_fma_f32 v[180:181], v[36:37], v[172:173], v[180:181]
	v_pk_fma_f32 v[182:183], v[38:39], v[174:175], v[182:183]
	v_pk_fma_f32 v[184:185], v[40:41], v[176:177], v[184:185]
	v_pk_fma_f32 v[186:187], v[42:43], v[178:179], v[186:187]
	v_pk_fma_f32 v[212:213], v[44:45], v[172:173], v[212:213]
	v_pk_fma_f32 v[214:215], v[46:47], v[174:175], v[214:215]
	v_pk_fma_f32 v[216:217], v[48:49], v[176:177], v[216:217]
	v_pk_fma_f32 v[218:219], v[50:51], v[178:179], v[218:219]
	v_pk_fma_f32 v[204:205], v[52:53], v[172:173], v[204:205]
	v_pk_fma_f32 v[206:207], v[54:55], v[174:175], v[206:207]
	v_pk_fma_f32 v[208:209], v[56:57], v[176:177], v[208:209]
	v_pk_fma_f32 v[210:211], v[58:59], v[178:179], v[210:211]
	v_pk_fma_f32 v[196:197], v[60:61], v[172:173], v[196:197]
	v_pk_fma_f32 v[198:199], v[62:63], v[174:175], v[198:199]
	v_pk_fma_f32 v[200:201], v[64:65], v[176:177], v[200:201]
	v_pk_fma_f32 v[202:203], v[66:67], v[178:179], v[202:203]
	v_mul_f32_e32 v220, 0xbfb8aa3b, v196
	v_mul_f32_e32 v221, 0xbfb8aa3b, v197
	v_mul_f32_e32 v222, 0xbfb8aa3b, v198
	v_mul_f32_e32 v223, 0xbfb8aa3b, v199
	v_mul_f32_e32 v224, 0xbfb8aa3b, v200
	v_mul_f32_e32 v225, 0xbfb8aa3b, v201
	v_mul_f32_e32 v226, 0xbfb8aa3b, v202
	v_mul_f32_e32 v227, 0xbfb8aa3b, v203
	v_exp_f32_e32 v220, v220
	v_exp_f32_e32 v221, v221
	v_exp_f32_e32 v222, v222
	v_exp_f32_e32 v223, v223
	v_exp_f32_e32 v224, v224
	v_exp_f32_e32 v225, v225
	v_exp_f32_e32 v226, v226
	v_exp_f32_e32 v227, v227
	v_add_f32_e32 v220, 1.0, v220
	v_add_f32_e32 v221, 1.0, v221
	v_add_f32_e32 v222, 1.0, v222
	v_add_f32_e32 v223, 1.0, v223
	v_add_f32_e32 v224, 1.0, v224
	v_add_f32_e32 v225, 1.0, v225
	v_add_f32_e32 v226, 1.0, v226
	v_add_f32_e32 v227, 1.0, v227
	v_rcp_f32_e32 v220, v220
	v_rcp_f32_e32 v221, v221
	v_rcp_f32_e32 v222, v222
	v_rcp_f32_e32 v223, v223
	v_rcp_f32_e32 v224, v224
	v_rcp_f32_e32 v225, v225
	v_rcp_f32_e32 v226, v226
	v_rcp_f32_e32 v227, v227
	v_mul_f32_e32 v220, v196, v220
	v_mul_f32_e32 v221, v197, v221
	v_mul_f32_e32 v222, v198, v222
	v_mul_f32_e32 v223, v199, v223
	v_mul_f32_e32 v224, v200, v224
	v_mul_f32_e32 v225, v201, v225
	v_mul_f32_e32 v226, v202, v226
	v_mul_f32_e32 v227, v203, v227
	v_cvt_pk_bf16_f32 v196, v220, v221
	v_cvt_pk_bf16_f32 v197, v222, v223
	v_cvt_pk_bf16_f32 v198, v224, v225
	v_cvt_pk_bf16_f32 v199, v226, v227
	global_store_dwordx4 v25, v[196:199], s[54:55]
	s_add_u32 s54, s54, 0x1000
	s_addc_u32 s55, s55, 0
	s_waitcnt vmcnt(15)
	v_lshlrev_b32_e32 v172, 16, v148
	v_and_b32_e32 v173, 0xffff0000, v148
	v_lshlrev_b32_e32 v174, 16, v149
	v_and_b32_e32 v175, 0xffff0000, v149
	v_lshlrev_b32_e32 v176, 16, v150
	v_and_b32_e32 v177, 0xffff0000, v150
	v_lshlrev_b32_e32 v178, 16, v151
	v_and_b32_e32 v179, 0xffff0000, v151
	v_pk_fma_f32 v[180:181], v[44:45], v[172:173], v[180:181]
	v_pk_fma_f32 v[182:183], v[46:47], v[174:175], v[182:183]
	v_pk_fma_f32 v[184:185], v[48:49], v[176:177], v[184:185]
	v_pk_fma_f32 v[186:187], v[50:51], v[178:179], v[186:187]
	v_pk_fma_f32 v[212:213], v[52:53], v[172:173], v[212:213]
	v_pk_fma_f32 v[214:215], v[54:55], v[174:175], v[214:215]
	v_pk_fma_f32 v[216:217], v[56:57], v[176:177], v[216:217]
	v_pk_fma_f32 v[218:219], v[58:59], v[178:179], v[218:219]
	v_pk_fma_f32 v[204:205], v[60:61], v[172:173], v[204:205]
	v_pk_fma_f32 v[206:207], v[62:63], v[174:175], v[206:207]
	v_pk_fma_f32 v[208:209], v[64:65], v[176:177], v[208:209]
	v_pk_fma_f32 v[210:211], v[66:67], v[178:179], v[210:211]
	v_mul_f32_e32 v220, 0xbfb8aa3b, v204
	v_mul_f32_e32 v221, 0xbfb8aa3b, v205
	v_mul_f32_e32 v222, 0xbfb8aa3b, v206
	v_mul_f32_e32 v223, 0xbfb8aa3b, v207
	v_mul_f32_e32 v224, 0xbfb8aa3b, v208
	v_mul_f32_e32 v225, 0xbfb8aa3b, v209
	v_mul_f32_e32 v226, 0xbfb8aa3b, v210
	v_mul_f32_e32 v227, 0xbfb8aa3b, v211
	v_exp_f32_e32 v220, v220
	v_exp_f32_e32 v221, v221
	v_exp_f32_e32 v222, v222
	v_exp_f32_e32 v223, v223
	v_exp_f32_e32 v224, v224
	v_exp_f32_e32 v225, v225
	v_exp_f32_e32 v226, v226
	v_exp_f32_e32 v227, v227
	v_add_f32_e32 v220, 1.0, v220
	v_add_f32_e32 v221, 1.0, v221
	v_add_f32_e32 v222, 1.0, v222
	v_add_f32_e32 v223, 1.0, v223
	v_add_f32_e32 v224, 1.0, v224
	v_add_f32_e32 v225, 1.0, v225
	v_add_f32_e32 v226, 1.0, v226
	v_add_f32_e32 v227, 1.0, v227
	v_rcp_f32_e32 v220, v220
	v_rcp_f32_e32 v221, v221
	v_rcp_f32_e32 v222, v222
	v_rcp_f32_e32 v223, v223
	v_rcp_f32_e32 v224, v224
	v_rcp_f32_e32 v225, v225
	v_rcp_f32_e32 v226, v226
	v_rcp_f32_e32 v227, v227
	v_mul_f32_e32 v220, v204, v220
	v_mul_f32_e32 v221, v205, v221
	v_mul_f32_e32 v222, v206, v222
	v_mul_f32_e32 v223, v207, v223
	v_mul_f32_e32 v224, v208, v224
	v_mul_f32_e32 v225, v209, v225
	v_mul_f32_e32 v226, v210, v226
	v_mul_f32_e32 v227, v211, v227
	v_cvt_pk_bf16_f32 v204, v220, v221
	v_cvt_pk_bf16_f32 v205, v222, v223
	v_cvt_pk_bf16_f32 v206, v224, v225
	v_cvt_pk_bf16_f32 v207, v226, v227
	global_store_dwordx4 v25, v[204:207], s[54:55]
	s_add_u32 s54, s54, 0x1000
	s_addc_u32 s55, s55, 0
	s_waitcnt vmcnt(15)
	v_and_b32_e32 v152, s63, v152
	v_and_b32_e32 v153, s63, v153
	v_and_b32_e32 v154, s63, v154
	v_and_b32_e32 v155, s63, v155
	v_lshlrev_b32_e32 v172, 16, v152
	v_and_b32_e32 v173, 0xffff0000, v152
	v_lshlrev_b32_e32 v174, 16, v153
	v_and_b32_e32 v175, 0xffff0000, v153
	v_lshlrev_b32_e32 v176, 16, v154
	v_and_b32_e32 v177, 0xffff0000, v154
	v_lshlrev_b32_e32 v178, 16, v155
	v_and_b32_e32 v179, 0xffff0000, v155
	v_pk_fma_f32 v[180:181], v[52:53], v[172:173], v[180:181]
	v_pk_fma_f32 v[182:183], v[54:55], v[174:175], v[182:183]
	v_pk_fma_f32 v[184:185], v[56:57], v[176:177], v[184:185]
	v_pk_fma_f32 v[186:187], v[58:59], v[178:179], v[186:187]
	v_pk_fma_f32 v[212:213], v[60:61], v[172:173], v[212:213]
	v_pk_fma_f32 v[214:215], v[62:63], v[174:175], v[214:215]
	v_pk_fma_f32 v[216:217], v[64:65], v[176:177], v[216:217]
	v_pk_fma_f32 v[218:219], v[66:67], v[178:179], v[218:219]
	v_mul_f32_e32 v220, 0xbfb8aa3b, v212
	v_mul_f32_e32 v221, 0xbfb8aa3b, v213
	v_mul_f32_e32 v222, 0xbfb8aa3b, v214
	v_mul_f32_e32 v223, 0xbfb8aa3b, v215
	v_mul_f32_e32 v224, 0xbfb8aa3b, v216
	v_mul_f32_e32 v225, 0xbfb8aa3b, v217
	v_mul_f32_e32 v226, 0xbfb8aa3b, v218
	v_mul_f32_e32 v227, 0xbfb8aa3b, v219
	v_exp_f32_e32 v220, v220
	v_exp_f32_e32 v221, v221
	v_exp_f32_e32 v222, v222
	v_exp_f32_e32 v223, v223
	v_exp_f32_e32 v224, v224
	v_exp_f32_e32 v225, v225
	v_exp_f32_e32 v226, v226
	v_exp_f32_e32 v227, v227
	v_add_f32_e32 v220, 1.0, v220
	v_add_f32_e32 v221, 1.0, v221
	v_add_f32_e32 v222, 1.0, v222
	v_add_f32_e32 v223, 1.0, v223
	v_add_f32_e32 v224, 1.0, v224
	v_add_f32_e32 v225, 1.0, v225
	v_add_f32_e32 v226, 1.0, v226
	v_add_f32_e32 v227, 1.0, v227
	v_rcp_f32_e32 v220, v220
	v_rcp_f32_e32 v221, v221
	v_rcp_f32_e32 v222, v222
	v_rcp_f32_e32 v223, v223
	v_rcp_f32_e32 v224, v224
	v_rcp_f32_e32 v225, v225
	v_rcp_f32_e32 v226, v226
	v_rcp_f32_e32 v227, v227
	v_mul_f32_e32 v220, v212, v220
	v_mul_f32_e32 v221, v213, v221
	v_mul_f32_e32 v222, v214, v222
	v_mul_f32_e32 v223, v215, v223
	v_mul_f32_e32 v224, v216, v224
	v_mul_f32_e32 v225, v217, v225
	v_mul_f32_e32 v226, v218, v226
	v_mul_f32_e32 v227, v219, v227
	v_cvt_pk_bf16_f32 v212, v220, v221
	v_cvt_pk_bf16_f32 v213, v222, v223
	v_cvt_pk_bf16_f32 v214, v224, v225
	v_cvt_pk_bf16_f32 v215, v226, v227
	global_store_dwordx4 v25, v[212:215], s[54:55]
	s_add_u32 s54, s54, 0x1000
	s_addc_u32 s55, s55, 0
	s_waitcnt vmcnt(15)
	v_and_b32_e32 v156, s63, v156
	v_and_b32_e32 v157, s63, v157
	v_and_b32_e32 v158, s63, v158
	v_and_b32_e32 v159, s63, v159
	v_lshlrev_b32_e32 v172, 16, v156
	v_and_b32_e32 v173, 0xffff0000, v156
	v_lshlrev_b32_e32 v174, 16, v157
	v_and_b32_e32 v175, 0xffff0000, v157
	v_lshlrev_b32_e32 v176, 16, v158
	v_and_b32_e32 v177, 0xffff0000, v158
	v_lshlrev_b32_e32 v178, 16, v159
	v_and_b32_e32 v179, 0xffff0000, v159
	v_pk_fma_f32 v[180:181], v[60:61], v[172:173], v[180:181]
	v_pk_fma_f32 v[182:183], v[62:63], v[174:175], v[182:183]
	v_pk_fma_f32 v[184:185], v[64:65], v[176:177], v[184:185]
	v_pk_fma_f32 v[186:187], v[66:67], v[178:179], v[186:187]
	v_mul_f32_e32 v220, 0xbfb8aa3b, v180
	v_mul_f32_e32 v221, 0xbfb8aa3b, v181
	v_mul_f32_e32 v222, 0xbfb8aa3b, v182
	v_mul_f32_e32 v223, 0xbfb8aa3b, v183
	v_mul_f32_e32 v224, 0xbfb8aa3b, v184
	v_mul_f32_e32 v225, 0xbfb8aa3b, v185
	v_mul_f32_e32 v226, 0xbfb8aa3b, v186
	v_mul_f32_e32 v227, 0xbfb8aa3b, v187
	v_exp_f32_e32 v220, v220
	v_exp_f32_e32 v221, v221
	v_exp_f32_e32 v222, v222
	v_exp_f32_e32 v223, v223
	v_exp_f32_e32 v224, v224
	v_exp_f32_e32 v225, v225
	v_exp_f32_e32 v226, v226
	v_exp_f32_e32 v227, v227
	v_add_f32_e32 v220, 1.0, v220
	v_add_f32_e32 v221, 1.0, v221
	v_add_f32_e32 v222, 1.0, v222
	v_add_f32_e32 v223, 1.0, v223
	v_add_f32_e32 v224, 1.0, v224
	v_add_f32_e32 v225, 1.0, v225
	v_add_f32_e32 v226, 1.0, v226
	v_add_f32_e32 v227, 1.0, v227
	v_rcp_f32_e32 v220, v220
	v_rcp_f32_e32 v221, v221
	v_rcp_f32_e32 v222, v222
	v_rcp_f32_e32 v223, v223
	v_rcp_f32_e32 v224, v224
	v_rcp_f32_e32 v225, v225
	v_rcp_f32_e32 v226, v226
	v_rcp_f32_e32 v227, v227
	v_mul_f32_e32 v220, v180, v220
	v_mul_f32_e32 v221, v181, v221
	v_mul_f32_e32 v222, v182, v222
	v_mul_f32_e32 v223, v183, v223
	v_mul_f32_e32 v224, v184, v224
	v_mul_f32_e32 v225, v185, v225
	v_mul_f32_e32 v226, v186, v226
	v_mul_f32_e32 v227, v187, v227
	v_cvt_pk_bf16_f32 v180, v220, v221
	v_cvt_pk_bf16_f32 v181, v222, v223
	v_cvt_pk_bf16_f32 v182, v224, v225
	v_cvt_pk_bf16_f32 v183, v226, v227
	global_store_dwordx4 v25, v[180:183], s[54:55]
	s_add_u32 s54, s54, 0x1000
	s_addc_u32 s55, s55, 0
	s_add_u32 s3, s3, s64
	s_branch .Lcv19_rb
.Lcv19_end:
.LBB0_1859:
	s_or_b64 exec, exec, s[14:15]
	s_mov_b32 s3, 0x40000
	v_cmp_gt_i32_e32 vcc, s3, v128
	s_and_saveexec_b64 s[4:5], vcc
	s_cbranch_execz .LBB0_1864
	s_load_dwordx2 s[12:13], s[12:13], 0x78
	v_and_b32_e32 v0, 31, v162
	v_ashrrev_i32_e32 v129, 31, v128
	v_mov_b32_e32 v1, 0
	v_lshlrev_b32_e32 v0, 2, v0
	v_lshl_add_u64 v[2:3], v[128:129], 2, s[10:11]
	s_mov_b64 s[10:11], 0x1247a100
	s_ashr_i32 s9, s8, 31
	s_waitcnt lgkmcnt(0)
	v_lshl_add_u64 v[0:1], s[12:13], 0, v[0:1]
	v_lshl_add_u64 v[2:3], v[2:3], 0, s[10:11]
	s_lshl_b64 s[10:11], s[8:9], 2
	s_mov_b64 s[12:13], 0
	s_mov_b32 s3, 0x41a00000
	s_mov_b32 s9, 0x3f2aaaab
	v_mov_b32_e32 v6, 0x3ecc95a3
	s_mov_b32 s16, 0x3f317218
	s_mov_b32 s17, 0x7f800000
	s_mov_b32 s18, 0x33800000
	s_mov_b32 s19, 0x3ffff
	v_mov_b32_e32 v4, 0x3f317218
	v_mov_b32_e32 v7, 0x7f800000
	v_mov_b32_e32 v8, 0x7fc00000
	v_mov_b32_e32 v9, 0xff800000
	s_branch .LBB0_1862

.LBB0_2295:
	s_lshl_b32 s6, s38, 7
	s_and_b32 s39, s6, 0x1f80
	s_lshl_b32 s6, s38, 1
	s_and_b32 s30, s6, 0xffffff80
	s_lshl_b32 s6, s39, 12
	v_lshl_add_u64 v[102:103], v[98:99], 0, s[6:7]
	v_add_co_u32_e32 v38, vcc, 0x20000, v102
	s_ashr_i32 s31, s30, 31
	s_nop 0
	v_addc_co_u32_e32 v39, vcc, 0, v103, vcc
	v_add_co_u32_e32 v44, vcc, 0x40000, v102
	s_lshl_b64 s[40:41], s[30:31], 12
	s_nop 0
	v_addc_co_u32_e32 v45, vcc, 0, v103, vcc
	v_add_co_u32_e32 v46, vcc, 0x60000, v102
	v_lshl_add_u64 v[104:105], v[100:101], 0, s[40:41]
	s_nop 0
	v_addc_co_u32_e32 v47, vcc, 0, v103, vcc
	v_add_co_u32_e32 v48, vcc, s35, v104
	s_nop 0
	v_addc_co_u32_e32 v49, vcc, 0, v105, vcc
	v_add_co_u32_e32 v50, vcc, s36, v104
	v_addc_co_u32_e32 v51, vcc, 0, v105, vcc
	v_add_co_u32_e32 v52, vcc, s37, v104
	v_addc_co_u32_e32 v53, vcc, 0, v105, vcc
	s_mov_b32 s31, -2
	v_mov_b32_e32 v8, 0
	v_mov_b32_e32 v9, v97
	v_mov_b32_e32 v10, v97
	v_mov_b32_e32 v11, v97
	v_mov_b32_e32 v24, 0
	v_mov_b32_e32 v25, v97
	v_mov_b32_e32 v26, v97
	v_mov_b32_e32 v27, v97
	v_mov_b32_e32 v36, 0
	v_mov_b32_e32 v37, v97
	v_mov_b32_e32 v38, v97
	v_lshl_add_u64 v[106:107], v[102:103], 0, s[8:9]
	v_lshl_add_u64 v[108:109], v[102:103], 0, s[10:11]
	v_lshl_add_u64 v[110:111], v[102:103], 0, s[12:13]
	v_lshl_add_u64 v[118:119], v[102:103], 0, s[14:15]
	v_lshl_add_u64 v[120:121], v[102:103], 0, s[16:17]
	v_lshl_add_u64 v[122:123], v[102:103], 0, s[18:19]
	v_lshl_add_u64 v[124:125], v[102:103], 0, s[20:21]
	v_lshl_add_u64 v[112:113], v[104:105], 0, s[8:9]
	v_lshl_add_u64 v[114:115], v[104:105], 0, s[10:11]
	v_lshl_add_u64 v[116:117], v[104:105], 0, s[12:13]
	v_lshl_add_u64 v[128:129], v[104:105], 0, s[14:15]
	v_lshl_add_u64 v[130:131], v[104:105], 0, s[16:17]
	v_lshl_add_u64 v[132:133], v[104:105], 0, s[18:19]
	v_lshl_add_u64 v[126:127], v[104:105], 0, s[20:21]
	v_mov_b32_e32 v39, v97
	v_mov_b32_e32 v48, 0
	v_mov_b32_e32 v49, v97
	v_mov_b32_e32 v50, v97
	v_mov_b32_e32 v51, v97
	v_mov_b32_e32 v52, 0
	v_mov_b32_e32 v53, v97
	v_mov_b32_e32 v54, v97
	v_mov_b32_e32 v55, v97
	v_mov_b32_e32 v56, 0
	v_mov_b32_e32 v57, v97
	v_mov_b32_e32 v58, v97
	v_mov_b32_e32 v59, v97
	v_mov_b32_e32 v44, 0
	v_mov_b32_e32 v45, v97
	v_mov_b32_e32 v46, v97
	v_mov_b32_e32 v47, v97
	v_mov_b32_e32 v60, 0
	v_mov_b32_e32 v61, v97
	v_mov_b32_e32 v62, v97
	v_mov_b32_e32 v63, v97
	v_mov_b32_e32 v0, 0
	v_mov_b32_e32 v1, v97
	v_mov_b32_e32 v2, v97
	v_mov_b32_e32 v3, v97
	v_mov_b32_e32 v16, 0
	v_mov_b32_e32 v17, v97
	v_mov_b32_e32 v18, v97
	v_mov_b32_e32 v19, v97
	v_mov_b32_e32 v32, 0
	v_mov_b32_e32 v33, v97
	v_mov_b32_e32 v34, v97
	v_mov_b32_e32 v35, v97
	v_mov_b32_e32 v4, 0
	v_mov_b32_e32 v5, v97
	v_mov_b32_e32 v6, v97
	v_mov_b32_e32 v7, v97
	v_mov_b32_e32 v20, 0
	v_mov_b32_e32 v21, v97
	v_mov_b32_e32 v22, v97
	v_mov_b32_e32 v23, v97
	v_mov_b32_e32 v40, 0
	v_mov_b32_e32 v41, v97
	v_mov_b32_e32 v42, v97
	v_mov_b32_e32 v43, v97
	v_mov_b32_e32 v12, 0
	v_mov_b32_e32 v13, v97
	v_mov_b32_e32 v14, v97
	v_mov_b32_e32 v15, v97
	v_mov_b32_e32 v28, 0
	v_mov_b32_e32 v29, v97
	v_mov_b32_e32 v30, v97
	v_mov_b32_e32 v31, v97
	v_readfirstlane_b32 s40, v102
	v_readfirstlane_b32 s41, v103
	v_readfirstlane_b32 s48, v104
	v_readfirstlane_b32 s49, v105
	v_readfirstlane_b32 s6, v247
	s_nop 3
	s_mul_i32 s32, s6, 0x8000
	s_sub_u32 s40, s40, s32
	s_subb_u32 s41, s41, 0
	s_sub_u32 s48, s48, s32
	s_subb_u32 s49, s49, 0
	s_lshl_b32 s6, s6, 12
	s_add_u32 m0, s6, 0x0
	v_mov_b32_e32 v60, 0
	global_load_lds_dwordx4 v248, s[40:41]
	v_mov_b32_e32 v61, 0
	s_add_u32 m0, s6, 0x400
	v_mov_b32_e32 v62, 0
	global_load_lds_dwordx4 v249, s[40:41]
	v_mov_b32_e32 v63, 0
	s_add_u32 m0, s6, 0x800
	v_mov_b32_e32 v44, 0
	global_load_lds_dwordx4 v250, s[40:41]
	v_mov_b32_e32 v45, 0
	s_add_u32 m0, s6, 0xc00
	v_mov_b32_e32 v46, 0
	global_load_lds_dwordx4 v251, s[40:41]
	v_mov_b32_e32 v47, 0
	s_add_u32 m0, s6, 0x8000
	v_mov_b32_e32 v28, 0
	global_load_lds_dwordx4 v248, s[48:49]
	v_mov_b32_e32 v29, 0
	s_add_u32 m0, s6, 0x8400
	v_mov_b32_e32 v30, 0
	global_load_lds_dwordx4 v249, s[48:49]
	v_mov_b32_e32 v31, 0
	s_add_u32 m0, s6, 0x8800
	v_mov_b32_e32 v12, 0
	global_load_lds_dwordx4 v250, s[48:49]
	v_mov_b32_e32 v13, 0
	s_add_u32 m0, s6, 0x8c00
	v_mov_b32_e32 v14, 0
	global_load_lds_dwordx4 v251, s[48:49]
	v_mov_b32_e32 v15, 0
	s_add_u32 s40, s40, 0x80
	s_addc_u32 s41, s41, 0
	s_add_u32 s48, s48, 0x80
	s_addc_u32 s49, s49, 0
	s_add_u32 m0, s6, 0x4000
	v_mov_b32_e32 v56, 0
	global_load_lds_dwordx4 v248, s[40:41]
	v_mov_b32_e32 v57, 0
	s_add_u32 m0, s6, 0x4400
	v_mov_b32_e32 v58, 0
	global_load_lds_dwordx4 v249, s[40:41]
	v_mov_b32_e32 v59, 0
	s_add_u32 m0, s6, 0x4800
	v_mov_b32_e32 v40, 0
	global_load_lds_dwordx4 v250, s[40:41]
	v_mov_b32_e32 v41, 0
	s_add_u32 m0, s6, 0x4c00
	v_mov_b32_e32 v42, 0
	global_load_lds_dwordx4 v251, s[40:41]
	v_mov_b32_e32 v43, 0
	s_add_u32 m0, s6, 0xc000
	v_mov_b32_e32 v20, 0
	global_load_lds_dwordx4 v248, s[48:49]
	v_mov_b32_e32 v21, 0
	s_add_u32 m0, s6, 0xc400
	v_mov_b32_e32 v22, 0
	global_load_lds_dwordx4 v249, s[48:49]
	v_mov_b32_e32 v23, 0
	s_add_u32 m0, s6, 0xc800
	v_mov_b32_e32 v4, 0
	global_load_lds_dwordx4 v250, s[48:49]
	v_mov_b32_e32 v5, 0
	s_add_u32 m0, s6, 0xcc00
	v_mov_b32_e32 v6, 0
	global_load_lds_dwordx4 v251, s[48:49]
	v_mov_b32_e32 v7, 0
	s_add_u32 s40, s40, 0x80
	s_addc_u32 s41, s41, 0
	s_add_u32 s48, s48, 0x80
	s_addc_u32 s49, s49, 0
	v_mov_b32_e32 v52, 0
	v_mov_b32_e32 v53, 0
	v_mov_b32_e32 v54, 0
	v_mov_b32_e32 v55, 0
	v_mov_b32_e32 v32, 0
	v_mov_b32_e32 v33, 0
	v_mov_b32_e32 v34, 0
	v_mov_b32_e32 v35, 0
	v_mov_b32_e32 v16, 0
	v_mov_b32_e32 v17, 0
	v_mov_b32_e32 v18, 0
	v_mov_b32_e32 v19, 0
	v_mov_b32_e32 v0, 0
	v_mov_b32_e32 v1, 0
	v_mov_b32_e32 v2, 0
	v_mov_b32_e32 v3, 0
	v_mov_b32_e32 v48, 0
	v_mov_b32_e32 v49, 0
	v_mov_b32_e32 v50, 0
	v_mov_b32_e32 v51, 0
	v_mov_b32_e32 v36, 0
	v_mov_b32_e32 v37, 0
	v_mov_b32_e32 v38, 0
	v_mov_b32_e32 v39, 0
	v_mov_b32_e32 v24, 0
	v_mov_b32_e32 v25, 0
	v_mov_b32_e32 v26, 0
	v_mov_b32_e32 v27, 0
	v_mov_b32_e32 v8, 0
	v_mov_b32_e32 v9, 0
	v_mov_b32_e32 v10, 0
	v_mov_b32_e32 v11, 0
	s_waitcnt vmcnt(8)
	s_barrier
	ds_read_b128 v[64:67], v252 offset:0
	ds_read_b128 v[104:107], v254 offset:32768
	ds_read_b128 v[108:111], v254 offset:34816
	ds_read_b128 v[112:115], v254 offset:36864
	ds_read_b128 v[116:119], v254 offset:38912
	ds_read_b128 v[68:71], v252 offset:2048
	ds_read_b128 v[72:75], v252 offset:4096
	ds_read_b128 v[76:79], v252 offset:6144
	ds_read_b128 v[80:83], v253 offset:0
	ds_read_b128 v[120:123], v255 offset:32768
	ds_read_b128 v[124:127], v255 offset:34816
	ds_read_b128 v[132:135], v255 offset:36864
	ds_read_b128 v[136:139], v255 offset:38912
	s_waitcnt lgkmcnt(11)
	v_mfma_f32_16x16x32_bf16 v[60:63], v[64:67], v[104:107], v[60:63]
	s_waitcnt lgkmcnt(10)
	v_mfma_f32_16x16x32_bf16 v[44:47], v[64:67], v[108:111], v[44:47]
	s_waitcnt lgkmcnt(9)
	v_mfma_f32_16x16x32_bf16 v[28:31], v[64:67], v[112:115], v[28:31]
	s_waitcnt lgkmcnt(8)
	v_mfma_f32_16x16x32_bf16 v[12:15], v[64:67], v[116:119], v[12:15]
	ds_read_b128 v[84:87], v253 offset:2048
	ds_read_b128 v[88:91], v253 offset:4096
	ds_read_b128 v[92:95], v253 offset:6144
	s_waitcnt lgkmcnt(10)
	v_mfma_f32_16x16x32_bf16 v[56:59], v[68:71], v[104:107], v[56:59]
	v_mfma_f32_16x16x32_bf16 v[40:43], v[68:71], v[108:111], v[40:43]
	v_mfma_f32_16x16x32_bf16 v[20:23], v[68:71], v[112:115], v[20:23]
	v_mfma_f32_16x16x32_bf16 v[4:7], v[68:71], v[116:119], v[4:7]
	s_waitcnt lgkmcnt(0)
	s_barrier
	s_add_u32 m0, s6, 0x0
	v_mfma_f32_16x16x32_bf16 v[52:55], v[72:75], v[104:107], v[52:55]
	global_load_lds_dwordx4 v248, s[40:41]
	s_add_u32 m0, s6, 0x400
	v_mfma_f32_16x16x32_bf16 v[32:35], v[72:75], v[108:111], v[32:35]
	global_load_lds_dwordx4 v249, s[40:41]
	s_add_u32 m0, s6, 0x800
	v_mfma_f32_16x16x32_bf16 v[16:19], v[72:75], v[112:115], v[16:19]
	global_load_lds_dwordx4 v250, s[40:41]
	s_add_u32 m0, s6, 0xc00
	v_mfma_f32_16x16x32_bf16 v[0:3], v[72:75], v[116:119], v[0:3]
	global_load_lds_dwordx4 v251, s[40:41]
	s_add_u32 m0, s6, 0x8000
	v_mfma_f32_16x16x32_bf16 v[48:51], v[76:79], v[104:107], v[48:51]
	global_load_lds_dwordx4 v248, s[48:49]
	s_add_u32 m0, s6, 0x8400
	v_mfma_f32_16x16x32_bf16 v[36:39], v[76:79], v[108:111], v[36:39]
	global_load_lds_dwordx4 v249, s[48:49]
	s_add_u32 m0, s6, 0x8800
	v_mfma_f32_16x16x32_bf16 v[24:27], v[76:79], v[112:115], v[24:27]
	global_load_lds_dwordx4 v250, s[48:49]
	s_add_u32 m0, s6, 0x8c00
	v_mfma_f32_16x16x32_bf16 v[8:11], v[76:79], v[116:119], v[8:11]
	global_load_lds_dwordx4 v251, s[48:49]
	s_add_u32 s40, s40, 0x80
	s_addc_u32 s41, s41, 0
	s_add_u32 s48, s48, 0x80
	s_addc_u32 s49, s49, 0
	s_waitcnt vmcnt(8)
	s_barrier
	ds_read_b128 v[64:67], v252 offset:16384
	ds_read_b128 v[104:107], v254 offset:49152
	ds_read_b128 v[108:111], v254 offset:51200
	ds_read_b128 v[112:115], v254 offset:53248
	ds_read_b128 v[116:119], v254 offset:55296
	ds_read_b128 v[68:71], v252 offset:18432
	ds_read_b128 v[72:75], v252 offset:20480
	ds_read_b128 v[76:79], v252 offset:22528
	v_mfma_f32_16x16x32_bf16 v[60:63], v[80:83], v[120:123], v[60:63]
	v_mfma_f32_16x16x32_bf16 v[44:47], v[80:83], v[124:127], v[44:47]
	v_mfma_f32_16x16x32_bf16 v[28:31], v[80:83], v[132:135], v[28:31]
	v_mfma_f32_16x16x32_bf16 v[12:15], v[80:83], v[136:139], v[12:15]
	v_mfma_f32_16x16x32_bf16 v[56:59], v[84:87], v[120:123], v[56:59]
	v_mfma_f32_16x16x32_bf16 v[40:43], v[84:87], v[124:127], v[40:43]
	v_mfma_f32_16x16x32_bf16 v[20:23], v[84:87], v[132:135], v[20:23]
	v_mfma_f32_16x16x32_bf16 v[4:7], v[84:87], v[136:139], v[4:7]
	v_mfma_f32_16x16x32_bf16 v[52:55], v[88:91], v[120:123], v[52:55]
	v_mfma_f32_16x16x32_bf16 v[32:35], v[88:91], v[124:127], v[32:35]
	v_mfma_f32_16x16x32_bf16 v[16:19], v[88:91], v[132:135], v[16:19]
	v_mfma_f32_16x16x32_bf16 v[0:3], v[88:91], v[136:139], v[0:3]
	v_mfma_f32_16x16x32_bf16 v[48:51], v[92:95], v[120:123], v[48:51]
	v_mfma_f32_16x16x32_bf16 v[36:39], v[92:95], v[124:127], v[36:39]
	v_mfma_f32_16x16x32_bf16 v[24:27], v[92:95], v[132:135], v[24:27]
	v_mfma_f32_16x16x32_bf16 v[8:11], v[92:95], v[136:139], v[8:11]
	ds_read_b128 v[80:83], v253 offset:16384
	ds_read_b128 v[120:123], v255 offset:49152
	ds_read_b128 v[124:127], v255 offset:51200
	ds_read_b128 v[132:135], v255 offset:53248
	ds_read_b128 v[136:139], v255 offset:55296
	ds_read_b128 v[84:87], v253 offset:18432
	ds_read_b128 v[88:91], v253 offset:20480
	ds_read_b128 v[92:95], v253 offset:22528
	s_waitcnt lgkmcnt(14)
	v_mfma_f32_16x16x32_bf16 v[60:63], v[64:67], v[104:107], v[60:63]
	s_waitcnt lgkmcnt(13)
	v_mfma_f32_16x16x32_bf16 v[44:47], v[64:67], v[108:111], v[44:47]
	s_waitcnt lgkmcnt(12)
	v_mfma_f32_16x16x32_bf16 v[28:31], v[64:67], v[112:115], v[28:31]
	s_waitcnt lgkmcnt(11)
	v_mfma_f32_16x16x32_bf16 v[12:15], v[64:67], v[116:119], v[12:15]
	s_waitcnt lgkmcnt(10)
	v_mfma_f32_16x16x32_bf16 v[56:59], v[68:71], v[104:107], v[56:59]
	v_mfma_f32_16x16x32_bf16 v[40:43], v[68:71], v[108:111], v[40:43]
	v_mfma_f32_16x16x32_bf16 v[20:23], v[68:71], v[112:115], v[20:23]
	v_mfma_f32_16x16x32_bf16 v[4:7], v[68:71], v[116:119], v[4:7]
	s_waitcnt lgkmcnt(0)
	s_barrier
	s_add_u32 m0, s6, 0x4000
	v_mfma_f32_16x16x32_bf16 v[52:55], v[72:75], v[104:107], v[52:55]
	global_load_lds_dwordx4 v248, s[40:41]
	s_add_u32 m0, s6, 0x4400
	v_mfma_f32_16x16x32_bf16 v[32:35], v[72:75], v[108:111], v[32:35]
	global_load_lds_dwordx4 v249, s[40:41]
	s_add_u32 m0, s6, 0x4800
	v_mfma_f32_16x16x32_bf16 v[16:19], v[72:75], v[112:115], v[16:19]
	global_load_lds_dwordx4 v250, s[40:41]
	s_add_u32 m0, s6, 0x4c00
	v_mfma_f32_16x16x32_bf16 v[0:3], v[72:75], v[116:119], v[0:3]
	global_load_lds_dwordx4 v251, s[40:41]
	s_add_u32 m0, s6, 0xc000
	v_mfma_f32_16x16x32_bf16 v[48:51], v[76:79], v[104:107], v[48:51]
	global_load_lds_dwordx4 v248, s[48:49]
	s_add_u32 m0, s6, 0xc400
	v_mfma_f32_16x16x32_bf16 v[36:39], v[76:79], v[108:111], v[36:39]
	global_load_lds_dwordx4 v249, s[48:49]
	s_add_u32 m0, s6, 0xc800
	v_mfma_f32_16x16x32_bf16 v[24:27], v[76:79], v[112:115], v[24:27]
	global_load_lds_dwordx4 v250, s[48:49]
	s_add_u32 m0, s6, 0xcc00
	v_mfma_f32_16x16x32_bf16 v[8:11], v[76:79], v[116:119], v[8:11]
	global_load_lds_dwordx4 v251, s[48:49]
	s_add_u32 s40, s40, 0x80
	s_addc_u32 s41, s41, 0
	s_add_u32 s48, s48, 0x80
	s_addc_u32 s49, s49, 0
	s_mov_b32 s31, 14
.Lg22_loop:
	s_waitcnt vmcnt(8)
	s_barrier
	ds_read_b128 v[64:67], v252 offset:0
	ds_read_b128 v[104:107], v254 offset:32768
	ds_read_b128 v[108:111], v254 offset:34816
	ds_read_b128 v[112:115], v254 offset:36864
	ds_read_b128 v[116:119], v254 offset:38912
	ds_read_b128 v[68:71], v252 offset:2048
	ds_read_b128 v[72:75], v252 offset:4096
	ds_read_b128 v[76:79], v252 offset:6144
	v_mfma_f32_16x16x32_bf16 v[60:63], v[80:83], v[120:123], v[60:63]
	v_mfma_f32_16x16x32_bf16 v[44:47], v[80:83], v[124:127], v[44:47]
	v_mfma_f32_16x16x32_bf16 v[28:31], v[80:83], v[132:135], v[28:31]
	v_mfma_f32_16x16x32_bf16 v[12:15], v[80:83], v[136:139], v[12:15]
	v_mfma_f32_16x16x32_bf16 v[56:59], v[84:87], v[120:123], v[56:59]
	v_mfma_f32_16x16x32_bf16 v[40:43], v[84:87], v[124:127], v[40:43]
	v_mfma_f32_16x16x32_bf16 v[20:23], v[84:87], v[132:135], v[20:23]
	v_mfma_f32_16x16x32_bf16 v[4:7], v[84:87], v[136:139], v[4:7]
	v_mfma_f32_16x16x32_bf16 v[52:55], v[88:91], v[120:123], v[52:55]
	v_mfma_f32_16x16x32_bf16 v[32:35], v[88:91], v[124:127], v[32:35]
	v_mfma_f32_16x16x32_bf16 v[16:19], v[88:91], v[132:135], v[16:19]
	v_mfma_f32_16x16x32_bf16 v[0:3], v[88:91], v[136:139], v[0:3]
	v_mfma_f32_16x16x32_bf16 v[48:51], v[92:95], v[120:123], v[48:51]
	v_mfma_f32_16x16x32_bf16 v[36:39], v[92:95], v[124:127], v[36:39]
	v_mfma_f32_16x16x32_bf16 v[24:27], v[92:95], v[132:135], v[24:27]
	v_mfma_f32_16x16x32_bf16 v[8:11], v[92:95], v[136:139], v[8:11]
	ds_read_b128 v[80:83], v253 offset:0
	ds_read_b128 v[120:123], v255 offset:32768
	ds_read_b128 v[124:127], v255 offset:34816
	ds_read_b128 v[132:135], v255 offset:36864
	ds_read_b128 v[136:139], v255 offset:38912
	ds_read_b128 v[84:87], v253 offset:2048
	ds_read_b128 v[88:91], v253 offset:4096
	ds_read_b128 v[92:95], v253 offset:6144
	s_waitcnt lgkmcnt(14)
	v_mfma_f32_16x16x32_bf16 v[60:63], v[64:67], v[104:107], v[60:63]
	s_waitcnt lgkmcnt(13)
	v_mfma_f32_16x16x32_bf16 v[44:47], v[64:67], v[108:111], v[44:47]
	s_waitcnt lgkmcnt(12)
	v_mfma_f32_16x16x32_bf16 v[28:31], v[64:67], v[112:115], v[28:31]
	s_waitcnt lgkmcnt(11)
	v_mfma_f32_16x16x32_bf16 v[12:15], v[64:67], v[116:119], v[12:15]
	s_waitcnt lgkmcnt(10)
	v_mfma_f32_16x16x32_bf16 v[56:59], v[68:71], v[104:107], v[56:59]
	v_mfma_f32_16x16x32_bf16 v[40:43], v[68:71], v[108:111], v[40:43]
	v_mfma_f32_16x16x32_bf16 v[20:23], v[68:71], v[112:115], v[20:23]
	v_mfma_f32_16x16x32_bf16 v[4:7], v[68:71], v[116:119], v[4:7]
	s_waitcnt lgkmcnt(0)
	s_barrier
	s_add_u32 m0, s6, 0x0
	v_mfma_f32_16x16x32_bf16 v[52:55], v[72:75], v[104:107], v[52:55]
	global_load_lds_dwordx4 v248, s[40:41]
	s_add_u32 m0, s6, 0x400
	v_mfma_f32_16x16x32_bf16 v[32:35], v[72:75], v[108:111], v[32:35]
	global_load_lds_dwordx4 v249, s[40:41]
	s_add_u32 m0, s6, 0x800
	v_mfma_f32_16x16x32_bf16 v[16:19], v[72:75], v[112:115], v[16:19]
	global_load_lds_dwordx4 v250, s[40:41]
	s_add_u32 m0, s6, 0xc00
	v_mfma_f32_16x16x32_bf16 v[0:3], v[72:75], v[116:119], v[0:3]
	global_load_lds_dwordx4 v251, s[40:41]
	s_add_u32 m0, s6, 0x8000
	v_mfma_f32_16x16x32_bf16 v[48:51], v[76:79], v[104:107], v[48:51]
	global_load_lds_dwordx4 v248, s[48:49]
	s_add_u32 m0, s6, 0x8400
	v_mfma_f32_16x16x32_bf16 v[36:39], v[76:79], v[108:111], v[36:39]
	global_load_lds_dwordx4 v249, s[48:49]
	s_add_u32 m0, s6, 0x8800
	v_mfma_f32_16x16x32_bf16 v[24:27], v[76:79], v[112:115], v[24:27]
	global_load_lds_dwordx4 v250, s[48:49]
	s_add_u32 m0, s6, 0x8c00
	v_mfma_f32_16x16x32_bf16 v[8:11], v[76:79], v[116:119], v[8:11]
	global_load_lds_dwordx4 v251, s[48:49]
	s_add_u32 s40, s40, 0x80
	s_addc_u32 s41, s41, 0
	s_add_u32 s48, s48, 0x80
	s_addc_u32 s49, s49, 0
	s_waitcnt vmcnt(8)
	s_barrier
	ds_read_b128 v[64:67], v252 offset:16384
	ds_read_b128 v[104:107], v254 offset:49152
	ds_read_b128 v[108:111], v254 offset:51200
	ds_read_b128 v[112:115], v254 offset:53248
	ds_read_b128 v[116:119], v254 offset:55296
	ds_read_b128 v[68:71], v252 offset:18432
	ds_read_b128 v[72:75], v252 offset:20480
	ds_read_b128 v[76:79], v252 offset:22528
	v_mfma_f32_16x16x32_bf16 v[60:63], v[80:83], v[120:123], v[60:63]
	v_mfma_f32_16x16x32_bf16 v[44:47], v[80:83], v[124:127], v[44:47]
	v_mfma_f32_16x16x32_bf16 v[28:31], v[80:83], v[132:135], v[28:31]
	v_mfma_f32_16x16x32_bf16 v[12:15], v[80:83], v[136:139], v[12:15]
	v_mfma_f32_16x16x32_bf16 v[56:59], v[84:87], v[120:123], v[56:59]
	v_mfma_f32_16x16x32_bf16 v[40:43], v[84:87], v[124:127], v[40:43]
	v_mfma_f32_16x16x32_bf16 v[20:23], v[84:87], v[132:135], v[20:23]
	v_mfma_f32_16x16x32_bf16 v[4:7], v[84:87], v[136:139], v[4:7]
	v_mfma_f32_16x16x32_bf16 v[52:55], v[88:91], v[120:123], v[52:55]
	v_mfma_f32_16x16x32_bf16 v[32:35], v[88:91], v[124:127], v[32:35]
	v_mfma_f32_16x16x32_bf16 v[16:19], v[88:91], v[132:135], v[16:19]
	v_mfma_f32_16x16x32_bf16 v[0:3], v[88:91], v[136:139], v[0:3]
	v_mfma_f32_16x16x32_bf16 v[48:51], v[92:95], v[120:123], v[48:51]
	v_mfma_f32_16x16x32_bf16 v[36:39], v[92:95], v[124:127], v[36:39]
	v_mfma_f32_16x16x32_bf16 v[24:27], v[92:95], v[132:135], v[24:27]
	v_mfma_f32_16x16x32_bf16 v[8:11], v[92:95], v[136:139], v[8:11]
	ds_read_b128 v[80:83], v253 offset:16384
	ds_read_b128 v[120:123], v255 offset:49152
	ds_read_b128 v[124:127], v255 offset:51200
	ds_read_b128 v[132:135], v255 offset:53248
	ds_read_b128 v[136:139], v255 offset:55296
	ds_read_b128 v[84:87], v253 offset:18432
	ds_read_b128 v[88:91], v253 offset:20480
	ds_read_b128 v[92:95], v253 offset:22528
	s_waitcnt lgkmcnt(14)
	v_mfma_f32_16x16x32_bf16 v[60:63], v[64:67], v[104:107], v[60:63]
	s_waitcnt lgkmcnt(13)
	v_mfma_f32_16x16x32_bf16 v[44:47], v[64:67], v[108:111], v[44:47]
	s_waitcnt lgkmcnt(12)
	v_mfma_f32_16x16x32_bf16 v[28:31], v[64:67], v[112:115], v[28:31]
	s_waitcnt lgkmcnt(11)
	v_mfma_f32_16x16x32_bf16 v[12:15], v[64:67], v[116:119], v[12:15]
	s_waitcnt lgkmcnt(10)
	v_mfma_f32_16x16x32_bf16 v[56:59], v[68:71], v[104:107], v[56:59]
	v_mfma_f32_16x16x32_bf16 v[40:43], v[68:71], v[108:111], v[40:43]
	v_mfma_f32_16x16x32_bf16 v[20:23], v[68:71], v[112:115], v[20:23]
	v_mfma_f32_16x16x32_bf16 v[4:7], v[68:71], v[116:119], v[4:7]
	s_waitcnt lgkmcnt(0)
	s_barrier
	s_add_u32 m0, s6, 0x4000
	v_mfma_f32_16x16x32_bf16 v[52:55], v[72:75], v[104:107], v[52:55]
	global_load_lds_dwordx4 v248, s[40:41]
	s_add_u32 m0, s6, 0x4400
	v_mfma_f32_16x16x32_bf16 v[32:35], v[72:75], v[108:111], v[32:35]
	global_load_lds_dwordx4 v249, s[40:41]
	s_add_u32 m0, s6, 0x4800
	v_mfma_f32_16x16x32_bf16 v[16:19], v[72:75], v[112:115], v[16:19]
	global_load_lds_dwordx4 v250, s[40:41]
	s_add_u32 m0, s6, 0x4c00
	v_mfma_f32_16x16x32_bf16 v[0:3], v[72:75], v[116:119], v[0:3]
	global_load_lds_dwordx4 v251, s[40:41]
	s_add_u32 m0, s6, 0xc000
	v_mfma_f32_16x16x32_bf16 v[48:51], v[76:79], v[104:107], v[48:51]
	global_load_lds_dwordx4 v248, s[48:49]
	s_add_u32 m0, s6, 0xc400
	v_mfma_f32_16x16x32_bf16 v[36:39], v[76:79], v[108:111], v[36:39]
	global_load_lds_dwordx4 v249, s[48:49]
	s_add_u32 m0, s6, 0xc800
	v_mfma_f32_16x16x32_bf16 v[24:27], v[76:79], v[112:115], v[24:27]
	global_load_lds_dwordx4 v250, s[48:49]
	s_add_u32 m0, s6, 0xcc00
	v_mfma_f32_16x16x32_bf16 v[8:11], v[76:79], v[116:119], v[8:11]
	global_load_lds_dwordx4 v251, s[48:49]
	s_add_u32 s40, s40, 0x80
	s_addc_u32 s41, s41, 0
	s_add_u32 s48, s48, 0x80
	s_addc_u32 s49, s49, 0
	s_sub_u32 s31, s31, 1
	s_cmp_lg_u32 s31, 0
	s_cbranch_scc1 .Lg22_loop
	s_waitcnt vmcnt(8)
	s_barrier
	ds_read_b128 v[64:67], v252 offset:0
	ds_read_b128 v[104:107], v254 offset:32768
	ds_read_b128 v[108:111], v254 offset:34816
	ds_read_b128 v[112:115], v254 offset:36864
	ds_read_b128 v[116:119], v254 offset:38912
	ds_read_b128 v[68:71], v252 offset:2048
	ds_read_b128 v[72:75], v252 offset:4096
	ds_read_b128 v[76:79], v252 offset:6144
	v_mfma_f32_16x16x32_bf16 v[60:63], v[80:83], v[120:123], v[60:63]
	v_mfma_f32_16x16x32_bf16 v[44:47], v[80:83], v[124:127], v[44:47]
	v_mfma_f32_16x16x32_bf16 v[28:31], v[80:83], v[132:135], v[28:31]
	v_mfma_f32_16x16x32_bf16 v[12:15], v[80:83], v[136:139], v[12:15]
	v_mfma_f32_16x16x32_bf16 v[56:59], v[84:87], v[120:123], v[56:59]
	v_mfma_f32_16x16x32_bf16 v[40:43], v[84:87], v[124:127], v[40:43]
	v_mfma_f32_16x16x32_bf16 v[20:23], v[84:87], v[132:135], v[20:23]
	v_mfma_f32_16x16x32_bf16 v[4:7], v[84:87], v[136:139], v[4:7]
	v_mfma_f32_16x16x32_bf16 v[52:55], v[88:91], v[120:123], v[52:55]
	v_mfma_f32_16x16x32_bf16 v[32:35], v[88:91], v[124:127], v[32:35]
	v_mfma_f32_16x16x32_bf16 v[16:19], v[88:91], v[132:135], v[16:19]
	v_mfma_f32_16x16x32_bf16 v[0:3], v[88:91], v[136:139], v[0:3]
	v_mfma_f32_16x16x32_bf16 v[48:51], v[92:95], v[120:123], v[48:51]
	v_mfma_f32_16x16x32_bf16 v[36:39], v[92:95], v[124:127], v[36:39]
	v_mfma_f32_16x16x32_bf16 v[24:27], v[92:95], v[132:135], v[24:27]
	v_mfma_f32_16x16x32_bf16 v[8:11], v[92:95], v[136:139], v[8:11]
	ds_read_b128 v[80:83], v253 offset:0
	ds_read_b128 v[120:123], v255 offset:32768
	ds_read_b128 v[124:127], v255 offset:34816
	ds_read_b128 v[132:135], v255 offset:36864
	ds_read_b128 v[136:139], v255 offset:38912
	ds_read_b128 v[84:87], v253 offset:2048
	ds_read_b128 v[88:91], v253 offset:4096
	ds_read_b128 v[92:95], v253 offset:6144
	s_waitcnt lgkmcnt(14)
	v_mfma_f32_16x16x32_bf16 v[60:63], v[64:67], v[104:107], v[60:63]
	s_waitcnt lgkmcnt(13)
	v_mfma_f32_16x16x32_bf16 v[44:47], v[64:67], v[108:111], v[44:47]
	s_waitcnt lgkmcnt(12)
	v_mfma_f32_16x16x32_bf16 v[28:31], v[64:67], v[112:115], v[28:31]
	s_waitcnt lgkmcnt(11)
	v_mfma_f32_16x16x32_bf16 v[12:15], v[64:67], v[116:119], v[12:15]
	s_waitcnt lgkmcnt(10)
	v_mfma_f32_16x16x32_bf16 v[56:59], v[68:71], v[104:107], v[56:59]
	v_mfma_f32_16x16x32_bf16 v[40:43], v[68:71], v[108:111], v[40:43]
	v_mfma_f32_16x16x32_bf16 v[20:23], v[68:71], v[112:115], v[20:23]
	v_mfma_f32_16x16x32_bf16 v[4:7], v[68:71], v[116:119], v[4:7]
	s_waitcnt lgkmcnt(0)
	s_barrier
	v_mfma_f32_16x16x32_bf16 v[52:55], v[72:75], v[104:107], v[52:55]
	v_mfma_f32_16x16x32_bf16 v[32:35], v[72:75], v[108:111], v[32:35]
	v_mfma_f32_16x16x32_bf16 v[16:19], v[72:75], v[112:115], v[16:19]
	v_mfma_f32_16x16x32_bf16 v[0:3], v[72:75], v[116:119], v[0:3]
	v_mfma_f32_16x16x32_bf16 v[48:51], v[76:79], v[104:107], v[48:51]
	v_mfma_f32_16x16x32_bf16 v[36:39], v[76:79], v[108:111], v[36:39]
	v_mfma_f32_16x16x32_bf16 v[24:27], v[76:79], v[112:115], v[24:27]
	v_mfma_f32_16x16x32_bf16 v[8:11], v[76:79], v[116:119], v[8:11]
	s_waitcnt vmcnt(0)
	s_barrier
	ds_read_b128 v[64:67], v252 offset:16384
	ds_read_b128 v[104:107], v254 offset:49152
	ds_read_b128 v[108:111], v254 offset:51200
	ds_read_b128 v[112:115], v254 offset:53248
	ds_read_b128 v[116:119], v254 offset:55296
	ds_read_b128 v[68:71], v252 offset:18432
	ds_read_b128 v[72:75], v252 offset:20480
	ds_read_b128 v[76:79], v252 offset:22528
	v_mfma_f32_16x16x32_bf16 v[60:63], v[80:83], v[120:123], v[60:63]
	v_mfma_f32_16x16x32_bf16 v[44:47], v[80:83], v[124:127], v[44:47]
	v_mfma_f32_16x16x32_bf16 v[28:31], v[80:83], v[132:135], v[28:31]
	v_mfma_f32_16x16x32_bf16 v[12:15], v[80:83], v[136:139], v[12:15]
	v_mfma_f32_16x16x32_bf16 v[56:59], v[84:87], v[120:123], v[56:59]
	v_mfma_f32_16x16x32_bf16 v[40:43], v[84:87], v[124:127], v[40:43]
	v_mfma_f32_16x16x32_bf16 v[20:23], v[84:87], v[132:135], v[20:23]
	v_mfma_f32_16x16x32_bf16 v[4:7], v[84:87], v[136:139], v[4:7]
	v_mfma_f32_16x16x32_bf16 v[52:55], v[88:91], v[120:123], v[52:55]
	v_mfma_f32_16x16x32_bf16 v[32:35], v[88:91], v[124:127], v[32:35]
	v_mfma_f32_16x16x32_bf16 v[16:19], v[88:91], v[132:135], v[16:19]
	v_mfma_f32_16x16x32_bf16 v[0:3], v[88:91], v[136:139], v[0:3]
	v_mfma_f32_16x16x32_bf16 v[48:51], v[92:95], v[120:123], v[48:51]
	v_mfma_f32_16x16x32_bf16 v[36:39], v[92:95], v[124:127], v[36:39]
	v_mfma_f32_16x16x32_bf16 v[24:27], v[92:95], v[132:135], v[24:27]
	v_mfma_f32_16x16x32_bf16 v[8:11], v[92:95], v[136:139], v[8:11]
	ds_read_b128 v[80:83], v253 offset:16384
	ds_read_b128 v[120:123], v255 offset:49152
	ds_read_b128 v[124:127], v255 offset:51200
	ds_read_b128 v[132:135], v255 offset:53248
	ds_read_b128 v[136:139], v255 offset:55296
	ds_read_b128 v[84:87], v253 offset:18432
	ds_read_b128 v[88:91], v253 offset:20480
	ds_read_b128 v[92:95], v253 offset:22528
	s_waitcnt lgkmcnt(14)
	v_mfma_f32_16x16x32_bf16 v[60:63], v[64:67], v[104:107], v[60:63]
	s_waitcnt lgkmcnt(13)
	v_mfma_f32_16x16x32_bf16 v[44:47], v[64:67], v[108:111], v[44:47]
	s_waitcnt lgkmcnt(12)
	v_mfma_f32_16x16x32_bf16 v[28:31], v[64:67], v[112:115], v[28:31]
	s_waitcnt lgkmcnt(11)
	v_mfma_f32_16x16x32_bf16 v[12:15], v[64:67], v[116:119], v[12:15]
	s_waitcnt lgkmcnt(10)
	v_mfma_f32_16x16x32_bf16 v[56:59], v[68:71], v[104:107], v[56:59]
	v_mfma_f32_16x16x32_bf16 v[40:43], v[68:71], v[108:111], v[40:43]
	v_mfma_f32_16x16x32_bf16 v[20:23], v[68:71], v[112:115], v[20:23]
	v_mfma_f32_16x16x32_bf16 v[4:7], v[68:71], v[116:119], v[4:7]
	s_waitcnt lgkmcnt(0)
	s_barrier
	v_mfma_f32_16x16x32_bf16 v[52:55], v[72:75], v[104:107], v[52:55]
	v_mfma_f32_16x16x32_bf16 v[32:35], v[72:75], v[108:111], v[32:35]
	v_mfma_f32_16x16x32_bf16 v[16:19], v[72:75], v[112:115], v[16:19]
	v_mfma_f32_16x16x32_bf16 v[0:3], v[72:75], v[116:119], v[0:3]
	v_mfma_f32_16x16x32_bf16 v[48:51], v[76:79], v[104:107], v[48:51]
	v_mfma_f32_16x16x32_bf16 v[36:39], v[76:79], v[108:111], v[36:39]
	v_mfma_f32_16x16x32_bf16 v[24:27], v[76:79], v[112:115], v[24:27]
	v_mfma_f32_16x16x32_bf16 v[8:11], v[76:79], v[116:119], v[8:11]
	v_mfma_f32_16x16x32_bf16 v[60:63], v[80:83], v[120:123], v[60:63]
	v_mfma_f32_16x16x32_bf16 v[44:47], v[80:83], v[124:127], v[44:47]
	v_mfma_f32_16x16x32_bf16 v[28:31], v[80:83], v[132:135], v[28:31]
	v_mfma_f32_16x16x32_bf16 v[12:15], v[80:83], v[136:139], v[12:15]
	v_mfma_f32_16x16x32_bf16 v[56:59], v[84:87], v[120:123], v[56:59]
	v_mfma_f32_16x16x32_bf16 v[40:43], v[84:87], v[124:127], v[40:43]
	v_mfma_f32_16x16x32_bf16 v[20:23], v[84:87], v[132:135], v[20:23]
	v_mfma_f32_16x16x32_bf16 v[4:7], v[84:87], v[136:139], v[4:7]
	v_mfma_f32_16x16x32_bf16 v[52:55], v[88:91], v[120:123], v[52:55]
	v_mfma_f32_16x16x32_bf16 v[32:35], v[88:91], v[124:127], v[32:35]
	v_mfma_f32_16x16x32_bf16 v[16:19], v[88:91], v[132:135], v[16:19]
	v_mfma_f32_16x16x32_bf16 v[0:3], v[88:91], v[136:139], v[0:3]
	v_mfma_f32_16x16x32_bf16 v[48:51], v[92:95], v[120:123], v[48:51]
	v_mfma_f32_16x16x32_bf16 v[36:39], v[92:95], v[124:127], v[36:39]
	v_mfma_f32_16x16x32_bf16 v[24:27], v[92:95], v[132:135], v[24:27]
	v_mfma_f32_16x16x32_bf16 v[8:11], v[92:95], v[136:139], v[8:11]
	s_nop 7
	s_nop 1
	v_sub_co_u32_e32 v64, vcc, s39, v149
	s_nop 0
	v_readfirstlane_b32 s6, v64
	s_lshr_b32 s6, s6, 10
	s_add_i32 s6, s6, 1
	s_and_b64 s[40:41], vcc, exec
	s_cselect_b32 s6, 0, s6
	s_mul_hi_u32 s31, s6, 0x6000
	s_mulk_i32 s6, 0x6000
	v_or_b32_e32 v64, s30, v147
	s_add_u32 s40, s2, s6
	v_ashrrev_i32_e32 v65, 31, v64
	s_addc_u32 s41, s3, s31
	v_add_lshl_u32 v94, v148, s39, 12
	v_lshlrev_b64 v[66:67], 2, v[64:65]
	v_lshl_add_u64 v[102:103], s[40:41], 0, v[66:67]
	v_lshl_add_u64 v[134:135], s[4:5], 0, v[66:67]
	v_mov_b32_e32 v95, v97
	v_or_b32_e32 v66, 0x1000, v94
	v_mov_b32_e32 v67, v97
	v_lshl_add_u64 v[104:105], v[134:135], 0, v[94:95]
	global_load_dword v65, v[102:103], off
	global_load_dword v150, v[104:105], off
	v_lshl_add_u64 v[106:107], v[134:135], 0, v[66:67]
	v_or_b32_e32 v68, 0x2000, v94
	v_mov_b32_e32 v69, v97
	v_or_b32_e32 v70, 0x3000, v94
	v_mov_b32_e32 v71, v97
	v_or_b32_e32 v72, 0x10000, v94
	v_mov_b32_e32 v73, v97
	global_load_dword v151, v[106:107], off
	v_lshl_add_u64 v[108:109], v[134:135], 0, v[68:69]
	v_lshl_add_u64 v[110:111], v[134:135], 0, v[70:71]
	v_lshl_add_u64 v[112:113], v[134:135], 0, v[72:73]
	v_or_b32_e32 v74, 0x11000, v94
	v_mov_b32_e32 v75, v97
	global_load_dword v152, v[108:109], off
	global_load_dword v153, v[110:111], off
	global_load_dword v154, v[112:113], off
	v_lshl_add_u64 v[114:115], v[134:135], 0, v[74:75]
	v_or_b32_e32 v76, 0x12000, v94
	v_mov_b32_e32 v77, v97
	v_or_b32_e32 v78, 0x13000, v94
	v_mov_b32_e32 v79, v97
	v_or_b32_e32 v80, 0x20000, v94
	v_mov_b32_e32 v81, v97
	global_load_dword v155, v[114:115], off
	v_or_b32_e32 v96, 0x30000, v94
	v_lshl_add_u64 v[116:117], v[134:135], 0, v[76:77]
	v_lshl_add_u64 v[118:119], v[134:135], 0, v[78:79]
	v_lshl_add_u64 v[120:121], v[134:135], 0, v[80:81]
	v_or_b32_e32 v82, 0x21000, v94
	v_mov_b32_e32 v83, v97
	global_load_dword v156, v[116:117], off
	global_load_dword v157, v[118:119], off
	global_load_dword v158, v[120:121], off
	v_lshl_add_u64 v[122:123], v[134:135], 0, v[82:83]
	v_or_b32_e32 v84, 0x22000, v94
	v_mov_b32_e32 v85, v97
	v_or_b32_e32 v86, 0x23000, v94
	v_mov_b32_e32 v87, v97
	v_lshl_add_u64 v[128:129], v[134:135], 0, v[96:97]
	v_lshl_add_u64 v[124:125], v[134:135], 0, v[84:85]
	v_lshl_add_u64 v[126:127], v[134:135], 0, v[86:87]
	global_load_dword v159, v[122:123], off
	global_load_dword v160, v[124:125], off
	global_load_dword v161, v[126:127], off
	global_load_dword v164, v[128:129], off
	v_or_b32_e32 v88, 0x31000, v94
	v_mov_b32_e32 v89, v97
	v_lshl_add_u64 v[130:131], v[134:135], 0, v[88:89]
	v_or_b32_e32 v90, 0x32000, v94
	v_mov_b32_e32 v91, v97
	v_or_b32_e32 v92, 0x33000, v94
	v_mov_b32_e32 v93, v97
	v_lshl_add_u64 v[132:133], v[134:135], 0, v[90:91]
	v_lshl_add_u64 v[134:135], v[134:135], 0, v[92:93]
	global_load_dword v165, v[130:131], off
	global_load_dword v166, v[132:133], off
	global_load_dword v167, v[134:135], off
	v_or_b32_e32 v136, 16, v64
	v_ashrrev_i32_e32 v137, 31, v136
	v_lshlrev_b64 v[136:137], 2, v[136:137]
	v_lshl_add_u64 v[94:95], s[4:5], 0, v[94:95]
	global_load_dword v168, v[102:103], off offset:64
	v_lshl_add_u64 v[140:141], s[4:5], 0, v[136:137]
	v_lshl_add_u64 v[136:137], v[94:95], 0, v[136:137]
	v_add_f32_e32 v60, 0, v60
	v_lshl_add_u64 v[138:139], v[140:141], 0, v[66:67]
	global_load_dword v169, v[136:137], off
	global_load_dword v170, v[138:139], off
	global_load_dword v171, v[102:103], off offset:128
	global_load_dword v172, v[102:103], off offset:192
	v_lshl_add_u64 v[102:103], v[140:141], 0, v[68:69]
	global_load_dword v173, v[102:103], off
	v_add_f32_e32 v56, 0, v56
	v_add_f32_e32 v58, 0, v58
	v_add_f32_e32 v52, 0, v52
	v_add_f32_e32 v48, 0, v48
	v_add_f32_e32 v44, 0, v44
	v_add_f32_e32 v50, 0, v50
	v_add_f32_e32 v32, 0, v32
	v_add_f32_e32 v34, 0, v34
	v_add_f32_e32 v40, 0, v40
	v_add_f32_e32 v38, 0, v38
	v_add_f32_e32 v36, 0, v36
	v_add_f32_e32 v28, 0, v28
	v_add_f32_e32 v30, 0, v30
	v_add_f32_e32 v20, 0, v20
	s_waitcnt vmcnt(21)
	v_fmac_f32_e32 v150, v60, v65
	v_add_f32_e32 v60, 0, v61
	global_store_dword v[104:105], v150, off
	v_lshl_add_u64 v[104:105], v[140:141], 0, v[72:73]
	v_add_f32_e32 v16, 0, v16
	v_add_f32_e32 v0, 0, v0
	v_add_f32_e32 v12, 0, v12
	v_add_f32_e32 v4, 0, v4
	s_waitcnt vmcnt(21)
	v_fmac_f32_e32 v151, v60, v65
	v_add_f32_e32 v60, 0, v62
	v_add_f32_e32 v62, 0, v63
	global_store_dword v[106:107], v151, off
	v_lshl_add_u64 v[106:107], v[140:141], 0, v[76:77]
	global_load_dword v151, v[104:105], off
	s_waitcnt vmcnt(22)
	v_fmac_f32_e32 v152, v60, v65
	global_store_dword v[108:109], v152, off
	s_waitcnt vmcnt(21)
	v_fmac_f32_e32 v154, v56, v65
	v_add_f32_e32 v56, 0, v57
	v_lshl_add_u64 v[108:109], v[140:141], 0, v[80:81]
	v_lshl_add_u64 v[60:61], v[140:141], 0, v[70:71]
	global_store_dword v[112:113], v154, off
	v_add_f32_e32 v112, 0, v59
	v_fmac_f32_e32 v153, v62, v65
	global_store_dword v[110:111], v153, off
	s_waitcnt vmcnt(22)
	v_fmac_f32_e32 v155, v56, v65
	global_store_dword v[114:115], v155, off
	global_load_dword v155, v[108:109], off
	v_lshl_add_u64 v[62:63], v[140:141], 0, v[74:75]
	global_load_dword v150, v[60:61], off
	global_load_dword v153, v[106:107], off
	v_lshl_add_u64 v[110:111], v[140:141], 0, v[82:83]
	s_waitcnt vmcnt(25)
	v_fmac_f32_e32 v156, v58, v65
	v_lshl_add_u64 v[58:59], v[140:141], 0, v[84:85]
	s_waitcnt vmcnt(23)
	v_fmac_f32_e32 v158, v52, v65
	v_add_f32_e32 v52, 0, v53
	global_store_dword v[116:117], v156, off
	global_load_dword v156, v[58:59], off
	v_fmac_f32_e32 v157, v112, v65
	v_lshl_add_u64 v[112:113], v[140:141], 0, v[86:87]
	global_load_dword v175, v[112:113], off
	s_waitcnt vmcnt(25)
	v_fmac_f32_e32 v159, v52, v65
	v_add_f32_e32 v52, 0, v54
	s_waitcnt vmcnt(24)
	v_fmac_f32_e32 v160, v52, v65
	s_waitcnt vmcnt(22)
	v_fmac_f32_e32 v164, v48, v65
	v_add_f32_e32 v48, 0, v49
	v_lshl_add_u64 v[52:53], v[140:141], 0, v[90:91]
	v_lshl_add_u64 v[114:115], v[140:141], 0, v[96:97]
	global_store_dword v[120:121], v158, off
	global_load_dword v120, v[52:53], off
	v_lshl_add_u64 v[56:57], v[140:141], 0, v[78:79]
	global_load_dword v174, v[110:111], off
	global_load_dword v154, v[56:57], off
	s_waitcnt vmcnt(25)
	v_fmac_f32_e32 v165, v48, v65
	v_lshl_add_u64 v[48:49], v[140:141], 0, v[92:93]
	global_load_dword v121, v[48:49], off
	s_waitcnt vmcnt(25)
	v_fmac_f32_e32 v166, v50, v65
	global_store_dword v[118:119], v157, off
	global_load_dword v118, v[114:115], off
	v_add_f32_e32 v50, 0, v51
	global_load_dword v152, v[62:63], off
	s_waitcnt vmcnt(25)
	v_fmac_f32_e32 v169, v44, v168
	v_add_f32_e32 v44, 0, v45
	s_waitcnt vmcnt(24)
	v_fmac_f32_e32 v170, v44, v168
	v_add_f32_e32 v44, 0, v46
	v_add_f32_e32 v54, 0, v55
	s_waitcnt vmcnt(21)
	v_fmac_f32_e32 v173, v44, v168
	v_or_b32_e32 v44, 32, v64
	v_ashrrev_i32_e32 v45, 31, v44
	v_lshlrev_b64 v[44:45], 2, v[44:45]
	v_fmac_f32_e32 v167, v50, v65
	v_lshl_add_u64 v[50:51], v[94:95], 0, v[44:45]
	v_lshl_add_u64 v[44:45], s[4:5], 0, v[44:45]
	v_fmac_f32_e32 v161, v54, v65
	v_lshl_add_u64 v[54:55], v[44:45], 0, v[78:79]
	v_add_f32_e32 v46, 0, v47
	v_lshl_add_u64 v[116:117], v[140:141], 0, v[88:89]
	global_load_dword v119, v[116:117], off
	v_or_b32_e32 v64, 48, v64
	global_store_dword v[102:103], v173, off
	v_ashrrev_i32_e32 v65, 31, v64
	v_lshlrev_b64 v[64:65], 2, v[64:65]
	global_store_dword v[122:123], v159, off
	global_store_dword v[124:125], v160, off
	global_store_dword v[126:127], v161, off
	global_store_dword v[128:129], v164, off
	global_store_dword v[130:131], v165, off
	global_store_dword v[132:133], v166, off
	global_store_dword v[134:135], v167, off
	global_store_dword v[136:137], v169, off
	global_store_dword v[138:139], v170, off
	v_lshl_add_u64 v[94:95], v[94:95], 0, v[64:65]
	v_lshl_add_u64 v[64:65], s[4:5], 0, v[64:65]
	v_add_f32_e32 v21, 0, v21
	s_waitcnt vmcnt(29)
	v_fmac_f32_e32 v151, v40, v168
	v_add_f32_e32 v40, 0, v41
	global_store_dword v[104:105], v151, off
	s_add_i32 s38, s38, s34
	s_cmpk_gt_i32 s38, 0x1ff
	s_waitcnt vmcnt(25)
	v_fmac_f32_e32 v155, v32, v168
	global_store_dword v[108:109], v155, off
	global_load_dword v109, v[54:55], off
	s_waitcnt vmcnt(26)
	v_fmac_f32_e32 v150, v46, v168
	v_lshl_add_u64 v[46:47], v[44:45], 0, v[66:67]
	global_load_dword v102, v[50:51], off
	global_load_dword v103, v[46:47], off
	v_add_f32_e32 v32, 0, v33
	global_store_dword v[60:61], v150, off
	v_lshl_add_u64 v[60:61], v[44:45], 0, v[88:89]
	s_waitcnt vmcnt(26)
	v_fmac_f32_e32 v156, v34, v168
	global_store_dword v[58:59], v156, off
	v_add_f32_e32 v34, 0, v35
	v_add_f32_e32 v58, 0, v39
	s_waitcnt vmcnt(26)
	v_fmac_f32_e32 v175, v34, v168
	global_store_dword v[112:113], v175, off
	v_lshl_add_u64 v[34:35], v[44:45], 0, v[72:73]
	v_lshl_add_u64 v[66:67], v[64:65], 0, v[66:67]
	s_waitcnt vmcnt(25)
	v_fmac_f32_e32 v120, v38, v168
	global_store_dword v[52:53], v120, off
	s_waitcnt vmcnt(25)
	v_fmac_f32_e32 v174, v32, v168
	v_lshl_add_u64 v[52:53], v[44:45], 0, v[82:83]
	global_store_dword v[110:111], v174, off
	v_lshl_add_u64 v[32:33], v[44:45], 0, v[70:71]
	s_waitcnt vmcnt(24)
	v_fmac_f32_e32 v121, v58, v168
	v_lshl_add_u64 v[58:59], v[44:45], 0, v[86:87]
	global_load_dword v113, v[58:59], off
	global_load_dword v111, v[52:53], off
	s_waitcnt vmcnt(24)
	v_fmac_f32_e32 v118, v36, v168
	s_waitcnt vmcnt(23)
	v_fmac_f32_e32 v152, v40, v168
	v_add_f32_e32 v40, 0, v42
	v_add_f32_e32 v42, 0, v43
	v_fmac_f32_e32 v154, v42, v168
	global_store_dword v[56:57], v154, off
	v_lshl_add_u64 v[56:57], v[44:45], 0, v[80:81]
	global_store_dword v[114:115], v118, off
	global_load_dword v110, v[56:57], off
	global_load_dword v105, v[32:33], off
	v_add_f32_e32 v36, 0, v37
	global_load_dword v115, v[60:61], off
	v_fmac_f32_e32 v153, v40, v168
	v_lshl_add_u64 v[40:41], v[44:45], 0, v[68:69]
	global_load_dword v104, v[40:41], off
	v_lshl_add_u64 v[42:43], v[44:45], 0, v[76:77]
	global_store_dword v[106:107], v153, off
	global_load_dword v106, v[34:35], off
	s_waitcnt vmcnt(30)
	v_fmac_f32_e32 v119, v36, v168
	global_store_dword v[48:49], v121, off
	v_lshl_add_u64 v[48:49], v[44:45], 0, v[96:97]
	global_store_dword v[62:63], v152, off
	v_lshl_add_u64 v[36:37], v[44:45], 0, v[74:75]
	global_store_dword v[116:117], v119, off
	v_lshl_add_u64 v[38:39], v[44:45], 0, v[84:85]
	global_load_dword v114, v[48:49], off
	v_lshl_add_u64 v[62:63], v[44:45], 0, v[90:91]
	global_load_dword v107, v[36:37], off
	global_load_dword v108, v[42:43], off
	global_load_dword v112, v[38:39], off
	v_lshl_add_u64 v[44:45], v[44:45], 0, v[92:93]
	global_load_dword v116, v[62:63], off
	global_load_dword v117, v[44:45], off
	v_lshl_add_u64 v[68:69], v[64:65], 0, v[68:69]
	global_load_dword v120, v[68:69], off
	global_load_dword v118, v[94:95], off
	global_load_dword v119, v[66:67], off
	s_waitcnt vmcnt(28)
	v_fmac_f32_e32 v102, v28, v171
	global_store_dword v[50:51], v102, off
	v_lshl_add_u64 v[50:51], v[64:65], 0, v[70:71]
	v_add_f32_e32 v70, 0, v29
	v_lshl_add_u64 v[28:29], v[64:65], 0, v[72:73]
	s_waitcnt vmcnt(28)
	v_fmac_f32_e32 v103, v70, v171
	v_lshl_add_u64 v[70:71], v[64:65], 0, v[74:75]
	v_lshl_add_u64 v[72:73], v[64:65], 0, v[78:79]
	v_lshl_add_u64 v[74:75], v[64:65], 0, v[80:81]
	global_load_dword v122, v[70:71], off
	global_load_dword v123, v[72:73], off
	global_load_dword v124, v[74:75], off
	global_load_dword v102, v[50:51], off
	global_load_dword v121, v[28:29], off
	v_lshl_add_u64 v[78:79], v[64:65], 0, v[88:89]
	global_store_dword v[46:47], v103, off
	v_lshl_add_u64 v[46:47], v[64:65], 0, v[76:77]
	global_load_dword v103, v[46:47], off
	v_add_f32_e32 v76, 0, v31
	v_lshl_add_u64 v[80:81], v[64:65], 0, v[90:91]
	s_waitcnt vmcnt(25)
	v_fmac_f32_e32 v110, v16, v171
	s_waitcnt vmcnt(24)
	v_fmac_f32_e32 v105, v76, v171
	v_lshl_add_u64 v[76:77], v[64:65], 0, v[86:87]
	global_store_dword v[32:33], v105, off
	v_lshl_add_u64 v[32:33], v[64:65], 0, v[96:97]
	global_load_dword v86, v[78:79], off
	s_waitcnt vmcnt(24)
	v_fmac_f32_e32 v104, v30, v171
	global_store_dword v[40:41], v104, off
	v_lshl_add_u64 v[40:41], v[64:65], 0, v[82:83]
	global_load_dword v82, v[40:41], off
	v_lshl_add_u64 v[30:31], v[64:65], 0, v[84:85]
	global_load_dword v83, v[30:31], off
	global_load_dword v85, v[32:33], off
	global_load_dword v84, v[76:77], off
	s_waitcnt vmcnt(27)
	v_fmac_f32_e32 v106, v20, v171
	global_load_dword v20, v[80:81], off
	v_add_f32_e32 v16, 0, v17
	global_store_dword v[34:35], v106, off
	v_lshl_add_u64 v[34:35], v[64:65], 0, v[92:93]
	global_load_dword v64, v[34:35], off
	v_fmac_f32_e32 v111, v16, v171
	v_add_f32_e32 v16, 0, v18
	s_waitcnt vmcnt(23)
	v_fmac_f32_e32 v112, v16, v171
	v_add_f32_e32 v16, 0, v19
	v_fmac_f32_e32 v113, v16, v171
	v_add_f32_e32 v16, 0, v24
	v_fmac_f32_e32 v114, v16, v171
	v_add_f32_e32 v16, 0, v25
	s_waitcnt vmcnt(19)
	v_fmac_f32_e32 v118, v12, v172
	v_add_f32_e32 v12, 0, v13
	v_fmac_f32_e32 v107, v21, v171
	v_add_f32_e32 v21, 0, v22
	v_fmac_f32_e32 v115, v16, v171
	v_add_f32_e32 v16, 0, v26
	s_waitcnt vmcnt(18)
	v_fmac_f32_e32 v119, v12, v172
	v_add_f32_e32 v12, 0, v14
	v_fmac_f32_e32 v108, v21, v171
	v_add_f32_e32 v21, 0, v23
	v_fmac_f32_e32 v116, v16, v171
	v_add_f32_e32 v16, 0, v27
	v_fmac_f32_e32 v120, v12, v172
	v_add_f32_e32 v12, 0, v15
	v_fmac_f32_e32 v109, v21, v171
	v_fmac_f32_e32 v117, v16, v171
	global_store_dword v[36:37], v107, off
	global_store_dword v[42:43], v108, off
	global_store_dword v[54:55], v109, off
	global_store_dword v[56:57], v110, off
	global_store_dword v[52:53], v111, off
	global_store_dword v[38:39], v112, off
	global_store_dword v[58:59], v113, off
	global_store_dword v[48:49], v114, off
	global_store_dword v[60:61], v115, off
	global_store_dword v[62:63], v116, off
	global_store_dword v[44:45], v117, off
	global_store_dword v[94:95], v118, off
	s_waitcnt vmcnt(26)
	v_fmac_f32_e32 v124, v0, v172
	v_add_f32_e32 v0, 0, v1
	s_waitcnt vmcnt(24)
	v_fmac_f32_e32 v121, v4, v172
	v_add_f32_e32 v4, 0, v5
	v_fmac_f32_e32 v122, v4, v172
	v_add_f32_e32 v4, 0, v6
	s_waitcnt vmcnt(22)
	v_fmac_f32_e32 v103, v4, v172
	v_add_f32_e32 v4, 0, v7
	v_fmac_f32_e32 v102, v12, v172
	v_fmac_f32_e32 v123, v4, v172
	global_store_dword v[66:67], v119, off
	global_store_dword v[68:69], v120, off
	global_store_dword v[50:51], v102, off
	global_store_dword v[28:29], v121, off
	global_store_dword v[70:71], v122, off
	global_store_dword v[46:47], v103, off
	global_store_dword v[72:73], v123, off
	global_store_dword v[74:75], v124, off
	s_waitcnt vmcnt(26)
	v_fmac_f32_e32 v82, v0, v172
	v_add_f32_e32 v0, 0, v2
	s_waitcnt vmcnt(25)
	v_fmac_f32_e32 v83, v0, v172
	v_add_f32_e32 v0, 0, v3
	s_waitcnt vmcnt(23)
	v_fmac_f32_e32 v84, v0, v172
	v_add_f32_e32 v0, 0, v8
	v_fmac_f32_e32 v85, v0, v172
	v_add_f32_e32 v0, 0, v9
	v_fmac_f32_e32 v86, v0, v172
	v_add_f32_e32 v0, 0, v10
	s_waitcnt vmcnt(22)
	v_fmac_f32_e32 v20, v0, v172
	v_add_f32_e32 v0, 0, v11
	s_waitcnt vmcnt(20)
	v_fmac_f32_e32 v64, v0, v172
	global_store_dword v[40:41], v82, off
	global_store_dword v[30:31], v83, off
	global_store_dword v[76:77], v84, off
	global_store_dword v[32:33], v85, off
	global_store_dword v[78:79], v86, off
	global_store_dword v[80:81], v20, off
	global_store_dword v[34:35], v64, off
	s_cbranch_scc0 .LBB0_2295

.LBB0_2417:
	s_lshl_b32 s8, s3, 11
	s_and_b32 s8, s8, 0xfc0000
	s_add_i32 s51, s55, s2
	s_cmpk_gt_i32 s51, 0xaff
	v_lshl_add_u64 v[116:117], v[106:107], 0, s[8:9]
	s_cselect_b64 s[26:27], -1, 0
	s_lshl_b32 s8, s51, 18
	s_and_b32 s8, s8, 0xfc0000
	s_add_u32 s8, s4, s8
	s_addc_u32 s59, s5, 0
	s_ashr_i32 s30, s51, 6
	s_ashr_i32 s31, s30, 31
	s_lshl_b64 s[30:31], s[30:31], 18
	s_add_u32 s62, s6, s30
	s_addc_u32 s63, s7, s31
	s_cmpk_lt_i32 s51, 0xb00
	s_cselect_b64 vcc, -1, 0
	s_and_b64 s[30:31], vcc, exec
	s_cselect_b32 s31, s59, 0
	s_cselect_b32 s30, s8, 0
	v_lshl_add_u64 v[2:3], s[30:31], 0, v[108:109]
	v_lshl_add_u64 v[0:1], v[112:113], 0, s[24:25]
	s_cselect_b32 s63, s63, 0
	s_cselect_b32 s62, s62, 0
	v_lshl_add_u64 v[2:3], v[2:3], 0, v[110:111]
	v_cndmask_b32_e32 v131, v1, v3, vcc
	v_cndmask_b32_e32 v96, v0, v2, vcc
	v_lshl_add_u64 v[0:1], s[62:63], 0, v[108:109]
	v_lshl_add_u64 v[0:1], v[0:1], 0, v[110:111]
	v_lshl_add_u64 v[2:3], v[114:115], 0, s[24:25]
	v_cndmask_b32_e32 v130, v2, v0, vcc
	v_mov_b32_e32 v0, 0
	v_lshl_add_u64 v[136:137], v[112:113], 0, s[10:11]
	v_lshl_add_u64 v[118:119], v[112:113], 0, s[12:13]
	v_lshl_add_u64 v[140:141], v[112:113], 0, s[14:15]
	v_lshl_add_u64 v[120:121], v[112:113], 0, s[16:17]
	v_lshl_add_u64 v[142:143], v[112:113], 0, s[18:19]
	v_lshl_add_u64 v[122:123], v[112:113], 0, s[20:21]
	v_lshl_add_u64 v[144:145], v[112:113], 0, s[22:23]
	v_lshl_add_u64 v[138:139], v[114:115], 0, s[10:11]
	v_lshl_add_u64 v[124:125], v[114:115], 0, s[12:13]
	v_lshl_add_u64 v[146:147], v[114:115], 0, s[14:15]
	v_lshl_add_u64 v[126:127], v[114:115], 0, s[16:17]
	v_lshl_add_u64 v[148:149], v[114:115], 0, s[18:19]
	v_lshl_add_u64 v[128:129], v[114:115], 0, s[20:21]
	v_lshl_add_u64 v[150:151], v[114:115], 0, s[22:23]
	v_cndmask_b32_e32 v133, v3, v1, vcc
	v_lshl_add_u64 v[134:135], v[104:105], 0, s[28:29]
	s_mov_b32 s28, -2
	v_mov_b32_e32 v1, v0
	v_mov_b32_e32 v2, v0
	v_mov_b32_e32 v3, v0
	v_mov_b32_e32 v16, v0
	v_mov_b32_e32 v17, v0
	v_mov_b32_e32 v18, v0
	v_mov_b32_e32 v19, v0
	v_mov_b32_e32 v4, v0
	v_mov_b32_e32 v5, v0
	v_mov_b32_e32 v6, v0
	v_mov_b32_e32 v7, v0
	v_mov_b32_e32 v20, v0
	v_mov_b32_e32 v21, v0
	v_mov_b32_e32 v22, v0
	v_mov_b32_e32 v23, v0
	v_mov_b32_e32 v12, v0
	v_mov_b32_e32 v13, v0
	v_mov_b32_e32 v14, v0
	v_mov_b32_e32 v15, v0
	v_mov_b32_e32 v24, v0
	v_mov_b32_e32 v25, v0
	v_mov_b32_e32 v26, v0
	v_mov_b32_e32 v27, v0
	v_mov_b32_e32 v8, v0
	v_mov_b32_e32 v9, v0
	v_mov_b32_e32 v10, v0
	v_mov_b32_e32 v11, v0
	v_mov_b32_e32 v32, v0
	v_mov_b32_e32 v33, v0
	v_mov_b32_e32 v34, v0
	v_mov_b32_e32 v35, v0
	v_mov_b32_e32 v64, v0
	v_mov_b32_e32 v65, v0
	v_mov_b32_e32 v66, v0
	v_mov_b32_e32 v67, v0
	v_mov_b32_e32 v72, v0
	v_mov_b32_e32 v73, v0
	v_mov_b32_e32 v74, v0
	v_mov_b32_e32 v75, v0
	v_mov_b32_e32 v68, v0
	v_mov_b32_e32 v69, v0
	v_mov_b32_e32 v70, v0
	v_mov_b32_e32 v71, v0
	v_mov_b32_e32 v76, v0
	v_mov_b32_e32 v77, v0
	v_mov_b32_e32 v78, v0
	v_mov_b32_e32 v79, v0
	v_mov_b32_e32 v80, v0
	v_mov_b32_e32 v81, v0
	v_mov_b32_e32 v82, v0
	v_mov_b32_e32 v83, v0
	v_mov_b32_e32 v88, v0
	v_mov_b32_e32 v89, v0
	v_mov_b32_e32 v90, v0
	v_mov_b32_e32 v91, v0
	v_mov_b32_e32 v84, v0
	v_mov_b32_e32 v85, v0
	v_mov_b32_e32 v86, v0
	v_mov_b32_e32 v87, v0
	v_mov_b32_e32 v92, v0
	v_mov_b32_e32 v93, v0
	v_mov_b32_e32 v94, v0
	v_mov_b32_e32 v95, v0
	v_readfirstlane_b32 s30, v112
	v_readfirstlane_b32 s31, v113
	v_readfirstlane_b32 s62, v114
	v_readfirstlane_b32 s63, v115
	v_readfirstlane_b32 s8, v247
	s_nop 3
	s_mul_i32 s59, s8, 0x4000
	s_sub_u32 s30, s30, s59
	s_subb_u32 s31, s31, 0
	s_sub_u32 s62, s62, s59
	s_subb_u32 s63, s63, 0
	s_lshl_b32 s8, s8, 12
	s_add_u32 m0, s8, 0x0
	v_mov_b32_e32 v92, 0
	global_load_lds_dwordx4 v248, s[30:31]
	v_mov_b32_e32 v93, 0
	s_add_u32 m0, s8, 0x400
	v_mov_b32_e32 v94, 0
	global_load_lds_dwordx4 v249, s[30:31]
	v_mov_b32_e32 v95, 0
	s_add_u32 m0, s8, 0x800
	v_mov_b32_e32 v84, 0
	global_load_lds_dwordx4 v250, s[30:31]
	v_mov_b32_e32 v85, 0
	s_add_u32 m0, s8, 0xc00
	v_mov_b32_e32 v86, 0
	global_load_lds_dwordx4 v251, s[30:31]
	v_mov_b32_e32 v87, 0
	s_add_u32 m0, s8, 0x8000
	v_mov_b32_e32 v88, 0
	global_load_lds_dwordx4 v248, s[62:63]
	v_mov_b32_e32 v89, 0
	s_add_u32 m0, s8, 0x8400
	v_mov_b32_e32 v90, 0
	global_load_lds_dwordx4 v249, s[62:63]
	v_mov_b32_e32 v91, 0
	s_add_u32 m0, s8, 0x8800
	v_mov_b32_e32 v80, 0
	global_load_lds_dwordx4 v250, s[62:63]
	v_mov_b32_e32 v81, 0
	s_add_u32 m0, s8, 0x8c00
	v_mov_b32_e32 v82, 0
	global_load_lds_dwordx4 v251, s[62:63]
	v_mov_b32_e32 v83, 0
	s_add_u32 s30, s30, 0x80
	s_addc_u32 s31, s31, 0
	s_add_u32 s62, s62, 0x80
	s_addc_u32 s63, s63, 0
	s_add_u32 m0, s8, 0x4000
	v_mov_b32_e32 v76, 0
	global_load_lds_dwordx4 v248, s[30:31]
	v_mov_b32_e32 v77, 0
	s_add_u32 m0, s8, 0x4400
	v_mov_b32_e32 v78, 0
	global_load_lds_dwordx4 v249, s[30:31]
	v_mov_b32_e32 v79, 0
	s_add_u32 m0, s8, 0x4800
	v_mov_b32_e32 v68, 0
	global_load_lds_dwordx4 v250, s[30:31]
	v_mov_b32_e32 v69, 0
	s_add_u32 m0, s8, 0x4c00
	v_mov_b32_e32 v70, 0
	global_load_lds_dwordx4 v251, s[30:31]
	v_mov_b32_e32 v71, 0
	s_add_u32 m0, s8, 0xc000
	v_mov_b32_e32 v72, 0
	global_load_lds_dwordx4 v248, s[62:63]
	v_mov_b32_e32 v73, 0
	s_add_u32 m0, s8, 0xc400
	v_mov_b32_e32 v74, 0
	global_load_lds_dwordx4 v249, s[62:63]
	v_mov_b32_e32 v75, 0
	s_add_u32 m0, s8, 0xc800
	v_mov_b32_e32 v64, 0
	global_load_lds_dwordx4 v250, s[62:63]
	v_mov_b32_e32 v65, 0
	s_add_u32 m0, s8, 0xcc00
	v_mov_b32_e32 v66, 0
	global_load_lds_dwordx4 v251, s[62:63]
	v_mov_b32_e32 v67, 0
	s_add_u32 s30, s30, 0x80
	s_addc_u32 s31, s31, 0
	s_add_u32 s62, s62, 0x80
	s_addc_u32 s63, s63, 0
	v_mov_b32_e32 v32, 0
	v_mov_b32_e32 v33, 0
	v_mov_b32_e32 v34, 0
	v_mov_b32_e32 v35, 0
	v_mov_b32_e32 v8, 0
	v_mov_b32_e32 v9, 0
	v_mov_b32_e32 v10, 0
	v_mov_b32_e32 v11, 0
	v_mov_b32_e32 v24, 0
	v_mov_b32_e32 v25, 0
	v_mov_b32_e32 v26, 0
	v_mov_b32_e32 v27, 0
	v_mov_b32_e32 v12, 0
	v_mov_b32_e32 v13, 0
	v_mov_b32_e32 v14, 0
	v_mov_b32_e32 v15, 0
	v_mov_b32_e32 v20, 0
	v_mov_b32_e32 v21, 0
	v_mov_b32_e32 v22, 0
	v_mov_b32_e32 v23, 0
	v_mov_b32_e32 v4, 0
	v_mov_b32_e32 v5, 0
	v_mov_b32_e32 v6, 0
	v_mov_b32_e32 v7, 0
	v_mov_b32_e32 v16, 0
	v_mov_b32_e32 v17, 0
	v_mov_b32_e32 v18, 0
	v_mov_b32_e32 v19, 0
	v_mov_b32_e32 v0, 0
	v_mov_b32_e32 v1, 0
	v_mov_b32_e32 v2, 0
	v_mov_b32_e32 v3, 0
	s_waitcnt vmcnt(8)
	s_barrier
	ds_read_b128 v[28:31], v252 offset:0
	ds_read_b128 v[112:115], v254 offset:32768
	ds_read_b128 v[116:119], v254 offset:34816
	ds_read_b128 v[120:123], v254 offset:36864
	ds_read_b128 v[124:127], v254 offset:38912
	ds_read_b128 v[36:39], v252 offset:2048
	ds_read_b128 v[40:43], v252 offset:4096
	ds_read_b128 v[44:47], v252 offset:6144
	ds_read_b128 v[48:51], v253 offset:0
	ds_read_b128 v[132:135], v255 offset:32768
	ds_read_b128 v[136:139], v255 offset:34816
	ds_read_b128 v[140:143], v255 offset:36864
	ds_read_b128 v[144:147], v255 offset:38912
	s_waitcnt lgkmcnt(11)
	v_mfma_f32_16x16x32_bf16 v[92:95], v[28:31], v[112:115], v[92:95]
	s_waitcnt lgkmcnt(10)
	v_mfma_f32_16x16x32_bf16 v[84:87], v[28:31], v[116:119], v[84:87]
	s_waitcnt lgkmcnt(9)
	v_mfma_f32_16x16x32_bf16 v[88:91], v[28:31], v[120:123], v[88:91]
	s_waitcnt lgkmcnt(8)
	v_mfma_f32_16x16x32_bf16 v[80:83], v[28:31], v[124:127], v[80:83]
	ds_read_b128 v[52:55], v253 offset:2048
	ds_read_b128 v[56:59], v253 offset:4096
	ds_read_b128 v[60:63], v253 offset:6144
	s_waitcnt lgkmcnt(10)
	v_mfma_f32_16x16x32_bf16 v[76:79], v[36:39], v[112:115], v[76:79]
	v_mfma_f32_16x16x32_bf16 v[68:71], v[36:39], v[116:119], v[68:71]
	v_mfma_f32_16x16x32_bf16 v[72:75], v[36:39], v[120:123], v[72:75]
	v_mfma_f32_16x16x32_bf16 v[64:67], v[36:39], v[124:127], v[64:67]
	s_waitcnt lgkmcnt(0)
	s_barrier
	s_add_u32 m0, s8, 0x0
	v_mfma_f32_16x16x32_bf16 v[32:35], v[40:43], v[112:115], v[32:35]
	global_load_lds_dwordx4 v248, s[30:31]
	s_add_u32 m0, s8, 0x400
	v_mfma_f32_16x16x32_bf16 v[8:11], v[40:43], v[116:119], v[8:11]
	global_load_lds_dwordx4 v249, s[30:31]
	s_add_u32 m0, s8, 0x800
	v_mfma_f32_16x16x32_bf16 v[24:27], v[40:43], v[120:123], v[24:27]
	global_load_lds_dwordx4 v250, s[30:31]
	s_add_u32 m0, s8, 0xc00
	v_mfma_f32_16x16x32_bf16 v[12:15], v[40:43], v[124:127], v[12:15]
	global_load_lds_dwordx4 v251, s[30:31]
	s_add_u32 m0, s8, 0x8000
	v_mfma_f32_16x16x32_bf16 v[20:23], v[44:47], v[112:115], v[20:23]
	global_load_lds_dwordx4 v248, s[62:63]
	s_add_u32 m0, s8, 0x8400
	v_mfma_f32_16x16x32_bf16 v[4:7], v[44:47], v[116:119], v[4:7]
	global_load_lds_dwordx4 v249, s[62:63]
	s_add_u32 m0, s8, 0x8800
	v_mfma_f32_16x16x32_bf16 v[16:19], v[44:47], v[120:123], v[16:19]
	global_load_lds_dwordx4 v250, s[62:63]
	s_add_u32 m0, s8, 0x8c00
	v_mfma_f32_16x16x32_bf16 v[0:3], v[44:47], v[124:127], v[0:3]
	global_load_lds_dwordx4 v251, s[62:63]
	s_add_u32 s30, s30, 0x80
	s_addc_u32 s31, s31, 0
	s_add_u32 s62, s62, 0x80
	s_addc_u32 s63, s63, 0
	s_waitcnt vmcnt(8)
	s_barrier
	ds_read_b128 v[28:31], v252 offset:16384
	ds_read_b128 v[112:115], v254 offset:49152
	ds_read_b128 v[116:119], v254 offset:51200
	ds_read_b128 v[120:123], v254 offset:53248
	ds_read_b128 v[124:127], v254 offset:55296
	ds_read_b128 v[36:39], v252 offset:18432
	ds_read_b128 v[40:43], v252 offset:20480
	ds_read_b128 v[44:47], v252 offset:22528
	v_mfma_f32_16x16x32_bf16 v[92:95], v[48:51], v[132:135], v[92:95]
	v_mfma_f32_16x16x32_bf16 v[84:87], v[48:51], v[136:139], v[84:87]
	v_mfma_f32_16x16x32_bf16 v[88:91], v[48:51], v[140:143], v[88:91]
	v_mfma_f32_16x16x32_bf16 v[80:83], v[48:51], v[144:147], v[80:83]
	v_mfma_f32_16x16x32_bf16 v[76:79], v[52:55], v[132:135], v[76:79]
	v_mfma_f32_16x16x32_bf16 v[68:71], v[52:55], v[136:139], v[68:71]
	v_mfma_f32_16x16x32_bf16 v[72:75], v[52:55], v[140:143], v[72:75]
	v_mfma_f32_16x16x32_bf16 v[64:67], v[52:55], v[144:147], v[64:67]
	v_mfma_f32_16x16x32_bf16 v[32:35], v[56:59], v[132:135], v[32:35]
	v_mfma_f32_16x16x32_bf16 v[8:11], v[56:59], v[136:139], v[8:11]
	v_mfma_f32_16x16x32_bf16 v[24:27], v[56:59], v[140:143], v[24:27]
	v_mfma_f32_16x16x32_bf16 v[12:15], v[56:59], v[144:147], v[12:15]
	v_mfma_f32_16x16x32_bf16 v[20:23], v[60:63], v[132:135], v[20:23]
	v_mfma_f32_16x16x32_bf16 v[4:7], v[60:63], v[136:139], v[4:7]
	v_mfma_f32_16x16x32_bf16 v[16:19], v[60:63], v[140:143], v[16:19]
	v_mfma_f32_16x16x32_bf16 v[0:3], v[60:63], v[144:147], v[0:3]
	ds_read_b128 v[48:51], v253 offset:16384
	ds_read_b128 v[132:135], v255 offset:49152
	ds_read_b128 v[136:139], v255 offset:51200
	ds_read_b128 v[140:143], v255 offset:53248
	ds_read_b128 v[144:147], v255 offset:55296
	ds_read_b128 v[52:55], v253 offset:18432
	ds_read_b128 v[56:59], v253 offset:20480
	ds_read_b128 v[60:63], v253 offset:22528
	s_waitcnt lgkmcnt(14)
	v_mfma_f32_16x16x32_bf16 v[92:95], v[28:31], v[112:115], v[92:95]
	s_waitcnt lgkmcnt(13)
	v_mfma_f32_16x16x32_bf16 v[84:87], v[28:31], v[116:119], v[84:87]
	s_waitcnt lgkmcnt(12)
	v_mfma_f32_16x16x32_bf16 v[88:91], v[28:31], v[120:123], v[88:91]
	s_waitcnt lgkmcnt(11)
	v_mfma_f32_16x16x32_bf16 v[80:83], v[28:31], v[124:127], v[80:83]
	s_waitcnt lgkmcnt(10)
	v_mfma_f32_16x16x32_bf16 v[76:79], v[36:39], v[112:115], v[76:79]
	v_mfma_f32_16x16x32_bf16 v[68:71], v[36:39], v[116:119], v[68:71]
	v_mfma_f32_16x16x32_bf16 v[72:75], v[36:39], v[120:123], v[72:75]
	v_mfma_f32_16x16x32_bf16 v[64:67], v[36:39], v[124:127], v[64:67]
	s_waitcnt lgkmcnt(0)
	s_barrier
	s_add_u32 m0, s8, 0x4000
	v_mfma_f32_16x16x32_bf16 v[32:35], v[40:43], v[112:115], v[32:35]
	global_load_lds_dwordx4 v248, s[30:31]
	s_add_u32 m0, s8, 0x4400
	v_mfma_f32_16x16x32_bf16 v[8:11], v[40:43], v[116:119], v[8:11]
	global_load_lds_dwordx4 v249, s[30:31]
	s_add_u32 m0, s8, 0x4800
	v_mfma_f32_16x16x32_bf16 v[24:27], v[40:43], v[120:123], v[24:27]
	global_load_lds_dwordx4 v250, s[30:31]
	s_add_u32 m0, s8, 0x4c00
	v_mfma_f32_16x16x32_bf16 v[12:15], v[40:43], v[124:127], v[12:15]
	global_load_lds_dwordx4 v251, s[30:31]
	s_add_u32 m0, s8, 0xc000
	v_mfma_f32_16x16x32_bf16 v[20:23], v[44:47], v[112:115], v[20:23]
	global_load_lds_dwordx4 v248, s[62:63]
	s_add_u32 m0, s8, 0xc400
	v_mfma_f32_16x16x32_bf16 v[4:7], v[44:47], v[116:119], v[4:7]
	global_load_lds_dwordx4 v249, s[62:63]
	s_add_u32 m0, s8, 0xc800
	v_mfma_f32_16x16x32_bf16 v[16:19], v[44:47], v[120:123], v[16:19]
	global_load_lds_dwordx4 v250, s[62:63]
	s_add_u32 m0, s8, 0xcc00
	v_mfma_f32_16x16x32_bf16 v[0:3], v[44:47], v[124:127], v[0:3]
	global_load_lds_dwordx4 v251, s[62:63]
	s_add_u32 s30, s30, 0x80
	s_addc_u32 s31, s31, 0
	s_add_u32 s62, s62, 0x80
	s_addc_u32 s63, s63, 0
	s_mov_b32 s32, 6
.Lg24_loop:
	s_waitcnt vmcnt(8)
	s_barrier
	ds_read_b128 v[28:31], v252 offset:0
	ds_read_b128 v[112:115], v254 offset:32768
	ds_read_b128 v[116:119], v254 offset:34816
	ds_read_b128 v[120:123], v254 offset:36864
	ds_read_b128 v[124:127], v254 offset:38912
	ds_read_b128 v[36:39], v252 offset:2048
	ds_read_b128 v[40:43], v252 offset:4096
	ds_read_b128 v[44:47], v252 offset:6144
	v_mfma_f32_16x16x32_bf16 v[92:95], v[48:51], v[132:135], v[92:95]
	v_mfma_f32_16x16x32_bf16 v[84:87], v[48:51], v[136:139], v[84:87]
	v_mfma_f32_16x16x32_bf16 v[88:91], v[48:51], v[140:143], v[88:91]
	v_mfma_f32_16x16x32_bf16 v[80:83], v[48:51], v[144:147], v[80:83]
	v_mfma_f32_16x16x32_bf16 v[76:79], v[52:55], v[132:135], v[76:79]
	v_mfma_f32_16x16x32_bf16 v[68:71], v[52:55], v[136:139], v[68:71]
	v_mfma_f32_16x16x32_bf16 v[72:75], v[52:55], v[140:143], v[72:75]
	v_mfma_f32_16x16x32_bf16 v[64:67], v[52:55], v[144:147], v[64:67]
	v_mfma_f32_16x16x32_bf16 v[32:35], v[56:59], v[132:135], v[32:35]
	v_mfma_f32_16x16x32_bf16 v[8:11], v[56:59], v[136:139], v[8:11]
	v_mfma_f32_16x16x32_bf16 v[24:27], v[56:59], v[140:143], v[24:27]
	v_mfma_f32_16x16x32_bf16 v[12:15], v[56:59], v[144:147], v[12:15]
	v_mfma_f32_16x16x32_bf16 v[20:23], v[60:63], v[132:135], v[20:23]
	v_mfma_f32_16x16x32_bf16 v[4:7], v[60:63], v[136:139], v[4:7]
	v_mfma_f32_16x16x32_bf16 v[16:19], v[60:63], v[140:143], v[16:19]
	v_mfma_f32_16x16x32_bf16 v[0:3], v[60:63], v[144:147], v[0:3]
	ds_read_b128 v[48:51], v253 offset:0
	ds_read_b128 v[132:135], v255 offset:32768
	ds_read_b128 v[136:139], v255 offset:34816
	ds_read_b128 v[140:143], v255 offset:36864
	ds_read_b128 v[144:147], v255 offset:38912
	ds_read_b128 v[52:55], v253 offset:2048
	ds_read_b128 v[56:59], v253 offset:4096
	ds_read_b128 v[60:63], v253 offset:6144
	s_waitcnt lgkmcnt(14)
	v_mfma_f32_16x16x32_bf16 v[92:95], v[28:31], v[112:115], v[92:95]
	s_waitcnt lgkmcnt(13)
	v_mfma_f32_16x16x32_bf16 v[84:87], v[28:31], v[116:119], v[84:87]
	s_waitcnt lgkmcnt(12)
	v_mfma_f32_16x16x32_bf16 v[88:91], v[28:31], v[120:123], v[88:91]
	s_waitcnt lgkmcnt(11)
	v_mfma_f32_16x16x32_bf16 v[80:83], v[28:31], v[124:127], v[80:83]
	s_waitcnt lgkmcnt(10)
	v_mfma_f32_16x16x32_bf16 v[76:79], v[36:39], v[112:115], v[76:79]
	v_mfma_f32_16x16x32_bf16 v[68:71], v[36:39], v[116:119], v[68:71]
	v_mfma_f32_16x16x32_bf16 v[72:75], v[36:39], v[120:123], v[72:75]
	v_mfma_f32_16x16x32_bf16 v[64:67], v[36:39], v[124:127], v[64:67]
	s_waitcnt lgkmcnt(0)
	s_barrier
	s_add_u32 m0, s8, 0x0
	v_mfma_f32_16x16x32_bf16 v[32:35], v[40:43], v[112:115], v[32:35]
	global_load_lds_dwordx4 v248, s[30:31]
	s_add_u32 m0, s8, 0x400
	v_mfma_f32_16x16x32_bf16 v[8:11], v[40:43], v[116:119], v[8:11]
	global_load_lds_dwordx4 v249, s[30:31]
	s_add_u32 m0, s8, 0x800
	v_mfma_f32_16x16x32_bf16 v[24:27], v[40:43], v[120:123], v[24:27]
	global_load_lds_dwordx4 v250, s[30:31]
	s_add_u32 m0, s8, 0xc00
	v_mfma_f32_16x16x32_bf16 v[12:15], v[40:43], v[124:127], v[12:15]
	global_load_lds_dwordx4 v251, s[30:31]
	s_add_u32 m0, s8, 0x8000
	v_mfma_f32_16x16x32_bf16 v[20:23], v[44:47], v[112:115], v[20:23]
	global_load_lds_dwordx4 v248, s[62:63]
	s_add_u32 m0, s8, 0x8400
	v_mfma_f32_16x16x32_bf16 v[4:7], v[44:47], v[116:119], v[4:7]
	global_load_lds_dwordx4 v249, s[62:63]
	s_add_u32 m0, s8, 0x8800
	v_mfma_f32_16x16x32_bf16 v[16:19], v[44:47], v[120:123], v[16:19]
	global_load_lds_dwordx4 v250, s[62:63]
	s_add_u32 m0, s8, 0x8c00
	v_mfma_f32_16x16x32_bf16 v[0:3], v[44:47], v[124:127], v[0:3]
	global_load_lds_dwordx4 v251, s[62:63]
	s_add_u32 s30, s30, 0x80
	s_addc_u32 s31, s31, 0
	s_add_u32 s62, s62, 0x80
	s_addc_u32 s63, s63, 0
	s_waitcnt vmcnt(8)
	s_barrier
	ds_read_b128 v[28:31], v252 offset:16384
	ds_read_b128 v[112:115], v254 offset:49152
	ds_read_b128 v[116:119], v254 offset:51200
	ds_read_b128 v[120:123], v254 offset:53248
	ds_read_b128 v[124:127], v254 offset:55296
	ds_read_b128 v[36:39], v252 offset:18432
	ds_read_b128 v[40:43], v252 offset:20480
	ds_read_b128 v[44:47], v252 offset:22528
	v_mfma_f32_16x16x32_bf16 v[92:95], v[48:51], v[132:135], v[92:95]
	v_mfma_f32_16x16x32_bf16 v[84:87], v[48:51], v[136:139], v[84:87]
	v_mfma_f32_16x16x32_bf16 v[88:91], v[48:51], v[140:143], v[88:91]
	v_mfma_f32_16x16x32_bf16 v[80:83], v[48:51], v[144:147], v[80:83]
	v_mfma_f32_16x16x32_bf16 v[76:79], v[52:55], v[132:135], v[76:79]
	v_mfma_f32_16x16x32_bf16 v[68:71], v[52:55], v[136:139], v[68:71]
	v_mfma_f32_16x16x32_bf16 v[72:75], v[52:55], v[140:143], v[72:75]
	v_mfma_f32_16x16x32_bf16 v[64:67], v[52:55], v[144:147], v[64:67]
	v_mfma_f32_16x16x32_bf16 v[32:35], v[56:59], v[132:135], v[32:35]
	v_mfma_f32_16x16x32_bf16 v[8:11], v[56:59], v[136:139], v[8:11]
	v_mfma_f32_16x16x32_bf16 v[24:27], v[56:59], v[140:143], v[24:27]
	v_mfma_f32_16x16x32_bf16 v[12:15], v[56:59], v[144:147], v[12:15]
	v_mfma_f32_16x16x32_bf16 v[20:23], v[60:63], v[132:135], v[20:23]
	v_mfma_f32_16x16x32_bf16 v[4:7], v[60:63], v[136:139], v[4:7]
	v_mfma_f32_16x16x32_bf16 v[16:19], v[60:63], v[140:143], v[16:19]
	v_mfma_f32_16x16x32_bf16 v[0:3], v[60:63], v[144:147], v[0:3]
	ds_read_b128 v[48:51], v253 offset:16384
	ds_read_b128 v[132:135], v255 offset:49152
	ds_read_b128 v[136:139], v255 offset:51200
	ds_read_b128 v[140:143], v255 offset:53248
	ds_read_b128 v[144:147], v255 offset:55296
	ds_read_b128 v[52:55], v253 offset:18432
	ds_read_b128 v[56:59], v253 offset:20480
	ds_read_b128 v[60:63], v253 offset:22528
	s_waitcnt lgkmcnt(14)
	v_mfma_f32_16x16x32_bf16 v[92:95], v[28:31], v[112:115], v[92:95]
	s_waitcnt lgkmcnt(13)
	v_mfma_f32_16x16x32_bf16 v[84:87], v[28:31], v[116:119], v[84:87]
	s_waitcnt lgkmcnt(12)
	v_mfma_f32_16x16x32_bf16 v[88:91], v[28:31], v[120:123], v[88:91]
	s_waitcnt lgkmcnt(11)
	v_mfma_f32_16x16x32_bf16 v[80:83], v[28:31], v[124:127], v[80:83]
	s_waitcnt lgkmcnt(10)
	v_mfma_f32_16x16x32_bf16 v[76:79], v[36:39], v[112:115], v[76:79]
	v_mfma_f32_16x16x32_bf16 v[68:71], v[36:39], v[116:119], v[68:71]
	v_mfma_f32_16x16x32_bf16 v[72:75], v[36:39], v[120:123], v[72:75]
	v_mfma_f32_16x16x32_bf16 v[64:67], v[36:39], v[124:127], v[64:67]
	s_waitcnt lgkmcnt(0)
	s_barrier
	s_add_u32 m0, s8, 0x4000
	v_mfma_f32_16x16x32_bf16 v[32:35], v[40:43], v[112:115], v[32:35]
	global_load_lds_dwordx4 v248, s[30:31]
	s_add_u32 m0, s8, 0x4400
	v_mfma_f32_16x16x32_bf16 v[8:11], v[40:43], v[116:119], v[8:11]
	global_load_lds_dwordx4 v249, s[30:31]
	s_add_u32 m0, s8, 0x4800
	v_mfma_f32_16x16x32_bf16 v[24:27], v[40:43], v[120:123], v[24:27]
	global_load_lds_dwordx4 v250, s[30:31]
	s_add_u32 m0, s8, 0x4c00
	v_mfma_f32_16x16x32_bf16 v[12:15], v[40:43], v[124:127], v[12:15]
	global_load_lds_dwordx4 v251, s[30:31]
	s_add_u32 m0, s8, 0xc000
	v_mfma_f32_16x16x32_bf16 v[20:23], v[44:47], v[112:115], v[20:23]
	global_load_lds_dwordx4 v248, s[62:63]
	s_add_u32 m0, s8, 0xc400
	v_mfma_f32_16x16x32_bf16 v[4:7], v[44:47], v[116:119], v[4:7]
	global_load_lds_dwordx4 v249, s[62:63]
	s_add_u32 m0, s8, 0xc800
	v_mfma_f32_16x16x32_bf16 v[16:19], v[44:47], v[120:123], v[16:19]
	global_load_lds_dwordx4 v250, s[62:63]
	s_add_u32 m0, s8, 0xcc00
	v_mfma_f32_16x16x32_bf16 v[0:3], v[44:47], v[124:127], v[0:3]
	global_load_lds_dwordx4 v251, s[62:63]
	s_add_u32 s30, s30, 0x80
	s_addc_u32 s31, s31, 0
	s_add_u32 s62, s62, 0x80
	s_addc_u32 s63, s63, 0
	s_sub_u32 s32, s32, 1
	s_cmp_lg_u32 s32, 0
	s_cbranch_scc1 .Lg24_loop
	s_waitcnt vmcnt(8)
	s_barrier
	ds_read_b128 v[28:31], v252 offset:0
	ds_read_b128 v[112:115], v254 offset:32768
	ds_read_b128 v[116:119], v254 offset:34816
	ds_read_b128 v[120:123], v254 offset:36864
	ds_read_b128 v[124:127], v254 offset:38912
	ds_read_b128 v[36:39], v252 offset:2048
	ds_read_b128 v[40:43], v252 offset:4096
	ds_read_b128 v[44:47], v252 offset:6144
	v_mfma_f32_16x16x32_bf16 v[92:95], v[48:51], v[132:135], v[92:95]
	v_mfma_f32_16x16x32_bf16 v[84:87], v[48:51], v[136:139], v[84:87]
	v_mfma_f32_16x16x32_bf16 v[88:91], v[48:51], v[140:143], v[88:91]
	v_mfma_f32_16x16x32_bf16 v[80:83], v[48:51], v[144:147], v[80:83]
	v_mfma_f32_16x16x32_bf16 v[76:79], v[52:55], v[132:135], v[76:79]
	v_mfma_f32_16x16x32_bf16 v[68:71], v[52:55], v[136:139], v[68:71]
	v_mfma_f32_16x16x32_bf16 v[72:75], v[52:55], v[140:143], v[72:75]
	v_mfma_f32_16x16x32_bf16 v[64:67], v[52:55], v[144:147], v[64:67]
	v_mfma_f32_16x16x32_bf16 v[32:35], v[56:59], v[132:135], v[32:35]
	v_mfma_f32_16x16x32_bf16 v[8:11], v[56:59], v[136:139], v[8:11]
	v_mfma_f32_16x16x32_bf16 v[24:27], v[56:59], v[140:143], v[24:27]
	v_mfma_f32_16x16x32_bf16 v[12:15], v[56:59], v[144:147], v[12:15]
	v_mfma_f32_16x16x32_bf16 v[20:23], v[60:63], v[132:135], v[20:23]
	v_mfma_f32_16x16x32_bf16 v[4:7], v[60:63], v[136:139], v[4:7]
	v_mfma_f32_16x16x32_bf16 v[16:19], v[60:63], v[140:143], v[16:19]
	v_mfma_f32_16x16x32_bf16 v[0:3], v[60:63], v[144:147], v[0:3]
	ds_read_b128 v[48:51], v253 offset:0
	ds_read_b128 v[132:135], v255 offset:32768
	ds_read_b128 v[136:139], v255 offset:34816
	ds_read_b128 v[140:143], v255 offset:36864
	ds_read_b128 v[144:147], v255 offset:38912
	ds_read_b128 v[52:55], v253 offset:2048
	ds_read_b128 v[56:59], v253 offset:4096
	ds_read_b128 v[60:63], v253 offset:6144
	s_waitcnt lgkmcnt(14)
	v_mfma_f32_16x16x32_bf16 v[92:95], v[28:31], v[112:115], v[92:95]
	s_waitcnt lgkmcnt(13)
	v_mfma_f32_16x16x32_bf16 v[84:87], v[28:31], v[116:119], v[84:87]
	s_waitcnt lgkmcnt(12)
	v_mfma_f32_16x16x32_bf16 v[88:91], v[28:31], v[120:123], v[88:91]
	s_waitcnt lgkmcnt(11)
	v_mfma_f32_16x16x32_bf16 v[80:83], v[28:31], v[124:127], v[80:83]
	s_waitcnt lgkmcnt(10)
	v_mfma_f32_16x16x32_bf16 v[76:79], v[36:39], v[112:115], v[76:79]
	v_mfma_f32_16x16x32_bf16 v[68:71], v[36:39], v[116:119], v[68:71]
	v_mfma_f32_16x16x32_bf16 v[72:75], v[36:39], v[120:123], v[72:75]
	v_mfma_f32_16x16x32_bf16 v[64:67], v[36:39], v[124:127], v[64:67]
	s_waitcnt lgkmcnt(0)
	s_barrier
	v_mfma_f32_16x16x32_bf16 v[32:35], v[40:43], v[112:115], v[32:35]
	v_mfma_f32_16x16x32_bf16 v[8:11], v[40:43], v[116:119], v[8:11]
	v_mfma_f32_16x16x32_bf16 v[24:27], v[40:43], v[120:123], v[24:27]
	v_mfma_f32_16x16x32_bf16 v[12:15], v[40:43], v[124:127], v[12:15]
	v_mfma_f32_16x16x32_bf16 v[20:23], v[44:47], v[112:115], v[20:23]
	v_mfma_f32_16x16x32_bf16 v[4:7], v[44:47], v[116:119], v[4:7]
	v_mfma_f32_16x16x32_bf16 v[16:19], v[44:47], v[120:123], v[16:19]
	v_mfma_f32_16x16x32_bf16 v[0:3], v[44:47], v[124:127], v[0:3]
	s_waitcnt vmcnt(0)
	s_barrier
	ds_read_b128 v[28:31], v252 offset:16384
	ds_read_b128 v[112:115], v254 offset:49152
	ds_read_b128 v[116:119], v254 offset:51200
	ds_read_b128 v[120:123], v254 offset:53248
	ds_read_b128 v[124:127], v254 offset:55296
	ds_read_b128 v[36:39], v252 offset:18432
	ds_read_b128 v[40:43], v252 offset:20480
	ds_read_b128 v[44:47], v252 offset:22528
	v_mfma_f32_16x16x32_bf16 v[92:95], v[48:51], v[132:135], v[92:95]
	v_mfma_f32_16x16x32_bf16 v[84:87], v[48:51], v[136:139], v[84:87]
	v_mfma_f32_16x16x32_bf16 v[88:91], v[48:51], v[140:143], v[88:91]
	v_mfma_f32_16x16x32_bf16 v[80:83], v[48:51], v[144:147], v[80:83]
	v_mfma_f32_16x16x32_bf16 v[76:79], v[52:55], v[132:135], v[76:79]
	v_mfma_f32_16x16x32_bf16 v[68:71], v[52:55], v[136:139], v[68:71]
	v_mfma_f32_16x16x32_bf16 v[72:75], v[52:55], v[140:143], v[72:75]
	v_mfma_f32_16x16x32_bf16 v[64:67], v[52:55], v[144:147], v[64:67]
	v_mfma_f32_16x16x32_bf16 v[32:35], v[56:59], v[132:135], v[32:35]
	v_mfma_f32_16x16x32_bf16 v[8:11], v[56:59], v[136:139], v[8:11]
	v_mfma_f32_16x16x32_bf16 v[24:27], v[56:59], v[140:143], v[24:27]
	v_mfma_f32_16x16x32_bf16 v[12:15], v[56:59], v[144:147], v[12:15]
	v_mfma_f32_16x16x32_bf16 v[20:23], v[60:63], v[132:135], v[20:23]
	v_mfma_f32_16x16x32_bf16 v[4:7], v[60:63], v[136:139], v[4:7]
	v_mfma_f32_16x16x32_bf16 v[16:19], v[60:63], v[140:143], v[16:19]
	v_mfma_f32_16x16x32_bf16 v[0:3], v[60:63], v[144:147], v[0:3]
	ds_read_b128 v[48:51], v253 offset:16384
	ds_read_b128 v[132:135], v255 offset:49152
	ds_read_b128 v[136:139], v255 offset:51200
	ds_read_b128 v[140:143], v255 offset:53248
	ds_read_b128 v[144:147], v255 offset:55296
	ds_read_b128 v[52:55], v253 offset:18432
	ds_read_b128 v[56:59], v253 offset:20480
	ds_read_b128 v[60:63], v253 offset:22528
	s_waitcnt lgkmcnt(14)
	v_mfma_f32_16x16x32_bf16 v[92:95], v[28:31], v[112:115], v[92:95]
	s_waitcnt lgkmcnt(13)
	v_mfma_f32_16x16x32_bf16 v[84:87], v[28:31], v[116:119], v[84:87]
	s_waitcnt lgkmcnt(12)
	v_mfma_f32_16x16x32_bf16 v[88:91], v[28:31], v[120:123], v[88:91]
	s_waitcnt lgkmcnt(11)
	v_mfma_f32_16x16x32_bf16 v[80:83], v[28:31], v[124:127], v[80:83]
	s_waitcnt lgkmcnt(10)
	v_mfma_f32_16x16x32_bf16 v[76:79], v[36:39], v[112:115], v[76:79]
	v_mfma_f32_16x16x32_bf16 v[68:71], v[36:39], v[116:119], v[68:71]
	v_mfma_f32_16x16x32_bf16 v[72:75], v[36:39], v[120:123], v[72:75]
	v_mfma_f32_16x16x32_bf16 v[64:67], v[36:39], v[124:127], v[64:67]
	s_waitcnt lgkmcnt(0)
	s_barrier
	v_mfma_f32_16x16x32_bf16 v[32:35], v[40:43], v[112:115], v[32:35]
	v_mfma_f32_16x16x32_bf16 v[8:11], v[40:43], v[116:119], v[8:11]
	v_mfma_f32_16x16x32_bf16 v[24:27], v[40:43], v[120:123], v[24:27]
	v_mfma_f32_16x16x32_bf16 v[12:15], v[40:43], v[124:127], v[12:15]
	v_mfma_f32_16x16x32_bf16 v[20:23], v[44:47], v[112:115], v[20:23]
	v_mfma_f32_16x16x32_bf16 v[4:7], v[44:47], v[116:119], v[4:7]
	v_mfma_f32_16x16x32_bf16 v[16:19], v[44:47], v[120:123], v[16:19]
	v_mfma_f32_16x16x32_bf16 v[0:3], v[44:47], v[124:127], v[0:3]
	v_mfma_f32_16x16x32_bf16 v[92:95], v[48:51], v[132:135], v[92:95]
	v_mfma_f32_16x16x32_bf16 v[84:87], v[48:51], v[136:139], v[84:87]
	v_mfma_f32_16x16x32_bf16 v[88:91], v[48:51], v[140:143], v[88:91]
	v_mfma_f32_16x16x32_bf16 v[80:83], v[48:51], v[144:147], v[80:83]
	v_mfma_f32_16x16x32_bf16 v[76:79], v[52:55], v[132:135], v[76:79]
	v_mfma_f32_16x16x32_bf16 v[68:71], v[52:55], v[136:139], v[68:71]
	v_mfma_f32_16x16x32_bf16 v[72:75], v[52:55], v[140:143], v[72:75]
	v_mfma_f32_16x16x32_bf16 v[64:67], v[52:55], v[144:147], v[64:67]
	v_mfma_f32_16x16x32_bf16 v[32:35], v[56:59], v[132:135], v[32:35]
	v_mfma_f32_16x16x32_bf16 v[8:11], v[56:59], v[136:139], v[8:11]
	v_mfma_f32_16x16x32_bf16 v[24:27], v[56:59], v[140:143], v[24:27]
	v_mfma_f32_16x16x32_bf16 v[12:15], v[56:59], v[144:147], v[12:15]
	v_mfma_f32_16x16x32_bf16 v[20:23], v[60:63], v[132:135], v[20:23]
	v_mfma_f32_16x16x32_bf16 v[4:7], v[60:63], v[136:139], v[4:7]
	v_mfma_f32_16x16x32_bf16 v[16:19], v[60:63], v[140:143], v[16:19]
	v_mfma_f32_16x16x32_bf16 v[0:3], v[60:63], v[144:147], v[0:3]
	s_nop 7
	s_nop 1
	v_mul_f32_e32 v28, 0xbfb8aa3b, v92
	v_exp_f32_e32 v30, v28
	v_mul_f32_e32 v36, 0xbfb8aa3b, v93
	v_exp_f32_e32 v36, v36
	s_and_b32 s8, s55, 0xffffffc0
	v_add_f32_e32 v30, 1.0, v30
	v_rcp_f32_e32 v30, v30
	v_add_f32_e32 v36, 1.0, v36
	v_or_b32_e32 v28, s8, v156
	v_rcp_f32_e32 v36, v36
	v_add_u32_e32 v31, s54, v157
	v_ashrrev_i32_e32 v29, 31, v28
	v_mul_f32_e32 v30, v92, v30
	v_lshl_add_u64 v[28:29], v[28:29], 1, v[102:103]
	v_mul_f32_e32 v30, v88, v30
	v_mul_u32_u24_e32 v96, 0x1600, v31
	v_cvt_pk_bf16_f32 v30, v30, s0
	v_lshl_add_u64 v[28:29], v[28:29], 0, v[96:97]
	global_store_short v[28:29], v30, off
	v_mul_f32_e32 v30, v93, v36
	v_mul_f32_e32 v30, v89, v30
	v_cvt_pk_bf16_f32 v36, v30, s0
	v_mul_f32_e32 v30, 0xbfb8aa3b, v94
	v_exp_f32_e32 v37, v30
	v_add_co_u32_e32 v30, vcc, s37, v28
	s_add_i32 s3, s3, s34
	s_nop 0
	v_addc_co_u32_e32 v31, vcc, 0, v29, vcc
	global_store_short v[30:31], v36, off offset:1536
	v_mul_f32_e32 v36, 0xbfb8aa3b, v95
	v_exp_f32_e32 v36, v36
	v_add_f32_e32 v37, 1.0, v37
	v_rcp_f32_e32 v37, v37
	s_mov_b64 s[30:31], -1
	v_add_f32_e32 v36, 1.0, v36
	v_rcp_f32_e32 v39, v36
	v_mul_f32_e32 v37, v94, v37
	v_mul_f32_e32 v37, v90, v37
	v_add_co_u32_e32 v36, vcc, s38, v28
	v_cvt_pk_bf16_f32 v38, v37, s0
	s_nop 0
	v_addc_co_u32_e32 v37, vcc, 0, v29, vcc
	global_store_short v[36:37], v38, off offset:3072
	v_mul_f32_e32 v38, v95, v39
	v_mul_f32_e32 v38, v91, v38
	v_cvt_pk_bf16_f32 v40, v38, s0
	v_mul_f32_e32 v38, 0xbfb8aa3b, v84
	v_exp_f32_e32 v41, v38
	v_add_co_u32_e32 v38, vcc, s39, v28
	s_mov_b32 s55, s51
	s_nop 0
	v_addc_co_u32_e32 v39, vcc, 0, v29, vcc
	global_store_short v[38:39], v40, off offset:512
	v_mul_f32_e32 v40, 0xbfb8aa3b, v85
	v_exp_f32_e32 v40, v40
	v_add_f32_e32 v41, 1.0, v41
	v_rcp_f32_e32 v41, v41
	v_add_f32_e32 v40, 1.0, v40
	v_rcp_f32_e32 v40, v40
	v_mul_f32_e32 v41, v84, v41
	v_mul_f32_e32 v41, v80, v41
	v_cvt_pk_bf16_f32 v41, v41, s0
	global_store_short v[28:29], v41, off offset:32
	v_mul_f32_e32 v41, 0xbfb8aa3b, v86
	v_mul_f32_e32 v40, v85, v40
	v_exp_f32_e32 v41, v41
	v_mul_f32_e32 v40, v81, v40
	v_cvt_pk_bf16_f32 v40, v40, s0
	global_store_short v[30:31], v40, off offset:1568
	v_mul_f32_e32 v30, 0xbfb8aa3b, v87
	v_exp_f32_e32 v30, v30
	v_add_f32_e32 v41, 1.0, v41
	v_rcp_f32_e32 v41, v41
	v_add_f32_e32 v30, 1.0, v30
	v_rcp_f32_e32 v30, v30
	v_mul_f32_e32 v31, v86, v41
	v_mul_f32_e32 v31, v82, v31
	v_cvt_pk_bf16_f32 v31, v31, s0
	global_store_short v[36:37], v31, off offset:3104
	v_mul_f32_e32 v31, 0xbfb8aa3b, v76
	v_mul_f32_e32 v30, v87, v30
	v_exp_f32_e32 v31, v31
	v_mul_f32_e32 v30, v83, v30
	v_cvt_pk_bf16_f32 v30, v30, s0
	global_store_short v[38:39], v30, off offset:544
	v_mul_f32_e32 v30, 0xbfb8aa3b, v77
	v_exp_f32_e32 v30, v30
	v_add_f32_e32 v31, 1.0, v31
	v_rcp_f32_e32 v31, v31
	v_add_f32_e32 v30, 1.0, v30
	v_rcp_f32_e32 v37, v30
	v_mul_f32_e32 v31, v76, v31
	v_mul_f32_e32 v31, v72, v31
	v_add_co_u32_e32 v30, vcc, s40, v28
	v_cvt_pk_bf16_f32 v36, v31, s0
	s_nop 0
	v_addc_co_u32_e32 v31, vcc, 0, v29, vcc
	global_store_short v[30:31], v36, off
	v_mul_f32_e32 v36, v77, v37
	v_mul_f32_e32 v36, v73, v36
	v_cvt_pk_bf16_f32 v38, v36, s0
	v_mul_f32_e32 v36, 0xbfb8aa3b, v78
	v_exp_f32_e32 v39, v36
	v_add_co_u32_e32 v36, vcc, s41, v28
	v_add_f32_e32 v39, 1.0, v39
	s_nop 0
	v_addc_co_u32_e32 v37, vcc, 0, v29, vcc
	global_store_short v[36:37], v38, off offset:1536
	v_mul_f32_e32 v38, 0xbfb8aa3b, v79
	v_exp_f32_e32 v38, v38
	v_rcp_f32_e32 v39, v39
	v_add_f32_e32 v38, 1.0, v38
	v_rcp_f32_e32 v41, v38
	v_mul_f32_e32 v39, v78, v39
	v_mul_f32_e32 v39, v74, v39
	v_add_co_u32_e32 v38, vcc, s42, v28
	v_cvt_pk_bf16_f32 v40, v39, s0
	s_nop 0
	v_addc_co_u32_e32 v39, vcc, 0, v29, vcc
	global_store_short v[38:39], v40, off offset:3072
	v_mul_f32_e32 v40, v79, v41
	v_mul_f32_e32 v40, v75, v40
	v_cvt_pk_bf16_f32 v42, v40, s0
	v_mul_f32_e32 v40, 0xbfb8aa3b, v68
	v_exp_f32_e32 v43, v40
	v_add_co_u32_e32 v40, vcc, s43, v28
	v_add_f32_e32 v43, 1.0, v43
	s_nop 0
	v_addc_co_u32_e32 v41, vcc, 0, v29, vcc
	v_rcp_f32_e32 v43, v43
	global_store_short v[40:41], v42, off offset:512
	v_mul_f32_e32 v42, 0xbfb8aa3b, v69
	v_exp_f32_e32 v42, v42
	v_mul_f32_e32 v43, v68, v43
	v_mul_f32_e32 v43, v64, v43
	v_cvt_pk_bf16_f32 v43, v43, s0
	v_add_f32_e32 v42, 1.0, v42
	v_rcp_f32_e32 v42, v42
	global_store_short v[30:31], v43, off offset:32
	v_mul_f32_e32 v30, 0xbfb8aa3b, v70
	v_exp_f32_e32 v30, v30
	v_mul_f32_e32 v31, v69, v42
	v_mul_f32_e32 v31, v65, v31
	v_cvt_pk_bf16_f32 v31, v31, s0
	v_add_f32_e32 v30, 1.0, v30
	v_rcp_f32_e32 v30, v30
	global_store_short v[36:37], v31, off offset:1568
	v_mul_f32_e32 v31, 0xbfb8aa3b, v71
	v_exp_f32_e32 v31, v31
	v_mul_f32_e32 v30, v70, v30
	v_mul_f32_e32 v30, v66, v30
	v_cvt_pk_bf16_f32 v30, v30, s0
	v_add_f32_e32 v31, 1.0, v31
	v_rcp_f32_e32 v31, v31
	global_store_short v[38:39], v30, off offset:3104
	v_mul_f32_e32 v30, 0xbfb8aa3b, v32
	v_exp_f32_e32 v30, v30
	v_mul_f32_e32 v31, v71, v31
	v_mul_f32_e32 v31, v67, v31
	v_cvt_pk_bf16_f32 v31, v31, s0
	v_add_f32_e32 v30, 1.0, v30
	v_rcp_f32_e32 v30, v30
	global_store_short v[40:41], v31, off offset:544
	v_mul_f32_e32 v31, 0xbfb8aa3b, v33
	v_exp_f32_e32 v31, v31
	v_mul_f32_e32 v30, v32, v30
	v_mul_f32_e32 v24, v24, v30
	v_cvt_pk_bf16_f32 v24, v24, s0
	v_add_f32_e32 v30, 1.0, v31
	v_rcp_f32_e32 v32, v30
	v_add_co_u32_e32 v30, vcc, s44, v28
	s_nop 1
	v_addc_co_u32_e32 v31, vcc, 0, v29, vcc
	global_store_short v[30:31], v24, off
	v_mul_f32_e32 v24, v33, v32
	v_mul_f32_e32 v24, v25, v24
	v_cvt_pk_bf16_f32 v32, v24, s0
	v_mul_f32_e32 v24, 0xbfb8aa3b, v34
	v_exp_f32_e32 v33, v24
	v_add_co_u32_e32 v24, vcc, s45, v28
	v_add_f32_e32 v33, 1.0, v33
	s_nop 0
	v_addc_co_u32_e32 v25, vcc, 0, v29, vcc
	global_store_short v[24:25], v32, off offset:1536
	v_mul_f32_e32 v32, 0xbfb8aa3b, v35
	v_exp_f32_e32 v32, v32
	v_rcp_f32_e32 v33, v33
	v_add_f32_e32 v32, 1.0, v32
	v_mul_f32_e32 v33, v34, v33
	v_rcp_f32_e32 v34, v32
	v_mul_f32_e32 v26, v26, v33
	v_add_co_u32_e32 v32, vcc, s46, v28
	v_cvt_pk_bf16_f32 v26, v26, s0
	s_nop 0
	v_addc_co_u32_e32 v33, vcc, 0, v29, vcc
	global_store_short v[32:33], v26, off offset:3072
	v_mul_f32_e32 v26, v35, v34
	v_mul_f32_e32 v26, v27, v26
	v_cvt_pk_bf16_f32 v34, v26, s0
	v_mul_f32_e32 v26, 0xbfb8aa3b, v8
	v_exp_f32_e32 v35, v26
	v_add_co_u32_e32 v26, vcc, s36, v28
	v_add_f32_e32 v35, 1.0, v35
	s_nop 0
	v_addc_co_u32_e32 v27, vcc, 0, v29, vcc
	v_rcp_f32_e32 v35, v35
	global_store_short v[26:27], v34, off offset:512
	v_mul_f32_e32 v34, 0xbfb8aa3b, v9
	v_exp_f32_e32 v34, v34
	v_mul_f32_e32 v8, v8, v35
	v_mul_f32_e32 v8, v12, v8
	v_cvt_pk_bf16_f32 v8, v8, s0
	v_add_f32_e32 v12, 1.0, v34
	v_rcp_f32_e32 v12, v12
	global_store_short v[30:31], v8, off offset:32
	v_mul_f32_e32 v8, 0xbfb8aa3b, v10
	v_exp_f32_e32 v8, v8
	v_mul_f32_e32 v9, v9, v12
	v_mul_f32_e32 v9, v13, v9
	v_cvt_pk_bf16_f32 v9, v9, s0
	v_add_f32_e32 v8, 1.0, v8
	v_rcp_f32_e32 v8, v8
	global_store_short v[24:25], v9, off offset:1568
	v_mul_f32_e32 v9, 0xbfb8aa3b, v11
	v_exp_f32_e32 v9, v9
	v_mul_f32_e32 v8, v10, v8
	v_mul_f32_e32 v8, v14, v8
	v_cvt_pk_bf16_f32 v8, v8, s0
	v_add_f32_e32 v9, 1.0, v9
	v_rcp_f32_e32 v9, v9
	global_store_short v[32:33], v8, off offset:3104
	v_mul_f32_e32 v8, 0xbfb8aa3b, v20
	v_exp_f32_e32 v8, v8
	v_mul_f32_e32 v9, v11, v9
	v_mul_f32_e32 v9, v15, v9
	v_cvt_pk_bf16_f32 v9, v9, s0
	v_add_f32_e32 v8, 1.0, v8
	v_rcp_f32_e32 v8, v8
	global_store_short v[26:27], v9, off offset:544
	v_mul_f32_e32 v9, 0xbfb8aa3b, v21
	v_exp_f32_e32 v9, v9
	v_mul_f32_e32 v8, v20, v8
	v_mul_f32_e32 v8, v16, v8
	v_cvt_pk_bf16_f32 v10, v8, s0
	v_add_f32_e32 v8, 1.0, v9
	v_rcp_f32_e32 v11, v8
	v_add_co_u32_e32 v8, vcc, s47, v28
	s_nop 1
	v_addc_co_u32_e32 v9, vcc, 0, v29, vcc
	global_store_short v[8:9], v10, off
	v_mul_f32_e32 v10, v21, v11
	v_mul_f32_e32 v10, v17, v10
	v_cvt_pk_bf16_f32 v12, v10, s0
	v_mul_f32_e32 v10, 0xbfb8aa3b, v22
	v_exp_f32_e32 v13, v10
	v_add_co_u32_e32 v10, vcc, s48, v28
	v_add_f32_e32 v13, 1.0, v13
	s_nop 0
	v_addc_co_u32_e32 v11, vcc, 0, v29, vcc
	global_store_short v[10:11], v12, off offset:1536
	v_mul_f32_e32 v12, 0xbfb8aa3b, v23
	v_exp_f32_e32 v12, v12
	v_rcp_f32_e32 v13, v13
	v_add_f32_e32 v12, 1.0, v12
	v_rcp_f32_e32 v15, v12
	v_mul_f32_e32 v13, v22, v13
	v_mul_f32_e32 v13, v18, v13
	v_add_co_u32_e32 v12, vcc, s49, v28
	v_cvt_pk_bf16_f32 v14, v13, s0
	s_nop 0
	v_addc_co_u32_e32 v13, vcc, 0, v29, vcc
	global_store_short v[12:13], v14, off offset:3072
	v_mul_f32_e32 v14, v23, v15
	v_mul_f32_e32 v14, v19, v14
	v_cvt_pk_bf16_f32 v16, v14, s0
	v_mul_f32_e32 v14, 0xbfb8aa3b, v4
	v_exp_f32_e32 v17, v14
	v_add_co_u32_e32 v14, vcc, s50, v28
	v_add_f32_e32 v17, 1.0, v17
	s_nop 0
	v_addc_co_u32_e32 v15, vcc, 0, v29, vcc
	v_rcp_f32_e32 v17, v17
	global_store_short v[14:15], v16, off offset:512
	v_mul_f32_e32 v16, 0xbfb8aa3b, v5
	v_exp_f32_e32 v16, v16
	v_mul_f32_e32 v4, v4, v17
	v_mul_f32_e32 v0, v0, v4
	v_cvt_pk_bf16_f32 v0, v0, s0
	v_add_f32_e32 v4, 1.0, v16
	v_rcp_f32_e32 v4, v4
	v_mul_f32_e32 v16, 0xbfb8aa3b, v6
	v_exp_f32_e32 v16, v16
	global_store_short v[8:9], v0, off offset:32
	v_mul_f32_e32 v0, v5, v4
	v_mul_f32_e32 v0, v1, v0
	v_add_f32_e32 v1, 1.0, v16
	v_mul_f32_e32 v4, 0xbfb8aa3b, v7
	v_rcp_f32_e32 v1, v1
	v_exp_f32_e32 v4, v4
	v_cvt_pk_bf16_f32 v0, v0, s0
	global_store_short v[10:11], v0, off offset:1568
	v_mul_f32_e32 v0, v6, v1
	v_add_f32_e32 v1, 1.0, v4
	v_rcp_f32_e32 v1, v1
	v_mul_f32_e32 v0, v2, v0
	v_cvt_pk_bf16_f32 v0, v0, s0
	global_store_short v[12:13], v0, off offset:3104
	v_mul_f32_e32 v0, v7, v1
	v_mul_f32_e32 v0, v3, v0
	v_cvt_pk_bf16_f32 v0, v0, s0
	s_andn2_b64 vcc, exec, s[26:27]
	global_store_short v[14:15], v0, off offset:544
	s_cbranch_vccnz .LBB0_2413

.LBB0_2477:
	s_lshl_b32 s6, s36, 7
	s_and_b32 s37, s6, 0x1f80
	s_lshl_b32 s6, s36, 1
	s_and_b32 s38, s6, 0xffffff80
	s_mul_i32 s6, s37, 0x1600
	v_lshl_add_u64 v[102:103], v[98:99], 0, s[6:7]
	v_add_co_u32_e32 v38, vcc, 0x2c000, v102
	v_mad_i64_i32 v[104:105], s[40:41], s38, v149, v[100:101]
	s_nop 0
	v_addc_co_u32_e32 v39, vcc, 0, v103, vcc
	v_add_co_u32_e32 v44, vcc, 0x58000, v102
	s_nop 0
	v_addc_co_u32_e32 v45, vcc, 0, v103, vcc
	v_add_co_u32_e32 v46, vcc, 0x84000, v102
	v_addc_co_u32_e32 v47, vcc, 0, v103, vcc
	v_add_co_u32_e32 v48, vcc, s31, v104
	v_addc_co_u32_e32 v49, vcc, 0, v105, vcc
	v_add_co_u32_e32 v50, vcc, s34, v104
	s_nop 0
	v_addc_co_u32_e32 v51, vcc, 0, v105, vcc
	v_add_co_u32_e32 v52, vcc, s35, v104
	s_nop 0
	v_addc_co_u32_e32 v53, vcc, 0, v105, vcc
	s_mov_b32 s39, -2
	v_mov_b32_e32 v8, 0
	v_mov_b32_e32 v9, v97
	v_mov_b32_e32 v10, v97
	v_mov_b32_e32 v11, v97
	v_mov_b32_e32 v24, 0
	v_mov_b32_e32 v25, v97
	v_mov_b32_e32 v26, v97
	v_mov_b32_e32 v27, v97
	v_mov_b32_e32 v36, 0
	v_mov_b32_e32 v37, v97
	v_mov_b32_e32 v38, v97
	v_mov_b32_e32 v39, v97
	v_lshl_add_u64 v[106:107], v[104:105], 0, s[8:9]
	v_lshl_add_u64 v[108:109], v[104:105], 0, s[10:11]
	v_lshl_add_u64 v[110:111], v[104:105], 0, s[12:13]
	v_lshl_add_u64 v[120:121], v[104:105], 0, s[14:15]
	v_lshl_add_u64 v[122:123], v[104:105], 0, s[16:17]
	v_lshl_add_u64 v[124:125], v[104:105], 0, s[18:19]
	v_lshl_add_u64 v[118:119], v[104:105], 0, s[20:21]
	v_lshl_add_u64 v[112:113], v[102:103], 0, s[8:9]
	v_lshl_add_u64 v[114:115], v[102:103], 0, s[10:11]
	v_lshl_add_u64 v[116:117], v[102:103], 0, s[12:13]
	v_lshl_add_u64 v[126:127], v[102:103], 0, s[14:15]
	v_lshl_add_u64 v[128:129], v[102:103], 0, s[16:17]
	v_lshl_add_u64 v[130:131], v[102:103], 0, s[18:19]
	v_lshl_add_u64 v[132:133], v[102:103], 0, s[20:21]
	v_mov_b32_e32 v48, 0
	v_mov_b32_e32 v49, v97
	v_mov_b32_e32 v50, v97
	v_mov_b32_e32 v51, v97
	v_mov_b32_e32 v52, 0
	v_mov_b32_e32 v53, v97
	v_mov_b32_e32 v54, v97
	v_mov_b32_e32 v55, v97
	v_mov_b32_e32 v56, 0
	v_mov_b32_e32 v57, v97
	v_mov_b32_e32 v58, v97
	v_mov_b32_e32 v59, v97
	v_mov_b32_e32 v44, 0
	v_mov_b32_e32 v45, v97
	v_mov_b32_e32 v46, v97
	v_mov_b32_e32 v47, v97
	v_mov_b32_e32 v60, 0
	v_mov_b32_e32 v61, v97
	v_mov_b32_e32 v62, v97
	v_mov_b32_e32 v63, v97
	v_mov_b32_e32 v0, 0
	v_mov_b32_e32 v1, v97
	v_mov_b32_e32 v2, v97
	v_mov_b32_e32 v3, v97
	v_mov_b32_e32 v16, 0
	v_mov_b32_e32 v17, v97
	v_mov_b32_e32 v18, v97
	v_mov_b32_e32 v19, v97
	v_mov_b32_e32 v32, 0
	v_mov_b32_e32 v33, v97
	v_mov_b32_e32 v34, v97
	v_mov_b32_e32 v35, v97
	v_mov_b32_e32 v4, 0
	v_mov_b32_e32 v5, v97
	v_mov_b32_e32 v6, v97
	v_mov_b32_e32 v7, v97
	v_mov_b32_e32 v20, 0
	v_mov_b32_e32 v21, v97
	v_mov_b32_e32 v22, v97
	v_mov_b32_e32 v23, v97
	v_mov_b32_e32 v40, 0
	v_mov_b32_e32 v41, v97
	v_mov_b32_e32 v42, v97
	v_mov_b32_e32 v43, v97
	v_mov_b32_e32 v12, 0
	v_mov_b32_e32 v13, v97
	v_mov_b32_e32 v14, v97
	v_mov_b32_e32 v15, v97
	v_mov_b32_e32 v28, 0
	v_mov_b32_e32 v29, v97
	v_mov_b32_e32 v30, v97
	v_mov_b32_e32 v31, v97
	v_readfirstlane_b32 s40, v102
	v_readfirstlane_b32 s41, v103
	v_readfirstlane_b32 s48, v104
	v_readfirstlane_b32 s49, v105
	v_readfirstlane_b32 s6, v247
	s_nop 3
	s_mul_i32 s39, s6, 0xb000
	s_sub_u32 s40, s40, s39
	s_subb_u32 s41, s41, 0
	s_sub_u32 s48, s48, s39
	s_subb_u32 s49, s49, 0
	s_lshl_b32 s6, s6, 12
	s_add_u32 m0, s6, 0x0
	v_mov_b32_e32 v60, 0
	global_load_lds_dwordx4 v248, s[40:41]
	v_mov_b32_e32 v61, 0
	s_add_u32 m0, s6, 0x400
	v_mov_b32_e32 v62, 0
	global_load_lds_dwordx4 v249, s[40:41]
	v_mov_b32_e32 v63, 0
	s_add_u32 m0, s6, 0x800
	v_mov_b32_e32 v44, 0
	global_load_lds_dwordx4 v250, s[40:41]
	v_mov_b32_e32 v45, 0
	s_add_u32 m0, s6, 0xc00
	v_mov_b32_e32 v46, 0
	global_load_lds_dwordx4 v251, s[40:41]
	v_mov_b32_e32 v47, 0
	s_add_u32 m0, s6, 0x8000
	v_mov_b32_e32 v28, 0
	global_load_lds_dwordx4 v248, s[48:49]
	v_mov_b32_e32 v29, 0
	s_add_u32 m0, s6, 0x8400
	v_mov_b32_e32 v30, 0
	global_load_lds_dwordx4 v249, s[48:49]
	v_mov_b32_e32 v31, 0
	s_add_u32 m0, s6, 0x8800
	v_mov_b32_e32 v12, 0
	global_load_lds_dwordx4 v250, s[48:49]
	v_mov_b32_e32 v13, 0
	s_add_u32 m0, s6, 0x8c00
	v_mov_b32_e32 v14, 0
	global_load_lds_dwordx4 v251, s[48:49]
	v_mov_b32_e32 v15, 0
	s_add_u32 s40, s40, 0x80
	s_addc_u32 s41, s41, 0
	s_add_u32 s48, s48, 0x80
	s_addc_u32 s49, s49, 0
	s_add_u32 m0, s6, 0x4000
	v_mov_b32_e32 v56, 0
	global_load_lds_dwordx4 v248, s[40:41]
	v_mov_b32_e32 v57, 0
	s_add_u32 m0, s6, 0x4400
	v_mov_b32_e32 v58, 0
	global_load_lds_dwordx4 v249, s[40:41]
	v_mov_b32_e32 v59, 0
	s_add_u32 m0, s6, 0x4800
	v_mov_b32_e32 v40, 0
	global_load_lds_dwordx4 v250, s[40:41]
	v_mov_b32_e32 v41, 0
	s_add_u32 m0, s6, 0x4c00
	v_mov_b32_e32 v42, 0
	global_load_lds_dwordx4 v251, s[40:41]
	v_mov_b32_e32 v43, 0
	s_add_u32 m0, s6, 0xc000
	v_mov_b32_e32 v20, 0
	global_load_lds_dwordx4 v248, s[48:49]
	v_mov_b32_e32 v21, 0
	s_add_u32 m0, s6, 0xc400
	v_mov_b32_e32 v22, 0
	global_load_lds_dwordx4 v249, s[48:49]
	v_mov_b32_e32 v23, 0
	s_add_u32 m0, s6, 0xc800
	v_mov_b32_e32 v4, 0
	global_load_lds_dwordx4 v250, s[48:49]
	v_mov_b32_e32 v5, 0
	s_add_u32 m0, s6, 0xcc00
	v_mov_b32_e32 v6, 0
	global_load_lds_dwordx4 v251, s[48:49]
	v_mov_b32_e32 v7, 0
	s_add_u32 s40, s40, 0x80
	s_addc_u32 s41, s41, 0
	s_add_u32 s48, s48, 0x80
	s_addc_u32 s49, s49, 0
	v_mov_b32_e32 v52, 0
	v_mov_b32_e32 v53, 0
	v_mov_b32_e32 v54, 0
	v_mov_b32_e32 v55, 0
	v_mov_b32_e32 v32, 0
	v_mov_b32_e32 v33, 0
	v_mov_b32_e32 v34, 0
	v_mov_b32_e32 v35, 0
	v_mov_b32_e32 v16, 0
	v_mov_b32_e32 v17, 0
	v_mov_b32_e32 v18, 0
	v_mov_b32_e32 v19, 0
	v_mov_b32_e32 v0, 0
	v_mov_b32_e32 v1, 0
	v_mov_b32_e32 v2, 0
	v_mov_b32_e32 v3, 0
	v_mov_b32_e32 v48, 0
	v_mov_b32_e32 v49, 0
	v_mov_b32_e32 v50, 0
	v_mov_b32_e32 v51, 0
	v_mov_b32_e32 v36, 0
	v_mov_b32_e32 v37, 0
	v_mov_b32_e32 v38, 0
	v_mov_b32_e32 v39, 0
	v_mov_b32_e32 v24, 0
	v_mov_b32_e32 v25, 0
	v_mov_b32_e32 v26, 0
	v_mov_b32_e32 v27, 0
	v_mov_b32_e32 v8, 0
	v_mov_b32_e32 v9, 0
	v_mov_b32_e32 v10, 0
	v_mov_b32_e32 v11, 0
	s_waitcnt vmcnt(8)
	s_barrier
	ds_read_b128 v[64:67], v252 offset:0
	ds_read_b128 v[104:107], v254 offset:32768
	ds_read_b128 v[108:111], v254 offset:34816
	ds_read_b128 v[112:115], v254 offset:36864
	ds_read_b128 v[116:119], v254 offset:38912
	ds_read_b128 v[68:71], v252 offset:2048
	ds_read_b128 v[72:75], v252 offset:4096
	ds_read_b128 v[76:79], v252 offset:6144
	ds_read_b128 v[80:83], v253 offset:0
	ds_read_b128 v[120:123], v255 offset:32768
	ds_read_b128 v[124:127], v255 offset:34816
	ds_read_b128 v[132:135], v255 offset:36864
	ds_read_b128 v[136:139], v255 offset:38912
	s_waitcnt lgkmcnt(11)
	v_mfma_f32_16x16x32_bf16 v[60:63], v[64:67], v[104:107], v[60:63]
	s_waitcnt lgkmcnt(10)
	v_mfma_f32_16x16x32_bf16 v[44:47], v[64:67], v[108:111], v[44:47]
	s_waitcnt lgkmcnt(9)
	v_mfma_f32_16x16x32_bf16 v[28:31], v[64:67], v[112:115], v[28:31]
	s_waitcnt lgkmcnt(8)
	v_mfma_f32_16x16x32_bf16 v[12:15], v[64:67], v[116:119], v[12:15]
	ds_read_b128 v[84:87], v253 offset:2048
	ds_read_b128 v[88:91], v253 offset:4096
	ds_read_b128 v[92:95], v253 offset:6144
	s_waitcnt lgkmcnt(10)
	v_mfma_f32_16x16x32_bf16 v[56:59], v[68:71], v[104:107], v[56:59]
	v_mfma_f32_16x16x32_bf16 v[40:43], v[68:71], v[108:111], v[40:43]
	v_mfma_f32_16x16x32_bf16 v[20:23], v[68:71], v[112:115], v[20:23]
	v_mfma_f32_16x16x32_bf16 v[4:7], v[68:71], v[116:119], v[4:7]
	s_waitcnt lgkmcnt(0)
	s_barrier
	s_add_u32 m0, s6, 0x0
	v_mfma_f32_16x16x32_bf16 v[52:55], v[72:75], v[104:107], v[52:55]
	global_load_lds_dwordx4 v248, s[40:41]
	s_add_u32 m0, s6, 0x400
	v_mfma_f32_16x16x32_bf16 v[32:35], v[72:75], v[108:111], v[32:35]
	global_load_lds_dwordx4 v249, s[40:41]
	s_add_u32 m0, s6, 0x800
	v_mfma_f32_16x16x32_bf16 v[16:19], v[72:75], v[112:115], v[16:19]
	global_load_lds_dwordx4 v250, s[40:41]
	s_add_u32 m0, s6, 0xc00
	v_mfma_f32_16x16x32_bf16 v[0:3], v[72:75], v[116:119], v[0:3]
	global_load_lds_dwordx4 v251, s[40:41]
	s_add_u32 m0, s6, 0x8000
	v_mfma_f32_16x16x32_bf16 v[48:51], v[76:79], v[104:107], v[48:51]
	global_load_lds_dwordx4 v248, s[48:49]
	s_add_u32 m0, s6, 0x8400
	v_mfma_f32_16x16x32_bf16 v[36:39], v[76:79], v[108:111], v[36:39]
	global_load_lds_dwordx4 v249, s[48:49]
	s_add_u32 m0, s6, 0x8800
	v_mfma_f32_16x16x32_bf16 v[24:27], v[76:79], v[112:115], v[24:27]
	global_load_lds_dwordx4 v250, s[48:49]
	s_add_u32 m0, s6, 0x8c00
	v_mfma_f32_16x16x32_bf16 v[8:11], v[76:79], v[116:119], v[8:11]
	global_load_lds_dwordx4 v251, s[48:49]
	s_add_u32 s40, s40, 0x80
	s_addc_u32 s41, s41, 0
	s_add_u32 s48, s48, 0x80
	s_addc_u32 s49, s49, 0
	s_waitcnt vmcnt(8)
	s_barrier
	ds_read_b128 v[64:67], v252 offset:16384
	ds_read_b128 v[104:107], v254 offset:49152
	ds_read_b128 v[108:111], v254 offset:51200
	ds_read_b128 v[112:115], v254 offset:53248
	ds_read_b128 v[116:119], v254 offset:55296
	ds_read_b128 v[68:71], v252 offset:18432
	ds_read_b128 v[72:75], v252 offset:20480
	ds_read_b128 v[76:79], v252 offset:22528
	v_mfma_f32_16x16x32_bf16 v[60:63], v[80:83], v[120:123], v[60:63]
	v_mfma_f32_16x16x32_bf16 v[44:47], v[80:83], v[124:127], v[44:47]
	v_mfma_f32_16x16x32_bf16 v[28:31], v[80:83], v[132:135], v[28:31]
	v_mfma_f32_16x16x32_bf16 v[12:15], v[80:83], v[136:139], v[12:15]
	v_mfma_f32_16x16x32_bf16 v[56:59], v[84:87], v[120:123], v[56:59]
	v_mfma_f32_16x16x32_bf16 v[40:43], v[84:87], v[124:127], v[40:43]
	v_mfma_f32_16x16x32_bf16 v[20:23], v[84:87], v[132:135], v[20:23]
	v_mfma_f32_16x16x32_bf16 v[4:7], v[84:87], v[136:139], v[4:7]
	v_mfma_f32_16x16x32_bf16 v[52:55], v[88:91], v[120:123], v[52:55]
	v_mfma_f32_16x16x32_bf16 v[32:35], v[88:91], v[124:127], v[32:35]
	v_mfma_f32_16x16x32_bf16 v[16:19], v[88:91], v[132:135], v[16:19]
	v_mfma_f32_16x16x32_bf16 v[0:3], v[88:91], v[136:139], v[0:3]
	v_mfma_f32_16x16x32_bf16 v[48:51], v[92:95], v[120:123], v[48:51]
	v_mfma_f32_16x16x32_bf16 v[36:39], v[92:95], v[124:127], v[36:39]
	v_mfma_f32_16x16x32_bf16 v[24:27], v[92:95], v[132:135], v[24:27]
	v_mfma_f32_16x16x32_bf16 v[8:11], v[92:95], v[136:139], v[8:11]
	ds_read_b128 v[80:83], v253 offset:16384
	ds_read_b128 v[120:123], v255 offset:49152
	ds_read_b128 v[124:127], v255 offset:51200
	ds_read_b128 v[132:135], v255 offset:53248
	ds_read_b128 v[136:139], v255 offset:55296
	ds_read_b128 v[84:87], v253 offset:18432
	ds_read_b128 v[88:91], v253 offset:20480
	ds_read_b128 v[92:95], v253 offset:22528
	s_waitcnt lgkmcnt(14)
	v_mfma_f32_16x16x32_bf16 v[60:63], v[64:67], v[104:107], v[60:63]
	s_waitcnt lgkmcnt(13)
	v_mfma_f32_16x16x32_bf16 v[44:47], v[64:67], v[108:111], v[44:47]
	s_waitcnt lgkmcnt(12)
	v_mfma_f32_16x16x32_bf16 v[28:31], v[64:67], v[112:115], v[28:31]
	s_waitcnt lgkmcnt(11)
	v_mfma_f32_16x16x32_bf16 v[12:15], v[64:67], v[116:119], v[12:15]
	s_waitcnt lgkmcnt(10)
	v_mfma_f32_16x16x32_bf16 v[56:59], v[68:71], v[104:107], v[56:59]
	v_mfma_f32_16x16x32_bf16 v[40:43], v[68:71], v[108:111], v[40:43]
	v_mfma_f32_16x16x32_bf16 v[20:23], v[68:71], v[112:115], v[20:23]
	v_mfma_f32_16x16x32_bf16 v[4:7], v[68:71], v[116:119], v[4:7]
	s_waitcnt lgkmcnt(0)
	s_barrier
	s_add_u32 m0, s6, 0x4000
	v_mfma_f32_16x16x32_bf16 v[52:55], v[72:75], v[104:107], v[52:55]
	global_load_lds_dwordx4 v248, s[40:41]
	s_add_u32 m0, s6, 0x4400
	v_mfma_f32_16x16x32_bf16 v[32:35], v[72:75], v[108:111], v[32:35]
	global_load_lds_dwordx4 v249, s[40:41]
	s_add_u32 m0, s6, 0x4800
	v_mfma_f32_16x16x32_bf16 v[16:19], v[72:75], v[112:115], v[16:19]
	global_load_lds_dwordx4 v250, s[40:41]
	s_add_u32 m0, s6, 0x4c00
	v_mfma_f32_16x16x32_bf16 v[0:3], v[72:75], v[116:119], v[0:3]
	global_load_lds_dwordx4 v251, s[40:41]
	s_add_u32 m0, s6, 0xc000
	v_mfma_f32_16x16x32_bf16 v[48:51], v[76:79], v[104:107], v[48:51]
	global_load_lds_dwordx4 v248, s[48:49]
	s_add_u32 m0, s6, 0xc400
	v_mfma_f32_16x16x32_bf16 v[36:39], v[76:79], v[108:111], v[36:39]
	global_load_lds_dwordx4 v249, s[48:49]
	s_add_u32 m0, s6, 0xc800
	v_mfma_f32_16x16x32_bf16 v[24:27], v[76:79], v[112:115], v[24:27]
	global_load_lds_dwordx4 v250, s[48:49]
	s_add_u32 m0, s6, 0xcc00
	v_mfma_f32_16x16x32_bf16 v[8:11], v[76:79], v[116:119], v[8:11]
	global_load_lds_dwordx4 v251, s[48:49]
	s_add_u32 s40, s40, 0x80
	s_addc_u32 s41, s41, 0
	s_add_u32 s48, s48, 0x80
	s_addc_u32 s49, s49, 0
	s_mov_b32 s32, 20
.Lg25_loop:
	s_waitcnt vmcnt(8)
	s_barrier
	ds_read_b128 v[64:67], v252 offset:0
	ds_read_b128 v[104:107], v254 offset:32768
	ds_read_b128 v[108:111], v254 offset:34816
	ds_read_b128 v[112:115], v254 offset:36864
	ds_read_b128 v[116:119], v254 offset:38912
	ds_read_b128 v[68:71], v252 offset:2048
	ds_read_b128 v[72:75], v252 offset:4096
	ds_read_b128 v[76:79], v252 offset:6144
	v_mfma_f32_16x16x32_bf16 v[60:63], v[80:83], v[120:123], v[60:63]
	v_mfma_f32_16x16x32_bf16 v[44:47], v[80:83], v[124:127], v[44:47]
	v_mfma_f32_16x16x32_bf16 v[28:31], v[80:83], v[132:135], v[28:31]
	v_mfma_f32_16x16x32_bf16 v[12:15], v[80:83], v[136:139], v[12:15]
	v_mfma_f32_16x16x32_bf16 v[56:59], v[84:87], v[120:123], v[56:59]
	v_mfma_f32_16x16x32_bf16 v[40:43], v[84:87], v[124:127], v[40:43]
	v_mfma_f32_16x16x32_bf16 v[20:23], v[84:87], v[132:135], v[20:23]
	v_mfma_f32_16x16x32_bf16 v[4:7], v[84:87], v[136:139], v[4:7]
	v_mfma_f32_16x16x32_bf16 v[52:55], v[88:91], v[120:123], v[52:55]
	v_mfma_f32_16x16x32_bf16 v[32:35], v[88:91], v[124:127], v[32:35]
	v_mfma_f32_16x16x32_bf16 v[16:19], v[88:91], v[132:135], v[16:19]
	v_mfma_f32_16x16x32_bf16 v[0:3], v[88:91], v[136:139], v[0:3]
	v_mfma_f32_16x16x32_bf16 v[48:51], v[92:95], v[120:123], v[48:51]
	v_mfma_f32_16x16x32_bf16 v[36:39], v[92:95], v[124:127], v[36:39]
	v_mfma_f32_16x16x32_bf16 v[24:27], v[92:95], v[132:135], v[24:27]
	v_mfma_f32_16x16x32_bf16 v[8:11], v[92:95], v[136:139], v[8:11]
	ds_read_b128 v[80:83], v253 offset:0
	ds_read_b128 v[120:123], v255 offset:32768
	ds_read_b128 v[124:127], v255 offset:34816
	ds_read_b128 v[132:135], v255 offset:36864
	ds_read_b128 v[136:139], v255 offset:38912
	ds_read_b128 v[84:87], v253 offset:2048
	ds_read_b128 v[88:91], v253 offset:4096
	ds_read_b128 v[92:95], v253 offset:6144
	s_waitcnt lgkmcnt(14)
	v_mfma_f32_16x16x32_bf16 v[60:63], v[64:67], v[104:107], v[60:63]
	s_waitcnt lgkmcnt(13)
	v_mfma_f32_16x16x32_bf16 v[44:47], v[64:67], v[108:111], v[44:47]
	s_waitcnt lgkmcnt(12)
	v_mfma_f32_16x16x32_bf16 v[28:31], v[64:67], v[112:115], v[28:31]
	s_waitcnt lgkmcnt(11)
	v_mfma_f32_16x16x32_bf16 v[12:15], v[64:67], v[116:119], v[12:15]
	s_waitcnt lgkmcnt(10)
	v_mfma_f32_16x16x32_bf16 v[56:59], v[68:71], v[104:107], v[56:59]
	v_mfma_f32_16x16x32_bf16 v[40:43], v[68:71], v[108:111], v[40:43]
	v_mfma_f32_16x16x32_bf16 v[20:23], v[68:71], v[112:115], v[20:23]
	v_mfma_f32_16x16x32_bf16 v[4:7], v[68:71], v[116:119], v[4:7]
	s_waitcnt lgkmcnt(0)
	s_barrier
	s_add_u32 m0, s6, 0x0
	v_mfma_f32_16x16x32_bf16 v[52:55], v[72:75], v[104:107], v[52:55]
	global_load_lds_dwordx4 v248, s[40:41]
	s_add_u32 m0, s6, 0x400
	v_mfma_f32_16x16x32_bf16 v[32:35], v[72:75], v[108:111], v[32:35]
	global_load_lds_dwordx4 v249, s[40:41]
	s_add_u32 m0, s6, 0x800
	v_mfma_f32_16x16x32_bf16 v[16:19], v[72:75], v[112:115], v[16:19]
	global_load_lds_dwordx4 v250, s[40:41]
	s_add_u32 m0, s6, 0xc00
	v_mfma_f32_16x16x32_bf16 v[0:3], v[72:75], v[116:119], v[0:3]
	global_load_lds_dwordx4 v251, s[40:41]
	s_add_u32 m0, s6, 0x8000
	v_mfma_f32_16x16x32_bf16 v[48:51], v[76:79], v[104:107], v[48:51]
	global_load_lds_dwordx4 v248, s[48:49]
	s_add_u32 m0, s6, 0x8400
	v_mfma_f32_16x16x32_bf16 v[36:39], v[76:79], v[108:111], v[36:39]
	global_load_lds_dwordx4 v249, s[48:49]
	s_add_u32 m0, s6, 0x8800
	v_mfma_f32_16x16x32_bf16 v[24:27], v[76:79], v[112:115], v[24:27]
	global_load_lds_dwordx4 v250, s[48:49]
	s_add_u32 m0, s6, 0x8c00
	v_mfma_f32_16x16x32_bf16 v[8:11], v[76:79], v[116:119], v[8:11]
	global_load_lds_dwordx4 v251, s[48:49]
	s_add_u32 s40, s40, 0x80
	s_addc_u32 s41, s41, 0
	s_add_u32 s48, s48, 0x80
	s_addc_u32 s49, s49, 0
	s_waitcnt vmcnt(8)
	s_barrier
	ds_read_b128 v[64:67], v252 offset:16384
	ds_read_b128 v[104:107], v254 offset:49152
	ds_read_b128 v[108:111], v254 offset:51200
	ds_read_b128 v[112:115], v254 offset:53248
	ds_read_b128 v[116:119], v254 offset:55296
	ds_read_b128 v[68:71], v252 offset:18432
	ds_read_b128 v[72:75], v252 offset:20480
	ds_read_b128 v[76:79], v252 offset:22528
	v_mfma_f32_16x16x32_bf16 v[60:63], v[80:83], v[120:123], v[60:63]
	v_mfma_f32_16x16x32_bf16 v[44:47], v[80:83], v[124:127], v[44:47]
	v_mfma_f32_16x16x32_bf16 v[28:31], v[80:83], v[132:135], v[28:31]
	v_mfma_f32_16x16x32_bf16 v[12:15], v[80:83], v[136:139], v[12:15]
	v_mfma_f32_16x16x32_bf16 v[56:59], v[84:87], v[120:123], v[56:59]
	v_mfma_f32_16x16x32_bf16 v[40:43], v[84:87], v[124:127], v[40:43]
	v_mfma_f32_16x16x32_bf16 v[20:23], v[84:87], v[132:135], v[20:23]
	v_mfma_f32_16x16x32_bf16 v[4:7], v[84:87], v[136:139], v[4:7]
	v_mfma_f32_16x16x32_bf16 v[52:55], v[88:91], v[120:123], v[52:55]
	v_mfma_f32_16x16x32_bf16 v[32:35], v[88:91], v[124:127], v[32:35]
	v_mfma_f32_16x16x32_bf16 v[16:19], v[88:91], v[132:135], v[16:19]
	v_mfma_f32_16x16x32_bf16 v[0:3], v[88:91], v[136:139], v[0:3]
	v_mfma_f32_16x16x32_bf16 v[48:51], v[92:95], v[120:123], v[48:51]
	v_mfma_f32_16x16x32_bf16 v[36:39], v[92:95], v[124:127], v[36:39]
	v_mfma_f32_16x16x32_bf16 v[24:27], v[92:95], v[132:135], v[24:27]
	v_mfma_f32_16x16x32_bf16 v[8:11], v[92:95], v[136:139], v[8:11]
	ds_read_b128 v[80:83], v253 offset:16384
	ds_read_b128 v[120:123], v255 offset:49152
	ds_read_b128 v[124:127], v255 offset:51200
	ds_read_b128 v[132:135], v255 offset:53248
	ds_read_b128 v[136:139], v255 offset:55296
	ds_read_b128 v[84:87], v253 offset:18432
	ds_read_b128 v[88:91], v253 offset:20480
	ds_read_b128 v[92:95], v253 offset:22528
	s_waitcnt lgkmcnt(14)
	v_mfma_f32_16x16x32_bf16 v[60:63], v[64:67], v[104:107], v[60:63]
	s_waitcnt lgkmcnt(13)
	v_mfma_f32_16x16x32_bf16 v[44:47], v[64:67], v[108:111], v[44:47]
	s_waitcnt lgkmcnt(12)
	v_mfma_f32_16x16x32_bf16 v[28:31], v[64:67], v[112:115], v[28:31]
	s_waitcnt lgkmcnt(11)
	v_mfma_f32_16x16x32_bf16 v[12:15], v[64:67], v[116:119], v[12:15]
	s_waitcnt lgkmcnt(10)
	v_mfma_f32_16x16x32_bf16 v[56:59], v[68:71], v[104:107], v[56:59]
	v_mfma_f32_16x16x32_bf16 v[40:43], v[68:71], v[108:111], v[40:43]
	v_mfma_f32_16x16x32_bf16 v[20:23], v[68:71], v[112:115], v[20:23]
	v_mfma_f32_16x16x32_bf16 v[4:7], v[68:71], v[116:119], v[4:7]
	s_waitcnt lgkmcnt(0)
	s_barrier
	s_add_u32 m0, s6, 0x4000
	v_mfma_f32_16x16x32_bf16 v[52:55], v[72:75], v[104:107], v[52:55]
	global_load_lds_dwordx4 v248, s[40:41]
	s_add_u32 m0, s6, 0x4400
	v_mfma_f32_16x16x32_bf16 v[32:35], v[72:75], v[108:111], v[32:35]
	global_load_lds_dwordx4 v249, s[40:41]
	s_add_u32 m0, s6, 0x4800
	v_mfma_f32_16x16x32_bf16 v[16:19], v[72:75], v[112:115], v[16:19]
	global_load_lds_dwordx4 v250, s[40:41]
	s_add_u32 m0, s6, 0x4c00
	v_mfma_f32_16x16x32_bf16 v[0:3], v[72:75], v[116:119], v[0:3]
	global_load_lds_dwordx4 v251, s[40:41]
	s_add_u32 m0, s6, 0xc000
	v_mfma_f32_16x16x32_bf16 v[48:51], v[76:79], v[104:107], v[48:51]
	global_load_lds_dwordx4 v248, s[48:49]
	s_add_u32 m0, s6, 0xc400
	v_mfma_f32_16x16x32_bf16 v[36:39], v[76:79], v[108:111], v[36:39]
	global_load_lds_dwordx4 v249, s[48:49]
	s_add_u32 m0, s6, 0xc800
	v_mfma_f32_16x16x32_bf16 v[24:27], v[76:79], v[112:115], v[24:27]
	global_load_lds_dwordx4 v250, s[48:49]
	s_add_u32 m0, s6, 0xcc00
	v_mfma_f32_16x16x32_bf16 v[8:11], v[76:79], v[116:119], v[8:11]
	global_load_lds_dwordx4 v251, s[48:49]
	s_add_u32 s40, s40, 0x80
	s_addc_u32 s41, s41, 0
	s_add_u32 s48, s48, 0x80
	s_addc_u32 s49, s49, 0
	s_sub_u32 s32, s32, 1
	s_cmp_lg_u32 s32, 0
	s_cbranch_scc1 .Lg25_loop
	s_waitcnt vmcnt(8)
	s_barrier
	ds_read_b128 v[64:67], v252 offset:0
	ds_read_b128 v[104:107], v254 offset:32768
	ds_read_b128 v[108:111], v254 offset:34816
	ds_read_b128 v[112:115], v254 offset:36864
	ds_read_b128 v[116:119], v254 offset:38912
	ds_read_b128 v[68:71], v252 offset:2048
	ds_read_b128 v[72:75], v252 offset:4096
	ds_read_b128 v[76:79], v252 offset:6144
	v_mfma_f32_16x16x32_bf16 v[60:63], v[80:83], v[120:123], v[60:63]
	v_mfma_f32_16x16x32_bf16 v[44:47], v[80:83], v[124:127], v[44:47]
	v_mfma_f32_16x16x32_bf16 v[28:31], v[80:83], v[132:135], v[28:31]
	v_mfma_f32_16x16x32_bf16 v[12:15], v[80:83], v[136:139], v[12:15]
	v_mfma_f32_16x16x32_bf16 v[56:59], v[84:87], v[120:123], v[56:59]
	v_mfma_f32_16x16x32_bf16 v[40:43], v[84:87], v[124:127], v[40:43]
	v_mfma_f32_16x16x32_bf16 v[20:23], v[84:87], v[132:135], v[20:23]
	v_mfma_f32_16x16x32_bf16 v[4:7], v[84:87], v[136:139], v[4:7]
	v_mfma_f32_16x16x32_bf16 v[52:55], v[88:91], v[120:123], v[52:55]
	v_mfma_f32_16x16x32_bf16 v[32:35], v[88:91], v[124:127], v[32:35]
	v_mfma_f32_16x16x32_bf16 v[16:19], v[88:91], v[132:135], v[16:19]
	v_mfma_f32_16x16x32_bf16 v[0:3], v[88:91], v[136:139], v[0:3]
	v_mfma_f32_16x16x32_bf16 v[48:51], v[92:95], v[120:123], v[48:51]
	v_mfma_f32_16x16x32_bf16 v[36:39], v[92:95], v[124:127], v[36:39]
	v_mfma_f32_16x16x32_bf16 v[24:27], v[92:95], v[132:135], v[24:27]
	v_mfma_f32_16x16x32_bf16 v[8:11], v[92:95], v[136:139], v[8:11]
	ds_read_b128 v[80:83], v253 offset:0
	ds_read_b128 v[120:123], v255 offset:32768
	ds_read_b128 v[124:127], v255 offset:34816
	ds_read_b128 v[132:135], v255 offset:36864
	ds_read_b128 v[136:139], v255 offset:38912
	ds_read_b128 v[84:87], v253 offset:2048
	ds_read_b128 v[88:91], v253 offset:4096
	ds_read_b128 v[92:95], v253 offset:6144
	s_waitcnt lgkmcnt(14)
	v_mfma_f32_16x16x32_bf16 v[60:63], v[64:67], v[104:107], v[60:63]
	s_waitcnt lgkmcnt(13)
	v_mfma_f32_16x16x32_bf16 v[44:47], v[64:67], v[108:111], v[44:47]
	s_waitcnt lgkmcnt(12)
	v_mfma_f32_16x16x32_bf16 v[28:31], v[64:67], v[112:115], v[28:31]
	s_waitcnt lgkmcnt(11)
	v_mfma_f32_16x16x32_bf16 v[12:15], v[64:67], v[116:119], v[12:15]
	s_waitcnt lgkmcnt(10)
	v_mfma_f32_16x16x32_bf16 v[56:59], v[68:71], v[104:107], v[56:59]
	v_mfma_f32_16x16x32_bf16 v[40:43], v[68:71], v[108:111], v[40:43]
	v_mfma_f32_16x16x32_bf16 v[20:23], v[68:71], v[112:115], v[20:23]
	v_mfma_f32_16x16x32_bf16 v[4:7], v[68:71], v[116:119], v[4:7]
	s_waitcnt lgkmcnt(0)
	s_barrier
	v_mfma_f32_16x16x32_bf16 v[52:55], v[72:75], v[104:107], v[52:55]
	v_mfma_f32_16x16x32_bf16 v[32:35], v[72:75], v[108:111], v[32:35]
	v_mfma_f32_16x16x32_bf16 v[16:19], v[72:75], v[112:115], v[16:19]
	v_mfma_f32_16x16x32_bf16 v[0:3], v[72:75], v[116:119], v[0:3]
	v_mfma_f32_16x16x32_bf16 v[48:51], v[76:79], v[104:107], v[48:51]
	v_mfma_f32_16x16x32_bf16 v[36:39], v[76:79], v[108:111], v[36:39]
	v_mfma_f32_16x16x32_bf16 v[24:27], v[76:79], v[112:115], v[24:27]
	v_mfma_f32_16x16x32_bf16 v[8:11], v[76:79], v[116:119], v[8:11]
	s_waitcnt vmcnt(0)
	s_barrier
	ds_read_b128 v[64:67], v252 offset:16384
	ds_read_b128 v[104:107], v254 offset:49152
	ds_read_b128 v[108:111], v254 offset:51200
	ds_read_b128 v[112:115], v254 offset:53248
	ds_read_b128 v[116:119], v254 offset:55296
	ds_read_b128 v[68:71], v252 offset:18432
	ds_read_b128 v[72:75], v252 offset:20480
	ds_read_b128 v[76:79], v252 offset:22528
	v_mfma_f32_16x16x32_bf16 v[60:63], v[80:83], v[120:123], v[60:63]
	v_mfma_f32_16x16x32_bf16 v[44:47], v[80:83], v[124:127], v[44:47]
	v_mfma_f32_16x16x32_bf16 v[28:31], v[80:83], v[132:135], v[28:31]
	v_mfma_f32_16x16x32_bf16 v[12:15], v[80:83], v[136:139], v[12:15]
	v_mfma_f32_16x16x32_bf16 v[56:59], v[84:87], v[120:123], v[56:59]
	v_mfma_f32_16x16x32_bf16 v[40:43], v[84:87], v[124:127], v[40:43]
	v_mfma_f32_16x16x32_bf16 v[20:23], v[84:87], v[132:135], v[20:23]
	v_mfma_f32_16x16x32_bf16 v[4:7], v[84:87], v[136:139], v[4:7]
	v_mfma_f32_16x16x32_bf16 v[52:55], v[88:91], v[120:123], v[52:55]
	v_mfma_f32_16x16x32_bf16 v[32:35], v[88:91], v[124:127], v[32:35]
	v_mfma_f32_16x16x32_bf16 v[16:19], v[88:91], v[132:135], v[16:19]
	v_mfma_f32_16x16x32_bf16 v[0:3], v[88:91], v[136:139], v[0:3]
	v_mfma_f32_16x16x32_bf16 v[48:51], v[92:95], v[120:123], v[48:51]
	v_mfma_f32_16x16x32_bf16 v[36:39], v[92:95], v[124:127], v[36:39]
	v_mfma_f32_16x16x32_bf16 v[24:27], v[92:95], v[132:135], v[24:27]
	v_mfma_f32_16x16x32_bf16 v[8:11], v[92:95], v[136:139], v[8:11]
	ds_read_b128 v[80:83], v253 offset:16384
	ds_read_b128 v[120:123], v255 offset:49152
	ds_read_b128 v[124:127], v255 offset:51200
	ds_read_b128 v[132:135], v255 offset:53248
	ds_read_b128 v[136:139], v255 offset:55296
	ds_read_b128 v[84:87], v253 offset:18432
	ds_read_b128 v[88:91], v253 offset:20480
	ds_read_b128 v[92:95], v253 offset:22528
	s_waitcnt lgkmcnt(14)
	v_mfma_f32_16x16x32_bf16 v[60:63], v[64:67], v[104:107], v[60:63]
	s_waitcnt lgkmcnt(13)
	v_mfma_f32_16x16x32_bf16 v[44:47], v[64:67], v[108:111], v[44:47]
	s_waitcnt lgkmcnt(12)
	v_mfma_f32_16x16x32_bf16 v[28:31], v[64:67], v[112:115], v[28:31]
	s_waitcnt lgkmcnt(11)
	v_mfma_f32_16x16x32_bf16 v[12:15], v[64:67], v[116:119], v[12:15]
	s_waitcnt lgkmcnt(10)
	v_mfma_f32_16x16x32_bf16 v[56:59], v[68:71], v[104:107], v[56:59]
	v_mfma_f32_16x16x32_bf16 v[40:43], v[68:71], v[108:111], v[40:43]
	v_mfma_f32_16x16x32_bf16 v[20:23], v[68:71], v[112:115], v[20:23]
	v_mfma_f32_16x16x32_bf16 v[4:7], v[68:71], v[116:119], v[4:7]
	s_waitcnt lgkmcnt(0)
	s_barrier
	v_mfma_f32_16x16x32_bf16 v[52:55], v[72:75], v[104:107], v[52:55]
	v_mfma_f32_16x16x32_bf16 v[32:35], v[72:75], v[108:111], v[32:35]
	v_mfma_f32_16x16x32_bf16 v[16:19], v[72:75], v[112:115], v[16:19]
	v_mfma_f32_16x16x32_bf16 v[0:3], v[72:75], v[116:119], v[0:3]
	v_mfma_f32_16x16x32_bf16 v[48:51], v[76:79], v[104:107], v[48:51]
	v_mfma_f32_16x16x32_bf16 v[36:39], v[76:79], v[108:111], v[36:39]
	v_mfma_f32_16x16x32_bf16 v[24:27], v[76:79], v[112:115], v[24:27]
	v_mfma_f32_16x16x32_bf16 v[8:11], v[76:79], v[116:119], v[8:11]
	v_mfma_f32_16x16x32_bf16 v[60:63], v[80:83], v[120:123], v[60:63]
	v_mfma_f32_16x16x32_bf16 v[44:47], v[80:83], v[124:127], v[44:47]
	v_mfma_f32_16x16x32_bf16 v[28:31], v[80:83], v[132:135], v[28:31]
	v_mfma_f32_16x16x32_bf16 v[12:15], v[80:83], v[136:139], v[12:15]
	v_mfma_f32_16x16x32_bf16 v[56:59], v[84:87], v[120:123], v[56:59]
	v_mfma_f32_16x16x32_bf16 v[40:43], v[84:87], v[124:127], v[40:43]
	v_mfma_f32_16x16x32_bf16 v[20:23], v[84:87], v[132:135], v[20:23]
	v_mfma_f32_16x16x32_bf16 v[4:7], v[84:87], v[136:139], v[4:7]
	v_mfma_f32_16x16x32_bf16 v[52:55], v[88:91], v[120:123], v[52:55]
	v_mfma_f32_16x16x32_bf16 v[32:35], v[88:91], v[124:127], v[32:35]
	v_mfma_f32_16x16x32_bf16 v[16:19], v[88:91], v[132:135], v[16:19]
	v_mfma_f32_16x16x32_bf16 v[0:3], v[88:91], v[136:139], v[0:3]
	v_mfma_f32_16x16x32_bf16 v[48:51], v[92:95], v[120:123], v[48:51]
	v_mfma_f32_16x16x32_bf16 v[36:39], v[92:95], v[124:127], v[36:39]
	v_mfma_f32_16x16x32_bf16 v[24:27], v[92:95], v[132:135], v[24:27]
	v_mfma_f32_16x16x32_bf16 v[8:11], v[92:95], v[136:139], v[8:11]
	s_nop 7
	s_nop 1
	v_sub_co_u32_e32 v64, vcc, s37, v150
	s_nop 0
	v_readfirstlane_b32 s6, v64
	s_lshr_b32 s6, s6, 10
	s_add_i32 s6, s6, 1
	s_and_b64 s[40:41], vcc, exec
	s_cselect_b32 s6, 0, s6
	s_mul_hi_u32 s39, s6, 0x6000
	s_mulk_i32 s6, 0x6000
	v_or_b32_e32 v64, s38, v147
	s_add_u32 s40, s2, s6
	v_ashrrev_i32_e32 v65, 31, v64
	s_addc_u32 s41, s3, s39
	v_add_lshl_u32 v94, v148, s37, 12
	v_lshlrev_b64 v[66:67], 2, v[64:65]
	v_lshl_add_u64 v[102:103], s[40:41], 0, v[66:67]
	v_lshl_add_u64 v[134:135], s[4:5], 0, v[66:67]
	v_mov_b32_e32 v95, v97
	v_or_b32_e32 v66, 0x1000, v94
	v_mov_b32_e32 v67, v97
	v_lshl_add_u64 v[104:105], v[134:135], 0, v[94:95]
	global_load_dword v65, v[102:103], off
	global_load_dword v151, v[104:105], off
	v_lshl_add_u64 v[106:107], v[134:135], 0, v[66:67]
	v_or_b32_e32 v68, 0x2000, v94
	v_mov_b32_e32 v69, v97
	v_or_b32_e32 v70, 0x3000, v94
	v_mov_b32_e32 v71, v97
	v_or_b32_e32 v72, 0x10000, v94
	v_mov_b32_e32 v73, v97
	global_load_dword v152, v[106:107], off
	v_lshl_add_u64 v[108:109], v[134:135], 0, v[68:69]
	v_lshl_add_u64 v[110:111], v[134:135], 0, v[70:71]
	v_lshl_add_u64 v[112:113], v[134:135], 0, v[72:73]
	v_or_b32_e32 v74, 0x11000, v94
	v_mov_b32_e32 v75, v97
	global_load_dword v153, v[108:109], off
	global_load_dword v154, v[110:111], off
	global_load_dword v155, v[112:113], off
	v_lshl_add_u64 v[114:115], v[134:135], 0, v[74:75]
	v_or_b32_e32 v76, 0x12000, v94
	v_mov_b32_e32 v77, v97
	v_or_b32_e32 v78, 0x13000, v94
	v_mov_b32_e32 v79, v97
	v_or_b32_e32 v80, 0x20000, v94
	v_mov_b32_e32 v81, v97
	global_load_dword v156, v[114:115], off
	v_or_b32_e32 v96, 0x30000, v94
	v_lshl_add_u64 v[116:117], v[134:135], 0, v[76:77]
	v_lshl_add_u64 v[118:119], v[134:135], 0, v[78:79]
	v_lshl_add_u64 v[120:121], v[134:135], 0, v[80:81]
	v_or_b32_e32 v82, 0x21000, v94
	v_mov_b32_e32 v83, v97
	global_load_dword v157, v[116:117], off
	global_load_dword v158, v[118:119], off
	global_load_dword v159, v[120:121], off
	v_lshl_add_u64 v[122:123], v[134:135], 0, v[82:83]
	v_or_b32_e32 v84, 0x22000, v94
	v_mov_b32_e32 v85, v97
	v_or_b32_e32 v86, 0x23000, v94
	v_mov_b32_e32 v87, v97
	v_lshl_add_u64 v[128:129], v[134:135], 0, v[96:97]
	v_lshl_add_u64 v[124:125], v[134:135], 0, v[84:85]
	v_lshl_add_u64 v[126:127], v[134:135], 0, v[86:87]
	global_load_dword v160, v[122:123], off
	global_load_dword v161, v[124:125], off
	global_load_dword v164, v[126:127], off
	global_load_dword v165, v[128:129], off
	v_or_b32_e32 v88, 0x31000, v94
	v_mov_b32_e32 v89, v97
	v_lshl_add_u64 v[130:131], v[134:135], 0, v[88:89]
	v_or_b32_e32 v90, 0x32000, v94
	v_mov_b32_e32 v91, v97
	v_or_b32_e32 v92, 0x33000, v94
	v_mov_b32_e32 v93, v97
	v_lshl_add_u64 v[132:133], v[134:135], 0, v[90:91]
	v_lshl_add_u64 v[134:135], v[134:135], 0, v[92:93]
	global_load_dword v166, v[130:131], off
	global_load_dword v167, v[132:133], off
	global_load_dword v168, v[134:135], off
	v_or_b32_e32 v136, 16, v64
	v_ashrrev_i32_e32 v137, 31, v136
	v_lshlrev_b64 v[136:137], 2, v[136:137]
	v_lshl_add_u64 v[94:95], s[4:5], 0, v[94:95]
	global_load_dword v169, v[102:103], off offset:64
	v_lshl_add_u64 v[140:141], s[4:5], 0, v[136:137]
	v_lshl_add_u64 v[136:137], v[94:95], 0, v[136:137]
	v_add_f32_e32 v60, 0, v60
	v_lshl_add_u64 v[138:139], v[140:141], 0, v[66:67]
	global_load_dword v170, v[136:137], off
	global_load_dword v171, v[138:139], off
	global_load_dword v172, v[102:103], off offset:128
	global_load_dword v173, v[102:103], off offset:192
	v_lshl_add_u64 v[102:103], v[140:141], 0, v[68:69]
	global_load_dword v174, v[102:103], off
	v_add_f32_e32 v56, 0, v56
	v_add_f32_e32 v58, 0, v58
	v_add_f32_e32 v52, 0, v52
	v_add_f32_e32 v48, 0, v48
	v_add_f32_e32 v44, 0, v44
	v_add_f32_e32 v50, 0, v50
	v_add_f32_e32 v32, 0, v32
	v_add_f32_e32 v34, 0, v34
	v_add_f32_e32 v40, 0, v40
	v_add_f32_e32 v38, 0, v38
	v_add_f32_e32 v36, 0, v36
	v_add_f32_e32 v28, 0, v28
	v_add_f32_e32 v30, 0, v30
	v_add_f32_e32 v20, 0, v20
	s_waitcnt vmcnt(21)
	v_fmac_f32_e32 v151, v60, v65
	v_add_f32_e32 v60, 0, v61
	global_store_dword v[104:105], v151, off
	v_lshl_add_u64 v[104:105], v[140:141], 0, v[72:73]
	v_add_f32_e32 v16, 0, v16
	v_add_f32_e32 v0, 0, v0
	v_add_f32_e32 v12, 0, v12
	v_add_f32_e32 v4, 0, v4
	s_waitcnt vmcnt(21)
	v_fmac_f32_e32 v152, v60, v65
	v_add_f32_e32 v60, 0, v62
	v_add_f32_e32 v62, 0, v63
	global_store_dword v[106:107], v152, off
	v_lshl_add_u64 v[106:107], v[140:141], 0, v[76:77]
	global_load_dword v152, v[104:105], off
	s_waitcnt vmcnt(22)
	v_fmac_f32_e32 v153, v60, v65
	global_store_dword v[108:109], v153, off
	s_waitcnt vmcnt(21)
	v_fmac_f32_e32 v155, v56, v65
	v_add_f32_e32 v56, 0, v57
	v_lshl_add_u64 v[108:109], v[140:141], 0, v[80:81]
	v_lshl_add_u64 v[60:61], v[140:141], 0, v[70:71]
	global_store_dword v[112:113], v155, off
	v_add_f32_e32 v112, 0, v59
	v_fmac_f32_e32 v154, v62, v65
	global_store_dword v[110:111], v154, off
	s_waitcnt vmcnt(22)
	v_fmac_f32_e32 v156, v56, v65
	global_store_dword v[114:115], v156, off
	global_load_dword v156, v[108:109], off
	v_lshl_add_u64 v[62:63], v[140:141], 0, v[74:75]
	global_load_dword v151, v[60:61], off
	global_load_dword v154, v[106:107], off
	v_lshl_add_u64 v[110:111], v[140:141], 0, v[82:83]
	s_waitcnt vmcnt(25)
	v_fmac_f32_e32 v157, v58, v65
	v_lshl_add_u64 v[58:59], v[140:141], 0, v[84:85]
	s_waitcnt vmcnt(23)
	v_fmac_f32_e32 v159, v52, v65
	v_add_f32_e32 v52, 0, v53
	global_store_dword v[116:117], v157, off
	global_load_dword v157, v[58:59], off
	v_fmac_f32_e32 v158, v112, v65
	v_lshl_add_u64 v[112:113], v[140:141], 0, v[86:87]
	global_load_dword v176, v[112:113], off
	s_waitcnt vmcnt(25)
	v_fmac_f32_e32 v160, v52, v65
	v_add_f32_e32 v52, 0, v54
	s_waitcnt vmcnt(24)
	v_fmac_f32_e32 v161, v52, v65
	s_waitcnt vmcnt(22)
	v_fmac_f32_e32 v165, v48, v65
	v_add_f32_e32 v48, 0, v49
	v_lshl_add_u64 v[52:53], v[140:141], 0, v[90:91]
	v_lshl_add_u64 v[114:115], v[140:141], 0, v[96:97]
	global_store_dword v[120:121], v159, off
	global_load_dword v120, v[52:53], off
	v_lshl_add_u64 v[56:57], v[140:141], 0, v[78:79]
	global_load_dword v175, v[110:111], off
	global_load_dword v155, v[56:57], off
	s_waitcnt vmcnt(25)
	v_fmac_f32_e32 v166, v48, v65
	v_lshl_add_u64 v[48:49], v[140:141], 0, v[92:93]
	global_load_dword v121, v[48:49], off
	s_waitcnt vmcnt(25)
	v_fmac_f32_e32 v167, v50, v65
	global_store_dword v[118:119], v158, off
	global_load_dword v118, v[114:115], off
	v_add_f32_e32 v50, 0, v51
	global_load_dword v153, v[62:63], off
	s_waitcnt vmcnt(25)
	v_fmac_f32_e32 v170, v44, v169
	v_add_f32_e32 v44, 0, v45
	s_waitcnt vmcnt(24)
	v_fmac_f32_e32 v171, v44, v169
	v_add_f32_e32 v44, 0, v46
	v_add_f32_e32 v54, 0, v55
	s_waitcnt vmcnt(21)
	v_fmac_f32_e32 v174, v44, v169
	v_or_b32_e32 v44, 32, v64
	v_ashrrev_i32_e32 v45, 31, v44
	v_lshlrev_b64 v[44:45], 2, v[44:45]
	v_fmac_f32_e32 v168, v50, v65
	v_lshl_add_u64 v[50:51], v[94:95], 0, v[44:45]
	v_lshl_add_u64 v[44:45], s[4:5], 0, v[44:45]
	v_fmac_f32_e32 v164, v54, v65
	v_lshl_add_u64 v[54:55], v[44:45], 0, v[78:79]
	v_add_f32_e32 v46, 0, v47
	v_lshl_add_u64 v[116:117], v[140:141], 0, v[88:89]
	global_load_dword v119, v[116:117], off
	v_or_b32_e32 v64, 48, v64
	global_store_dword v[102:103], v174, off
	v_ashrrev_i32_e32 v65, 31, v64
	v_lshlrev_b64 v[64:65], 2, v[64:65]
	global_store_dword v[122:123], v160, off
	global_store_dword v[124:125], v161, off
	global_store_dword v[126:127], v164, off
	global_store_dword v[128:129], v165, off
	global_store_dword v[130:131], v166, off
	global_store_dword v[132:133], v167, off
	global_store_dword v[134:135], v168, off
	global_store_dword v[136:137], v170, off
	global_store_dword v[138:139], v171, off
	v_lshl_add_u64 v[94:95], v[94:95], 0, v[64:65]
	v_lshl_add_u64 v[64:65], s[4:5], 0, v[64:65]
	v_add_f32_e32 v21, 0, v21
	s_waitcnt vmcnt(29)
	v_fmac_f32_e32 v152, v40, v169
	v_add_f32_e32 v40, 0, v41
	global_store_dword v[104:105], v152, off
	s_add_i32 s36, s36, s30
	s_cmpk_gt_i32 s36, 0x1ff
	s_waitcnt vmcnt(25)
	v_fmac_f32_e32 v156, v32, v169
	global_store_dword v[108:109], v156, off
	global_load_dword v109, v[54:55], off
	s_waitcnt vmcnt(26)
	v_fmac_f32_e32 v151, v46, v169
	v_lshl_add_u64 v[46:47], v[44:45], 0, v[66:67]
	global_load_dword v102, v[50:51], off
	global_load_dword v103, v[46:47], off
	v_add_f32_e32 v32, 0, v33
	global_store_dword v[60:61], v151, off
	v_lshl_add_u64 v[60:61], v[44:45], 0, v[88:89]
	s_waitcnt vmcnt(26)
	v_fmac_f32_e32 v157, v34, v169
	global_store_dword v[58:59], v157, off
	v_add_f32_e32 v34, 0, v35
	v_add_f32_e32 v58, 0, v39
	s_waitcnt vmcnt(26)
	v_fmac_f32_e32 v176, v34, v169
	global_store_dword v[112:113], v176, off
	v_lshl_add_u64 v[34:35], v[44:45], 0, v[72:73]
	v_lshl_add_u64 v[66:67], v[64:65], 0, v[66:67]
	s_waitcnt vmcnt(25)
	v_fmac_f32_e32 v120, v38, v169
	global_store_dword v[52:53], v120, off
	s_waitcnt vmcnt(25)
	v_fmac_f32_e32 v175, v32, v169
	v_lshl_add_u64 v[52:53], v[44:45], 0, v[82:83]
	global_store_dword v[110:111], v175, off
	v_lshl_add_u64 v[32:33], v[44:45], 0, v[70:71]
	s_waitcnt vmcnt(24)
	v_fmac_f32_e32 v121, v58, v169
	v_lshl_add_u64 v[58:59], v[44:45], 0, v[86:87]
	global_load_dword v113, v[58:59], off
	global_load_dword v111, v[52:53], off
	s_waitcnt vmcnt(24)
	v_fmac_f32_e32 v118, v36, v169
	s_waitcnt vmcnt(23)
	v_fmac_f32_e32 v153, v40, v169
	v_add_f32_e32 v40, 0, v42
	v_add_f32_e32 v42, 0, v43
	v_fmac_f32_e32 v155, v42, v169
	global_store_dword v[56:57], v155, off
	v_lshl_add_u64 v[56:57], v[44:45], 0, v[80:81]
	global_store_dword v[114:115], v118, off
	global_load_dword v110, v[56:57], off
	global_load_dword v105, v[32:33], off
	v_add_f32_e32 v36, 0, v37
	global_load_dword v115, v[60:61], off
	v_fmac_f32_e32 v154, v40, v169
	v_lshl_add_u64 v[40:41], v[44:45], 0, v[68:69]
	global_load_dword v104, v[40:41], off
	v_lshl_add_u64 v[42:43], v[44:45], 0, v[76:77]
	global_store_dword v[106:107], v154, off
	global_load_dword v106, v[34:35], off
	s_waitcnt vmcnt(30)
	v_fmac_f32_e32 v119, v36, v169
	global_store_dword v[48:49], v121, off
	v_lshl_add_u64 v[48:49], v[44:45], 0, v[96:97]
	global_store_dword v[62:63], v153, off
	v_lshl_add_u64 v[36:37], v[44:45], 0, v[74:75]
	global_store_dword v[116:117], v119, off
	v_lshl_add_u64 v[38:39], v[44:45], 0, v[84:85]
	global_load_dword v114, v[48:49], off
	v_lshl_add_u64 v[62:63], v[44:45], 0, v[90:91]
	global_load_dword v107, v[36:37], off
	global_load_dword v108, v[42:43], off
	global_load_dword v112, v[38:39], off
	v_lshl_add_u64 v[44:45], v[44:45], 0, v[92:93]
	global_load_dword v116, v[62:63], off
	global_load_dword v117, v[44:45], off
	v_lshl_add_u64 v[68:69], v[64:65], 0, v[68:69]
	global_load_dword v120, v[68:69], off
	global_load_dword v118, v[94:95], off
	global_load_dword v119, v[66:67], off
	s_waitcnt vmcnt(28)
	v_fmac_f32_e32 v102, v28, v172
	global_store_dword v[50:51], v102, off
	v_lshl_add_u64 v[50:51], v[64:65], 0, v[70:71]
	v_add_f32_e32 v70, 0, v29
	v_lshl_add_u64 v[28:29], v[64:65], 0, v[72:73]
	s_waitcnt vmcnt(28)
	v_fmac_f32_e32 v103, v70, v172
	v_lshl_add_u64 v[70:71], v[64:65], 0, v[74:75]
	v_lshl_add_u64 v[72:73], v[64:65], 0, v[78:79]
	v_lshl_add_u64 v[74:75], v[64:65], 0, v[80:81]
	global_load_dword v122, v[70:71], off
	global_load_dword v123, v[72:73], off
	global_load_dword v124, v[74:75], off
	global_load_dword v102, v[50:51], off
	global_load_dword v121, v[28:29], off
	v_lshl_add_u64 v[78:79], v[64:65], 0, v[88:89]
	global_store_dword v[46:47], v103, off
	v_lshl_add_u64 v[46:47], v[64:65], 0, v[76:77]
	global_load_dword v103, v[46:47], off
	v_add_f32_e32 v76, 0, v31
	v_lshl_add_u64 v[80:81], v[64:65], 0, v[90:91]
	s_waitcnt vmcnt(25)
	v_fmac_f32_e32 v110, v16, v172
	s_waitcnt vmcnt(24)
	v_fmac_f32_e32 v105, v76, v172
	v_lshl_add_u64 v[76:77], v[64:65], 0, v[86:87]
	global_store_dword v[32:33], v105, off
	v_lshl_add_u64 v[32:33], v[64:65], 0, v[96:97]
	global_load_dword v86, v[78:79], off
	s_waitcnt vmcnt(24)
	v_fmac_f32_e32 v104, v30, v172
	global_store_dword v[40:41], v104, off
	v_lshl_add_u64 v[40:41], v[64:65], 0, v[82:83]
	global_load_dword v82, v[40:41], off
	v_lshl_add_u64 v[30:31], v[64:65], 0, v[84:85]
	global_load_dword v83, v[30:31], off
	global_load_dword v85, v[32:33], off
	global_load_dword v84, v[76:77], off
	s_waitcnt vmcnt(27)
	v_fmac_f32_e32 v106, v20, v172
	global_load_dword v20, v[80:81], off
	v_add_f32_e32 v16, 0, v17
	global_store_dword v[34:35], v106, off
	v_lshl_add_u64 v[34:35], v[64:65], 0, v[92:93]
	global_load_dword v64, v[34:35], off
	v_fmac_f32_e32 v111, v16, v172
	v_add_f32_e32 v16, 0, v18
	s_waitcnt vmcnt(23)
	v_fmac_f32_e32 v112, v16, v172
	v_add_f32_e32 v16, 0, v19
	v_fmac_f32_e32 v113, v16, v172
	v_add_f32_e32 v16, 0, v24
	v_fmac_f32_e32 v114, v16, v172
	v_add_f32_e32 v16, 0, v25
	s_waitcnt vmcnt(19)
	v_fmac_f32_e32 v118, v12, v173
	v_add_f32_e32 v12, 0, v13
	v_fmac_f32_e32 v107, v21, v172
	v_add_f32_e32 v21, 0, v22
	v_fmac_f32_e32 v115, v16, v172
	v_add_f32_e32 v16, 0, v26
	s_waitcnt vmcnt(18)
	v_fmac_f32_e32 v119, v12, v173
	v_add_f32_e32 v12, 0, v14
	v_fmac_f32_e32 v108, v21, v172
	v_add_f32_e32 v21, 0, v23
	v_fmac_f32_e32 v116, v16, v172
	v_add_f32_e32 v16, 0, v27
	v_fmac_f32_e32 v120, v12, v173
	v_add_f32_e32 v12, 0, v15
	v_fmac_f32_e32 v109, v21, v172
	v_fmac_f32_e32 v117, v16, v172
	global_store_dword v[36:37], v107, off
	global_store_dword v[42:43], v108, off
	global_store_dword v[54:55], v109, off
	global_store_dword v[56:57], v110, off
	global_store_dword v[52:53], v111, off
	global_store_dword v[38:39], v112, off
	global_store_dword v[58:59], v113, off
	global_store_dword v[48:49], v114, off
	global_store_dword v[60:61], v115, off
	global_store_dword v[62:63], v116, off
	global_store_dword v[44:45], v117, off
	global_store_dword v[94:95], v118, off
	s_waitcnt vmcnt(26)
	v_fmac_f32_e32 v124, v0, v173
	v_add_f32_e32 v0, 0, v1
	s_waitcnt vmcnt(24)
	v_fmac_f32_e32 v121, v4, v173
	v_add_f32_e32 v4, 0, v5
	v_fmac_f32_e32 v122, v4, v173
	v_add_f32_e32 v4, 0, v6
	s_waitcnt vmcnt(22)
	v_fmac_f32_e32 v103, v4, v173
	v_add_f32_e32 v4, 0, v7
	v_fmac_f32_e32 v102, v12, v173
	v_fmac_f32_e32 v123, v4, v173
	global_store_dword v[66:67], v119, off
	global_store_dword v[68:69], v120, off
	global_store_dword v[50:51], v102, off
	global_store_dword v[28:29], v121, off
	global_store_dword v[70:71], v122, off
	global_store_dword v[46:47], v103, off
	global_store_dword v[72:73], v123, off
	global_store_dword v[74:75], v124, off
	s_waitcnt vmcnt(26)
	v_fmac_f32_e32 v82, v0, v173
	v_add_f32_e32 v0, 0, v2
	s_waitcnt vmcnt(25)
	v_fmac_f32_e32 v83, v0, v173
	v_add_f32_e32 v0, 0, v3
	s_waitcnt vmcnt(23)
	v_fmac_f32_e32 v84, v0, v173
	v_add_f32_e32 v0, 0, v8
	v_fmac_f32_e32 v85, v0, v173
	v_add_f32_e32 v0, 0, v9
	v_fmac_f32_e32 v86, v0, v173
	v_add_f32_e32 v0, 0, v10
	s_waitcnt vmcnt(22)
	v_fmac_f32_e32 v20, v0, v173
	v_add_f32_e32 v0, 0, v11
	s_waitcnt vmcnt(20)
	v_fmac_f32_e32 v64, v0, v173
	global_store_dword v[40:41], v82, off
	global_store_dword v[30:31], v83, off
	global_store_dword v[76:77], v84, off
	global_store_dword v[32:33], v85, off
	global_store_dword v[78:79], v86, off
	global_store_dword v[80:81], v20, off
	global_store_dword v[34:35], v64, off
	s_cbranch_scc0 .LBB0_2477

.LBB0_2723:
	s_lshl_b32 s4, s42, 7
	s_and_b32 s43, s4, 0x1f80
	s_lshl_b32 s12, s43, 11
	v_lshl_add_u64 v[102:103], v[98:99], 0, s[12:13]
	v_add_co_u32_e32 v40, vcc, 0x10000, v102
	s_lshl_b32 s4, s42, 1
	s_nop 0
	v_addc_co_u32_e32 v41, vcc, 0, v103, vcc
	s_and_b32 s4, s4, 0xffffff80
	v_add_co_u32_e32 v42, vcc, 0x20000, v102
	s_ashr_i32 s5, s4, 31
	s_nop 0
	v_addc_co_u32_e32 v43, vcc, 0, v103, vcc
	s_lshl_b64 s[44:45], s[4:5], 11
	v_add_co_u32_e32 v46, vcc, 0x30000, v102
	v_lshl_add_u64 v[104:105], v[100:101], 0, s[44:45]
	s_nop 0
	v_addc_co_u32_e32 v47, vcc, 0, v103, vcc
	v_add_co_u32_e32 v48, vcc, s39, v104
	s_nop 0
	v_addc_co_u32_e32 v49, vcc, 0, v105, vcc
	v_add_co_u32_e32 v50, vcc, s40, v104
	v_addc_co_u32_e32 v51, vcc, 0, v105, vcc
	v_add_co_u32_e32 v52, vcc, s41, v104
	v_addc_co_u32_e32 v53, vcc, 0, v105, vcc
	s_mov_b32 s5, -2
	v_mov_b32_e32 v12, v97
	v_mov_b32_e32 v13, v97
	v_mov_b32_e32 v14, v97
	v_mov_b32_e32 v15, v97
	v_mov_b32_e32 v28, v97
	v_mov_b32_e32 v29, v97
	v_mov_b32_e32 v30, v97
	v_mov_b32_e32 v31, v97
	v_mov_b32_e32 v44, v97
	v_mov_b32_e32 v45, v97
	v_mov_b32_e32 v46, v97
	v_lshl_add_u64 v[106:107], v[102:103], 0, s[14:15]
	v_lshl_add_u64 v[108:109], v[102:103], 0, s[16:17]
	v_lshl_add_u64 v[110:111], v[102:103], 0, s[18:19]
	v_lshl_add_u64 v[118:119], v[102:103], 0, s[20:21]
	v_lshl_add_u64 v[120:121], v[102:103], 0, s[22:23]
	v_lshl_add_u64 v[122:123], v[102:103], 0, s[24:25]
	v_lshl_add_u64 v[124:125], v[102:103], 0, s[26:27]
	v_lshl_add_u64 v[112:113], v[104:105], 0, s[14:15]
	v_lshl_add_u64 v[114:115], v[104:105], 0, s[16:17]
	v_lshl_add_u64 v[116:117], v[104:105], 0, s[18:19]
	v_lshl_add_u64 v[128:129], v[104:105], 0, s[20:21]
	v_lshl_add_u64 v[130:131], v[104:105], 0, s[22:23]
	v_lshl_add_u64 v[132:133], v[104:105], 0, s[24:25]
	v_lshl_add_u64 v[126:127], v[104:105], 0, s[26:27]
	v_mov_b32_e32 v47, v97
	v_mov_b32_e32 v52, v97
	v_mov_b32_e32 v53, v97
	v_mov_b32_e32 v54, v97
	v_mov_b32_e32 v55, v97
	v_mov_b32_e32 v48, v97
	v_mov_b32_e32 v49, v97
	v_mov_b32_e32 v50, v97
	v_mov_b32_e32 v51, v97
	v_mov_b32_e32 v56, v97
	v_mov_b32_e32 v57, v97
	v_mov_b32_e32 v58, v97
	v_mov_b32_e32 v59, v97
	v_mov_b32_e32 v40, v97
	v_mov_b32_e32 v41, v97
	v_mov_b32_e32 v42, v97
	v_mov_b32_e32 v43, v97
	v_mov_b32_e32 v60, v97
	v_mov_b32_e32 v61, v97
	v_mov_b32_e32 v62, v97
	v_mov_b32_e32 v63, v97
	v_mov_b32_e32 v4, v97
	v_mov_b32_e32 v5, v97
	v_mov_b32_e32 v6, v97
	v_mov_b32_e32 v7, v97
	v_mov_b32_e32 v16, v97
	v_mov_b32_e32 v17, v97
	v_mov_b32_e32 v18, v97
	v_mov_b32_e32 v19, v97
	v_mov_b32_e32 v32, v97
	v_mov_b32_e32 v33, v97
	v_mov_b32_e32 v34, v97
	v_mov_b32_e32 v35, v97
	v_mov_b32_e32 v0, v97
	v_mov_b32_e32 v1, v97
	v_mov_b32_e32 v2, v97
	v_mov_b32_e32 v3, v97
	v_mov_b32_e32 v20, v97
	v_mov_b32_e32 v21, v97
	v_mov_b32_e32 v22, v97
	v_mov_b32_e32 v23, v97
	v_mov_b32_e32 v36, v97
	v_mov_b32_e32 v37, v97
	v_mov_b32_e32 v38, v97
	v_mov_b32_e32 v39, v97
	v_mov_b32_e32 v8, v97
	v_mov_b32_e32 v9, v97
	v_mov_b32_e32 v10, v97
	v_mov_b32_e32 v11, v97
	v_mov_b32_e32 v24, v97
	v_mov_b32_e32 v25, v97
	v_mov_b32_e32 v26, v97
	v_mov_b32_e32 v27, v97
	v_readfirstlane_b32 s44, v102
	v_readfirstlane_b32 s45, v103
	v_readfirstlane_b32 s48, v104
	v_readfirstlane_b32 s49, v105
	v_readfirstlane_b32 s5, v247
	s_nop 3
	s_mul_i32 s32, s5, 0x4000
	s_sub_u32 s44, s44, s32
	s_subb_u32 s45, s45, 0
	s_sub_u32 s48, s48, s32
	s_subb_u32 s49, s49, 0
	s_lshl_b32 s5, s5, 12
	s_add_u32 m0, s5, 0x0
	v_mov_b32_e32 v60, 0
	global_load_lds_dwordx4 v248, s[44:45]
	v_mov_b32_e32 v61, 0
	s_add_u32 m0, s5, 0x400
	v_mov_b32_e32 v62, 0
	global_load_lds_dwordx4 v249, s[44:45]
	v_mov_b32_e32 v63, 0
	s_add_u32 m0, s5, 0x800
	v_mov_b32_e32 v40, 0
	global_load_lds_dwordx4 v250, s[44:45]
	v_mov_b32_e32 v41, 0
	s_add_u32 m0, s5, 0xc00
	v_mov_b32_e32 v42, 0
	global_load_lds_dwordx4 v251, s[44:45]
	v_mov_b32_e32 v43, 0
	s_add_u32 m0, s5, 0x8000
	v_mov_b32_e32 v24, 0
	global_load_lds_dwordx4 v248, s[48:49]
	v_mov_b32_e32 v25, 0
	s_add_u32 m0, s5, 0x8400
	v_mov_b32_e32 v26, 0
	global_load_lds_dwordx4 v249, s[48:49]
	v_mov_b32_e32 v27, 0
	s_add_u32 m0, s5, 0x8800
	v_mov_b32_e32 v8, 0
	global_load_lds_dwordx4 v250, s[48:49]
	v_mov_b32_e32 v9, 0
	s_add_u32 m0, s5, 0x8c00
	v_mov_b32_e32 v10, 0
	global_load_lds_dwordx4 v251, s[48:49]
	v_mov_b32_e32 v11, 0
	s_add_u32 s44, s44, 0x80
	s_addc_u32 s45, s45, 0
	s_add_u32 s48, s48, 0x80
	s_addc_u32 s49, s49, 0
	s_add_u32 m0, s5, 0x4000
	v_mov_b32_e32 v56, 0
	global_load_lds_dwordx4 v248, s[44:45]
	v_mov_b32_e32 v57, 0
	s_add_u32 m0, s5, 0x4400
	v_mov_b32_e32 v58, 0
	global_load_lds_dwordx4 v249, s[44:45]
	v_mov_b32_e32 v59, 0
	s_add_u32 m0, s5, 0x4800
	v_mov_b32_e32 v36, 0
	global_load_lds_dwordx4 v250, s[44:45]
	v_mov_b32_e32 v37, 0
	s_add_u32 m0, s5, 0x4c00
	v_mov_b32_e32 v38, 0
	global_load_lds_dwordx4 v251, s[44:45]
	v_mov_b32_e32 v39, 0
	s_add_u32 m0, s5, 0xc000
	v_mov_b32_e32 v20, 0
	global_load_lds_dwordx4 v248, s[48:49]
	v_mov_b32_e32 v21, 0
	s_add_u32 m0, s5, 0xc400
	v_mov_b32_e32 v22, 0
	global_load_lds_dwordx4 v249, s[48:49]
	v_mov_b32_e32 v23, 0
	s_add_u32 m0, s5, 0xc800
	v_mov_b32_e32 v0, 0
	global_load_lds_dwordx4 v250, s[48:49]
	v_mov_b32_e32 v1, 0
	s_add_u32 m0, s5, 0xcc00
	v_mov_b32_e32 v2, 0
	global_load_lds_dwordx4 v251, s[48:49]
	v_mov_b32_e32 v3, 0
	s_add_u32 s44, s44, 0x80
	s_addc_u32 s45, s45, 0
	s_add_u32 s48, s48, 0x80
	s_addc_u32 s49, s49, 0
	v_mov_b32_e32 v48, 0
	v_mov_b32_e32 v49, 0
	v_mov_b32_e32 v50, 0
	v_mov_b32_e32 v51, 0
	v_mov_b32_e32 v32, 0
	v_mov_b32_e32 v33, 0
	v_mov_b32_e32 v34, 0
	v_mov_b32_e32 v35, 0
	v_mov_b32_e32 v16, 0
	v_mov_b32_e32 v17, 0
	v_mov_b32_e32 v18, 0
	v_mov_b32_e32 v19, 0
	v_mov_b32_e32 v4, 0
	v_mov_b32_e32 v5, 0
	v_mov_b32_e32 v6, 0
	v_mov_b32_e32 v7, 0
	v_mov_b32_e32 v52, 0
	v_mov_b32_e32 v53, 0
	v_mov_b32_e32 v54, 0
	v_mov_b32_e32 v55, 0
	v_mov_b32_e32 v44, 0
	v_mov_b32_e32 v45, 0
	v_mov_b32_e32 v46, 0
	v_mov_b32_e32 v47, 0
	v_mov_b32_e32 v28, 0
	v_mov_b32_e32 v29, 0
	v_mov_b32_e32 v30, 0
	v_mov_b32_e32 v31, 0
	v_mov_b32_e32 v12, 0
	v_mov_b32_e32 v13, 0
	v_mov_b32_e32 v14, 0
	v_mov_b32_e32 v15, 0
	s_waitcnt vmcnt(8)
	s_barrier
	ds_read_b128 v[64:67], v252 offset:0
	ds_read_b128 v[104:107], v254 offset:32768
	ds_read_b128 v[108:111], v254 offset:34816
	ds_read_b128 v[112:115], v254 offset:36864
	ds_read_b128 v[116:119], v254 offset:38912
	ds_read_b128 v[68:71], v252 offset:2048
	ds_read_b128 v[72:75], v252 offset:4096
	ds_read_b128 v[76:79], v252 offset:6144
	ds_read_b128 v[80:83], v253 offset:0
	ds_read_b128 v[120:123], v255 offset:32768
	ds_read_b128 v[124:127], v255 offset:34816
	ds_read_b128 v[132:135], v255 offset:36864
	ds_read_b128 v[144:147], v255 offset:38912
	s_waitcnt lgkmcnt(11)
	v_mfma_f32_16x16x32_bf16 v[60:63], v[64:67], v[104:107], v[60:63]
	s_waitcnt lgkmcnt(10)
	v_mfma_f32_16x16x32_bf16 v[40:43], v[64:67], v[108:111], v[40:43]
	s_waitcnt lgkmcnt(9)
	v_mfma_f32_16x16x32_bf16 v[24:27], v[64:67], v[112:115], v[24:27]
	s_waitcnt lgkmcnt(8)
	v_mfma_f32_16x16x32_bf16 v[8:11], v[64:67], v[116:119], v[8:11]
	ds_read_b128 v[84:87], v253 offset:2048
	ds_read_b128 v[88:91], v253 offset:4096
	ds_read_b128 v[92:95], v253 offset:6144
	s_waitcnt lgkmcnt(10)
	v_mfma_f32_16x16x32_bf16 v[56:59], v[68:71], v[104:107], v[56:59]
	v_mfma_f32_16x16x32_bf16 v[36:39], v[68:71], v[108:111], v[36:39]
	v_mfma_f32_16x16x32_bf16 v[20:23], v[68:71], v[112:115], v[20:23]
	v_mfma_f32_16x16x32_bf16 v[0:3], v[68:71], v[116:119], v[0:3]
	s_waitcnt lgkmcnt(0)
	s_barrier
	s_add_u32 m0, s5, 0x0
	v_mfma_f32_16x16x32_bf16 v[48:51], v[72:75], v[104:107], v[48:51]
	global_load_lds_dwordx4 v248, s[44:45]
	s_add_u32 m0, s5, 0x400
	v_mfma_f32_16x16x32_bf16 v[32:35], v[72:75], v[108:111], v[32:35]
	global_load_lds_dwordx4 v249, s[44:45]
	s_add_u32 m0, s5, 0x800
	v_mfma_f32_16x16x32_bf16 v[16:19], v[72:75], v[112:115], v[16:19]
	global_load_lds_dwordx4 v250, s[44:45]
	s_add_u32 m0, s5, 0xc00
	v_mfma_f32_16x16x32_bf16 v[4:7], v[72:75], v[116:119], v[4:7]
	global_load_lds_dwordx4 v251, s[44:45]
	s_add_u32 m0, s5, 0x8000
	v_mfma_f32_16x16x32_bf16 v[52:55], v[76:79], v[104:107], v[52:55]
	global_load_lds_dwordx4 v248, s[48:49]
	s_add_u32 m0, s5, 0x8400
	v_mfma_f32_16x16x32_bf16 v[44:47], v[76:79], v[108:111], v[44:47]
	global_load_lds_dwordx4 v249, s[48:49]
	s_add_u32 m0, s5, 0x8800
	v_mfma_f32_16x16x32_bf16 v[28:31], v[76:79], v[112:115], v[28:31]
	global_load_lds_dwordx4 v250, s[48:49]
	s_add_u32 m0, s5, 0x8c00
	v_mfma_f32_16x16x32_bf16 v[12:15], v[76:79], v[116:119], v[12:15]
	global_load_lds_dwordx4 v251, s[48:49]
	s_add_u32 s44, s44, 0x80
	s_addc_u32 s45, s45, 0
	s_add_u32 s48, s48, 0x80
	s_addc_u32 s49, s49, 0
	s_waitcnt vmcnt(8)
	s_barrier
	ds_read_b128 v[64:67], v252 offset:16384
	ds_read_b128 v[104:107], v254 offset:49152
	ds_read_b128 v[108:111], v254 offset:51200
	ds_read_b128 v[112:115], v254 offset:53248
	ds_read_b128 v[116:119], v254 offset:55296
	ds_read_b128 v[68:71], v252 offset:18432
	ds_read_b128 v[72:75], v252 offset:20480
	ds_read_b128 v[76:79], v252 offset:22528
	v_mfma_f32_16x16x32_bf16 v[60:63], v[80:83], v[120:123], v[60:63]
	v_mfma_f32_16x16x32_bf16 v[40:43], v[80:83], v[124:127], v[40:43]
	v_mfma_f32_16x16x32_bf16 v[24:27], v[80:83], v[132:135], v[24:27]
	v_mfma_f32_16x16x32_bf16 v[8:11], v[80:83], v[144:147], v[8:11]
	v_mfma_f32_16x16x32_bf16 v[56:59], v[84:87], v[120:123], v[56:59]
	v_mfma_f32_16x16x32_bf16 v[36:39], v[84:87], v[124:127], v[36:39]
	v_mfma_f32_16x16x32_bf16 v[20:23], v[84:87], v[132:135], v[20:23]
	v_mfma_f32_16x16x32_bf16 v[0:3], v[84:87], v[144:147], v[0:3]
	v_mfma_f32_16x16x32_bf16 v[48:51], v[88:91], v[120:123], v[48:51]
	v_mfma_f32_16x16x32_bf16 v[32:35], v[88:91], v[124:127], v[32:35]
	v_mfma_f32_16x16x32_bf16 v[16:19], v[88:91], v[132:135], v[16:19]
	v_mfma_f32_16x16x32_bf16 v[4:7], v[88:91], v[144:147], v[4:7]
	v_mfma_f32_16x16x32_bf16 v[52:55], v[92:95], v[120:123], v[52:55]
	v_mfma_f32_16x16x32_bf16 v[44:47], v[92:95], v[124:127], v[44:47]
	v_mfma_f32_16x16x32_bf16 v[28:31], v[92:95], v[132:135], v[28:31]
	v_mfma_f32_16x16x32_bf16 v[12:15], v[92:95], v[144:147], v[12:15]
	ds_read_b128 v[80:83], v253 offset:16384
	ds_read_b128 v[120:123], v255 offset:49152
	ds_read_b128 v[124:127], v255 offset:51200
	ds_read_b128 v[132:135], v255 offset:53248
	ds_read_b128 v[144:147], v255 offset:55296
	ds_read_b128 v[84:87], v253 offset:18432
	ds_read_b128 v[88:91], v253 offset:20480
	ds_read_b128 v[92:95], v253 offset:22528
	s_waitcnt lgkmcnt(14)
	v_mfma_f32_16x16x32_bf16 v[60:63], v[64:67], v[104:107], v[60:63]
	s_waitcnt lgkmcnt(13)
	v_mfma_f32_16x16x32_bf16 v[40:43], v[64:67], v[108:111], v[40:43]
	s_waitcnt lgkmcnt(12)
	v_mfma_f32_16x16x32_bf16 v[24:27], v[64:67], v[112:115], v[24:27]
	s_waitcnt lgkmcnt(11)
	v_mfma_f32_16x16x32_bf16 v[8:11], v[64:67], v[116:119], v[8:11]
	s_waitcnt lgkmcnt(10)
	v_mfma_f32_16x16x32_bf16 v[56:59], v[68:71], v[104:107], v[56:59]
	v_mfma_f32_16x16x32_bf16 v[36:39], v[68:71], v[108:111], v[36:39]
	v_mfma_f32_16x16x32_bf16 v[20:23], v[68:71], v[112:115], v[20:23]
	v_mfma_f32_16x16x32_bf16 v[0:3], v[68:71], v[116:119], v[0:3]
	s_waitcnt lgkmcnt(0)
	s_barrier
	s_add_u32 m0, s5, 0x4000
	v_mfma_f32_16x16x32_bf16 v[48:51], v[72:75], v[104:107], v[48:51]
	global_load_lds_dwordx4 v248, s[44:45]
	s_add_u32 m0, s5, 0x4400
	v_mfma_f32_16x16x32_bf16 v[32:35], v[72:75], v[108:111], v[32:35]
	global_load_lds_dwordx4 v249, s[44:45]
	s_add_u32 m0, s5, 0x4800
	v_mfma_f32_16x16x32_bf16 v[16:19], v[72:75], v[112:115], v[16:19]
	global_load_lds_dwordx4 v250, s[44:45]
	s_add_u32 m0, s5, 0x4c00
	v_mfma_f32_16x16x32_bf16 v[4:7], v[72:75], v[116:119], v[4:7]
	global_load_lds_dwordx4 v251, s[44:45]
	s_add_u32 m0, s5, 0xc000
	v_mfma_f32_16x16x32_bf16 v[52:55], v[76:79], v[104:107], v[52:55]
	global_load_lds_dwordx4 v248, s[48:49]
	s_add_u32 m0, s5, 0xc400
	v_mfma_f32_16x16x32_bf16 v[44:47], v[76:79], v[108:111], v[44:47]
	global_load_lds_dwordx4 v249, s[48:49]
	s_add_u32 m0, s5, 0xc800
	v_mfma_f32_16x16x32_bf16 v[28:31], v[76:79], v[112:115], v[28:31]
	global_load_lds_dwordx4 v250, s[48:49]
	s_add_u32 m0, s5, 0xcc00
	v_mfma_f32_16x16x32_bf16 v[12:15], v[76:79], v[116:119], v[12:15]
	global_load_lds_dwordx4 v251, s[48:49]
	s_add_u32 s44, s44, 0x80
	s_addc_u32 s45, s45, 0
	s_add_u32 s48, s48, 0x80
	s_addc_u32 s49, s49, 0
	s_mov_b32 s12, 6
.Lg29_loop:
	s_waitcnt vmcnt(8)
	s_barrier
	ds_read_b128 v[64:67], v252 offset:0
	ds_read_b128 v[104:107], v254 offset:32768
	ds_read_b128 v[108:111], v254 offset:34816
	ds_read_b128 v[112:115], v254 offset:36864
	ds_read_b128 v[116:119], v254 offset:38912
	ds_read_b128 v[68:71], v252 offset:2048
	ds_read_b128 v[72:75], v252 offset:4096
	ds_read_b128 v[76:79], v252 offset:6144
	v_mfma_f32_16x16x32_bf16 v[60:63], v[80:83], v[120:123], v[60:63]
	v_mfma_f32_16x16x32_bf16 v[40:43], v[80:83], v[124:127], v[40:43]
	v_mfma_f32_16x16x32_bf16 v[24:27], v[80:83], v[132:135], v[24:27]
	v_mfma_f32_16x16x32_bf16 v[8:11], v[80:83], v[144:147], v[8:11]
	v_mfma_f32_16x16x32_bf16 v[56:59], v[84:87], v[120:123], v[56:59]
	v_mfma_f32_16x16x32_bf16 v[36:39], v[84:87], v[124:127], v[36:39]
	v_mfma_f32_16x16x32_bf16 v[20:23], v[84:87], v[132:135], v[20:23]
	v_mfma_f32_16x16x32_bf16 v[0:3], v[84:87], v[144:147], v[0:3]
	v_mfma_f32_16x16x32_bf16 v[48:51], v[88:91], v[120:123], v[48:51]
	v_mfma_f32_16x16x32_bf16 v[32:35], v[88:91], v[124:127], v[32:35]
	v_mfma_f32_16x16x32_bf16 v[16:19], v[88:91], v[132:135], v[16:19]
	v_mfma_f32_16x16x32_bf16 v[4:7], v[88:91], v[144:147], v[4:7]
	v_mfma_f32_16x16x32_bf16 v[52:55], v[92:95], v[120:123], v[52:55]
	v_mfma_f32_16x16x32_bf16 v[44:47], v[92:95], v[124:127], v[44:47]
	v_mfma_f32_16x16x32_bf16 v[28:31], v[92:95], v[132:135], v[28:31]
	v_mfma_f32_16x16x32_bf16 v[12:15], v[92:95], v[144:147], v[12:15]
	ds_read_b128 v[80:83], v253 offset:0
	ds_read_b128 v[120:123], v255 offset:32768
	ds_read_b128 v[124:127], v255 offset:34816
	ds_read_b128 v[132:135], v255 offset:36864
	ds_read_b128 v[144:147], v255 offset:38912
	ds_read_b128 v[84:87], v253 offset:2048
	ds_read_b128 v[88:91], v253 offset:4096
	ds_read_b128 v[92:95], v253 offset:6144
	s_waitcnt lgkmcnt(14)
	v_mfma_f32_16x16x32_bf16 v[60:63], v[64:67], v[104:107], v[60:63]
	s_waitcnt lgkmcnt(13)
	v_mfma_f32_16x16x32_bf16 v[40:43], v[64:67], v[108:111], v[40:43]
	s_waitcnt lgkmcnt(12)
	v_mfma_f32_16x16x32_bf16 v[24:27], v[64:67], v[112:115], v[24:27]
	s_waitcnt lgkmcnt(11)
	v_mfma_f32_16x16x32_bf16 v[8:11], v[64:67], v[116:119], v[8:11]
	s_waitcnt lgkmcnt(10)
	v_mfma_f32_16x16x32_bf16 v[56:59], v[68:71], v[104:107], v[56:59]
	v_mfma_f32_16x16x32_bf16 v[36:39], v[68:71], v[108:111], v[36:39]
	v_mfma_f32_16x16x32_bf16 v[20:23], v[68:71], v[112:115], v[20:23]
	v_mfma_f32_16x16x32_bf16 v[0:3], v[68:71], v[116:119], v[0:3]
	s_waitcnt lgkmcnt(0)
	s_barrier
	s_add_u32 m0, s5, 0x0
	v_mfma_f32_16x16x32_bf16 v[48:51], v[72:75], v[104:107], v[48:51]
	global_load_lds_dwordx4 v248, s[44:45]
	s_add_u32 m0, s5, 0x400
	v_mfma_f32_16x16x32_bf16 v[32:35], v[72:75], v[108:111], v[32:35]
	global_load_lds_dwordx4 v249, s[44:45]
	s_add_u32 m0, s5, 0x800
	v_mfma_f32_16x16x32_bf16 v[16:19], v[72:75], v[112:115], v[16:19]
	global_load_lds_dwordx4 v250, s[44:45]
	s_add_u32 m0, s5, 0xc00
	v_mfma_f32_16x16x32_bf16 v[4:7], v[72:75], v[116:119], v[4:7]
	global_load_lds_dwordx4 v251, s[44:45]
	s_add_u32 m0, s5, 0x8000
	v_mfma_f32_16x16x32_bf16 v[52:55], v[76:79], v[104:107], v[52:55]
	global_load_lds_dwordx4 v248, s[48:49]
	s_add_u32 m0, s5, 0x8400
	v_mfma_f32_16x16x32_bf16 v[44:47], v[76:79], v[108:111], v[44:47]
	global_load_lds_dwordx4 v249, s[48:49]
	s_add_u32 m0, s5, 0x8800
	v_mfma_f32_16x16x32_bf16 v[28:31], v[76:79], v[112:115], v[28:31]
	global_load_lds_dwordx4 v250, s[48:49]
	s_add_u32 m0, s5, 0x8c00
	v_mfma_f32_16x16x32_bf16 v[12:15], v[76:79], v[116:119], v[12:15]
	global_load_lds_dwordx4 v251, s[48:49]
	s_add_u32 s44, s44, 0x80
	s_addc_u32 s45, s45, 0
	s_add_u32 s48, s48, 0x80
	s_addc_u32 s49, s49, 0
	s_waitcnt vmcnt(8)
	s_barrier
	ds_read_b128 v[64:67], v252 offset:16384
	ds_read_b128 v[104:107], v254 offset:49152
	ds_read_b128 v[108:111], v254 offset:51200
	ds_read_b128 v[112:115], v254 offset:53248
	ds_read_b128 v[116:119], v254 offset:55296
	ds_read_b128 v[68:71], v252 offset:18432
	ds_read_b128 v[72:75], v252 offset:20480
	ds_read_b128 v[76:79], v252 offset:22528
	v_mfma_f32_16x16x32_bf16 v[60:63], v[80:83], v[120:123], v[60:63]
	v_mfma_f32_16x16x32_bf16 v[40:43], v[80:83], v[124:127], v[40:43]
	v_mfma_f32_16x16x32_bf16 v[24:27], v[80:83], v[132:135], v[24:27]
	v_mfma_f32_16x16x32_bf16 v[8:11], v[80:83], v[144:147], v[8:11]
	v_mfma_f32_16x16x32_bf16 v[56:59], v[84:87], v[120:123], v[56:59]
	v_mfma_f32_16x16x32_bf16 v[36:39], v[84:87], v[124:127], v[36:39]
	v_mfma_f32_16x16x32_bf16 v[20:23], v[84:87], v[132:135], v[20:23]
	v_mfma_f32_16x16x32_bf16 v[0:3], v[84:87], v[144:147], v[0:3]
	v_mfma_f32_16x16x32_bf16 v[48:51], v[88:91], v[120:123], v[48:51]
	v_mfma_f32_16x16x32_bf16 v[32:35], v[88:91], v[124:127], v[32:35]
	v_mfma_f32_16x16x32_bf16 v[16:19], v[88:91], v[132:135], v[16:19]
	v_mfma_f32_16x16x32_bf16 v[4:7], v[88:91], v[144:147], v[4:7]
	v_mfma_f32_16x16x32_bf16 v[52:55], v[92:95], v[120:123], v[52:55]
	v_mfma_f32_16x16x32_bf16 v[44:47], v[92:95], v[124:127], v[44:47]
	v_mfma_f32_16x16x32_bf16 v[28:31], v[92:95], v[132:135], v[28:31]
	v_mfma_f32_16x16x32_bf16 v[12:15], v[92:95], v[144:147], v[12:15]
	ds_read_b128 v[80:83], v253 offset:16384
	ds_read_b128 v[120:123], v255 offset:49152
	ds_read_b128 v[124:127], v255 offset:51200
	ds_read_b128 v[132:135], v255 offset:53248
	ds_read_b128 v[144:147], v255 offset:55296
	ds_read_b128 v[84:87], v253 offset:18432
	ds_read_b128 v[88:91], v253 offset:20480
	ds_read_b128 v[92:95], v253 offset:22528
	s_waitcnt lgkmcnt(14)
	v_mfma_f32_16x16x32_bf16 v[60:63], v[64:67], v[104:107], v[60:63]
	s_waitcnt lgkmcnt(13)
	v_mfma_f32_16x16x32_bf16 v[40:43], v[64:67], v[108:111], v[40:43]
	s_waitcnt lgkmcnt(12)
	v_mfma_f32_16x16x32_bf16 v[24:27], v[64:67], v[112:115], v[24:27]
	s_waitcnt lgkmcnt(11)
	v_mfma_f32_16x16x32_bf16 v[8:11], v[64:67], v[116:119], v[8:11]
	s_waitcnt lgkmcnt(10)
	v_mfma_f32_16x16x32_bf16 v[56:59], v[68:71], v[104:107], v[56:59]
	v_mfma_f32_16x16x32_bf16 v[36:39], v[68:71], v[108:111], v[36:39]
	v_mfma_f32_16x16x32_bf16 v[20:23], v[68:71], v[112:115], v[20:23]
	v_mfma_f32_16x16x32_bf16 v[0:3], v[68:71], v[116:119], v[0:3]
	s_waitcnt lgkmcnt(0)
	s_barrier
	s_add_u32 m0, s5, 0x4000
	v_mfma_f32_16x16x32_bf16 v[48:51], v[72:75], v[104:107], v[48:51]
	global_load_lds_dwordx4 v248, s[44:45]
	s_add_u32 m0, s5, 0x4400
	v_mfma_f32_16x16x32_bf16 v[32:35], v[72:75], v[108:111], v[32:35]
	global_load_lds_dwordx4 v249, s[44:45]
	s_add_u32 m0, s5, 0x4800
	v_mfma_f32_16x16x32_bf16 v[16:19], v[72:75], v[112:115], v[16:19]
	global_load_lds_dwordx4 v250, s[44:45]
	s_add_u32 m0, s5, 0x4c00
	v_mfma_f32_16x16x32_bf16 v[4:7], v[72:75], v[116:119], v[4:7]
	global_load_lds_dwordx4 v251, s[44:45]
	s_add_u32 m0, s5, 0xc000
	v_mfma_f32_16x16x32_bf16 v[52:55], v[76:79], v[104:107], v[52:55]
	global_load_lds_dwordx4 v248, s[48:49]
	s_add_u32 m0, s5, 0xc400
	v_mfma_f32_16x16x32_bf16 v[44:47], v[76:79], v[108:111], v[44:47]
	global_load_lds_dwordx4 v249, s[48:49]
	s_add_u32 m0, s5, 0xc800
	v_mfma_f32_16x16x32_bf16 v[28:31], v[76:79], v[112:115], v[28:31]
	global_load_lds_dwordx4 v250, s[48:49]
	s_add_u32 m0, s5, 0xcc00
	v_mfma_f32_16x16x32_bf16 v[12:15], v[76:79], v[116:119], v[12:15]
	global_load_lds_dwordx4 v251, s[48:49]
	s_add_u32 s44, s44, 0x80
	s_addc_u32 s45, s45, 0
	s_add_u32 s48, s48, 0x80
	s_addc_u32 s49, s49, 0
	s_sub_u32 s12, s12, 1
	s_cmp_lg_u32 s12, 0
	s_cbranch_scc1 .Lg29_loop
	s_waitcnt vmcnt(8)
	s_barrier
	ds_read_b128 v[64:67], v252 offset:0
	ds_read_b128 v[104:107], v254 offset:32768
	ds_read_b128 v[108:111], v254 offset:34816
	ds_read_b128 v[112:115], v254 offset:36864
	ds_read_b128 v[116:119], v254 offset:38912
	ds_read_b128 v[68:71], v252 offset:2048
	ds_read_b128 v[72:75], v252 offset:4096
	ds_read_b128 v[76:79], v252 offset:6144
	v_mfma_f32_16x16x32_bf16 v[60:63], v[80:83], v[120:123], v[60:63]
	v_mfma_f32_16x16x32_bf16 v[40:43], v[80:83], v[124:127], v[40:43]
	v_mfma_f32_16x16x32_bf16 v[24:27], v[80:83], v[132:135], v[24:27]
	v_mfma_f32_16x16x32_bf16 v[8:11], v[80:83], v[144:147], v[8:11]
	v_mfma_f32_16x16x32_bf16 v[56:59], v[84:87], v[120:123], v[56:59]
	v_mfma_f32_16x16x32_bf16 v[36:39], v[84:87], v[124:127], v[36:39]
	v_mfma_f32_16x16x32_bf16 v[20:23], v[84:87], v[132:135], v[20:23]
	v_mfma_f32_16x16x32_bf16 v[0:3], v[84:87], v[144:147], v[0:3]
	v_mfma_f32_16x16x32_bf16 v[48:51], v[88:91], v[120:123], v[48:51]
	v_mfma_f32_16x16x32_bf16 v[32:35], v[88:91], v[124:127], v[32:35]
	v_mfma_f32_16x16x32_bf16 v[16:19], v[88:91], v[132:135], v[16:19]
	v_mfma_f32_16x16x32_bf16 v[4:7], v[88:91], v[144:147], v[4:7]
	v_mfma_f32_16x16x32_bf16 v[52:55], v[92:95], v[120:123], v[52:55]
	v_mfma_f32_16x16x32_bf16 v[44:47], v[92:95], v[124:127], v[44:47]
	v_mfma_f32_16x16x32_bf16 v[28:31], v[92:95], v[132:135], v[28:31]
	v_mfma_f32_16x16x32_bf16 v[12:15], v[92:95], v[144:147], v[12:15]
	ds_read_b128 v[80:83], v253 offset:0
	ds_read_b128 v[120:123], v255 offset:32768
	ds_read_b128 v[124:127], v255 offset:34816
	ds_read_b128 v[132:135], v255 offset:36864
	ds_read_b128 v[144:147], v255 offset:38912
	ds_read_b128 v[84:87], v253 offset:2048
	ds_read_b128 v[88:91], v253 offset:4096
	ds_read_b128 v[92:95], v253 offset:6144
	s_waitcnt lgkmcnt(14)
	v_mfma_f32_16x16x32_bf16 v[60:63], v[64:67], v[104:107], v[60:63]
	s_waitcnt lgkmcnt(13)
	v_mfma_f32_16x16x32_bf16 v[40:43], v[64:67], v[108:111], v[40:43]
	s_waitcnt lgkmcnt(12)
	v_mfma_f32_16x16x32_bf16 v[24:27], v[64:67], v[112:115], v[24:27]
	s_waitcnt lgkmcnt(11)
	v_mfma_f32_16x16x32_bf16 v[8:11], v[64:67], v[116:119], v[8:11]
	s_waitcnt lgkmcnt(10)
	v_mfma_f32_16x16x32_bf16 v[56:59], v[68:71], v[104:107], v[56:59]
	v_mfma_f32_16x16x32_bf16 v[36:39], v[68:71], v[108:111], v[36:39]
	v_mfma_f32_16x16x32_bf16 v[20:23], v[68:71], v[112:115], v[20:23]
	v_mfma_f32_16x16x32_bf16 v[0:3], v[68:71], v[116:119], v[0:3]
	s_waitcnt lgkmcnt(0)
	s_barrier
	v_mfma_f32_16x16x32_bf16 v[48:51], v[72:75], v[104:107], v[48:51]
	v_mfma_f32_16x16x32_bf16 v[32:35], v[72:75], v[108:111], v[32:35]
	v_mfma_f32_16x16x32_bf16 v[16:19], v[72:75], v[112:115], v[16:19]
	v_mfma_f32_16x16x32_bf16 v[4:7], v[72:75], v[116:119], v[4:7]
	v_mfma_f32_16x16x32_bf16 v[52:55], v[76:79], v[104:107], v[52:55]
	v_mfma_f32_16x16x32_bf16 v[44:47], v[76:79], v[108:111], v[44:47]
	v_mfma_f32_16x16x32_bf16 v[28:31], v[76:79], v[112:115], v[28:31]
	v_mfma_f32_16x16x32_bf16 v[12:15], v[76:79], v[116:119], v[12:15]
	s_waitcnt vmcnt(0)
	s_barrier
	ds_read_b128 v[64:67], v252 offset:16384
	ds_read_b128 v[104:107], v254 offset:49152
	ds_read_b128 v[108:111], v254 offset:51200
	ds_read_b128 v[112:115], v254 offset:53248
	ds_read_b128 v[116:119], v254 offset:55296
	ds_read_b128 v[68:71], v252 offset:18432
	ds_read_b128 v[72:75], v252 offset:20480
	ds_read_b128 v[76:79], v252 offset:22528
	v_mfma_f32_16x16x32_bf16 v[60:63], v[80:83], v[120:123], v[60:63]
	v_mfma_f32_16x16x32_bf16 v[40:43], v[80:83], v[124:127], v[40:43]
	v_mfma_f32_16x16x32_bf16 v[24:27], v[80:83], v[132:135], v[24:27]
	v_mfma_f32_16x16x32_bf16 v[8:11], v[80:83], v[144:147], v[8:11]
	v_mfma_f32_16x16x32_bf16 v[56:59], v[84:87], v[120:123], v[56:59]
	v_mfma_f32_16x16x32_bf16 v[36:39], v[84:87], v[124:127], v[36:39]
	v_mfma_f32_16x16x32_bf16 v[20:23], v[84:87], v[132:135], v[20:23]
	v_mfma_f32_16x16x32_bf16 v[0:3], v[84:87], v[144:147], v[0:3]
	v_mfma_f32_16x16x32_bf16 v[48:51], v[88:91], v[120:123], v[48:51]
	v_mfma_f32_16x16x32_bf16 v[32:35], v[88:91], v[124:127], v[32:35]
	v_mfma_f32_16x16x32_bf16 v[16:19], v[88:91], v[132:135], v[16:19]
	v_mfma_f32_16x16x32_bf16 v[4:7], v[88:91], v[144:147], v[4:7]
	v_mfma_f32_16x16x32_bf16 v[52:55], v[92:95], v[120:123], v[52:55]
	v_mfma_f32_16x16x32_bf16 v[44:47], v[92:95], v[124:127], v[44:47]
	v_mfma_f32_16x16x32_bf16 v[28:31], v[92:95], v[132:135], v[28:31]
	v_mfma_f32_16x16x32_bf16 v[12:15], v[92:95], v[144:147], v[12:15]
	ds_read_b128 v[80:83], v253 offset:16384
	ds_read_b128 v[120:123], v255 offset:49152
	ds_read_b128 v[124:127], v255 offset:51200
	ds_read_b128 v[132:135], v255 offset:53248
	ds_read_b128 v[144:147], v255 offset:55296
	ds_read_b128 v[84:87], v253 offset:18432
	ds_read_b128 v[88:91], v253 offset:20480
	ds_read_b128 v[92:95], v253 offset:22528
	s_waitcnt lgkmcnt(14)
	v_mfma_f32_16x16x32_bf16 v[60:63], v[64:67], v[104:107], v[60:63]
	s_waitcnt lgkmcnt(13)
	v_mfma_f32_16x16x32_bf16 v[40:43], v[64:67], v[108:111], v[40:43]
	s_waitcnt lgkmcnt(12)
	v_mfma_f32_16x16x32_bf16 v[24:27], v[64:67], v[112:115], v[24:27]
	s_waitcnt lgkmcnt(11)
	v_mfma_f32_16x16x32_bf16 v[8:11], v[64:67], v[116:119], v[8:11]
	s_waitcnt lgkmcnt(10)
	v_mfma_f32_16x16x32_bf16 v[56:59], v[68:71], v[104:107], v[56:59]
	v_mfma_f32_16x16x32_bf16 v[36:39], v[68:71], v[108:111], v[36:39]
	v_mfma_f32_16x16x32_bf16 v[20:23], v[68:71], v[112:115], v[20:23]
	v_mfma_f32_16x16x32_bf16 v[0:3], v[68:71], v[116:119], v[0:3]
	s_waitcnt lgkmcnt(0)
	s_barrier
	v_mfma_f32_16x16x32_bf16 v[48:51], v[72:75], v[104:107], v[48:51]
	v_mfma_f32_16x16x32_bf16 v[32:35], v[72:75], v[108:111], v[32:35]
	v_mfma_f32_16x16x32_bf16 v[16:19], v[72:75], v[112:115], v[16:19]
	v_mfma_f32_16x16x32_bf16 v[4:7], v[72:75], v[116:119], v[4:7]
	v_mfma_f32_16x16x32_bf16 v[52:55], v[76:79], v[104:107], v[52:55]
	v_mfma_f32_16x16x32_bf16 v[44:47], v[76:79], v[108:111], v[44:47]
	v_mfma_f32_16x16x32_bf16 v[28:31], v[76:79], v[112:115], v[28:31]
	v_mfma_f32_16x16x32_bf16 v[12:15], v[76:79], v[116:119], v[12:15]
	v_mfma_f32_16x16x32_bf16 v[60:63], v[80:83], v[120:123], v[60:63]
	v_mfma_f32_16x16x32_bf16 v[40:43], v[80:83], v[124:127], v[40:43]
	v_mfma_f32_16x16x32_bf16 v[24:27], v[80:83], v[132:135], v[24:27]
	v_mfma_f32_16x16x32_bf16 v[8:11], v[80:83], v[144:147], v[8:11]
	v_mfma_f32_16x16x32_bf16 v[56:59], v[84:87], v[120:123], v[56:59]
	v_mfma_f32_16x16x32_bf16 v[36:39], v[84:87], v[124:127], v[36:39]
	v_mfma_f32_16x16x32_bf16 v[20:23], v[84:87], v[132:135], v[20:23]
	v_mfma_f32_16x16x32_bf16 v[0:3], v[84:87], v[144:147], v[0:3]
	v_mfma_f32_16x16x32_bf16 v[48:51], v[88:91], v[120:123], v[48:51]
	v_mfma_f32_16x16x32_bf16 v[32:35], v[88:91], v[124:127], v[32:35]
	v_mfma_f32_16x16x32_bf16 v[16:19], v[88:91], v[132:135], v[16:19]
	v_mfma_f32_16x16x32_bf16 v[4:7], v[88:91], v[144:147], v[4:7]
	v_mfma_f32_16x16x32_bf16 v[52:55], v[92:95], v[120:123], v[52:55]
	v_mfma_f32_16x16x32_bf16 v[44:47], v[92:95], v[124:127], v[44:47]
	v_mfma_f32_16x16x32_bf16 v[28:31], v[92:95], v[132:135], v[28:31]
	v_mfma_f32_16x16x32_bf16 v[12:15], v[92:95], v[144:147], v[12:15]
	s_nop 7
	s_nop 1
	v_sub_co_u32_e32 v64, vcc, s43, v141
	s_nop 0
	v_readfirstlane_b32 s5, v64
	s_lshr_b32 s5, s5, 10
	s_add_i32 s5, s5, 1
	s_and_b64 s[44:45], vcc, exec
	s_cselect_b32 s5, 0, s5
	s_mul_hi_u32 s12, s5, 0x6000
	s_mulk_i32 s5, 0x6000
	s_add_u32 s44, s2, s5
	v_or_b32_e32 v64, s4, v139
	s_addc_u32 s45, s3, s12
	v_ashrrev_i32_e32 v65, 31, v64
	v_lshl_add_u64 v[66:67], v[64:65], 2, s[44:45]
	global_load_dword v105, v[66:67], off
	s_waitcnt vmcnt(7)
	v_cndmask_b32_e64 v68, 0, 1, s[10:11]
	v_mov_b32_e32 v104, 0
	v_cmp_ne_u32_e64 s[4:5], 1, v68
	s_andn2_b64 vcc, exec, s[10:11]
	v_mov_b32_e32 v106, 0
	s_cbranch_vccnz .LBB0_2727
	v_lshl_add_u64 v[68:69], v[64:65], 2, s[6:7]
	global_load_dword v106, v[68:69], off
